# gemm loop: next-segment setup moved after the barrier; 16-byte stores write-through (sc0 sc1)
# speedup vs baseline: 1.0047x; 1.0047x over previous
; __global__ void __launch_bounds__(512) fwd_megakernel(Params p) {
;     ...
;         { const size_t nc4 = (size_t)NCTX * DM / 4;
;           for (size_t i = (size_t)bid * 512 + tid; i < nc4; i += (size_t)G * 512) ((f32x4*)(X + (size_t)NLAT * DM))[i] = ((const f32x4*)p.in[2])[i]; }
.LBB0_39:
	v_lshl_add_u64 v[4:5], s[60:61], 0, v[2:3]
	global_load_dwordx4 v[4:7], v[4:5], off
	v_lshl_add_u64 v[0:1], v[0:1], 0, s[10:11]
	v_cmp_lt_u64_e32 vcc, s[18:19], v[0:1]
	v_lshl_add_u64 v[8:9], s[4:5], 0, v[2:3]
	v_lshl_add_u64 v[2:3], v[2:3], 0, s[14:15]
	s_or_b64 s[16:17], vcc, s[16:17]
	s_waitcnt vmcnt(0)
	global_store_dwordx4 v[8:9], v[4:7], off sc0 sc1
	s_andn2_b64 exec, exec, s[16:17]
	s_cbranch_execnz .LBB0_39

; __device__ __forceinline__ bf16_t f2bf(float x) { return (bf16_t)(cvt_pk_bf16(x, 0.f) & 0xffffu); }
; __device__ __forceinline__ void titem_store(const TItem& it, int tid, const f32x4 (&v)[4], bf16_t* T) {
; #pragma unroll
;     for (int i = 0; i < 4; ++i) { const int idx = tid + 512 * i, kk = idx >> 4, r4 = idx & 15;
; #pragma unroll
;         for (int j = 0; j < 4; ++j) T[(4 * r4 + j) * 136 + kk] = f2bf(v[i][j]); }
;     __syncthreads();
; #pragma unroll
;     for (int i = 0; i < 2; ++i) { const int c = tid + 512 * i, row = c >> 4, k8 = (c & 15) * 8;
;         const u32x4 w = *(const u32x4*)(T + row * 136 + k8);
;         *(u32x4*)(it.dst + (size_t)(it.r0 + row) * it.K + it.k0 + k8) = w; }
; }
;     ...
;         titem_store(c0, tid, v0, (bf16_t*)(lds + buf * 17408));
;         buf ^= 1; c0 = c1; c1 = c2;
; #pragma unroll
;         for (int q = 0; q < 4; ++q) { v0[q] = v1[q]; v1[q] = v2[q]; }
.LBB0_110:
	s_mul_i32 s3, s34, 0x4400
	s_add_i32 s3, s3, 0
	v_add_u32_e32 v34, s3, v44
	v_cvt_pk_bf16_f32 v0, v0, v33
	v_lshl_add_u32 v35, v37, 1, v34
	ds_write_b16 v35, v0
	v_cvt_pk_bf16_f32 v0, v1, v33
	ds_write_b16 v35, v0 offset:272
	v_cvt_pk_bf16_f32 v0, v2, v33
	ds_write_b16 v35, v0 offset:544
	v_cvt_pk_bf16_f32 v0, v3, v33
	ds_write_b16 v35, v0 offset:816
	v_cvt_pk_bf16_f32 v0, v4, v33
	v_lshl_add_u32 v1, v39, 1, v34
	ds_write_b16 v1, v0
	v_cvt_pk_bf16_f32 v0, v5, v33
	ds_write_b16 v1, v0 offset:272
	v_cvt_pk_bf16_f32 v0, v6, v33
	ds_write_b16 v1, v0 offset:544
	v_cvt_pk_bf16_f32 v0, v7, v33
	ds_write_b16 v1, v0 offset:816
	v_cvt_pk_bf16_f32 v0, v8, v33
	v_lshl_add_u32 v1, v40, 1, v34
	ds_write_b16 v1, v0
	v_cvt_pk_bf16_f32 v0, v9, v33
	ds_write_b16 v1, v0 offset:272
	v_cvt_pk_bf16_f32 v0, v10, v33
	ds_write_b16 v1, v0 offset:544
	v_cvt_pk_bf16_f32 v0, v11, v33
	ds_write_b16 v1, v0 offset:816
	v_cvt_pk_bf16_f32 v0, v12, v33
	v_lshl_add_u32 v1, v41, 1, v34
	ds_write_b16 v1, v0
	v_cvt_pk_bf16_f32 v0, v13, v33
	ds_write_b16 v1, v0 offset:272
	v_cvt_pk_bf16_f32 v0, v14, v33
	v_add_u32_e32 v4, s22, v37
	ds_write_b16 v1, v0 offset:544
	v_cvt_pk_bf16_f32 v0, v15, v33
	v_add_u32_e32 v10, s3, v32
	v_ashrrev_i32_e32 v7, 31, v4
	v_mad_u64_u32 v[4:5], s[4:5], v4, s13, 0
	ds_write_b16 v1, v0 offset:816
	v_add_u32_e32 v0, v10, v42
	v_mov_b32_e32 v6, v5
	s_waitcnt lgkmcnt(0)
	s_barrier
	ds_read_b128 v[0:3], v0
	v_mad_u64_u32 v[6:7], s[4:5], v7, s13, v[6:7]
	v_mov_b32_e32 v5, v6
	s_ashr_i32 s3, s2, 31
	v_lshl_add_u64 v[4:5], v[4:5], 1, s[0:1]
	s_lshl_b64 s[2:3], s[2:3], 1
	v_lshl_add_u64 v[4:5], v[4:5], 0, s[2:3]
	v_lshl_add_u64 v[8:9], v[4:5], 0, v[32:33]
	v_add_u32_e32 v4, v10, v43
	ds_read_b128 v[4:7], v4
	s_waitcnt lgkmcnt(1)
	global_store_dwordx4 v[8:9], v[0:3], off sc0 sc1
	s_xor_b32 s34, s34, 1
	s_add_i32 s36, s36, s96
	v_add_u32_e32 v0, s22, v39
	v_ashrrev_i32_e32 v3, 31, v0
	v_mad_u64_u32 v[0:1], s[4:5], v0, s13, 0
	v_mov_b32_e32 v2, v1
	v_mad_u64_u32 v[2:3], s[4:5], v3, s13, v[2:3]
	v_mov_b32_e32 v1, v2
	v_lshl_add_u64 v[0:1], v[0:1], 1, s[0:1]
	v_lshl_add_u64 v[0:1], v[0:1], 0, s[2:3]
	v_lshl_add_u64 v[0:1], v[0:1], 0, v[32:33]
	s_waitcnt lgkmcnt(0)
	global_store_dwordx4 v[0:1], v[4:7], off sc0 sc1
	s_cmpk_gt_i32 s36, 0x101f
	s_mov_b64 s[0:1], s[14:15]
	s_mov_b32 s13, s39
	s_mov_b32 s22, s38
	s_mov_b32 s2, s37
	v_mov_b32_e32 v0, v60
	v_mov_b32_e32 v1, v56
	v_mov_b32_e32 v2, v52
	v_mov_b32_e32 v3, v48
	v_mov_b32_e32 v4, v59
	v_mov_b32_e32 v5, v55
	v_mov_b32_e32 v6, v51
	v_mov_b32_e32 v7, v47
	v_mov_b32_e32 v8, v58
	v_mov_b32_e32 v9, v54
	v_mov_b32_e32 v10, v50
	v_mov_b32_e32 v11, v46
	v_mov_b32_e32 v12, v57
	v_mov_b32_e32 v13, v53
	v_mov_b32_e32 v14, v49
	v_mov_b32_e32 v15, v45
	s_waitcnt vmcnt(2)
	v_mov_b32_e32 v34, v16
	v_mov_b32_e32 v35, v17
	v_mov_b32_e32 v61, v18
	v_mov_b32_e32 v62, v19
	v_mov_b32_e32 v63, v20
	v_mov_b32_e32 v64, v21
	v_mov_b32_e32 v65, v22
	v_mov_b32_e32 v66, v23
	v_mov_b32_e32 v67, v24
	v_mov_b32_e32 v68, v25
	v_mov_b32_e32 v69, v26
	v_mov_b32_e32 v70, v27
	v_mov_b32_e32 v71, v28
	v_mov_b32_e32 v72, v29
	v_mov_b32_e32 v73, v30
	v_mov_b32_e32 v74, v31
	s_cbranch_scc1 .LBB0_136

; __device__ __forceinline__ bf16_t f2bf(float x) { return (bf16_t)(cvt_pk_bf16(x, 0.f) & 0xffffu); }
; __device__ __forceinline__ void titem_store(const TItem& it, int tid, const f32x4 (&v)[4], bf16_t* T) {
; #pragma unroll
;     for (int i = 0; i < 4; ++i) { const int idx = tid + 512 * i, kk = idx >> 4, r4 = idx & 15;
; #pragma unroll
;         for (int j = 0; j < 4; ++j) T[(4 * r4 + j) * 136 + kk] = f2bf(v[i][j]); }
;     __syncthreads();
; #pragma unroll
;     for (int i = 0; i < 2; ++i) { const int c = tid + 512 * i, row = c >> 4, k8 = (c & 15) * 8;
;         const u32x4 w = *(const u32x4*)(T + row * 136 + k8);
;         *(u32x4*)(it.dst + (size_t)(it.r0 + row) * it.K + it.k0 + k8) = w; }
; }
;     ...
;         titem_store(c0, tid, v0, (bf16_t*)(lds + buf * 17408));
;         buf ^= 1; c0 = c1; c1 = c2;
; #pragma unroll
;         for (int q = 0; q < 4; ++q) { v0[q] = v1[q]; v1[q] = v2[q]; }
.LBB0_347:
	s_mul_i32 s5, s44, 0x4400
	s_add_i32 s5, s5, 0
	v_add_u32_e32 v34, s5, v45
	v_cvt_pk_bf16_f32 v0, v0, v33
	v_lshl_add_u32 v35, v37, 1, v34
	ds_write_b16 v35, v0
	v_cvt_pk_bf16_f32 v0, v1, v33
	ds_write_b16 v35, v0 offset:272
	v_cvt_pk_bf16_f32 v0, v2, v33
	ds_write_b16 v35, v0 offset:544
	v_cvt_pk_bf16_f32 v0, v3, v33
	ds_write_b16 v35, v0 offset:816
	v_cvt_pk_bf16_f32 v0, v4, v33
	v_lshl_add_u32 v1, v40, 1, v34
	ds_write_b16 v1, v0
	v_cvt_pk_bf16_f32 v0, v5, v33
	ds_write_b16 v1, v0 offset:272
	v_cvt_pk_bf16_f32 v0, v6, v33
	ds_write_b16 v1, v0 offset:544
	v_cvt_pk_bf16_f32 v0, v7, v33
	ds_write_b16 v1, v0 offset:816
	v_cvt_pk_bf16_f32 v0, v8, v33
	v_lshl_add_u32 v1, v41, 1, v34
	ds_write_b16 v1, v0
	v_cvt_pk_bf16_f32 v0, v9, v33
	ds_write_b16 v1, v0 offset:272
	v_cvt_pk_bf16_f32 v0, v10, v33
	ds_write_b16 v1, v0 offset:544
	v_cvt_pk_bf16_f32 v0, v11, v33
	ds_write_b16 v1, v0 offset:816
	v_cvt_pk_bf16_f32 v0, v12, v33
	v_lshl_add_u32 v1, v42, 1, v34
	ds_write_b16 v1, v0
	v_cvt_pk_bf16_f32 v0, v13, v33
	ds_write_b16 v1, v0 offset:272
	v_cvt_pk_bf16_f32 v0, v14, v33
	v_add_u32_e32 v4, s24, v37
	ds_write_b16 v1, v0 offset:544
	v_cvt_pk_bf16_f32 v0, v15, v33
	v_add_u32_e32 v10, s5, v32
	v_ashrrev_i32_e32 v7, 31, v4
	v_mad_u64_u32 v[4:5], s[16:17], v4, s13, 0
	ds_write_b16 v1, v0 offset:816
	v_add_u32_e32 v0, v10, v43
	v_mov_b32_e32 v6, v5
	s_waitcnt lgkmcnt(0)
	s_barrier
	ds_read_b128 v[0:3], v0
	v_mad_u64_u32 v[6:7], s[16:17], v7, s13, v[6:7]
	v_mov_b32_e32 v5, v6
	s_ashr_i32 s5, s4, 31
	v_lshl_add_u64 v[4:5], v[4:5], 1, s[2:3]
	s_lshl_b64 s[4:5], s[4:5], 1
	v_lshl_add_u64 v[4:5], v[4:5], 0, s[4:5]
	v_lshl_add_u64 v[8:9], v[4:5], 0, v[32:33]
	v_add_u32_e32 v4, v10, v44
	ds_read_b128 v[4:7], v4
	s_waitcnt lgkmcnt(1)
	global_store_dwordx4 v[8:9], v[0:3], off sc0 sc1
	s_xor_b32 s44, s44, 1
	s_add_i32 s50, s50, s96
	v_add_u32_e32 v0, s24, v40
	v_ashrrev_i32_e32 v3, 31, v0
	v_mad_u64_u32 v[0:1], s[16:17], v0, s13, 0
	v_mov_b32_e32 v2, v1
	v_mad_u64_u32 v[2:3], s[16:17], v3, s13, v[2:3]
	v_mov_b32_e32 v1, v2
	v_lshl_add_u64 v[0:1], v[0:1], 1, s[2:3]
	v_lshl_add_u64 v[0:1], v[0:1], 0, s[4:5]
	v_lshl_add_u64 v[0:1], v[0:1], 0, v[32:33]
	s_waitcnt lgkmcnt(0)
	global_store_dwordx4 v[0:1], v[4:7], off sc0 sc1
	s_cmpk_gt_i32 s50, 0x74f
	s_mov_b64 s[2:3], s[14:15]
	s_mov_b32 s13, s53
	s_mov_b32 s24, s52
	s_mov_b32 s4, s51
	v_mov_b32_e32 v0, v61
	v_mov_b32_e32 v1, v57
	v_mov_b32_e32 v2, v53
	v_mov_b32_e32 v3, v49
	v_mov_b32_e32 v4, v60
	v_mov_b32_e32 v5, v56
	v_mov_b32_e32 v6, v52
	v_mov_b32_e32 v7, v48
	v_mov_b32_e32 v8, v59
	v_mov_b32_e32 v9, v55
	v_mov_b32_e32 v10, v51
	v_mov_b32_e32 v11, v47
	v_mov_b32_e32 v12, v58
	v_mov_b32_e32 v13, v54
	v_mov_b32_e32 v14, v50
	v_mov_b32_e32 v15, v46
	s_waitcnt vmcnt(2)
	v_mov_b32_e32 v34, v16
	v_mov_b32_e32 v35, v17
	v_mov_b32_e32 v62, v18
	v_mov_b32_e32 v63, v19
	v_mov_b32_e32 v64, v20
	v_mov_b32_e32 v65, v21
	v_mov_b32_e32 v66, v22
	v_mov_b32_e32 v67, v23
	v_mov_b32_e32 v68, v24
	v_mov_b32_e32 v69, v25
	v_mov_b32_e32 v70, v26
	v_mov_b32_e32 v71, v27
	v_mov_b32_e32 v72, v28
	v_mov_b32_e32 v73, v29
	v_mov_b32_e32 v74, v30
	v_mov_b32_e32 v75, v31
	s_cbranch_scc1 .LBB0_439

; __device__ __forceinline__ bf16_t f2bf(float x) { return (bf16_t)(cvt_pk_bf16(x, 0.f) & 0xffffu); }
; __device__ __forceinline__ void titem_store(const TItem& it, int tid, const f32x4 (&v)[4], bf16_t* T) {
; #pragma unroll
;     for (int i = 0; i < 4; ++i) { const int idx = tid + 512 * i, kk = idx >> 4, r4 = idx & 15;
; #pragma unroll
;         for (int j = 0; j < 4; ++j) T[(4 * r4 + j) * 136 + kk] = f2bf(v[i][j]); }
;     __syncthreads();
; #pragma unroll
;     for (int i = 0; i < 2; ++i) { const int c = tid + 512 * i, row = c >> 4, k8 = (c & 15) * 8;
;         const u32x4 w = *(const u32x4*)(T + row * 136 + k8);
;         *(u32x4*)(it.dst + (size_t)(it.r0 + row) * it.K + it.k0 + k8) = w; }
; }
;     ...
;         titem_store(c0, tid, v0, (bf16_t*)(lds + buf * 17408));
;         buf ^= 1; c0 = c1; c1 = c2;
; #pragma unroll
;         for (int q = 0; q < 4; ++q) { v0[q] = v1[q]; v1[q] = v2[q]; }
.LBB0_650:
	s_mul_i32 s3, s42, 0x4400
	s_add_i32 s3, s3, 0
	v_add_u32_e32 v34, s3, v45
	v_cvt_pk_bf16_f32 v0, v0, v33
	v_lshl_add_u32 v35, v37, 1, v34
	ds_write_b16 v35, v0
	v_cvt_pk_bf16_f32 v0, v1, v33
	ds_write_b16 v35, v0 offset:272
	v_cvt_pk_bf16_f32 v0, v2, v33
	ds_write_b16 v35, v0 offset:544
	v_cvt_pk_bf16_f32 v0, v3, v33
	ds_write_b16 v35, v0 offset:816
	v_cvt_pk_bf16_f32 v0, v4, v33
	v_lshl_add_u32 v1, v40, 1, v34
	ds_write_b16 v1, v0
	v_cvt_pk_bf16_f32 v0, v5, v33
	ds_write_b16 v1, v0 offset:272
	v_cvt_pk_bf16_f32 v0, v6, v33
	ds_write_b16 v1, v0 offset:544
	v_cvt_pk_bf16_f32 v0, v7, v33
	ds_write_b16 v1, v0 offset:816
	v_cvt_pk_bf16_f32 v0, v8, v33
	v_lshl_add_u32 v1, v41, 1, v34
	ds_write_b16 v1, v0
	v_cvt_pk_bf16_f32 v0, v9, v33
	ds_write_b16 v1, v0 offset:272
	v_cvt_pk_bf16_f32 v0, v10, v33
	ds_write_b16 v1, v0 offset:544
	v_cvt_pk_bf16_f32 v0, v11, v33
	ds_write_b16 v1, v0 offset:816
	v_cvt_pk_bf16_f32 v0, v12, v33
	v_lshl_add_u32 v1, v42, 1, v34
	ds_write_b16 v1, v0
	v_cvt_pk_bf16_f32 v0, v13, v33
	ds_write_b16 v1, v0 offset:272
	v_cvt_pk_bf16_f32 v0, v14, v33
	v_add_u32_e32 v4, s22, v37
	ds_write_b16 v1, v0 offset:544
	v_cvt_pk_bf16_f32 v0, v15, v33
	v_add_u32_e32 v10, s3, v32
	v_ashrrev_i32_e32 v7, 31, v4
	v_mad_u64_u32 v[4:5], s[14:15], v4, s13, 0
	ds_write_b16 v1, v0 offset:816
	v_add_u32_e32 v0, v10, v43
	v_mov_b32_e32 v6, v5
	s_waitcnt lgkmcnt(0)
	s_barrier
	ds_read_b128 v[0:3], v0
	v_mad_u64_u32 v[6:7], s[14:15], v7, s13, v[6:7]
	v_mov_b32_e32 v5, v6
	s_ashr_i32 s3, s2, 31
	v_lshl_add_u64 v[4:5], v[4:5], 1, s[0:1]
	s_lshl_b64 s[2:3], s[2:3], 1
	v_lshl_add_u64 v[4:5], v[4:5], 0, s[2:3]
	v_lshl_add_u64 v[8:9], v[4:5], 0, v[32:33]
	v_add_u32_e32 v4, v10, v44
	ds_read_b128 v[4:7], v4
	s_waitcnt lgkmcnt(1)
	global_store_dwordx4 v[8:9], v[0:3], off sc0 sc1
	s_xor_b32 s42, s42, 1
	s_add_i32 s46, s46, s96
	v_add_u32_e32 v0, s22, v40
	v_ashrrev_i32_e32 v3, 31, v0
	v_mad_u64_u32 v[0:1], s[14:15], v0, s13, 0
	v_mov_b32_e32 v2, v1
	v_mad_u64_u32 v[2:3], s[14:15], v3, s13, v[2:3]
	v_mov_b32_e32 v1, v2
	v_lshl_add_u64 v[0:1], v[0:1], 1, s[0:1]
	v_lshl_add_u64 v[0:1], v[0:1], 0, s[2:3]
	v_lshl_add_u64 v[0:1], v[0:1], 0, v[32:33]
	s_waitcnt lgkmcnt(0)
	global_store_dwordx4 v[0:1], v[4:7], off sc0 sc1
	s_cmpk_gt_i32 s46, 0x74f
	s_mov_b64 s[0:1], s[10:11]
	s_mov_b32 s13, s51
	s_mov_b32 s22, s50
	s_mov_b32 s2, s47
	v_mov_b32_e32 v0, v61
	v_mov_b32_e32 v1, v57
	v_mov_b32_e32 v2, v53
	v_mov_b32_e32 v3, v49
	v_mov_b32_e32 v4, v60
	v_mov_b32_e32 v5, v56
	v_mov_b32_e32 v6, v52
	v_mov_b32_e32 v7, v48
	v_mov_b32_e32 v8, v59
	v_mov_b32_e32 v9, v55
	v_mov_b32_e32 v10, v51
	v_mov_b32_e32 v11, v47
	v_mov_b32_e32 v12, v58
	v_mov_b32_e32 v13, v54
	v_mov_b32_e32 v14, v50
	v_mov_b32_e32 v15, v46
	s_waitcnt vmcnt(2)
	v_mov_b32_e32 v34, v16
	v_mov_b32_e32 v35, v17
	v_mov_b32_e32 v62, v18
	v_mov_b32_e32 v63, v19
	v_mov_b32_e32 v64, v20
	v_mov_b32_e32 v65, v21
	v_mov_b32_e32 v66, v22
	v_mov_b32_e32 v67, v23
	v_mov_b32_e32 v68, v24
	v_mov_b32_e32 v69, v25
	v_mov_b32_e32 v70, v26
	v_mov_b32_e32 v71, v27
	v_mov_b32_e32 v72, v28
	v_mov_b32_e32 v73, v29
	v_mov_b32_e32 v74, v30
	v_mov_b32_e32 v75, v31
	s_cbranch_scc1 .LBB0_742

; __device__ __forceinline__ bf16_t f2bf(float x) { return (bf16_t)(cvt_pk_bf16(x, 0.f) & 0xffffu); }
; __device__ __forceinline__ void titem_store(const TItem& it, int tid, const f32x4 (&v)[4], bf16_t* T) {
; #pragma unroll
;     for (int i = 0; i < 4; ++i) { const int idx = tid + 512 * i, kk = idx >> 4, r4 = idx & 15;
; #pragma unroll
;         for (int j = 0; j < 4; ++j) T[(4 * r4 + j) * 136 + kk] = f2bf(v[i][j]); }
;     __syncthreads();
; #pragma unroll
;     for (int i = 0; i < 2; ++i) { const int c = tid + 512 * i, row = c >> 4, k8 = (c & 15) * 8;
;         const u32x4 w = *(const u32x4*)(T + row * 136 + k8);
;         *(u32x4*)(it.dst + (size_t)(it.r0 + row) * it.K + it.k0 + k8) = w; }
; }
;     ...
;     for (int i = start; i < n; i += stride) {
;         TItem c2 = c1;
;         if (i + 2 * stride < n) { c2 = titem_decode(p, tset_item(l, which, i + 2 * stride)); titem_load(c2, tid, v2); }
;         titem_store(c0, tid, v0, (bf16_t*)(lds + buf * 17408));
;         buf ^= 1; c0 = c1; c1 = c2;
; #pragma unroll
;         for (int q = 0; q < 4; ++q) { v0[q] = v1[q]; v1[q] = v2[q]; }
.LBB0_799:
	s_mul_i32 s3, s52, 0x4400
	s_add_i32 s3, s3, 0
	v_add_u32_e32 v34, s3, v44
	v_cvt_pk_bf16_f32 v0, v0, v33
	v_lshl_add_u32 v35, v38, 1, v34
	ds_write_b16 v35, v0
	v_cvt_pk_bf16_f32 v0, v1, v33
	ds_write_b16 v35, v0 offset:272
	v_cvt_pk_bf16_f32 v0, v2, v33
	ds_write_b16 v35, v0 offset:544
	v_cvt_pk_bf16_f32 v0, v3, v33
	ds_write_b16 v35, v0 offset:816
	v_cvt_pk_bf16_f32 v0, v4, v33
	v_lshl_add_u32 v1, v39, 1, v34
	ds_write_b16 v1, v0
	v_cvt_pk_bf16_f32 v0, v5, v33
	ds_write_b16 v1, v0 offset:272
	v_cvt_pk_bf16_f32 v0, v6, v33
	ds_write_b16 v1, v0 offset:544
	v_cvt_pk_bf16_f32 v0, v7, v33
	ds_write_b16 v1, v0 offset:816
	v_cvt_pk_bf16_f32 v0, v8, v33
	v_lshl_add_u32 v1, v40, 1, v34
	ds_write_b16 v1, v0
	v_cvt_pk_bf16_f32 v0, v9, v33
	ds_write_b16 v1, v0 offset:272
	v_cvt_pk_bf16_f32 v0, v10, v33
	ds_write_b16 v1, v0 offset:544
	v_cvt_pk_bf16_f32 v0, v11, v33
	ds_write_b16 v1, v0 offset:816
	v_cvt_pk_bf16_f32 v0, v12, v33
	v_lshl_add_u32 v1, v41, 1, v34
	ds_write_b16 v1, v0
	v_cvt_pk_bf16_f32 v0, v13, v33
	ds_write_b16 v1, v0 offset:272
	v_cvt_pk_bf16_f32 v0, v14, v33
	v_add_u32_e32 v4, s23, v38
	ds_write_b16 v1, v0 offset:544
	v_cvt_pk_bf16_f32 v0, v15, v33
	v_add_u32_e32 v10, s3, v32
	v_ashrrev_i32_e32 v7, 31, v4
	v_mad_u64_u32 v[4:5], s[4:5], v4, s22, 0
	ds_write_b16 v1, v0 offset:816
	v_add_u32_e32 v0, v10, v42
	v_mov_b32_e32 v6, v5
	s_waitcnt lgkmcnt(0)
	s_barrier
	ds_read_b128 v[0:3], v0
	v_mad_u64_u32 v[6:7], s[4:5], v7, s22, v[6:7]
	v_mov_b32_e32 v5, v6
	s_ashr_i32 s3, s2, 31
	v_lshl_add_u64 v[4:5], v[4:5], 1, s[0:1]
	s_lshl_b64 s[2:3], s[2:3], 1
	v_lshl_add_u64 v[4:5], v[4:5], 0, s[2:3]
	v_lshl_add_u64 v[8:9], v[4:5], 0, v[32:33]
	v_add_u32_e32 v4, v10, v43
	ds_read_b128 v[4:7], v4
	s_waitcnt lgkmcnt(1)
	global_store_dwordx4 v[8:9], v[0:3], off sc0 sc1
	s_xor_b32 s52, s52, 1
	v_mov_b32_e32 v8, v58
	v_add_u32_e32 v0, s23, v39
	v_ashrrev_i32_e32 v3, 31, v0
	v_mad_u64_u32 v[0:1], s[4:5], v0, s22, 0
	v_mov_b32_e32 v2, v1
	v_mad_u64_u32 v[2:3], s[4:5], v3, s22, v[2:3]
	v_mov_b32_e32 v1, v2
	v_lshl_add_u64 v[0:1], v[0:1], 1, s[0:1]
	v_lshl_add_u64 v[0:1], v[0:1], 0, s[2:3]
	v_lshl_add_u64 v[0:1], v[0:1], 0, v[32:33]
	s_add_i32 s0, s53, 0x2c0
	s_waitcnt lgkmcnt(0)
	global_store_dwordx4 v[0:1], v[4:7], off sc0 sc1
	s_cmpk_gt_i32 s53, 0xd5f
	s_mov_b32 s53, s0
	s_mov_b64 s[0:1], s[14:15]
	s_mov_b32 s22, s56
	s_mov_b32 s23, s55
	s_mov_b32 s2, s54
	v_mov_b32_e32 v0, v60
	v_mov_b32_e32 v1, v56
	v_mov_b32_e32 v2, v52
	v_mov_b32_e32 v3, v48
	v_mov_b32_e32 v4, v59
	v_mov_b32_e32 v5, v55
	v_mov_b32_e32 v6, v51
	v_mov_b32_e32 v7, v47
	v_mov_b32_e32 v9, v54
	v_mov_b32_e32 v10, v50
	v_mov_b32_e32 v11, v46
	v_mov_b32_e32 v12, v57
	v_mov_b32_e32 v13, v53
	v_mov_b32_e32 v14, v49
	v_mov_b32_e32 v15, v45
	s_waitcnt vmcnt(2)
	v_mov_b32_e32 v34, v16
	v_mov_b32_e32 v35, v17
	v_mov_b32_e32 v61, v18
	v_mov_b32_e32 v62, v19
	v_mov_b32_e32 v63, v20
	v_mov_b32_e32 v64, v21
	v_mov_b32_e32 v65, v22
	v_mov_b32_e32 v66, v23
	v_mov_b32_e32 v67, v24
	v_mov_b32_e32 v68, v25
	v_mov_b32_e32 v69, v26
	v_mov_b32_e32 v70, v27
	v_mov_b32_e32 v71, v28
	v_mov_b32_e32 v72, v29
	v_mov_b32_e32 v73, v30
	v_mov_b32_e32 v74, v31
	s_cbranch_scc1 .LBB0_825

; __device__ __forceinline__ bf16_t f2bf(float x) { return (bf16_t)(cvt_pk_bf16(x, 0.f) & 0xffffu); }
; __device__ __forceinline__ void titem_store(const TItem& it, int tid, const f32x4 (&v)[4], bf16_t* T) {
; #pragma unroll
;     for (int i = 0; i < 4; ++i) { const int idx = tid + 512 * i, kk = idx >> 4, r4 = idx & 15;
; #pragma unroll
;         for (int j = 0; j < 4; ++j) T[(4 * r4 + j) * 136 + kk] = f2bf(v[i][j]); }
;     __syncthreads();
; #pragma unroll
;     for (int i = 0; i < 2; ++i) { const int c = tid + 512 * i, row = c >> 4, k8 = (c & 15) * 8;
;         const u32x4 w = *(const u32x4*)(T + row * 136 + k8);
;         *(u32x4*)(it.dst + (size_t)(it.r0 + row) * it.K + it.k0 + k8) = w; }
; }
;     ...
;     for (int i = start; i < n; i += stride) {
;         TItem c2 = c1;
;         if (i + 2 * stride < n) { c2 = titem_decode(p, tset_item(l, which, i + 2 * stride)); titem_load(c2, tid, v2); }
;         titem_store(c0, tid, v0, (bf16_t*)(lds + buf * 17408));
;         buf ^= 1; c0 = c1; c1 = c2;
; #pragma unroll
;         for (int q = 0; q < 4; ++q) { v0[q] = v1[q]; v1[q] = v2[q]; }
.LBB0_1013:
	s_mul_i32 s5, s52, 0x4400
	s_add_i32 s5, s5, 0
	v_add_u32_e32 v34, s5, v45
	v_cvt_pk_bf16_f32 v0, v0, v33
	v_lshl_add_u32 v35, v37, 1, v34
	ds_write_b16 v35, v0
	v_cvt_pk_bf16_f32 v0, v1, v33
	ds_write_b16 v35, v0 offset:272
	v_cvt_pk_bf16_f32 v0, v2, v33
	ds_write_b16 v35, v0 offset:544
	v_cvt_pk_bf16_f32 v0, v3, v33
	ds_write_b16 v35, v0 offset:816
	v_cvt_pk_bf16_f32 v0, v4, v33
	v_lshl_add_u32 v1, v38, 1, v34
	ds_write_b16 v1, v0
	v_cvt_pk_bf16_f32 v0, v5, v33
	ds_write_b16 v1, v0 offset:272
	v_cvt_pk_bf16_f32 v0, v6, v33
	ds_write_b16 v1, v0 offset:544
	v_cvt_pk_bf16_f32 v0, v7, v33
	ds_write_b16 v1, v0 offset:816
	v_cvt_pk_bf16_f32 v0, v8, v33
	v_lshl_add_u32 v1, v39, 1, v34
	ds_write_b16 v1, v0
	v_cvt_pk_bf16_f32 v0, v9, v33
	ds_write_b16 v1, v0 offset:272
	v_cvt_pk_bf16_f32 v0, v10, v33
	ds_write_b16 v1, v0 offset:544
	v_cvt_pk_bf16_f32 v0, v11, v33
	ds_write_b16 v1, v0 offset:816
	v_cvt_pk_bf16_f32 v0, v12, v33
	v_lshl_add_u32 v1, v40, 1, v34
	ds_write_b16 v1, v0
	v_cvt_pk_bf16_f32 v0, v13, v33
	ds_write_b16 v1, v0 offset:272
	v_cvt_pk_bf16_f32 v0, v14, v33
	v_add_u32_e32 v4, s50, v37
	ds_write_b16 v1, v0 offset:544
	v_cvt_pk_bf16_f32 v0, v15, v33
	v_add_u32_e32 v10, s5, v32
	v_ashrrev_i32_e32 v7, 31, v4
	v_mad_u64_u32 v[4:5], s[16:17], v4, s47, 0
	ds_write_b16 v1, v0 offset:816
	v_add_u32_e32 v0, v10, v43
	v_mov_b32_e32 v6, v5
	s_waitcnt lgkmcnt(0)
	s_barrier
	ds_read_b128 v[0:3], v0
	v_mad_u64_u32 v[6:7], s[16:17], v7, s47, v[6:7]
	v_mov_b32_e32 v5, v6
	s_ashr_i32 s5, s4, 31
	v_lshl_add_u64 v[4:5], v[4:5], 1, s[2:3]
	s_lshl_b64 s[4:5], s[4:5], 1
	v_lshl_add_u64 v[4:5], v[4:5], 0, s[4:5]
	v_lshl_add_u64 v[8:9], v[4:5], 0, v[32:33]
	v_add_u32_e32 v4, v10, v44
	ds_read_b128 v[4:7], v4
	s_waitcnt lgkmcnt(1)
	global_store_dwordx4 v[8:9], v[0:3], off sc0 sc1
	s_xor_b32 s52, s52, 1
	v_mov_b32_e32 v8, v59
	v_add_u32_e32 v0, s50, v38
	v_ashrrev_i32_e32 v3, 31, v0
	v_mad_u64_u32 v[0:1], s[16:17], v0, s47, 0
	v_mov_b32_e32 v2, v1
	v_mad_u64_u32 v[2:3], s[16:17], v3, s47, v[2:3]
	v_mov_b32_e32 v1, v2
	v_lshl_add_u64 v[0:1], v[0:1], 1, s[2:3]
	v_lshl_add_u64 v[0:1], v[0:1], 0, s[4:5]
	v_lshl_add_u64 v[0:1], v[0:1], 0, v[32:33]
	s_add_i32 s2, s53, 0x2c0
	s_waitcnt lgkmcnt(0)
	global_store_dwordx4 v[0:1], v[4:7], off sc0 sc1
	s_cmpk_gt_i32 s53, 0x48f
	s_mov_b32 s53, s2
	s_mov_b64 s[2:3], s[14:15]
	s_mov_b32 s47, s56
	s_mov_b32 s50, s55
	s_mov_b32 s4, s54
	v_mov_b32_e32 v0, v61
	v_mov_b32_e32 v1, v57
	v_mov_b32_e32 v2, v53
	v_mov_b32_e32 v3, v49
	v_mov_b32_e32 v4, v60
	v_mov_b32_e32 v5, v56
	v_mov_b32_e32 v6, v52
	v_mov_b32_e32 v7, v48
	v_mov_b32_e32 v9, v55
	v_mov_b32_e32 v10, v51
	v_mov_b32_e32 v11, v47
	v_mov_b32_e32 v12, v58
	v_mov_b32_e32 v13, v54
	v_mov_b32_e32 v14, v50
	v_mov_b32_e32 v15, v46
	s_waitcnt vmcnt(2)
	v_mov_b32_e32 v34, v16
	v_mov_b32_e32 v35, v17
	v_mov_b32_e32 v62, v18
	v_mov_b32_e32 v63, v19
	v_mov_b32_e32 v64, v20
	v_mov_b32_e32 v65, v21
	v_mov_b32_e32 v66, v22
	v_mov_b32_e32 v67, v23
	v_mov_b32_e32 v68, v24
	v_mov_b32_e32 v69, v25
	v_mov_b32_e32 v70, v26
	v_mov_b32_e32 v71, v27
	v_mov_b32_e32 v72, v28
	v_mov_b32_e32 v73, v29
	v_mov_b32_e32 v74, v30
	v_mov_b32_e32 v75, v31
	s_cbranch_scc1 .LBB0_1105

; __device__ __forceinline__ bf16_t f2bf(float x) { return (bf16_t)(cvt_pk_bf16(x, 0.f) & 0xffffu); }
; __device__ __forceinline__ void titem_store(const TItem& it, int tid, const f32x4 (&v)[4], bf16_t* T) {
; #pragma unroll
;     for (int i = 0; i < 4; ++i) { const int idx = tid + 512 * i, kk = idx >> 4, r4 = idx & 15;
; #pragma unroll
;         for (int j = 0; j < 4; ++j) T[(4 * r4 + j) * 136 + kk] = f2bf(v[i][j]); }
;     __syncthreads();
; #pragma unroll
;     for (int i = 0; i < 2; ++i) { const int c = tid + 512 * i, row = c >> 4, k8 = (c & 15) * 8;
;         const u32x4 w = *(const u32x4*)(T + row * 136 + k8);
;         *(u32x4*)(it.dst + (size_t)(it.r0 + row) * it.K + it.k0 + k8) = w; }
; }
;     ...
;     for (int i = start; i < n; i += stride) {
;         TItem c2 = c1;
;         if (i + 2 * stride < n) { c2 = titem_decode(p, tset_item(l, which, i + 2 * stride)); titem_load(c2, tid, v2); }
;         titem_store(c0, tid, v0, (bf16_t*)(lds + buf * 17408));
;         buf ^= 1; c0 = c1; c1 = c2;
; #pragma unroll
;         for (int q = 0; q < 4; ++q) { v0[q] = v1[q]; v1[q] = v2[q]; }
.LBB0_1291:
	s_mul_i32 s3, s50, 0x4400
	s_add_i32 s3, s3, 0
	v_add_u32_e32 v34, s3, v45
	v_cvt_pk_bf16_f32 v0, v0, v33
	v_lshl_add_u32 v35, v37, 1, v34
	ds_write_b16 v35, v0
	v_cvt_pk_bf16_f32 v0, v1, v33
	ds_write_b16 v35, v0 offset:272
	v_cvt_pk_bf16_f32 v0, v2, v33
	ds_write_b16 v35, v0 offset:544
	v_cvt_pk_bf16_f32 v0, v3, v33
	ds_write_b16 v35, v0 offset:816
	v_cvt_pk_bf16_f32 v0, v4, v33
	v_lshl_add_u32 v1, v38, 1, v34
	ds_write_b16 v1, v0
	v_cvt_pk_bf16_f32 v0, v5, v33
	ds_write_b16 v1, v0 offset:272
	v_cvt_pk_bf16_f32 v0, v6, v33
	ds_write_b16 v1, v0 offset:544
	v_cvt_pk_bf16_f32 v0, v7, v33
	ds_write_b16 v1, v0 offset:816
	v_cvt_pk_bf16_f32 v0, v8, v33
	v_lshl_add_u32 v1, v39, 1, v34
	ds_write_b16 v1, v0
	v_cvt_pk_bf16_f32 v0, v9, v33
	ds_write_b16 v1, v0 offset:272
	v_cvt_pk_bf16_f32 v0, v10, v33
	ds_write_b16 v1, v0 offset:544
	v_cvt_pk_bf16_f32 v0, v11, v33
	ds_write_b16 v1, v0 offset:816
	v_cvt_pk_bf16_f32 v0, v12, v33
	v_lshl_add_u32 v1, v40, 1, v34
	ds_write_b16 v1, v0
	v_cvt_pk_bf16_f32 v0, v13, v33
	ds_write_b16 v1, v0 offset:272
	v_cvt_pk_bf16_f32 v0, v14, v33
	v_add_u32_e32 v4, s23, v37
	ds_write_b16 v1, v0 offset:544
	v_cvt_pk_bf16_f32 v0, v15, v33
	v_add_u32_e32 v10, s3, v32
	v_ashrrev_i32_e32 v7, 31, v4
	v_mad_u64_u32 v[4:5], s[14:15], v4, s22, 0
	ds_write_b16 v1, v0 offset:816
	v_add_u32_e32 v0, v10, v43
	v_mov_b32_e32 v6, v5
	s_waitcnt lgkmcnt(0)
	s_barrier
	ds_read_b128 v[0:3], v0
	v_mad_u64_u32 v[6:7], s[14:15], v7, s22, v[6:7]
	v_mov_b32_e32 v5, v6
	s_ashr_i32 s3, s2, 31
	v_lshl_add_u64 v[4:5], v[4:5], 1, s[0:1]
	s_lshl_b64 s[2:3], s[2:3], 1
	v_lshl_add_u64 v[4:5], v[4:5], 0, s[2:3]
	v_lshl_add_u64 v[8:9], v[4:5], 0, v[32:33]
	v_add_u32_e32 v4, v10, v44
	ds_read_b128 v[4:7], v4
	s_waitcnt lgkmcnt(1)
	global_store_dwordx4 v[8:9], v[0:3], off sc0 sc1
	s_xor_b32 s50, s50, 1
	v_mov_b32_e32 v8, v59
	v_add_u32_e32 v0, s23, v38
	v_ashrrev_i32_e32 v3, 31, v0
	v_mad_u64_u32 v[0:1], s[14:15], v0, s22, 0
	v_mov_b32_e32 v2, v1
	v_mad_u64_u32 v[2:3], s[14:15], v3, s22, v[2:3]
	v_mov_b32_e32 v1, v2
	v_lshl_add_u64 v[0:1], v[0:1], 1, s[0:1]
	v_lshl_add_u64 v[0:1], v[0:1], 0, s[2:3]
	v_lshl_add_u64 v[0:1], v[0:1], 0, v[32:33]
	s_add_i32 s0, s51, 0x2c0
	s_waitcnt lgkmcnt(0)
	global_store_dwordx4 v[0:1], v[4:7], off sc0 sc1
	s_cmpk_gt_i32 s51, 0x48f
	s_mov_b32 s51, s0
	s_mov_b64 s[0:1], s[10:11]
	s_mov_b32 s22, s54
	s_mov_b32 s23, s53
	s_mov_b32 s2, s52
	v_mov_b32_e32 v0, v61
	v_mov_b32_e32 v1, v57
	v_mov_b32_e32 v2, v53
	v_mov_b32_e32 v3, v49
	v_mov_b32_e32 v4, v60
	v_mov_b32_e32 v5, v56
	v_mov_b32_e32 v6, v52
	v_mov_b32_e32 v7, v48
	v_mov_b32_e32 v9, v55
	v_mov_b32_e32 v10, v51
	v_mov_b32_e32 v11, v47
	v_mov_b32_e32 v12, v58
	v_mov_b32_e32 v13, v54
	v_mov_b32_e32 v14, v50
	v_mov_b32_e32 v15, v46
	s_waitcnt vmcnt(2)
	v_mov_b32_e32 v34, v16
	v_mov_b32_e32 v35, v17
	v_mov_b32_e32 v62, v18
	v_mov_b32_e32 v63, v19
	v_mov_b32_e32 v64, v20
	v_mov_b32_e32 v65, v21
	v_mov_b32_e32 v66, v22
	v_mov_b32_e32 v67, v23
	v_mov_b32_e32 v68, v24
	v_mov_b32_e32 v69, v25
	v_mov_b32_e32 v70, v26
	v_mov_b32_e32 v71, v27
	v_mov_b32_e32 v72, v28
	v_mov_b32_e32 v73, v29
	v_mov_b32_e32 v74, v30
	v_mov_b32_e32 v75, v31
	s_cbranch_scc1 .LBB0_746

; __device__ __forceinline__ bf16_t f2bf(float x) { return (bf16_t)(cvt_pk_bf16(x, 0.f) & 0xffffu); }
; __device__ __forceinline__ void titem_store(const TItem& it, int tid, const f32x4 (&v)[4], bf16_t* T) {
; #pragma unroll
;     for (int i = 0; i < 4; ++i) { const int idx = tid + 512 * i, kk = idx >> 4, r4 = idx & 15;
; #pragma unroll
;         for (int j = 0; j < 4; ++j) T[(4 * r4 + j) * 136 + kk] = f2bf(v[i][j]); }
;     __syncthreads();
; #pragma unroll
;     for (int i = 0; i < 2; ++i) { const int c = tid + 512 * i, row = c >> 4, k8 = (c & 15) * 8;
;         const u32x4 w = *(const u32x4*)(T + row * 136 + k8);
;         *(u32x4*)(it.dst + (size_t)(it.r0 + row) * it.K + it.k0 + k8) = w; }
; }
;     ...
;         titem_store(c0, tid, v0, (bf16_t*)(lds + buf * 17408));
;         buf ^= 1; c0 = c1; c1 = c2;
; #pragma unroll
;         for (int q = 0; q < 4; ++q) { v0[q] = v1[q]; v1[q] = v2[q]; }
.LBB0_1451:
	s_mul_i32 s4, s38, 0x4400
	s_add_i32 s4, s4, 0
	v_add_u32_e32 v34, s4, v44
	v_cvt_pk_bf16_f32 v0, v0, v33
	v_lshl_add_u32 v35, v37, 1, v34
	ds_write_b16 v35, v0
	v_cvt_pk_bf16_f32 v0, v1, v33
	ds_write_b16 v35, v0 offset:272
	v_cvt_pk_bf16_f32 v0, v2, v33
	ds_write_b16 v35, v0 offset:544
	v_cvt_pk_bf16_f32 v0, v3, v33
	ds_write_b16 v35, v0 offset:816
	v_cvt_pk_bf16_f32 v0, v4, v33
	v_lshl_add_u32 v1, v39, 1, v34
	ds_write_b16 v1, v0
	v_cvt_pk_bf16_f32 v0, v5, v33
	ds_write_b16 v1, v0 offset:272
	v_cvt_pk_bf16_f32 v0, v6, v33
	ds_write_b16 v1, v0 offset:544
	v_cvt_pk_bf16_f32 v0, v7, v33
	ds_write_b16 v1, v0 offset:816
	v_cvt_pk_bf16_f32 v0, v8, v33
	v_lshl_add_u32 v1, v40, 1, v34
	ds_write_b16 v1, v0
	v_cvt_pk_bf16_f32 v0, v9, v33
	ds_write_b16 v1, v0 offset:272
	v_cvt_pk_bf16_f32 v0, v10, v33
	ds_write_b16 v1, v0 offset:544
	v_cvt_pk_bf16_f32 v0, v11, v33
	ds_write_b16 v1, v0 offset:816
	v_cvt_pk_bf16_f32 v0, v12, v33
	v_lshl_add_u32 v1, v41, 1, v34
	ds_write_b16 v1, v0
	v_cvt_pk_bf16_f32 v0, v13, v33
	ds_write_b16 v1, v0 offset:272
	v_cvt_pk_bf16_f32 v0, v14, v33
	v_add_u32_e32 v4, s24, v37
	ds_write_b16 v1, v0 offset:544
	v_cvt_pk_bf16_f32 v0, v15, v33
	v_add_u32_e32 v10, s4, v32
	v_ashrrev_i32_e32 v7, 31, v4
	v_mad_u64_u32 v[4:5], s[4:5], v4, s13, 0
	ds_write_b16 v1, v0 offset:816
	v_add_u32_e32 v0, v10, v42
	v_mov_b32_e32 v6, v5
	s_waitcnt lgkmcnt(0)
	s_barrier
	ds_read_b128 v[0:3], v0
	v_mad_u64_u32 v[6:7], s[4:5], v7, s13, v[6:7]
	v_mov_b32_e32 v5, v6
	s_ashr_i32 s11, s10, 31
	v_lshl_add_u64 v[4:5], v[4:5], 1, s[2:3]
	s_lshl_b64 s[4:5], s[10:11], 1
	v_lshl_add_u64 v[4:5], v[4:5], 0, s[4:5]
	v_lshl_add_u64 v[8:9], v[4:5], 0, v[32:33]
	v_add_u32_e32 v4, v10, v43
	ds_read_b128 v[4:7], v4
	s_waitcnt lgkmcnt(1)
	global_store_dwordx4 v[8:9], v[0:3], off sc0 sc1
	s_xor_b32 s38, s38, 1
	s_add_i32 s41, s41, s96
	v_add_u32_e32 v0, s24, v39
	v_ashrrev_i32_e32 v3, 31, v0
	v_mad_u64_u32 v[0:1], s[10:11], v0, s13, 0
	v_mov_b32_e32 v2, v1
	v_mad_u64_u32 v[2:3], s[10:11], v3, s13, v[2:3]
	v_mov_b32_e32 v1, v2
	v_lshl_add_u64 v[0:1], v[0:1], 1, s[2:3]
	v_lshl_add_u64 v[0:1], v[0:1], 0, s[4:5]
	v_lshl_add_u64 v[0:1], v[0:1], 0, v[32:33]
	s_waitcnt lgkmcnt(0)
	global_store_dwordx4 v[0:1], v[4:7], off sc0 sc1
	s_cmpk_gt_i32 s41, 0x101f
	s_mov_b64 s[2:3], s[16:17]
	s_mov_b32 s13, s44
	s_mov_b32 s24, s43
	s_mov_b32 s10, s42
	v_mov_b32_e32 v0, v60
	v_mov_b32_e32 v1, v56
	v_mov_b32_e32 v2, v52
	v_mov_b32_e32 v3, v48
	v_mov_b32_e32 v4, v59
	v_mov_b32_e32 v5, v55
	v_mov_b32_e32 v6, v51
	v_mov_b32_e32 v7, v47
	v_mov_b32_e32 v8, v58
	v_mov_b32_e32 v9, v54
	v_mov_b32_e32 v10, v50
	v_mov_b32_e32 v11, v46
	v_mov_b32_e32 v12, v57
	v_mov_b32_e32 v13, v53
	v_mov_b32_e32 v14, v49
	v_mov_b32_e32 v15, v45
	s_waitcnt vmcnt(2)
	v_mov_b32_e32 v34, v16
	v_mov_b32_e32 v35, v17
	v_mov_b32_e32 v61, v18
	v_mov_b32_e32 v62, v19
	v_mov_b32_e32 v63, v20
	v_mov_b32_e32 v64, v21
	v_mov_b32_e32 v65, v22
	v_mov_b32_e32 v66, v23
	v_mov_b32_e32 v67, v24
	v_mov_b32_e32 v68, v25
	v_mov_b32_e32 v69, v26
	v_mov_b32_e32 v70, v27
	v_mov_b32_e32 v71, v28
	v_mov_b32_e32 v72, v29
	v_mov_b32_e32 v73, v30
	v_mov_b32_e32 v74, v31
	s_cbranch_scc1 .LBB0_1481

; __device__ __forceinline__ bf16_t f2bf(float x) { return (bf16_t)(cvt_pk_bf16(x, 0.f) & 0xffffu); }
; __device__ __forceinline__ void titem_store(const TItem& it, int tid, const f32x4 (&v)[4], bf16_t* T) {
; #pragma unroll
;     for (int i = 0; i < 4; ++i) { const int idx = tid + 512 * i, kk = idx >> 4, r4 = idx & 15;
; #pragma unroll
;         for (int j = 0; j < 4; ++j) T[(4 * r4 + j) * 136 + kk] = f2bf(v[i][j]); }
;     __syncthreads();
; #pragma unroll
;     for (int i = 0; i < 2; ++i) { const int c = tid + 512 * i, row = c >> 4, k8 = (c & 15) * 8;
;         const u32x4 w = *(const u32x4*)(T + row * 136 + k8);
;         *(u32x4*)(it.dst + (size_t)(it.r0 + row) * it.K + it.k0 + k8) = w; }
; }
;     ...
;         titem_store(c0, tid, v0, (bf16_t*)(lds + buf * 17408));
;         buf ^= 1; c0 = c1; c1 = c2;
; #pragma unroll
;         for (int q = 0; q < 4; ++q) { v0[q] = v1[q]; v1[q] = v2[q]; }
.LBB0_1692:
	s_mul_i32 s3, s44, 0x4400
	s_add_i32 s3, s3, 0
	v_add_u32_e32 v34, s3, v45
	v_cvt_pk_bf16_f32 v0, v0, v33
	v_lshl_add_u32 v35, v37, 1, v34
	ds_write_b16 v35, v0
	v_cvt_pk_bf16_f32 v0, v1, v33
	ds_write_b16 v35, v0 offset:272
	v_cvt_pk_bf16_f32 v0, v2, v33
	ds_write_b16 v35, v0 offset:544
	v_cvt_pk_bf16_f32 v0, v3, v33
	ds_write_b16 v35, v0 offset:816
	v_cvt_pk_bf16_f32 v0, v4, v33
	v_lshl_add_u32 v1, v40, 1, v34
	ds_write_b16 v1, v0
	v_cvt_pk_bf16_f32 v0, v5, v33
	ds_write_b16 v1, v0 offset:272
	v_cvt_pk_bf16_f32 v0, v6, v33
	ds_write_b16 v1, v0 offset:544
	v_cvt_pk_bf16_f32 v0, v7, v33
	ds_write_b16 v1, v0 offset:816
	v_cvt_pk_bf16_f32 v0, v8, v33
	v_lshl_add_u32 v1, v41, 1, v34
	ds_write_b16 v1, v0
	v_cvt_pk_bf16_f32 v0, v9, v33
	ds_write_b16 v1, v0 offset:272
	v_cvt_pk_bf16_f32 v0, v10, v33
	ds_write_b16 v1, v0 offset:544
	v_cvt_pk_bf16_f32 v0, v11, v33
	ds_write_b16 v1, v0 offset:816
	v_cvt_pk_bf16_f32 v0, v12, v33
	v_lshl_add_u32 v1, v42, 1, v34
	ds_write_b16 v1, v0
	v_cvt_pk_bf16_f32 v0, v13, v33
	ds_write_b16 v1, v0 offset:272
	v_cvt_pk_bf16_f32 v0, v14, v33
	v_add_u32_e32 v4, s24, v37
	ds_write_b16 v1, v0 offset:544
	v_cvt_pk_bf16_f32 v0, v15, v33
	v_add_u32_e32 v10, s3, v32
	v_ashrrev_i32_e32 v7, 31, v4
	v_mad_u64_u32 v[4:5], s[16:17], v4, s13, 0
	ds_write_b16 v1, v0 offset:816
	v_add_u32_e32 v0, v10, v43
	v_mov_b32_e32 v6, v5
	s_waitcnt lgkmcnt(0)
	s_barrier
	ds_read_b128 v[0:3], v0
	v_mad_u64_u32 v[6:7], s[16:17], v7, s13, v[6:7]
	v_mov_b32_e32 v5, v6
	s_ashr_i32 s3, s2, 31
	v_lshl_add_u64 v[4:5], v[4:5], 1, s[0:1]
	s_lshl_b64 s[2:3], s[2:3], 1
	v_lshl_add_u64 v[4:5], v[4:5], 0, s[2:3]
	v_lshl_add_u64 v[8:9], v[4:5], 0, v[32:33]
	v_add_u32_e32 v4, v10, v44
	ds_read_b128 v[4:7], v4
	s_waitcnt lgkmcnt(1)
	global_store_dwordx4 v[8:9], v[0:3], off sc0 sc1
	s_xor_b32 s44, s44, 1
	s_add_i32 s50, s50, s96
	v_add_u32_e32 v0, s24, v40
	v_ashrrev_i32_e32 v3, 31, v0
	v_mad_u64_u32 v[0:1], s[16:17], v0, s13, 0
	v_mov_b32_e32 v2, v1
	v_mad_u64_u32 v[2:3], s[16:17], v3, s13, v[2:3]
	v_mov_b32_e32 v1, v2
	v_lshl_add_u64 v[0:1], v[0:1], 1, s[0:1]
	v_lshl_add_u64 v[0:1], v[0:1], 0, s[2:3]
	v_lshl_add_u64 v[0:1], v[0:1], 0, v[32:33]
	s_waitcnt lgkmcnt(0)
	global_store_dwordx4 v[0:1], v[4:7], off sc0 sc1
	s_cmpk_gt_i32 s50, 0x101f
	s_mov_b64 s[0:1], s[14:15]
	s_mov_b32 s13, s53
	s_mov_b32 s24, s52
	s_mov_b32 s2, s51
	v_mov_b32_e32 v0, v61
	v_mov_b32_e32 v1, v57
	v_mov_b32_e32 v2, v53
	v_mov_b32_e32 v3, v49
	v_mov_b32_e32 v4, v60
	v_mov_b32_e32 v5, v56
	v_mov_b32_e32 v6, v52
	v_mov_b32_e32 v7, v48
	v_mov_b32_e32 v8, v59
	v_mov_b32_e32 v9, v55
	v_mov_b32_e32 v10, v51
	v_mov_b32_e32 v11, v47
	v_mov_b32_e32 v12, v58
	v_mov_b32_e32 v13, v54
	v_mov_b32_e32 v14, v50
	v_mov_b32_e32 v15, v46
	s_waitcnt vmcnt(2)
	v_mov_b32_e32 v34, v16
	v_mov_b32_e32 v35, v17
	v_mov_b32_e32 v62, v18
	v_mov_b32_e32 v63, v19
	v_mov_b32_e32 v64, v20
	v_mov_b32_e32 v65, v21
	v_mov_b32_e32 v66, v22
	v_mov_b32_e32 v67, v23
	v_mov_b32_e32 v68, v24
	v_mov_b32_e32 v69, v25
	v_mov_b32_e32 v70, v26
	v_mov_b32_e32 v71, v27
	v_mov_b32_e32 v72, v28
	v_mov_b32_e32 v73, v29
	v_mov_b32_e32 v74, v30
	v_mov_b32_e32 v75, v31
	s_cbranch_scc1 .LBB0_1784

; __device__ __forceinline__ bf16_t f2bf(float x) { return (bf16_t)(cvt_pk_bf16(x, 0.f) & 0xffffu); }
; __device__ __forceinline__ void titem_store(const TItem& it, int tid, const f32x4 (&v)[4], bf16_t* T) {
; #pragma unroll
;     for (int i = 0; i < 4; ++i) { const int idx = tid + 512 * i, kk = idx >> 4, r4 = idx & 15;
; #pragma unroll
;         for (int j = 0; j < 4; ++j) T[(4 * r4 + j) * 136 + kk] = f2bf(v[i][j]); }
;     __syncthreads();
; #pragma unroll
;     for (int i = 0; i < 2; ++i) { const int c = tid + 512 * i, row = c >> 4, k8 = (c & 15) * 8;
;         const u32x4 w = *(const u32x4*)(T + row * 136 + k8);
;         *(u32x4*)(it.dst + (size_t)(it.r0 + row) * it.K + it.k0 + k8) = w; }
; }
;     ...
;         titem_store(c0, tid, v0, (bf16_t*)(lds + buf * 17408));
;         buf ^= 1; c0 = c1; c1 = c2;
; #pragma unroll
;         for (int q = 0; q < 4; ++q) { v0[q] = v1[q]; v1[q] = v2[q]; }
.LBB0_1995:
	s_mul_i32 s3, s42, 0x4400
	s_add_i32 s3, s3, 0
	v_add_u32_e32 v34, s3, v45
	v_cvt_pk_bf16_f32 v0, v0, v33
	v_lshl_add_u32 v35, v37, 1, v34
	ds_write_b16 v35, v0
	v_cvt_pk_bf16_f32 v0, v1, v33
	ds_write_b16 v35, v0 offset:272
	v_cvt_pk_bf16_f32 v0, v2, v33
	ds_write_b16 v35, v0 offset:544
	v_cvt_pk_bf16_f32 v0, v3, v33
	ds_write_b16 v35, v0 offset:816
	v_cvt_pk_bf16_f32 v0, v4, v33
	v_lshl_add_u32 v1, v40, 1, v34
	ds_write_b16 v1, v0
	v_cvt_pk_bf16_f32 v0, v5, v33
	ds_write_b16 v1, v0 offset:272
	v_cvt_pk_bf16_f32 v0, v6, v33
	ds_write_b16 v1, v0 offset:544
	v_cvt_pk_bf16_f32 v0, v7, v33
	ds_write_b16 v1, v0 offset:816
	v_cvt_pk_bf16_f32 v0, v8, v33
	v_lshl_add_u32 v1, v41, 1, v34
	ds_write_b16 v1, v0
	v_cvt_pk_bf16_f32 v0, v9, v33
	ds_write_b16 v1, v0 offset:272
	v_cvt_pk_bf16_f32 v0, v10, v33
	ds_write_b16 v1, v0 offset:544
	v_cvt_pk_bf16_f32 v0, v11, v33
	ds_write_b16 v1, v0 offset:816
	v_cvt_pk_bf16_f32 v0, v12, v33
	v_lshl_add_u32 v1, v42, 1, v34
	ds_write_b16 v1, v0
	v_cvt_pk_bf16_f32 v0, v13, v33
	ds_write_b16 v1, v0 offset:272
	v_cvt_pk_bf16_f32 v0, v14, v33
	v_add_u32_e32 v4, s22, v37
	ds_write_b16 v1, v0 offset:544
	v_cvt_pk_bf16_f32 v0, v15, v33
	v_add_u32_e32 v10, s3, v32
	v_ashrrev_i32_e32 v7, 31, v4
	v_mad_u64_u32 v[4:5], s[14:15], v4, s13, 0
	ds_write_b16 v1, v0 offset:816
	v_add_u32_e32 v0, v10, v43
	v_mov_b32_e32 v6, v5
	s_waitcnt lgkmcnt(0)
	s_barrier
	ds_read_b128 v[0:3], v0
	v_mad_u64_u32 v[6:7], s[14:15], v7, s13, v[6:7]
	v_mov_b32_e32 v5, v6
	s_ashr_i32 s3, s2, 31
	v_lshl_add_u64 v[4:5], v[4:5], 1, s[0:1]
	s_lshl_b64 s[2:3], s[2:3], 1
	v_lshl_add_u64 v[4:5], v[4:5], 0, s[2:3]
	v_lshl_add_u64 v[8:9], v[4:5], 0, v[32:33]
	v_add_u32_e32 v4, v10, v44
	ds_read_b128 v[4:7], v4
	s_waitcnt lgkmcnt(1)
	global_store_dwordx4 v[8:9], v[0:3], off sc0 sc1
	s_xor_b32 s42, s42, 1
	s_add_i32 s46, s46, s96
	v_add_u32_e32 v0, s22, v40
	v_ashrrev_i32_e32 v3, 31, v0
	v_mad_u64_u32 v[0:1], s[14:15], v0, s13, 0
	v_mov_b32_e32 v2, v1
	v_mad_u64_u32 v[2:3], s[14:15], v3, s13, v[2:3]
	v_mov_b32_e32 v1, v2
	v_lshl_add_u64 v[0:1], v[0:1], 1, s[0:1]
	v_lshl_add_u64 v[0:1], v[0:1], 0, s[2:3]
	v_lshl_add_u64 v[0:1], v[0:1], 0, v[32:33]
	s_waitcnt lgkmcnt(0)
	global_store_dwordx4 v[0:1], v[4:7], off sc0 sc1
	s_cmpk_gt_i32 s46, 0x101f
	s_mov_b64 s[0:1], s[10:11]
	s_mov_b32 s13, s51
	s_mov_b32 s22, s50
	s_mov_b32 s2, s47
	v_mov_b32_e32 v0, v61
	v_mov_b32_e32 v1, v57
	v_mov_b32_e32 v2, v53
	v_mov_b32_e32 v3, v49
	v_mov_b32_e32 v4, v60
	v_mov_b32_e32 v5, v56
	v_mov_b32_e32 v6, v52
	v_mov_b32_e32 v7, v48
	v_mov_b32_e32 v8, v59
	v_mov_b32_e32 v9, v55
	v_mov_b32_e32 v10, v51
	v_mov_b32_e32 v11, v47
	v_mov_b32_e32 v12, v58
	v_mov_b32_e32 v13, v54
	v_mov_b32_e32 v14, v50
	v_mov_b32_e32 v15, v46
	s_waitcnt vmcnt(2)
	v_mov_b32_e32 v34, v16
	v_mov_b32_e32 v35, v17
	v_mov_b32_e32 v62, v18
	v_mov_b32_e32 v63, v19
	v_mov_b32_e32 v64, v20
	v_mov_b32_e32 v65, v21
	v_mov_b32_e32 v66, v22
	v_mov_b32_e32 v67, v23
	v_mov_b32_e32 v68, v24
	v_mov_b32_e32 v69, v25
	v_mov_b32_e32 v70, v26
	v_mov_b32_e32 v71, v27
	v_mov_b32_e32 v72, v28
	v_mov_b32_e32 v73, v29
	v_mov_b32_e32 v74, v30
	v_mov_b32_e32 v75, v31
	s_cbranch_scc1 .LBB0_2087

; __device__ __forceinline__ void norm_phase(float* __restrict__ X, bf16_t* __restrict__ H, const float* __restrict__ modl, int shiftIdx, int scaleIdx, int nrows, const float* __restrict__ PART, const float* __restrict__ XLAT) {
;     ...
;         const float* xs = (XLAT != nullptr && row < NLAT) ? XLAT + (size_t)row * DM : xr;
;         f32x4 x[8]; float ss = 0.f;
; #pragma unroll
;         for (int i = 0; i < 8; ++i) x[i] = *(const f32x4*)(xs + (i * 64 + lane) * 4);
;         if (PART != nullptr && row >= NLAT) {
; #pragma unroll
;             for (int s = 0; s < 8; ++s) { f32x4 pt[8];
; #pragma unroll
;                 for (int i = 0; i < 8; ++i) pt[i] = *(const f32x4*)(PART + ((size_t)s * NCTX + (row - NLAT)) * DM + (i * 64 + lane) * 4);
; #pragma unroll
;                 for (int i = 0; i < 8; ++i) x[i] += pt[i]; }
.LBB0_2150:
	s_movk_i32 s4, 0x2000
	v_cmp_gt_i32_e32 vcc, s4, v32
	v_mov_b32_e32 v0, s83
	v_mov_b32_e32 v1, s41
	s_and_b64 vcc, s[44:45], vcc
	v_cndmask_b32_e32 v1, v0, v1, vcc
	v_mov_b32_e32 v0, s82
	v_mov_b32_e32 v2, s40
	v_cndmask_b32_e32 v0, v0, v2, vcc
	v_lshl_add_u64 v[0:1], v[0:1], 0, v[38:39]
	global_load_dwordx4 v[28:31], v[0:1], off
	global_load_dwordx4 v[24:27], v[0:1], off offset:1024
	global_load_dwordx4 v[20:23], v[0:1], off offset:2048
	global_load_dwordx4 v[16:19], v[0:1], off offset:3072
	v_add_co_u32_e32 v0, vcc, s17, v0
	s_movk_i32 s4, 0x1fff
	s_nop 0
	v_addc_co_u32_e32 v1, vcc, 0, v1, vcc
	global_load_dwordx4 v[12:15], v[0:1], off
	global_load_dwordx4 v[8:11], v[0:1], off offset:1024
	global_load_dwordx4 v[4:7], v[0:1], off offset:2048
	s_nop 0
	global_load_dwordx4 v[0:3], v[0:1], off offset:3072
	v_cmp_lt_i32_e32 vcc, s4, v32
	s_and_b64 s[6:7], s[10:11], vcc
	v_lshlrev_b32_e32 v178, 2, v34
	s_and_saveexec_b64 s[46:47], s[6:7]
	s_cbranch_execz .LBB0_2149
	v_add_u32_e32 v54, 0xffffe000, v32
	v_mov_b32_e32 v55, v179
	v_lshlrev_b64 v[54:55], 13, v[54:55]
	v_lshl_add_u64 v[54:55], s[38:39], 0, v[54:55]
	v_lshl_add_u64 v[64:65], v[54:55], 0, v[178:179]
	global_load_dwordx4 v[56:59], v[64:65], off
	global_load_dwordx4 v[60:63], v[64:65], off offset:1024
	global_load_dwordx4 v[72:75], v[64:65], off offset:2048
	global_load_dwordx4 v[76:79], v[64:65], off offset:3072
	v_mov_b32_e32 v47, v179
	v_lshl_add_u64 v[64:65], v[54:55], 0, v[46:47]
	v_mov_b32_e32 v49, v179
	global_load_dwordx4 v[80:83], v[64:65], off
	v_lshl_add_u64 v[64:65], v[54:55], 0, v[48:49]
	v_mov_b32_e32 v51, v179
	global_load_dwordx4 v[84:87], v[64:65], off
	v_lshl_add_u64 v[64:65], v[54:55], 0, v[50:51]
	v_mov_b32_e32 v53, v179
	global_load_dwordx4 v[88:91], v[64:65], off
	v_lshl_add_u64 v[64:65], v[54:55], 0, v[52:53]
	s_mov_b64 s[6:7], 0x800000
	global_load_dwordx4 v[92:95], v[64:65], off
	v_lshl_add_u64 v[64:65], v[54:55], 0, s[6:7]
	v_lshl_add_u64 v[96:97], v[64:65], 0, v[178:179]
	v_mov_b32_e32 v41, v179
	v_mov_b32_e32 v43, v179
	v_mov_b32_e32 v45, v179
	s_mov_b64 s[6:7], 0x1000000
	s_mov_b32 s4, 0x142dd000
	s_waitcnt vmcnt(0)
	v_pk_add_f32 v[98:99], v[30:31], v[58:59]
	v_pk_add_f32 v[100:101], v[28:29], v[56:57]
	global_load_dwordx4 v[28:31], v[96:97], off
	v_lshl_add_u64 v[56:57], v[64:65], 0, v[40:41]
	v_lshl_add_u64 v[58:59], v[64:65], 0, v[42:43]
	s_waitcnt vmcnt(7)
	v_pk_add_f32 v[62:63], v[26:27], v[62:63]
	v_pk_add_f32 v[60:61], v[24:25], v[60:61]
	global_load_dwordx4 v[24:27], v[56:57], off
	s_waitcnt vmcnt(7)
	v_pk_add_f32 v[74:75], v[22:23], v[74:75]
	v_pk_add_f32 v[72:73], v[20:21], v[72:73]
	global_load_dwordx4 v[20:23], v[58:59], off
	v_lshl_add_u64 v[56:57], v[64:65], 0, v[44:45]
	v_lshl_add_u64 v[58:59], v[64:65], 0, v[46:47]
	s_waitcnt vmcnt(7)
	v_pk_add_f32 v[78:79], v[18:19], v[78:79]
	v_pk_add_f32 v[76:77], v[16:17], v[76:77]
	global_load_dwordx4 v[16:19], v[56:57], off
	s_waitcnt vmcnt(7)
	v_pk_add_f32 v[82:83], v[14:15], v[82:83]
	v_pk_add_f32 v[80:81], v[12:13], v[80:81]
	global_load_dwordx4 v[12:15], v[58:59], off
	v_lshl_add_u64 v[56:57], v[64:65], 0, v[48:49]
	s_waitcnt vmcnt(7)
	v_pk_add_f32 v[86:87], v[10:11], v[86:87]
	v_pk_add_f32 v[84:85], v[8:9], v[84:85]
	global_load_dwordx4 v[8:11], v[56:57], off
	v_lshl_add_u64 v[56:57], v[64:65], 0, v[50:51]
	v_lshl_add_u64 v[96:97], v[54:55], 0, s[6:7]
	s_waitcnt vmcnt(7)
	v_pk_add_f32 v[90:91], v[6:7], v[90:91]
	v_pk_add_f32 v[88:89], v[4:5], v[88:89]
	global_load_dwordx4 v[4:7], v[56:57], off
	v_lshl_add_u64 v[56:57], v[64:65], 0, v[52:53]
	v_lshl_add_u64 v[58:59], v[96:97], 0, v[178:179]
	s_waitcnt vmcnt(7)
	v_pk_add_f32 v[64:65], v[2:3], v[94:95]
	v_pk_add_f32 v[92:93], v[0:1], v[92:93]
	global_load_dwordx4 v[0:3], v[56:57], off
	s_nop 0
	global_load_dwordx4 v[56:59], v[58:59], off
	s_mov_b64 s[6:7], 0x1800000
	s_waitcnt vmcnt(0)
	v_pk_add_f32 v[94:95], v[98:99], v[30:31]
	v_pk_add_f32 v[98:99], v[100:101], v[28:29]
	v_lshl_add_u64 v[28:29], v[96:97], 0, v[40:41]
	global_load_dwordx4 v[28:31], v[28:29], off
	v_lshl_add_u64 v[100:101], v[96:97], 0, v[50:51]
	s_waitcnt vmcnt(8)
	v_pk_add_f32 v[62:63], v[62:63], v[26:27]
	v_pk_add_f32 v[60:61], v[60:61], v[24:25]
	v_lshl_add_u64 v[24:25], v[96:97], 0, v[42:43]
	v_lshl_add_u64 v[26:27], v[96:97], 0, v[44:45]
	s_waitcnt vmcnt(7)
	v_pk_add_f32 v[74:75], v[74:75], v[22:23]
	v_pk_add_f32 v[72:73], v[72:73], v[20:21]
	v_lshl_add_u64 v[20:21], v[96:97], 0, v[46:47]
	v_lshl_add_u64 v[22:23], v[96:97], 0, v[48:49]
	s_waitcnt vmcnt(6)
	v_pk_add_f32 v[78:79], v[78:79], v[18:19]
	v_pk_add_f32 v[76:77], v[76:77], v[16:17]
	s_waitcnt vmcnt(5)
	v_pk_add_f32 v[82:83], v[82:83], v[14:15]
	v_pk_add_f32 v[80:81], v[80:81], v[12:13]
	global_load_dwordx4 v[12:15], v[24:25], off
	global_load_dwordx4 v[16:19], v[26:27], off
	s_waitcnt vmcnt(6)
	v_pk_add_f32 v[86:87], v[86:87], v[10:11]
	v_pk_add_f32 v[84:85], v[84:85], v[8:9]
	global_load_dwordx4 v[8:11], v[20:21], off
	s_nop 0
	global_load_dwordx4 v[20:23], v[22:23], off
	s_nop 0
	global_load_dwordx4 v[24:27], v[100:101], off
	s_waitcnt vmcnt(8)
	v_pk_add_f32 v[88:89], v[88:89], v[4:5]
	v_lshl_add_u64 v[4:5], v[96:97], 0, v[52:53]
	v_pk_add_f32 v[90:91], v[90:91], v[6:7]
	global_load_dwordx4 v[4:7], v[4:5], off
	s_waitcnt vmcnt(8)
	v_pk_add_f32 v[92:93], v[92:93], v[0:1]
	s_waitcnt vmcnt(7)
	v_pk_add_f32 v[96:97], v[98:99], v[56:57]
	v_lshl_add_u64 v[98:99], v[54:55], 0, s[6:7]
	v_lshl_add_u64 v[0:1], v[98:99], 0, v[178:179]
	v_lshl_add_u64 v[56:57], v[98:99], 0, v[42:43]
	v_pk_add_f32 v[64:65], v[64:65], v[2:3]
	v_pk_add_f32 v[94:95], v[94:95], v[58:59]
	global_load_dwordx4 v[0:3], v[0:1], off
	s_mov_b64 s[6:7], 0x2000000
	global_load_dwordx4 v[56:59], v[56:57], off
	s_waitcnt vmcnt(0)
; __device__ __forceinline__ void norm_phase(float* __restrict__ X, bf16_t* __restrict__ H, const float* __restrict__ modl, int shiftIdx, int scaleIdx, int nrows, const float* __restrict__ PART, const float* __restrict__ XLAT) {
;     ...
;             for (int s = 0; s < 8; ++s) { f32x4 pt[8];
; #pragma unroll
;                 for (int i = 0; i < 8; ++i) pt[i] = *(const f32x4*)(PART + ((size_t)s * NCTX + (row - NLAT)) * DM + (i * 64 + lane) * 4);
; #pragma unroll
;                 for (int i = 0; i < 8; ++i) x[i] += pt[i]; }
	v_pk_add_f32 v[60:61], v[60:61], v[28:29]
	v_lshl_add_u64 v[28:29], v[98:99], 0, v[40:41]
	v_pk_add_f32 v[62:63], v[62:63], v[30:31]
	global_load_dwordx4 v[28:31], v[28:29], off
	s_waitcnt vmcnt(8)
	v_pk_add_f32 v[74:75], v[74:75], v[14:15]
	s_waitcnt vmcnt(7)
	v_pk_add_f32 v[78:79], v[78:79], v[18:19]
	v_lshl_add_u64 v[14:15], v[98:99], 0, v[48:49]
	s_waitcnt vmcnt(6)
	v_pk_add_f32 v[82:83], v[82:83], v[10:11]
	s_waitcnt vmcnt(5)
	v_pk_add_f32 v[86:87], v[86:87], v[22:23]
	v_lshl_add_u64 v[10:11], v[98:99], 0, v[46:47]
	v_lshl_add_u64 v[18:19], v[98:99], 0, v[50:51]
	v_lshl_add_u64 v[22:23], v[98:99], 0, v[52:53]
	v_pk_add_f32 v[72:73], v[72:73], v[12:13]
	s_waitcnt vmcnt(4)
	v_pk_add_f32 v[90:91], v[90:91], v[26:27]
	v_pk_add_f32 v[80:81], v[80:81], v[8:9]
	s_waitcnt vmcnt(3)
	v_pk_add_f32 v[64:65], v[64:65], v[6:7]
	v_lshl_add_u64 v[6:7], v[98:99], 0, v[44:45]
	v_lshl_add_u64 v[98:99], v[54:55], 0, s[6:7]
	v_lshl_add_u64 v[26:27], v[98:99], 0, v[40:41]
	global_load_dwordx4 v[6:9], v[6:7], off
	v_pk_add_f32 v[4:5], v[92:93], v[4:5]
	v_pk_add_f32 v[76:77], v[76:77], v[16:17]
	v_pk_add_f32 v[84:85], v[84:85], v[20:21]
	s_waitcnt vmcnt(3)
	v_pk_add_f32 v[92:93], v[94:95], v[2:3]
	v_pk_add_f32 v[94:95], v[96:97], v[0:1]
	v_lshl_add_u64 v[0:1], v[98:99], 0, v[178:179]
	v_pk_add_f32 v[88:89], v[88:89], v[24:25]
	global_load_dwordx4 v[10:13], v[10:11], off
	s_mov_b64 s[6:7], 0x2800000
	global_load_dwordx4 v[14:17], v[14:15], off
	s_waitcnt vmcnt(0)
	v_pk_add_f32 v[96:97], v[60:61], v[28:29]
	global_load_dwordx4 v[26:29], v[26:27], off
	v_pk_add_f32 v[72:73], v[72:73], v[56:57]
	v_lshl_add_u64 v[56:57], v[98:99], 0, v[42:43]
	v_lshl_add_u64 v[60:61], v[98:99], 0, v[44:45]
	v_pk_add_f32 v[30:31], v[62:63], v[30:31]
	v_pk_add_f32 v[74:75], v[74:75], v[58:59]
	global_load_dwordx4 v[56:59], v[56:57], off
	s_waitcnt vmcnt(3)
	v_pk_add_f32 v[82:83], v[82:83], v[12:13]
	global_load_dwordx4 v[60:63], v[60:61], off
	s_waitcnt vmcnt(3)
	v_pk_add_f32 v[86:87], v[86:87], v[16:17]
	global_load_dwordx4 v[18:21], v[18:19], off
	v_lshl_add_u64 v[12:13], v[98:99], 0, v[50:51]
	global_load_dwordx4 v[22:25], v[22:23], off
	v_lshl_add_u64 v[16:17], v[98:99], 0, v[52:53]
	global_load_dwordx4 v[0:3], v[0:1], off
	v_pk_add_f32 v[76:77], v[76:77], v[6:7]
	v_pk_add_f32 v[78:79], v[78:79], v[8:9]
	v_lshl_add_u64 v[8:9], v[98:99], 0, v[48:49]
	v_pk_add_f32 v[80:81], v[80:81], v[10:11]
	v_pk_add_f32 v[84:85], v[84:85], v[14:15]
	s_waitcnt vmcnt(0)
	v_pk_add_f32 v[96:97], v[96:97], v[26:27]
	s_waitcnt vmcnt(4)
	v_pk_add_f32 v[72:73], v[72:73], v[56:57]
	v_pk_add_f32 v[74:75], v[74:75], v[58:59]
	s_waitcnt vmcnt(3)
	v_pk_add_f32 v[60:61], v[76:77], v[60:61]
	v_lshl_add_u64 v[76:77], v[54:55], 0, s[6:7]
	s_waitcnt vmcnt(2)
	v_pk_add_f32 v[88:89], v[88:89], v[18:19]
	v_pk_add_f32 v[90:91], v[90:91], v[20:21]
	s_waitcnt vmcnt(1)
	v_pk_add_f32 v[100:101], v[4:5], v[22:23]
	v_lshl_add_u64 v[4:5], v[98:99], 0, v[46:47]
	s_waitcnt vmcnt(0)
	v_pk_add_f32 v[94:95], v[94:95], v[0:1]
	v_lshl_add_u64 v[0:1], v[76:77], 0, v[178:179]
	global_load_dwordx4 v[4:7], v[4:5], off
	s_nop 0
	global_load_dwordx4 v[8:11], v[8:9], off
	s_nop 0
	global_load_dwordx4 v[12:15], v[12:13], off
	s_nop 0
	global_load_dwordx4 v[16:19], v[16:17], off
	v_pk_add_f32 v[92:93], v[92:93], v[2:3]
	global_load_dwordx4 v[0:3], v[0:1], off
	v_lshl_add_u64 v[20:21], v[76:77], 0, v[40:41]
	v_pk_add_f32 v[98:99], v[30:31], v[28:29]
	global_load_dwordx4 v[20:23], v[20:21], off
	v_lshl_add_u64 v[28:29], v[76:77], 0, v[44:45]
	v_lshl_add_u64 v[56:57], v[76:77], 0, v[46:47]
	global_load_dwordx4 v[28:31], v[28:29], off
	v_pk_add_f32 v[64:65], v[64:65], v[24:25]
	global_load_dwordx4 v[56:59], v[56:57], off
	v_lshl_add_u64 v[24:25], v[76:77], 0, v[42:43]
	global_load_dwordx4 v[24:27], v[24:25], off
	s_mov_b64 s[6:7], 0x3000000
	v_pk_add_f32 v[62:63], v[78:79], v[62:63]
	s_waitcnt vmcnt(0)
	v_pk_add_f32 v[80:81], v[80:81], v[4:5]
	v_lshl_add_u64 v[4:5], v[76:77], 0, v[48:49]
	v_pk_add_f32 v[78:79], v[82:83], v[6:7]
	global_load_dwordx4 v[4:7], v[4:5], off
	s_waitcnt vmcnt(5)
	v_pk_add_f32 v[94:95], v[94:95], v[0:1]
	v_lshl_add_u64 v[0:1], v[54:55], 0, s[6:7]
	v_pk_add_f32 v[86:87], v[86:87], v[10:11]
	v_pk_add_f32 v[8:9], v[84:85], v[8:9]
	v_pk_add_f32 v[84:85], v[90:91], v[14:15]
	v_lshl_add_u64 v[10:11], v[76:77], 0, v[50:51]
	v_lshl_add_u64 v[14:15], v[76:77], 0, v[52:53]
	v_pk_add_f32 v[92:93], v[92:93], v[2:3]
	v_lshl_add_u64 v[2:3], v[0:1], 0, v[178:179]
	v_pk_add_f32 v[88:89], v[88:89], v[12:13]
	v_pk_add_f32 v[64:65], v[64:65], v[18:19]
	v_pk_add_f32 v[90:91], v[100:101], v[16:17]
	global_load_dwordx4 v[10:13], v[10:11], off
	s_nop 0
	global_load_dwordx4 v[14:17], v[14:15], off
	s_waitcnt vmcnt(6)
; __device__ __forceinline__ void norm_phase(float* __restrict__ X, bf16_t* __restrict__ H, const float* __restrict__ modl, int shiftIdx, int scaleIdx, int nrows, const float* __restrict__ PART, const float* __restrict__ XLAT) {
;     ...
;             for (int s = 0; s < 8; ++s) { f32x4 pt[8];
; #pragma unroll
;                 for (int i = 0; i < 8; ++i) pt[i] = *(const f32x4*)(PART + ((size_t)s * NCTX + (row - NLAT)) * DM + (i * 64 + lane) * 4);
; #pragma unroll
;                 for (int i = 0; i < 8; ++i) x[i] += pt[i]; }
; #pragma unroll
;             for (int i = 0; i < 8; ++i) *(f32x4*)(xr + (i * 64 + lane) * 4) = x[i];
	v_pk_add_f32 v[96:97], v[96:97], v[20:21]
	global_load_dwordx4 v[18:21], v[2:3], off
	v_lshl_add_u64 v[2:3], v[0:1], 0, v[40:41]
	s_waitcnt vmcnt(5)
	v_pk_add_f32 v[104:105], v[78:79], v[58:59]
	v_pk_add_f32 v[106:107], v[80:81], v[56:57]
	global_load_dwordx4 v[56:59], v[2:3], off
	v_lshl_add_u64 v[2:3], v[0:1], 0, v[42:43]
	v_pk_add_f32 v[30:31], v[62:63], v[30:31]
	v_pk_add_f32 v[102:103], v[60:61], v[28:29]
	global_load_dwordx4 v[60:63], v[2:3], off
	v_lshl_add_u64 v[2:3], v[0:1], 0, v[44:45]
	v_pk_add_f32 v[22:23], v[98:99], v[22:23]
	s_waitcnt vmcnt(6)
	v_pk_add_f32 v[98:99], v[74:75], v[26:27]
	v_pk_add_f32 v[100:101], v[72:73], v[24:25]
	global_load_dwordx4 v[72:75], v[2:3], off
	v_lshl_add_u64 v[2:3], v[0:1], 0, v[46:47]
	global_load_dwordx4 v[76:79], v[2:3], off
	v_lshl_add_u64 v[2:3], v[0:1], 0, v[48:49]
	global_load_dwordx4 v[80:83], v[2:3], off
	s_mov_b64 s[6:7], 0x3800000
	v_lshl_add_u64 v[2:3], v[0:1], 0, v[50:51]
	v_lshl_add_u64 v[0:1], v[0:1], 0, v[52:53]
	s_waitcnt vmcnt(0)
	v_pk_add_f32 v[108:109], v[8:9], v[4:5]
	v_pk_add_f32 v[86:87], v[86:87], v[6:7]
	global_load_dwordx4 v[4:7], v[2:3], off
	s_nop 0
	global_load_dwordx4 v[0:3], v[0:1], off
	s_waitcnt vmcnt(9)
	v_pk_add_f32 v[8:9], v[84:85], v[12:13]
	s_waitcnt vmcnt(8)
	v_pk_add_f32 v[12:13], v[64:65], v[16:17]
	v_pk_add_f32 v[10:11], v[88:89], v[10:11]
	s_waitcnt vmcnt(7)
	v_pk_add_f32 v[26:27], v[92:93], v[20:21]
	v_pk_add_f32 v[28:29], v[94:95], v[18:19]
	v_pk_add_f32 v[14:15], v[90:91], v[14:15]
	s_waitcnt vmcnt(6)
	v_pk_add_f32 v[22:23], v[22:23], v[58:59]
	v_pk_add_f32 v[24:25], v[96:97], v[56:57]
	s_waitcnt vmcnt(5)
	v_pk_add_f32 v[18:19], v[98:99], v[62:63]
	v_pk_add_f32 v[20:21], v[100:101], v[60:61]
	s_waitcnt vmcnt(4)
	v_pk_add_f32 v[16:17], v[30:31], v[74:75]
	v_lshl_add_u64 v[30:31], v[54:55], 0, s[6:7]
	v_lshl_add_u64 v[54:55], v[30:31], 0, v[178:179]
	v_pk_add_f32 v[64:65], v[102:103], v[72:73]
	global_load_dwordx4 v[72:75], v[54:55], off
	v_lshl_add_u64 v[54:55], v[30:31], 0, v[40:41]
	s_waitcnt vmcnt(4)
	v_pk_add_f32 v[60:61], v[104:105], v[78:79]
	v_pk_add_f32 v[62:63], v[106:107], v[76:77]
	global_load_dwordx4 v[76:79], v[54:55], off
	v_lshl_add_u64 v[54:55], v[30:31], 0, v[42:43]
	s_waitcnt vmcnt(4)
	v_pk_add_f32 v[56:57], v[86:87], v[82:83]
	v_pk_add_f32 v[58:59], v[108:109], v[80:81]
	global_load_dwordx4 v[80:83], v[54:55], off
	v_lshl_add_u64 v[54:55], v[30:31], 0, v[44:45]
	global_load_dwordx4 v[84:87], v[54:55], off
	v_lshl_add_u64 v[54:55], v[30:31], 0, v[46:47]
	global_load_dwordx4 v[88:91], v[54:55], off
	v_lshl_add_u64 v[54:55], v[30:31], 0, v[48:49]
	global_load_dwordx4 v[92:95], v[54:55], off
	v_lshl_add_u64 v[54:55], v[30:31], 0, v[50:51]
	v_lshl_add_u64 v[30:31], v[30:31], 0, v[52:53]
	global_load_dwordx4 v[96:99], v[54:55], off
	global_load_dwordx4 v[100:103], v[30:31], off
	v_lshl_add_u64 v[54:55], s[92:93], 0, v[38:39]
	s_waitcnt vmcnt(0)
	v_pk_add_f32 v[4:5], v[10:11], v[4:5]
	v_pk_add_f32 v[6:7], v[8:9], v[6:7]
	s_waitcnt vmcnt(8)
	v_pk_add_f32 v[2:3], v[12:13], v[2:3]
	v_pk_add_f32 v[0:1], v[14:15], v[0:1]
	s_waitcnt vmcnt(7)
	v_pk_add_f32 v[30:31], v[26:27], v[74:75]
	v_pk_add_f32 v[28:29], v[28:29], v[72:73]
	s_waitcnt vmcnt(6)
	v_pk_add_f32 v[26:27], v[22:23], v[78:79]
	v_pk_add_f32 v[24:25], v[24:25], v[76:77]
	s_waitcnt vmcnt(5)
	v_pk_add_f32 v[22:23], v[18:19], v[82:83]
	v_pk_add_f32 v[20:21], v[20:21], v[80:81]
	s_waitcnt vmcnt(4)
	v_pk_add_f32 v[18:19], v[16:17], v[86:87]
	v_pk_add_f32 v[16:17], v[64:65], v[84:85]
	s_waitcnt vmcnt(3)
	v_pk_add_f32 v[14:15], v[60:61], v[90:91]
	v_pk_add_f32 v[12:13], v[62:63], v[88:89]
	s_waitcnt vmcnt(2)
	v_pk_add_f32 v[10:11], v[56:57], v[94:95]
	v_add_co_u32_e32 v56, vcc, s4, v54
	s_mov_b32 s4, 0x142de000
	s_nop 0
	v_addc_co_u32_e32 v57, vcc, 0, v55, vcc
	v_add_co_u32_e32 v54, vcc, s4, v54
	v_pk_add_f32 v[8:9], v[58:59], v[92:93]
	s_waitcnt vmcnt(1)
	v_pk_add_f32 v[6:7], v[6:7], v[98:99]
	v_pk_add_f32 v[4:5], v[4:5], v[96:97]
	s_waitcnt vmcnt(0)
	v_pk_add_f32 v[2:3], v[2:3], v[102:103]
	v_pk_add_f32 v[0:1], v[0:1], v[100:101]
	v_addc_co_u32_e32 v55, vcc, 0, v55, vcc
	global_store_dwordx4 v[54:55], v[28:31], off offset:-4096 sc0 sc1
	global_store_dwordx4 v[56:57], v[24:27], off offset:1024 sc0 sc1
	global_store_dwordx4 v[56:57], v[20:23], off offset:2048 sc0 sc1
	global_store_dwordx4 v[56:57], v[16:19], off offset:3072 sc0 sc1
	global_store_dwordx4 v[54:55], v[12:15], off sc0 sc1
	global_store_dwordx4 v[54:55], v[8:11], off offset:1024 sc0 sc1
	global_store_dwordx4 v[54:55], v[4:7], off offset:2048 sc0 sc1
	global_store_dwordx4 v[54:55], v[0:3], off offset:3072 sc0 sc1
	s_branch .LBB0_2149

; #define PG8_STAGE(bufoff, gbase, voff) do { _Pragma("unroll") for (int _i = 0; _i < 2; ++_i) \
;         __builtin_amdgcn_global_load_lds((const unsigned*)((const char*)(gbase) + (voff)[_i]), (LAS unsigned*)(lds + (bufoff) + ldsw + _i * 8192), 16, 0, 0); } while (0)
; #define PG8_LDA(dst, b, h) do { _Pragma("unroll") for (int m = 0; m < 4; ++m) _Pragma("unroll") for (int k = 0; k < 2; ++k) dst[m][k] = *(const LAS bf16x8*)(lds + PG8_SA(b, h) + aoff + m * 2048 + k * 1024); } while (0)
; #define PG8_LDB(dst, b, h) do { _Pragma("unroll") for (int n = 0; n < 2; ++n) _Pragma("unroll") for (int k = 0; k < 2; ++k) dst[n][k] = *(const LAS bf16x8*)(lds + PG8_SB(b, h) + boff + n * 2048 + k * 1024); } while (0)
; #define PG8_MMA(ai, bj, At, Bt) do { __builtin_amdgcn_s_setprio(1); _Pragma("unroll") for (int m = 0; m < 4; ++m) _Pragma("unroll") for (int n = 0; n < 2; ++n) _Pragma("unroll") for (int k = 0; k < 2; ++k) \
;         acc[ai][bj][m][n] = __builtin_amdgcn_mfma_f32_16x16x32_bf16(Bt[n][k], At[m][k], acc[ai][bj][m][n], 0, 0, 0); __builtin_amdgcn_s_setprio(0); } while (0)
; #define PG8_WAIT_V(n) asm volatile("s_waitcnt vmcnt(" #n ")" ::: "memory")
; #define PG8_WAIT_L(n) asm volatile("s_waitcnt lgkmcnt(" #n ")" ::: "memory")
; #define PG8_BAR __builtin_amdgcn_s_barrier()
; #define PG8_SCHED __builtin_amdgcn_sched_barrier(0)
; template <class Epi>
; __device__ __forceinline__ void gemm_phase(LAS unsigned char* lds, const Gemm g, const StaticOrder S, const Epi E) {
;     ...
;             PG8_LDB(B0, 0, 0); PG8_SCHED; PG8_LDA(At, 0, 0); PG8_STAGE(PG8_SA(1, 1), a1 + hstep, voffA);
;             PG8_WAIT_L(8); PG8_BAR; PG8_WAIT_L(0); PG8_MMA(0, 0, At, B0); PG8_BAR; PG8_SCHED;
;             PG8_LDB(B1, 0, 1); PG8_STAGE(PG8_SB(0, 0), b2, voffA);
;             PG8_BAR; PG8_WAIT_L(0); PG8_MMA(0, 1, At, B1); PG8_BAR;
;             PG8_LDA(At, 0, 1); PG8_STAGE(PG8_SA(0, 0), a2, voffA);
;             PG8_BAR; PG8_WAIT_L(0); PG8_MMA(1, 0, At, B0); PG8_BAR; PG8_SCHED;
;             PG8_STAGE(PG8_SB(0, 1), b2 + hstep, voffA);
;             PG8_WAIT_V(6); PG8_BAR; PG8_MMA(1, 1, At, B1); PG8_BAR;
.LBB0_2219:
	s_add_u32 s30, s44, 0xfff80080
	s_addc_u32 s31, s45, -1
	s_add_i32 s57, 0, 0x10000
	v_add_u32_e32 v134, s57, v137
	ds_read_b128 v[140:143], v134
	ds_read_b128 v[144:147], v134 offset:1024
	ds_read_b128 v[148:151], v134 offset:2048
	ds_read_b128 v[152:155], v134 offset:3072
	s_cmp_eq_u32 s56, 28
	s_cselect_b32 s49, s11, s31
	s_cselect_b32 s48, s28, s30
	s_cselect_b32 s47, s3, s55
	s_cselect_b32 s46, s29, s54
	v_lshl_add_u64 v[134:135], s[44:45], 0, v[130:131]
	s_add_i32 m0, s23, 0xc000
	ds_read_b128 v[156:159], v139
	ds_read_b128 v[160:163], v139 offset:1024
	ds_read_b128 v[164:167], v139 offset:2048
	ds_read_b128 v[168:171], v139 offset:3072
	ds_read_b128 v[172:175], v139 offset:4096
	ds_read_b128 v[194:197], v139 offset:5120
	ds_read_b128 v[198:201], v139 offset:6144
	ds_read_b128 v[202:205], v139 offset:7168
	global_load_lds_dwordx4 v[134:135], off
	v_lshl_add_u64 v[134:135], s[44:45], 0, v[132:133]
	s_add_i32 m0, s23, 0xe000
	s_nop 0
	global_load_lds_dwordx4 v[134:135], off
	s_waitcnt lgkmcnt(8)
	s_barrier
	s_waitcnt lgkmcnt(0)
	s_setprio 1
	s_waitcnt lgkmcnt(0)
	v_mfma_f32_16x16x32_bf16 v[120:123], v[140:143], v[156:159], v[120:123]
	v_mfma_f32_16x16x32_bf16 v[124:127], v[148:151], v[156:159], v[124:127]
	v_mfma_f32_16x16x32_bf16 v[104:107], v[140:143], v[164:167], v[104:107]
	v_mfma_f32_16x16x32_bf16 v[108:111], v[148:151], v[164:167], v[108:111]
	v_mfma_f32_16x16x32_bf16 v[88:91], v[140:143], v[172:175], v[88:91]
	v_mfma_f32_16x16x32_bf16 v[92:95], v[148:151], v[172:175], v[92:95]
	v_mfma_f32_16x16x32_bf16 v[72:75], v[140:143], v[198:201], v[72:75]
	v_mfma_f32_16x16x32_bf16 v[76:79], v[148:151], v[198:201], v[76:79]
	v_mfma_f32_16x16x32_bf16 v[120:123], v[144:147], v[160:163], v[120:123]
	v_mfma_f32_16x16x32_bf16 v[124:127], v[152:155], v[160:163], v[124:127]
	v_mfma_f32_16x16x32_bf16 v[104:107], v[144:147], v[168:171], v[104:107]
	v_mfma_f32_16x16x32_bf16 v[108:111], v[152:155], v[168:171], v[108:111]
	v_mfma_f32_16x16x32_bf16 v[88:91], v[144:147], v[194:197], v[88:91]
	v_mfma_f32_16x16x32_bf16 v[92:95], v[152:155], v[194:197], v[92:95]
	v_mfma_f32_16x16x32_bf16 v[72:75], v[144:147], v[202:205], v[72:75]
	v_mfma_f32_16x16x32_bf16 v[76:79], v[152:155], v[202:205], v[76:79]
	s_setprio 0
	s_barrier
	s_add_i32 s58, 0, 0x14000
	v_add_u32_e32 v134, s58, v137
	s_add_i32 s30, s57, s22
	ds_read_b128 v[206:209], v134
	ds_read_b128 v[228:231], v134 offset:1024
	ds_read_b128 v[232:235], v134 offset:2048
	ds_read_b128 v[236:239], v134 offset:3072
	v_lshl_add_u64 v[134:135], s[46:47], 0, v[178:179]
	s_mov_b32 m0, s30
	v_lshl_add_u64 v[210:211], s[46:47], 0, v[128:129]
	global_load_lds_dwordx4 v[134:135], off
	s_add_i32 m0, s30, 0x2000
	s_nop 0
	global_load_lds_dwordx4 v[210:211], off
	s_barrier
	s_waitcnt lgkmcnt(0)
	s_setprio 1
	s_waitcnt lgkmcnt(0)
	v_mfma_f32_16x16x32_bf16 v[112:115], v[206:209], v[156:159], v[112:115]
	v_mfma_f32_16x16x32_bf16 v[116:119], v[232:235], v[156:159], v[116:119]
	v_mfma_f32_16x16x32_bf16 v[96:99], v[206:209], v[164:167], v[96:99]
	v_mfma_f32_16x16x32_bf16 v[100:103], v[232:235], v[164:167], v[100:103]
	v_mfma_f32_16x16x32_bf16 v[80:83], v[206:209], v[172:175], v[80:83]
	v_mfma_f32_16x16x32_bf16 v[84:87], v[232:235], v[172:175], v[84:87]
	v_mfma_f32_16x16x32_bf16 v[64:67], v[206:209], v[198:201], v[64:67]
	v_mfma_f32_16x16x32_bf16 v[68:71], v[232:235], v[198:201], v[68:71]
	v_mfma_f32_16x16x32_bf16 v[112:115], v[228:231], v[160:163], v[112:115]
	v_mfma_f32_16x16x32_bf16 v[116:119], v[236:239], v[160:163], v[116:119]
	v_mfma_f32_16x16x32_bf16 v[96:99], v[228:231], v[168:171], v[96:99]
	v_mfma_f32_16x16x32_bf16 v[100:103], v[236:239], v[168:171], v[100:103]
	v_mfma_f32_16x16x32_bf16 v[80:83], v[228:231], v[194:197], v[80:83]
	v_mfma_f32_16x16x32_bf16 v[84:87], v[236:239], v[194:197], v[84:87]
	v_mfma_f32_16x16x32_bf16 v[64:67], v[228:231], v[202:205], v[64:67]
	v_mfma_f32_16x16x32_bf16 v[68:71], v[236:239], v[202:205], v[68:71]
	s_setprio 0
	s_barrier
	s_mov_b32 m0, s23
	v_lshl_add_u64 v[220:221], s[48:49], 0, v[178:179]
	ds_read_b128 v[156:159], v139 offset:16384
	ds_read_b128 v[160:163], v139 offset:17408
	ds_read_b128 v[164:167], v139 offset:18432
	ds_read_b128 v[168:171], v139 offset:19456
	ds_read_b128 v[172:175], v139 offset:20480
	ds_read_b128 v[194:197], v139 offset:21504
	ds_read_b128 v[198:201], v139 offset:22528
	ds_read_b128 v[202:205], v139 offset:23552
	global_load_lds_dwordx4 v[220:221], off
	v_lshl_add_u64 v[222:223], s[48:49], 0, v[128:129]
	s_mov_b32 m0, s24
	s_nop 0
	global_load_lds_dwordx4 v[222:223], off
	s_barrier
	s_waitcnt lgkmcnt(0)
	s_setprio 1
	s_waitcnt lgkmcnt(0)
	v_mfma_f32_16x16x32_bf16 v[56:59], v[140:143], v[156:159], v[56:59]
	v_mfma_f32_16x16x32_bf16 v[60:63], v[148:151], v[156:159], v[60:63]
	v_mfma_f32_16x16x32_bf16 v[40:43], v[140:143], v[164:167], v[40:43]
	v_mfma_f32_16x16x32_bf16 v[44:47], v[148:151], v[164:167], v[44:47]
	v_mfma_f32_16x16x32_bf16 v[24:27], v[140:143], v[172:175], v[24:27]
	v_mfma_f32_16x16x32_bf16 v[28:31], v[148:151], v[172:175], v[28:31]
	v_mfma_f32_16x16x32_bf16 v[8:11], v[140:143], v[198:201], v[8:11]
	v_mfma_f32_16x16x32_bf16 v[12:15], v[148:151], v[198:201], v[12:15]
	v_mfma_f32_16x16x32_bf16 v[56:59], v[144:147], v[160:163], v[56:59]
	v_mfma_f32_16x16x32_bf16 v[60:63], v[152:155], v[160:163], v[60:63]
	v_mfma_f32_16x16x32_bf16 v[40:43], v[144:147], v[168:171], v[40:43]
	v_mfma_f32_16x16x32_bf16 v[44:47], v[152:155], v[168:171], v[44:47]
	v_mfma_f32_16x16x32_bf16 v[24:27], v[144:147], v[194:197], v[24:27]
	v_mfma_f32_16x16x32_bf16 v[28:31], v[152:155], v[194:197], v[28:31]
	v_mfma_f32_16x16x32_bf16 v[8:11], v[144:147], v[202:205], v[8:11]
	v_mfma_f32_16x16x32_bf16 v[12:15], v[152:155], v[202:205], v[12:15]
	s_setprio 0
	s_barrier
; #define PG8_STAGE(bufoff, gbase, voff) do { _Pragma("unroll") for (int _i = 0; _i < 2; ++_i) \
;         __builtin_amdgcn_global_load_lds((const unsigned*)((const char*)(gbase) + (voff)[_i]), (LAS unsigned*)(lds + (bufoff) + ldsw + _i * 8192), 16, 0, 0); } while (0)
; #define PG8_LDA(dst, b, h) do { _Pragma("unroll") for (int m = 0; m < 4; ++m) _Pragma("unroll") for (int k = 0; k < 2; ++k) dst[m][k] = *(const LAS bf16x8*)(lds + PG8_SA(b, h) + aoff + m * 2048 + k * 1024); } while (0)
; #define PG8_LDB(dst, b, h) do { _Pragma("unroll") for (int n = 0; n < 2; ++n) _Pragma("unroll") for (int k = 0; k < 2; ++k) dst[n][k] = *(const LAS bf16x8*)(lds + PG8_SB(b, h) + boff + n * 2048 + k * 1024); } while (0)
; #define PG8_MMA(ai, bj, At, Bt) do { __builtin_amdgcn_s_setprio(1); _Pragma("unroll") for (int m = 0; m < 4; ++m) _Pragma("unroll") for (int n = 0; n < 2; ++n) _Pragma("unroll") for (int k = 0; k < 2; ++k) \
;         acc[ai][bj][m][n] = __builtin_amdgcn_mfma_f32_16x16x32_bf16(Bt[n][k], At[m][k], acc[ai][bj][m][n], 0, 0, 0); __builtin_amdgcn_s_setprio(0); } while (0)
; #define PG8_WAIT_V(n) asm volatile("s_waitcnt vmcnt(" #n ")" ::: "memory")
; #define PG8_WAIT_L(n) asm volatile("s_waitcnt lgkmcnt(" #n ")" ::: "memory")
; #define PG8_BAR __builtin_amdgcn_s_barrier()
; #define PG8_SCHED __builtin_amdgcn_sched_barrier(0)
; template <class Epi>
; __device__ __forceinline__ void gemm_phase(LAS unsigned char* lds, const Gemm g, const StaticOrder S, const Epi E) {
;     ...
;             PG8_STAGE(PG8_SB(0, 1), b2 + hstep, voffA);
;             PG8_WAIT_V(6); PG8_BAR; PG8_MMA(1, 1, At, B1); PG8_BAR;
;             PG8_LDB(B0, 1, 0); PG8_SCHED; PG8_LDA(At, 1, 0); PG8_STAGE(PG8_SA(0, 1), a2 + hstep, voffA);
;             PG8_WAIT_L(8); PG8_BAR; PG8_WAIT_L(0); PG8_MMA(0, 0, At, B0); PG8_BAR; PG8_SCHED;
;             PG8_LDB(B1, 1, 1); PG8_STAGE(PG8_SB(1, 0), b3, voffA);
;             PG8_BAR; PG8_WAIT_L(0); PG8_MMA(0, 1, At, B1); PG8_BAR;
;             PG8_LDA(At, 1, 1); PG8_STAGE(PG8_SA(1, 0), a3, voffA);
;             PG8_BAR; PG8_WAIT_L(0); PG8_MMA(1, 0, At, B0); PG8_BAR; PG8_SCHED;
;             PG8_STAGE(PG8_SB(1, 1), b3 + hstep, voffA);
;             PG8_WAIT_V(6); PG8_BAR; PG8_MMA(1, 1, At, B1); PG8_BAR;
	s_add_u32 s30, s46, 0x80000
	s_addc_u32 s31, s47, 0
	s_add_i32 s57, s58, s22
	v_lshl_add_u64 v[140:141], s[30:31], 0, v[178:179]
	s_mov_b32 m0, s57
	s_nop 0
	global_load_lds_dwordx4 v[140:141], off
	v_lshl_add_u64 v[140:141], s[30:31], 0, v[128:129]
	s_add_i32 m0, s57, 0x2000
	s_nop 0
	global_load_lds_dwordx4 v[140:141], off
	s_waitcnt vmcnt(6)
	s_barrier
	s_setprio 1
	v_mfma_f32_16x16x32_bf16 v[48:51], v[206:209], v[156:159], v[48:51]
	v_mfma_f32_16x16x32_bf16 v[52:55], v[232:235], v[156:159], v[52:55]
	v_mfma_f32_16x16x32_bf16 v[32:35], v[206:209], v[164:167], v[32:35]
	v_mfma_f32_16x16x32_bf16 v[36:39], v[232:235], v[164:167], v[36:39]
	v_mfma_f32_16x16x32_bf16 v[16:19], v[206:209], v[172:175], v[16:19]
	v_mfma_f32_16x16x32_bf16 v[20:23], v[232:235], v[172:175], v[20:23]
	v_mfma_f32_16x16x32_bf16 v[0:3], v[206:209], v[198:201], v[0:3]
	v_mfma_f32_16x16x32_bf16 v[4:7], v[232:235], v[198:201], v[4:7]
	v_mfma_f32_16x16x32_bf16 v[48:51], v[228:231], v[160:163], v[48:51]
	v_mfma_f32_16x16x32_bf16 v[52:55], v[236:239], v[160:163], v[52:55]
	v_mfma_f32_16x16x32_bf16 v[32:35], v[228:231], v[168:171], v[32:35]
	v_mfma_f32_16x16x32_bf16 v[36:39], v[236:239], v[168:171], v[36:39]
	v_mfma_f32_16x16x32_bf16 v[16:19], v[228:231], v[194:197], v[16:19]
	v_mfma_f32_16x16x32_bf16 v[20:23], v[236:239], v[194:197], v[20:23]
	v_mfma_f32_16x16x32_bf16 v[0:3], v[228:231], v[202:205], v[0:3]
	v_mfma_f32_16x16x32_bf16 v[4:7], v[236:239], v[202:205], v[4:7]
	s_setprio 0
	s_barrier
	s_add_i32 s57, 0, 0x18000
	v_add_u32_e32 v152, s57, v137
	ds_read_b128 v[140:143], v152
	ds_read_b128 v[144:147], v152 offset:1024
	ds_read_b128 v[148:151], v152 offset:2048
	ds_read_b128 v[152:155], v152 offset:3072
	s_add_u32 s30, s48, 0x80000
	s_addc_u32 s31, s49, 0
	s_mov_b32 m0, s25
	v_lshl_add_u64 v[206:207], s[30:31], 0, v[178:179]
	ds_read_b128 v[156:159], v139 offset:32768
	ds_read_b128 v[160:163], v139 offset:33792
	ds_read_b128 v[164:167], v139 offset:34816
	ds_read_b128 v[168:171], v139 offset:35840
	ds_read_b128 v[172:175], v139 offset:36864
	ds_read_b128 v[194:197], v139 offset:37888
	ds_read_b128 v[198:201], v139 offset:38912
	ds_read_b128 v[202:205], v139 offset:39936
	global_load_lds_dwordx4 v[206:207], off
	v_lshl_add_u64 v[206:207], s[30:31], 0, v[128:129]
	s_mov_b32 m0, s50
	s_nop 0
	global_load_lds_dwordx4 v[206:207], off
	s_waitcnt lgkmcnt(8)
	s_barrier
	s_waitcnt lgkmcnt(0)
	s_setprio 1
	s_waitcnt lgkmcnt(0)
	v_mfma_f32_16x16x32_bf16 v[120:123], v[140:143], v[156:159], v[120:123]
	v_mfma_f32_16x16x32_bf16 v[124:127], v[148:151], v[156:159], v[124:127]
	v_mfma_f32_16x16x32_bf16 v[104:107], v[140:143], v[164:167], v[104:107]
	v_mfma_f32_16x16x32_bf16 v[108:111], v[148:151], v[164:167], v[108:111]
	v_mfma_f32_16x16x32_bf16 v[88:91], v[140:143], v[172:175], v[88:91]
	v_mfma_f32_16x16x32_bf16 v[92:95], v[148:151], v[172:175], v[92:95]
	v_mfma_f32_16x16x32_bf16 v[72:75], v[140:143], v[198:201], v[72:75]
	v_mfma_f32_16x16x32_bf16 v[76:79], v[148:151], v[198:201], v[76:79]
	v_mfma_f32_16x16x32_bf16 v[120:123], v[144:147], v[160:163], v[120:123]
	v_mfma_f32_16x16x32_bf16 v[124:127], v[152:155], v[160:163], v[124:127]
	v_mfma_f32_16x16x32_bf16 v[104:107], v[144:147], v[168:171], v[104:107]
	v_mfma_f32_16x16x32_bf16 v[108:111], v[152:155], v[168:171], v[108:111]
	v_mfma_f32_16x16x32_bf16 v[88:91], v[144:147], v[194:197], v[88:91]
	v_mfma_f32_16x16x32_bf16 v[92:95], v[152:155], v[194:197], v[92:95]
	v_mfma_f32_16x16x32_bf16 v[72:75], v[144:147], v[202:205], v[72:75]
	v_mfma_f32_16x16x32_bf16 v[76:79], v[152:155], v[202:205], v[76:79]
	s_setprio 0
	s_barrier
	s_add_i32 s48, 0, 0x1c000
	s_add_i32 s30, s57, s22
	v_add_u32_e32 v227, s48, v137
	v_lshl_add_u64 v[134:135], v[134:135], 0, s[34:35]
	s_mov_b32 m0, s30
	ds_read_b128 v[206:209], v227
	ds_read_b128 v[228:231], v227 offset:1024
	ds_read_b128 v[232:235], v227 offset:2048
	ds_read_b128 v[236:239], v227 offset:3072
	global_load_lds_dwordx4 v[134:135], off
	v_lshl_add_u64 v[134:135], v[210:211], 0, s[34:35]
	s_add_i32 m0, s30, 0x2000
	s_nop 0
	global_load_lds_dwordx4 v[134:135], off
	s_barrier
	s_waitcnt lgkmcnt(0)
	s_setprio 1
	s_waitcnt lgkmcnt(0)
	v_mfma_f32_16x16x32_bf16 v[112:115], v[206:209], v[156:159], v[112:115]
	v_mfma_f32_16x16x32_bf16 v[116:119], v[232:235], v[156:159], v[116:119]
	v_mfma_f32_16x16x32_bf16 v[96:99], v[206:209], v[164:167], v[96:99]
	v_mfma_f32_16x16x32_bf16 v[100:103], v[232:235], v[164:167], v[100:103]
	v_mfma_f32_16x16x32_bf16 v[80:83], v[206:209], v[172:175], v[80:83]
	v_mfma_f32_16x16x32_bf16 v[84:87], v[232:235], v[172:175], v[84:87]
	v_mfma_f32_16x16x32_bf16 v[64:67], v[206:209], v[198:201], v[64:67]
	v_mfma_f32_16x16x32_bf16 v[68:71], v[232:235], v[198:201], v[68:71]
	v_mfma_f32_16x16x32_bf16 v[112:115], v[228:231], v[160:163], v[112:115]
	v_mfma_f32_16x16x32_bf16 v[116:119], v[236:239], v[160:163], v[116:119]
	v_mfma_f32_16x16x32_bf16 v[96:99], v[228:231], v[168:171], v[96:99]
	v_mfma_f32_16x16x32_bf16 v[100:103], v[236:239], v[168:171], v[100:103]
	v_mfma_f32_16x16x32_bf16 v[80:83], v[228:231], v[194:197], v[80:83]
	v_mfma_f32_16x16x32_bf16 v[84:87], v[236:239], v[194:197], v[84:87]
	v_mfma_f32_16x16x32_bf16 v[64:67], v[228:231], v[202:205], v[64:67]
	v_mfma_f32_16x16x32_bf16 v[68:71], v[236:239], v[202:205], v[68:71]
	s_setprio 0
	s_barrier
	s_mov_b32 m0, s51
	v_lshl_add_u64 v[134:135], v[220:221], 0, s[34:35]
	ds_read_b128 v[156:159], v139 offset:49152
	ds_read_b128 v[160:163], v139 offset:50176
	ds_read_b128 v[164:167], v139 offset:51200
	ds_read_b128 v[168:171], v139 offset:52224
	ds_read_b128 v[172:175], v139 offset:53248
	ds_read_b128 v[194:197], v139 offset:54272
	ds_read_b128 v[198:201], v139 offset:55296
	ds_read_b128 v[202:205], v139 offset:56320
	global_load_lds_dwordx4 v[134:135], off
	v_lshl_add_u64 v[134:135], v[222:223], 0, s[34:35]
	s_mov_b32 m0, s52
	s_nop 0
	global_load_lds_dwordx4 v[134:135], off
	s_barrier
; __device__ __forceinline__ unsigned cvt_pk_bf16(float lo, float hi) { unsigned r; asm("v_cvt_pk_bf16_f32 %0, %1, %2" : "=v"(r) : "v"(lo), "v"(hi)); return r; }
; #define PG8_STAGE(bufoff, gbase, voff) do { _Pragma("unroll") for (int _i = 0; _i < 2; ++_i) \
;         __builtin_amdgcn_global_load_lds((const unsigned*)((const char*)(gbase) + (voff)[_i]), (LAS unsigned*)(lds + (bufoff) + ldsw + _i * 8192), 16, 0, 0); } while (0)
; #define PG8_LDA(dst, b, h) do { _Pragma("unroll") for (int m = 0; m < 4; ++m) _Pragma("unroll") for (int k = 0; k < 2; ++k) dst[m][k] = *(const LAS bf16x8*)(lds + PG8_SA(b, h) + aoff + m * 2048 + k * 1024); } while (0)
; #define PG8_MMA(ai, bj, At, Bt) do { __builtin_amdgcn_s_setprio(1); _Pragma("unroll") for (int m = 0; m < 4; ++m) _Pragma("unroll") for (int n = 0; n < 2; ++n) _Pragma("unroll") for (int k = 0; k < 2; ++k) \
;         acc[ai][bj][m][n] = __builtin_amdgcn_mfma_f32_16x16x32_bf16(Bt[n][k], At[m][k], acc[ai][bj][m][n], 0, 0, 0); __builtin_amdgcn_s_setprio(0); } while (0)
; #define PG8_WAIT_V(n) asm volatile("s_waitcnt vmcnt(" #n ")" ::: "memory")
; #define PG8_WAIT_L(n) asm volatile("s_waitcnt lgkmcnt(" #n ")" ::: "memory")
; #define PG8_BAR __builtin_amdgcn_s_barrier()
; template <class Epi>
; __device__ __forceinline__ void gemm_phase(LAS unsigned char* lds, const Gemm g, const StaticOrder S, const Epi E) {
;     ...
;             PG8_LDA(At, 1, 1); PG8_STAGE(PG8_SA(1, 0), a3, voffA);
;             PG8_BAR; PG8_WAIT_L(0); PG8_MMA(1, 0, At, B0); PG8_BAR; PG8_SCHED;
;             PG8_STAGE(PG8_SB(1, 1), b3 + hstep, voffA);
;             PG8_WAIT_V(6); PG8_BAR; PG8_MMA(1, 1, At, B1); PG8_BAR;
;         }
;         E(acc, cur, wr, wc, fr, fq);
;     __device__ __forceinline__ void operator()(AccRef acc, const pg8::Unit& u, int wr, int wc, int fr, int fq) const {
;     ...
;             for (int m = 0; m < 4; ++m) { bf16_t* rowp = G + (size_t)(row0 + ai * 128 + m * 16) * FH + col0;
; #pragma unroll
;                 for (int bj = 0; bj < 2; ++bj) { const f32x4 gq = acc[ai][bj][m][0], uq = acc[ai][bj][m][1]; float v[4];
; #pragma unroll
;                     for (int i = 0; i < 4; ++i) v[i] = gq[i] * uq[i] * __builtin_amdgcn_rcpf(1.f + __builtin_amdgcn_exp2f(-gq[i] * LOG2E));
;                     u32x2 w; w.x = cvt_pk_bf16(v[0], v[1]); w.y = cvt_pk_bf16(v[2], v[3]);
;                     *(u32x2*)(rowp + bj * 64) = w; } }
	s_waitcnt lgkmcnt(0)
	s_setprio 1
	s_waitcnt lgkmcnt(0)
	v_mfma_f32_16x16x32_bf16 v[56:59], v[140:143], v[156:159], v[56:59]
	v_mfma_f32_16x16x32_bf16 v[60:63], v[148:151], v[156:159], v[60:63]
	v_mfma_f32_16x16x32_bf16 v[40:43], v[140:143], v[164:167], v[40:43]
	v_mfma_f32_16x16x32_bf16 v[44:47], v[148:151], v[164:167], v[44:47]
	v_mfma_f32_16x16x32_bf16 v[24:27], v[140:143], v[172:175], v[24:27]
	v_mfma_f32_16x16x32_bf16 v[28:31], v[148:151], v[172:175], v[28:31]
	v_mfma_f32_16x16x32_bf16 v[8:11], v[140:143], v[198:201], v[8:11]
	v_mfma_f32_16x16x32_bf16 v[12:15], v[148:151], v[198:201], v[12:15]
	v_mfma_f32_16x16x32_bf16 v[56:59], v[144:147], v[160:163], v[56:59]
	v_mfma_f32_16x16x32_bf16 v[60:63], v[152:155], v[160:163], v[60:63]
	v_mfma_f32_16x16x32_bf16 v[40:43], v[144:147], v[168:171], v[40:43]
	v_mfma_f32_16x16x32_bf16 v[44:47], v[152:155], v[168:171], v[44:47]
	v_mfma_f32_16x16x32_bf16 v[24:27], v[144:147], v[194:197], v[24:27]
	v_mfma_f32_16x16x32_bf16 v[28:31], v[152:155], v[194:197], v[28:31]
	v_mfma_f32_16x16x32_bf16 v[8:11], v[144:147], v[202:205], v[8:11]
	v_mfma_f32_16x16x32_bf16 v[12:15], v[152:155], v[202:205], v[12:15]
	s_setprio 0
	s_barrier
	s_add_u32 s30, s46, 0x80080
	s_addc_u32 s31, s47, 0
	s_add_i32 s46, s48, s22
	v_lshl_add_u64 v[134:135], s[30:31], 0, v[178:179]
	s_mov_b32 m0, s46
	s_nop 0
	global_load_lds_dwordx4 v[134:135], off
	v_lshl_add_u64 v[134:135], s[30:31], 0, v[128:129]
	s_add_i32 m0, s46, 0x2000
	s_nop 0
	global_load_lds_dwordx4 v[134:135], off
	s_waitcnt vmcnt(6)
	s_barrier
	s_setprio 1
	v_mfma_f32_16x16x32_bf16 v[48:51], v[206:209], v[156:159], v[48:51]
	v_mfma_f32_16x16x32_bf16 v[52:55], v[232:235], v[156:159], v[52:55]
	v_mfma_f32_16x16x32_bf16 v[32:35], v[206:209], v[164:167], v[32:35]
	v_mfma_f32_16x16x32_bf16 v[36:39], v[232:235], v[164:167], v[36:39]
	v_mfma_f32_16x16x32_bf16 v[16:19], v[206:209], v[172:175], v[16:19]
	v_mfma_f32_16x16x32_bf16 v[20:23], v[232:235], v[172:175], v[20:23]
	v_mfma_f32_16x16x32_bf16 v[0:3], v[206:209], v[198:201], v[0:3]
	v_mfma_f32_16x16x32_bf16 v[4:7], v[232:235], v[198:201], v[4:7]
	v_mfma_f32_16x16x32_bf16 v[48:51], v[228:231], v[160:163], v[48:51]
	v_mfma_f32_16x16x32_bf16 v[52:55], v[236:239], v[160:163], v[52:55]
	v_mfma_f32_16x16x32_bf16 v[32:35], v[228:231], v[168:171], v[32:35]
	v_mfma_f32_16x16x32_bf16 v[36:39], v[236:239], v[168:171], v[36:39]
	v_mfma_f32_16x16x32_bf16 v[16:19], v[228:231], v[194:197], v[16:19]
	v_mfma_f32_16x16x32_bf16 v[20:23], v[236:239], v[194:197], v[20:23]
	v_mfma_f32_16x16x32_bf16 v[0:3], v[228:231], v[202:205], v[0:3]
	v_mfma_f32_16x16x32_bf16 v[4:7], v[236:239], v[202:205], v[4:7]
	s_setprio 0
	s_barrier
	s_add_i32 s56, s56, 2
	s_add_u32 s44, s44, 0x100
	s_addc_u32 s45, s45, 0
	s_add_u32 s54, s54, 0x100
	s_addc_u32 s55, s55, 0
	s_cmp_gt_u32 s56, 29
	s_cbranch_scc0 .LBB0_2219
	v_mul_f32_e32 v116, v116, v112
	v_mul_f32_e32 v112, 0xbfb8aa3b, v112
	v_exp_f32_e32 v112, v112
	v_mul_f32_e32 v100, v100, v96
	v_mul_f32_e32 v96, 0xbfb8aa3b, v96
	v_exp_f32_e32 v96, v96
	v_mul_f32_e32 v84, v84, v80
	v_mul_f32_e32 v80, 0xbfb8aa3b, v80
	v_add_f32_e32 v112, 1.0, v112
	v_exp_f32_e32 v80, v80
	v_rcp_f32_e32 v112, v112
	v_mul_f32_e32 v68, v68, v64
	v_mul_f32_e32 v64, 0xbfb8aa3b, v64
	v_add_f32_e32 v96, 1.0, v96
	v_exp_f32_e32 v64, v64
	v_rcp_f32_e32 v96, v96
	v_mul_f32_e32 v52, v52, v48
	v_mul_f32_e32 v48, 0xbfb8aa3b, v48
	v_add_f32_e32 v80, 1.0, v80
	v_exp_f32_e32 v48, v48
	v_mul_f32_e32 v112, v116, v112
	v_mul_f32_e32 v116, v117, v113
	v_mul_f32_e32 v113, 0xbfb8aa3b, v113
	v_rcp_f32_e32 v80, v80
	v_mul_f32_e32 v36, v36, v32
	v_mul_f32_e32 v32, 0xbfb8aa3b, v32
	v_exp_f32_e32 v113, v113
	v_add_f32_e32 v64, 1.0, v64
	v_exp_f32_e32 v32, v32
	v_mul_f32_e32 v96, v100, v96
	v_mul_f32_e32 v100, v101, v97
	v_mul_f32_e32 v97, 0xbfb8aa3b, v97
	v_rcp_f32_e32 v64, v64
	v_mul_f32_e32 v20, v20, v16
	v_mul_f32_e32 v16, 0xbfb8aa3b, v16
	v_exp_f32_e32 v97, v97
	v_add_f32_e32 v48, 1.0, v48
	v_exp_f32_e32 v16, v16
	v_mul_f32_e32 v80, v84, v80
	v_mul_f32_e32 v84, v85, v81
	v_mul_f32_e32 v81, 0xbfb8aa3b, v81
	v_rcp_f32_e32 v48, v48
	v_mul_f32_e32 v124, v124, v120
	v_mul_f32_e32 v120, 0xbfb8aa3b, v120
	v_add_f32_e32 v113, 1.0, v113
	v_mul_f32_e32 v108, v108, v104
	v_mul_f32_e32 v104, 0xbfb8aa3b, v104
	v_mul_f32_e32 v92, v92, v88
	v_mul_f32_e32 v88, 0xbfb8aa3b, v88
	v_exp_f32_e32 v81, v81
	v_mul_f32_e32 v76, v76, v72
	v_mul_f32_e32 v72, 0xbfb8aa3b, v72
	v_mul_f32_e32 v60, v60, v56
	v_mul_f32_e32 v56, 0xbfb8aa3b, v56
	v_mul_f32_e32 v44, v44, v40
	v_mul_f32_e32 v40, 0xbfb8aa3b, v40
	v_add_f32_e32 v32, 1.0, v32
	v_mul_f32_e32 v28, v28, v24
	v_mul_f32_e32 v24, 0xbfb8aa3b, v24
	v_mul_f32_e32 v12, v12, v8
	v_mul_f32_e32 v8, 0xbfb8aa3b, v8
	v_mul_f32_e32 v4, v4, v0
	v_mul_f32_e32 v0, 0xbfb8aa3b, v0
	v_exp_f32_e32 v120, v120
	v_rcp_f32_e32 v113, v113
	v_exp_f32_e32 v104, v104
	v_exp_f32_e32 v88, v88
	v_exp_f32_e32 v72, v72
	v_mul_f32_e32 v64, v68, v64
	v_mul_f32_e32 v68, v69, v65
	v_mul_f32_e32 v65, 0xbfb8aa3b, v65
	v_exp_f32_e32 v56, v56
	v_exp_f32_e32 v40, v40
	v_rcp_f32_e32 v32, v32
	v_exp_f32_e32 v24, v24
	v_exp_f32_e32 v8, v8
	v_exp_f32_e32 v0, v0
	v_add_f32_e32 v97, 1.0, v97
	v_exp_f32_e32 v65, v65
	v_add_f32_e32 v16, 1.0, v16
	v_rcp_f32_e32 v97, v97
	v_mul_f32_e32 v48, v52, v48
	v_mul_f32_e32 v52, v53, v49
	v_mul_f32_e32 v49, 0xbfb8aa3b, v49
	v_rcp_f32_e32 v16, v16
	v_add_f32_e32 v81, 1.0, v81
	v_exp_f32_e32 v49, v49
	v_add_f32_e32 v120, 1.0, v120
	v_mul_f32_e32 v113, v116, v113
	v_mul_f32_e32 v116, v118, v114
	v_mul_f32_e32 v114, 0xbfb8aa3b, v114
	v_add_f32_e32 v104, 1.0, v104
	v_add_f32_e32 v88, 1.0, v88
	v_rcp_f32_e32 v81, v81
	v_add_f32_e32 v72, 1.0, v72
;     __device__ __forceinline__ void operator()(AccRef acc, const pg8::Unit& u, int wr, int wc, int fr, int fq) const {
;     ...
;                 for (int bj = 0; bj < 2; ++bj) { const f32x4 gq = acc[ai][bj][m][0], uq = acc[ai][bj][m][1]; float v[4];
; #pragma unroll
;                     for (int i = 0; i < 4; ++i) v[i] = gq[i] * uq[i] * __builtin_amdgcn_rcpf(1.f + __builtin_amdgcn_exp2f(-gq[i] * LOG2E));
	v_add_f32_e32 v56, 1.0, v56
	v_add_f32_e32 v40, 1.0, v40
	v_mul_f32_e32 v32, v36, v32
	v_mul_f32_e32 v36, v37, v33
	v_mul_f32_e32 v33, 0xbfb8aa3b, v33
	v_add_f32_e32 v24, 1.0, v24
	v_add_f32_e32 v8, 1.0, v8
	v_add_f32_e32 v0, 1.0, v0
	v_rcp_f32_e32 v120, v120
	v_exp_f32_e32 v114, v114
	v_rcp_f32_e32 v104, v104
	v_rcp_f32_e32 v88, v88
	v_rcp_f32_e32 v72, v72
	v_add_f32_e32 v65, 1.0, v65
	v_rcp_f32_e32 v56, v56
	v_rcp_f32_e32 v40, v40
	v_exp_f32_e32 v33, v33
	v_rcp_f32_e32 v24, v24
	v_rcp_f32_e32 v8, v8
	v_rcp_f32_e32 v0, v0
	v_mul_f32_e32 v97, v100, v97
	v_mul_f32_e32 v100, v102, v98
	v_mul_f32_e32 v98, 0xbfb8aa3b, v98
	v_rcp_f32_e32 v65, v65
	v_mul_f32_e32 v16, v20, v16
	v_mul_f32_e32 v20, v21, v17
	v_mul_f32_e32 v17, 0xbfb8aa3b, v17
	v_exp_f32_e32 v98, v98
	v_add_f32_e32 v49, 1.0, v49
	v_exp_f32_e32 v17, v17
	v_mul_f32_e32 v81, v84, v81
	v_mul_f32_e32 v84, v86, v82
	v_mul_f32_e32 v82, 0xbfb8aa3b, v82
	v_rcp_f32_e32 v49, v49
	v_mul_f32_e32 v120, v124, v120
	v_mul_f32_e32 v124, v125, v121
	v_mul_f32_e32 v121, 0xbfb8aa3b, v121
	v_add_f32_e32 v114, 1.0, v114
	v_mul_f32_e32 v104, v108, v104
	v_mul_f32_e32 v108, v109, v105
	v_mul_f32_e32 v105, 0xbfb8aa3b, v105
	v_mul_f32_e32 v88, v92, v88
	v_mul_f32_e32 v92, v93, v89
	v_mul_f32_e32 v89, 0xbfb8aa3b, v89
	v_exp_f32_e32 v82, v82
	v_mul_f32_e32 v72, v76, v72
	v_mul_f32_e32 v76, v77, v73
	v_mul_f32_e32 v73, 0xbfb8aa3b, v73
	v_mul_f32_e32 v56, v60, v56
	v_mul_f32_e32 v60, v61, v57
	v_mul_f32_e32 v57, 0xbfb8aa3b, v57
	v_mul_f32_e32 v40, v44, v40
	v_mul_f32_e32 v44, v45, v41
	v_mul_f32_e32 v41, 0xbfb8aa3b, v41
	v_add_f32_e32 v33, 1.0, v33
	v_mul_f32_e32 v24, v28, v24
	v_mul_f32_e32 v28, v29, v25
	v_mul_f32_e32 v25, 0xbfb8aa3b, v25
	v_mul_f32_e32 v8, v12, v8
	v_mul_f32_e32 v12, v13, v9
	v_mul_f32_e32 v9, 0xbfb8aa3b, v9
	v_mul_f32_e32 v0, v4, v0
	v_mul_f32_e32 v4, v5, v1
	v_mul_f32_e32 v1, 0xbfb8aa3b, v1
	v_exp_f32_e32 v121, v121
	v_rcp_f32_e32 v114, v114
	v_exp_f32_e32 v105, v105
	v_exp_f32_e32 v89, v89
	v_exp_f32_e32 v73, v73
	v_mul_f32_e32 v65, v68, v65
	v_mul_f32_e32 v68, v70, v66
	v_mul_f32_e32 v66, 0xbfb8aa3b, v66
	v_exp_f32_e32 v57, v57
	v_exp_f32_e32 v41, v41
	v_rcp_f32_e32 v33, v33
	v_exp_f32_e32 v25, v25
	v_exp_f32_e32 v9, v9
	v_exp_f32_e32 v1, v1
	v_add_f32_e32 v98, 1.0, v98
	v_exp_f32_e32 v66, v66
	v_add_f32_e32 v17, 1.0, v17
	v_rcp_f32_e32 v98, v98
	v_mul_f32_e32 v49, v52, v49
	v_mul_f32_e32 v52, v54, v50
	v_mul_f32_e32 v50, 0xbfb8aa3b, v50
	v_rcp_f32_e32 v17, v17
	v_add_f32_e32 v82, 1.0, v82
	v_exp_f32_e32 v50, v50
	v_add_f32_e32 v121, 1.0, v121
	v_mul_f32_e32 v114, v116, v114
	v_mul_f32_e32 v116, v119, v115
	v_mul_f32_e32 v115, 0xbfb8aa3b, v115
	v_add_f32_e32 v105, 1.0, v105
	v_add_f32_e32 v89, 1.0, v89
	v_rcp_f32_e32 v82, v82
	v_add_f32_e32 v73, 1.0, v73
	v_add_f32_e32 v57, 1.0, v57
	v_add_f32_e32 v41, 1.0, v41
	v_mul_f32_e32 v33, v36, v33
	v_mul_f32_e32 v36, v38, v34
	v_mul_f32_e32 v34, 0xbfb8aa3b, v34
	v_add_f32_e32 v25, 1.0, v25
	v_add_f32_e32 v9, 1.0, v9
	v_add_f32_e32 v1, 1.0, v1
	v_rcp_f32_e32 v121, v121
	v_exp_f32_e32 v115, v115
	v_rcp_f32_e32 v105, v105
	v_rcp_f32_e32 v89, v89
	v_rcp_f32_e32 v73, v73
	v_add_f32_e32 v66, 1.0, v66
	v_rcp_f32_e32 v57, v57
	v_rcp_f32_e32 v41, v41
	v_exp_f32_e32 v34, v34
	v_rcp_f32_e32 v25, v25
	v_rcp_f32_e32 v9, v9
	v_rcp_f32_e32 v1, v1
	v_mul_f32_e32 v98, v100, v98
	v_mul_f32_e32 v100, v103, v99
	v_mul_f32_e32 v99, 0xbfb8aa3b, v99
	v_rcp_f32_e32 v66, v66
	v_mul_f32_e32 v17, v20, v17
	v_mul_f32_e32 v20, v22, v18
	v_mul_f32_e32 v18, 0xbfb8aa3b, v18
	v_exp_f32_e32 v99, v99
	v_add_f32_e32 v50, 1.0, v50
	v_exp_f32_e32 v18, v18
	v_mul_f32_e32 v82, v84, v82
	v_mul_f32_e32 v84, v87, v83
	v_mul_f32_e32 v83, 0xbfb8aa3b, v83
	v_rcp_f32_e32 v50, v50
	v_mul_f32_e32 v121, v124, v121
	v_mul_f32_e32 v124, v126, v122
	v_mul_f32_e32 v122, 0xbfb8aa3b, v122
	v_add_f32_e32 v115, 1.0, v115
	v_mul_f32_e32 v105, v108, v105
	v_mul_f32_e32 v108, v110, v106
	v_mul_f32_e32 v106, 0xbfb8aa3b, v106
	v_mul_f32_e32 v89, v92, v89
	v_mul_f32_e32 v92, v94, v90
	v_mul_f32_e32 v90, 0xbfb8aa3b, v90
	v_exp_f32_e32 v83, v83
	v_mul_f32_e32 v73, v76, v73
	v_mul_f32_e32 v76, v78, v74
	v_mul_f32_e32 v74, 0xbfb8aa3b, v74
	v_mul_f32_e32 v57, v60, v57
	v_mul_f32_e32 v60, v62, v58
	v_mul_f32_e32 v58, 0xbfb8aa3b, v58
	v_mul_f32_e32 v41, v44, v41
	v_mul_f32_e32 v44, v46, v42
	v_mul_f32_e32 v42, 0xbfb8aa3b, v42
	v_add_f32_e32 v34, 1.0, v34
	v_mul_f32_e32 v25, v28, v25
	v_mul_f32_e32 v28, v30, v26
	v_mul_f32_e32 v26, 0xbfb8aa3b, v26
	v_mul_f32_e32 v9, v12, v9
	v_mul_f32_e32 v12, v14, v10
	v_mul_f32_e32 v10, 0xbfb8aa3b, v10
	v_mul_f32_e32 v1, v4, v1
	v_mul_f32_e32 v4, v6, v2
	v_mul_f32_e32 v2, 0xbfb8aa3b, v2
	v_lshl_or_b32 v134, s26, 7, v138
	v_exp_f32_e32 v122, v122
	v_rcp_f32_e32 v115, v115
	v_exp_f32_e32 v106, v106
	v_exp_f32_e32 v90, v90
	v_exp_f32_e32 v74, v74
	v_mul_f32_e32 v66, v68, v66
	v_mul_f32_e32 v68, v71, v67
	v_mul_f32_e32 v67, 0xbfb8aa3b, v67
	v_exp_f32_e32 v58, v58
	v_exp_f32_e32 v42, v42
	v_rcp_f32_e32 v34, v34
	v_exp_f32_e32 v26, v26
	v_exp_f32_e32 v10, v10
	v_exp_f32_e32 v2, v2
	v_ashrrev_i32_e32 v135, 31, v134
	v_add_f32_e32 v99, 1.0, v99
	v_exp_f32_e32 v67, v67
	v_add_f32_e32 v18, 1.0, v18
	v_lshl_add_u32 v140, s27, 8, v136
	v_lshl_add_u64 v[134:135], v[134:135], 1, s[74:75]
	v_rcp_f32_e32 v99, v99
	v_mul_f32_e32 v50, v52, v50
	v_mul_f32_e32 v52, v55, v51
	v_mul_f32_e32 v51, 0xbfb8aa3b, v51
	v_rcp_f32_e32 v18, v18
	v_mad_i64_i32 v[142:143], s[26:27], v140, s33, v[134:135]
	v_cvt_pk_bf16_f32 v112, v112, v113
	v_add_f32_e32 v83, 1.0, v83
	v_exp_f32_e32 v51, v51
	v_add_f32_e32 v122, 1.0, v122
	v_mul_f32_e32 v115, v116, v115
; __device__ __forceinline__ unsigned cvt_pk_bf16(float lo, float hi) { unsigned r; asm("v_cvt_pk_bf16_f32 %0, %1, %2" : "=v"(r) : "v"(lo), "v"(hi)); return r; }
; template <class Epi>
; __device__ __forceinline__ void gemm_phase(LAS unsigned char* lds, const Gemm g, const StaticOrder S, const Epi E) {
;     ...
;         E(acc, cur, wr, wc, fr, fq);
;         if (!has_next) break;
;     __device__ __forceinline__ void operator()(AccRef acc, const pg8::Unit& u, int wr, int wc, int fr, int fq) const {
;     ...
;             for (int m = 0; m < 4; ++m) { bf16_t* rowp = G + (size_t)(row0 + ai * 128 + m * 16) * FH + col0;
; #pragma unroll
;                 for (int bj = 0; bj < 2; ++bj) { const f32x4 gq = acc[ai][bj][m][0], uq = acc[ai][bj][m][1]; float v[4];
; #pragma unroll
;                     for (int i = 0; i < 4; ++i) v[i] = gq[i] * uq[i] * __builtin_amdgcn_rcpf(1.f + __builtin_amdgcn_exp2f(-gq[i] * LOG2E));
;                     u32x2 w; w.x = cvt_pk_bf16(v[0], v[1]); w.y = cvt_pk_bf16(v[2], v[3]);
;                     *(u32x2*)(rowp + bj * 64) = w; } }
	v_cvt_pk_bf16_f32 v113, v114, v115
	global_store_dwordx2 v[142:143], v[112:113], off offset:128
	v_or_b32_e32 v112, 16, v140
	v_add_f32_e32 v106, 1.0, v106
	v_add_f32_e32 v90, 1.0, v90
	v_rcp_f32_e32 v83, v83
	v_add_f32_e32 v74, 1.0, v74
	v_add_f32_e32 v58, 1.0, v58
	v_add_f32_e32 v42, 1.0, v42
	v_mul_f32_e32 v34, v36, v34
	v_mul_f32_e32 v36, v39, v35
	v_mul_f32_e32 v35, 0xbfb8aa3b, v35
	v_add_f32_e32 v26, 1.0, v26
	v_add_f32_e32 v10, 1.0, v10
	v_add_f32_e32 v2, 1.0, v2
	v_rcp_f32_e32 v122, v122
	v_mad_i64_i32 v[112:113], s[26:27], v112, s33, v[134:135]
	v_rcp_f32_e32 v106, v106
	v_cvt_pk_bf16_f32 v96, v96, v97
	v_rcp_f32_e32 v90, v90
	v_rcp_f32_e32 v74, v74
	v_add_f32_e32 v67, 1.0, v67
	v_rcp_f32_e32 v58, v58
	v_rcp_f32_e32 v42, v42
	v_exp_f32_e32 v35, v35
	v_rcp_f32_e32 v26, v26
	v_rcp_f32_e32 v10, v10
	v_rcp_f32_e32 v2, v2
	v_mul_f32_e32 v99, v100, v99
	v_cvt_pk_bf16_f32 v97, v98, v99
	global_store_dwordx2 v[112:113], v[96:97], off offset:128
	v_or_b32_e32 v96, 32, v140
	v_rcp_f32_e32 v67, v67
	v_mul_f32_e32 v18, v20, v18
	v_mul_f32_e32 v20, v23, v19
	v_mul_f32_e32 v19, 0xbfb8aa3b, v19
	v_mad_i64_i32 v[96:97], s[26:27], v96, s33, v[134:135]
	v_cvt_pk_bf16_f32 v80, v80, v81
	v_add_f32_e32 v51, 1.0, v51
	v_exp_f32_e32 v19, v19
	v_mul_f32_e32 v83, v84, v83
	v_cvt_pk_bf16_f32 v81, v82, v83
	global_store_dwordx2 v[96:97], v[80:81], off offset:128
	v_or_b32_e32 v80, 48, v140
	v_rcp_f32_e32 v51, v51
	v_mul_f32_e32 v122, v124, v122
	v_mul_f32_e32 v124, v127, v123
	v_mul_f32_e32 v123, 0xbfb8aa3b, v123
	v_mul_f32_e32 v106, v108, v106
	v_mul_f32_e32 v108, v111, v107
	v_mul_f32_e32 v107, 0xbfb8aa3b, v107
	v_mul_f32_e32 v90, v92, v90
	v_mul_f32_e32 v92, v95, v91
	v_mul_f32_e32 v91, 0xbfb8aa3b, v91
	v_mad_i64_i32 v[80:81], s[26:27], v80, s33, v[134:135]
	v_mul_f32_e32 v74, v76, v74
	v_mul_f32_e32 v76, v79, v75
	v_mul_f32_e32 v75, 0xbfb8aa3b, v75
	v_cvt_pk_bf16_f32 v64, v64, v65
	v_mul_f32_e32 v58, v60, v58
	v_mul_f32_e32 v60, v63, v59
	v_mul_f32_e32 v59, 0xbfb8aa3b, v59
	v_mul_f32_e32 v42, v44, v42
	v_mul_f32_e32 v44, v47, v43
	v_mul_f32_e32 v43, 0xbfb8aa3b, v43
	v_add_f32_e32 v35, 1.0, v35
	v_mul_f32_e32 v26, v28, v26
	v_mul_f32_e32 v28, v31, v27
	v_mul_f32_e32 v27, 0xbfb8aa3b, v27
	v_mul_f32_e32 v10, v12, v10
	v_mul_f32_e32 v12, v15, v11
	v_mul_f32_e32 v11, 0xbfb8aa3b, v11
	v_mul_f32_e32 v2, v4, v2
	v_mul_f32_e32 v4, v7, v3
	v_mul_f32_e32 v3, 0xbfb8aa3b, v3
	v_exp_f32_e32 v123, v123
	v_exp_f32_e32 v107, v107
	v_exp_f32_e32 v91, v91
	v_exp_f32_e32 v75, v75
	v_mul_f32_e32 v67, v68, v67
	v_cvt_pk_bf16_f32 v65, v66, v67
	global_store_dwordx2 v[80:81], v[64:65], off offset:128
	v_add_u32_e32 v64, 0x80, v140
	v_exp_f32_e32 v59, v59
	v_exp_f32_e32 v43, v43
	v_rcp_f32_e32 v35, v35
	v_exp_f32_e32 v27, v27
	v_exp_f32_e32 v11, v11
	v_exp_f32_e32 v3, v3
	v_mad_i64_i32 v[64:65], s[26:27], v64, s33, v[134:135]
	v_cvt_pk_bf16_f32 v48, v48, v49
	v_add_f32_e32 v19, 1.0, v19
	v_mul_f32_e32 v51, v52, v51
	v_cvt_pk_bf16_f32 v49, v50, v51
	global_store_dwordx2 v[64:65], v[48:49], off offset:128
	v_add_u32_e32 v48, 0x90, v140
	v_rcp_f32_e32 v19, v19
	v_mad_i64_i32 v[48:49], s[26:27], v48, s33, v[134:135]
	v_cvt_pk_bf16_f32 v32, v32, v33
	v_add_f32_e32 v123, 1.0, v123
	v_add_f32_e32 v107, 1.0, v107
	v_add_f32_e32 v91, 1.0, v91
	v_add_f32_e32 v75, 1.0, v75
	v_add_f32_e32 v59, 1.0, v59
	v_add_f32_e32 v43, 1.0, v43
	v_mul_f32_e32 v35, v36, v35
	v_cvt_pk_bf16_f32 v33, v34, v35
	global_store_dwordx2 v[48:49], v[32:33], off offset:128
	v_add_u32_e32 v32, 0xa0, v140
	v_add_f32_e32 v27, 1.0, v27
	v_add_f32_e32 v11, 1.0, v11
	v_add_f32_e32 v3, 1.0, v3
	v_rcp_f32_e32 v123, v123
	v_rcp_f32_e32 v107, v107
	v_rcp_f32_e32 v91, v91
	v_rcp_f32_e32 v75, v75
	v_rcp_f32_e32 v59, v59
	v_rcp_f32_e32 v43, v43
	v_mad_i64_i32 v[32:33], s[26:27], v32, s33, v[134:135]
	v_rcp_f32_e32 v27, v27
	v_cvt_pk_bf16_f32 v16, v16, v17
	v_rcp_f32_e32 v11, v11
	v_rcp_f32_e32 v3, v3
	v_mul_f32_e32 v19, v20, v19
	v_cvt_pk_bf16_f32 v17, v18, v19
	global_store_dwordx2 v[32:33], v[16:17], off offset:128
	v_add_u32_e32 v16, 0xb0, v140
	v_mad_i64_i32 v[16:17], s[26:27], v16, s33, v[134:135]
	s_and_b64 vcc, exec, s[38:39]
	s_mov_b32 s26, s2
	s_mov_b32 s27, s10
	s_mov_b64 s[46:47], s[42:43]
	s_mov_b64 s[44:45], s[40:41]
	v_mul_f32_e32 v123, v124, v123
	v_cvt_pk_bf16_f32 v120, v120, v121
	v_cvt_pk_bf16_f32 v121, v122, v123
	global_store_dwordx2 v[142:143], v[120:121], off
	v_mul_f32_e32 v107, v108, v107
	v_cvt_pk_bf16_f32 v104, v104, v105
	v_cvt_pk_bf16_f32 v105, v106, v107
	global_store_dwordx2 v[112:113], v[104:105], off
	v_mul_f32_e32 v91, v92, v91
	v_cvt_pk_bf16_f32 v88, v88, v89
	v_cvt_pk_bf16_f32 v89, v90, v91
	global_store_dwordx2 v[96:97], v[88:89], off
	v_mul_f32_e32 v75, v76, v75
	v_cvt_pk_bf16_f32 v72, v72, v73
	v_cvt_pk_bf16_f32 v73, v74, v75
	global_store_dwordx2 v[80:81], v[72:73], off
	v_mul_f32_e32 v59, v60, v59
	v_cvt_pk_bf16_f32 v56, v56, v57
	v_cvt_pk_bf16_f32 v57, v58, v59
	global_store_dwordx2 v[64:65], v[56:57], off
	v_mul_f32_e32 v43, v44, v43
	v_cvt_pk_bf16_f32 v40, v40, v41
	v_cvt_pk_bf16_f32 v41, v42, v43
	global_store_dwordx2 v[48:49], v[40:41], off
	v_mul_f32_e32 v27, v28, v27
	v_cvt_pk_bf16_f32 v24, v24, v25
	v_cvt_pk_bf16_f32 v25, v26, v27
	global_store_dwordx2 v[32:33], v[24:25], off
	v_mul_f32_e32 v11, v12, v11
	v_cvt_pk_bf16_f32 v8, v8, v9
	v_cvt_pk_bf16_f32 v9, v10, v11
	global_store_dwordx2 v[16:17], v[8:9], off
	v_mul_f32_e32 v3, v4, v3
	v_cvt_pk_bf16_f32 v0, v0, v1
	v_cvt_pk_bf16_f32 v1, v2, v3
	global_store_dwordx2 v[16:17], v[0:1], off offset:128
	s_cbranch_vccz .LBB0_2212
	s_waitcnt vmcnt(0)
	s_cmpk_gt_u32 s4, 0xff
	s_cbranch_scc1 .LBB0_2223
	s_barrier

; __device__ __forceinline__ bf16_t f2bf(float x) { return (bf16_t)(cvt_pk_bf16(x, 0.f) & 0xffffu); }
; __device__ __forceinline__ void titem_store(const TItem& it, int tid, const f32x4 (&v)[4], bf16_t* T) {
; #pragma unroll
;     for (int i = 0; i < 4; ++i) { const int idx = tid + 512 * i, kk = idx >> 4, r4 = idx & 15;
; #pragma unroll
;         for (int j = 0; j < 4; ++j) T[(4 * r4 + j) * 136 + kk] = f2bf(v[i][j]); }
;     __syncthreads();
; #pragma unroll
;     for (int i = 0; i < 2; ++i) { const int c = tid + 512 * i, row = c >> 4, k8 = (c & 15) * 8;
;         const u32x4 w = *(const u32x4*)(T + row * 136 + k8);
;         *(u32x4*)(it.dst + (size_t)(it.r0 + row) * it.K + it.k0 + k8) = w; }
; }
;     ...
;     for (int i = start; i < n; i += stride) {
;         TItem c2 = c1;
;         if (i + 2 * stride < n) { c2 = titem_decode(p, tset_item(l, which, i + 2 * stride)); titem_load(c2, tid, v2); }
;         titem_store(c0, tid, v0, (bf16_t*)(lds + buf * 17408));
;         buf ^= 1; c0 = c1; c1 = c2;
; #pragma unroll
;         for (int q = 0; q < 4; ++q) { v0[q] = v1[q]; v1[q] = v2[q]; }
.LBB0_2410:
	s_mul_i32 s11, s24, 0x4400
	s_add_i32 s11, s11, 0
	v_add_u32_e32 v32, s11, v43
	v_cvt_pk_bf16_f32 v0, v0, v179
	v_lshl_add_u32 v33, v35, 1, v32
	ds_write_b16 v33, v0
	v_cvt_pk_bf16_f32 v0, v1, v179
	ds_write_b16 v33, v0 offset:272
	v_cvt_pk_bf16_f32 v0, v2, v179
	ds_write_b16 v33, v0 offset:544
	v_cvt_pk_bf16_f32 v0, v3, v179
	ds_write_b16 v33, v0 offset:816
	v_cvt_pk_bf16_f32 v0, v4, v179
	v_lshl_add_u32 v1, v36, 1, v32
	ds_write_b16 v1, v0
	v_cvt_pk_bf16_f32 v0, v5, v179
	ds_write_b16 v1, v0 offset:272
	v_cvt_pk_bf16_f32 v0, v6, v179
	ds_write_b16 v1, v0 offset:544
	v_cvt_pk_bf16_f32 v0, v7, v179
	ds_write_b16 v1, v0 offset:816
	v_cvt_pk_bf16_f32 v0, v8, v179
	v_lshl_add_u32 v1, v37, 1, v32
	ds_write_b16 v1, v0
	v_cvt_pk_bf16_f32 v0, v9, v179
	ds_write_b16 v1, v0 offset:272
	v_cvt_pk_bf16_f32 v0, v10, v179
	ds_write_b16 v1, v0 offset:544
	v_cvt_pk_bf16_f32 v0, v11, v179
	ds_write_b16 v1, v0 offset:816
	v_cvt_pk_bf16_f32 v0, v12, v179
	v_lshl_add_u32 v1, v38, 1, v32
	ds_write_b16 v1, v0
	v_cvt_pk_bf16_f32 v0, v13, v179
	ds_write_b16 v1, v0 offset:272
	v_cvt_pk_bf16_f32 v0, v14, v179
	v_add_u32_e32 v4, s7, v35
	ds_write_b16 v1, v0 offset:544
	v_cvt_pk_bf16_f32 v0, v15, v179
	v_add_u32_e32 v10, s11, v178
	v_ashrrev_i32_e32 v7, 31, v4
	v_mad_u64_u32 v[4:5], s[30:31], v4, s6, 0
	ds_write_b16 v1, v0 offset:816
	v_add_u32_e32 v0, v10, v41
	v_mov_b32_e32 v6, v5
	s_waitcnt lgkmcnt(0)
	s_barrier
	ds_read_b128 v[0:3], v0
	v_mad_u64_u32 v[6:7], s[30:31], v7, s6, v[6:7]
	v_mov_b32_e32 v5, v6
	s_ashr_i32 s11, s10, 31
	v_lshl_add_u64 v[4:5], v[4:5], 1, s[2:3]
	s_lshl_b64 s[10:11], s[10:11], 1
	v_lshl_add_u64 v[4:5], v[4:5], 0, s[10:11]
	v_lshl_add_u64 v[8:9], v[4:5], 0, v[178:179]
	v_add_u32_e32 v4, v10, v42
	ds_read_b128 v[4:7], v4
	s_waitcnt lgkmcnt(1)
	global_store_dwordx4 v[8:9], v[0:3], off sc0 sc1
	s_xor_b32 s24, s24, 1
	v_mov_b32_e32 v8, v57
	v_add_u32_e32 v0, s7, v36
	v_ashrrev_i32_e32 v3, 31, v0
	v_mad_u64_u32 v[0:1], s[30:31], v0, s6, 0
	v_mov_b32_e32 v2, v1
	v_mad_u64_u32 v[2:3], s[6:7], v3, s6, v[2:3]
	v_mov_b32_e32 v1, v2
	v_lshl_add_u64 v[0:1], v[0:1], 1, s[2:3]
	v_readlane_b32 s2, v253, 3
	v_lshl_add_u64 v[0:1], v[0:1], 0, s[10:11]
	s_add_i32 s25, s25, s2
	v_lshl_add_u64 v[0:1], v[0:1], 0, v[178:179]
	s_add_i32 s2, s25, 24
	s_waitcnt lgkmcnt(0)
	global_store_dwordx4 v[0:1], v[4:7], off sc0 sc1
	s_cmp_ge_i32 s2, s63
	s_mov_b64 s[2:3], s[40:41]
	s_mov_b32 s6, s29
	s_mov_b32 s7, s28
	s_mov_b32 s10, s27
	v_mov_b32_e32 v0, v59
	v_mov_b32_e32 v1, v55
	v_mov_b32_e32 v2, v51
	v_mov_b32_e32 v3, v47
	v_mov_b32_e32 v4, v58
	v_mov_b32_e32 v5, v54
	v_mov_b32_e32 v6, v50
	v_mov_b32_e32 v7, v46
	v_mov_b32_e32 v9, v53
	v_mov_b32_e32 v10, v49
	v_mov_b32_e32 v11, v45
	v_mov_b32_e32 v12, v56
	v_mov_b32_e32 v13, v52
	v_mov_b32_e32 v14, v48
	v_mov_b32_e32 v15, v44
	s_waitcnt vmcnt(2)
	v_mov_b32_e32 v32, v16
	v_mov_b32_e32 v33, v17
	v_mov_b32_e32 v60, v18
	v_mov_b32_e32 v61, v19
	v_mov_b32_e32 v62, v20
	v_mov_b32_e32 v63, v21
	v_mov_b32_e32 v64, v22
	v_mov_b32_e32 v65, v23
	v_mov_b32_e32 v66, v24
	v_mov_b32_e32 v67, v25
	v_mov_b32_e32 v68, v26
	v_mov_b32_e32 v69, v27
	v_mov_b32_e32 v70, v28
	v_mov_b32_e32 v71, v29
	v_mov_b32_e32 v72, v30
	v_mov_b32_e32 v73, v31
	s_cbranch_scc1 .LBB0_2502

;     __device__ __forceinline__ void operator()(AccRef acc, const pg8::Unit& u, int wr, int wc, int fr, int fq) const {
;     ...
;                 for (int mm = 0; mm < 2; ++mm)
; #pragma unroll
;                     for (int bj = 0; bj < 2; ++bj)
; #pragma unroll
;                         for (int n = 0; n < 2; ++n) { const int m = 2 * mp + mm; const f32x4 d = gv[bj][n] * acc[ai][bj][m][n];
;                             *(f32x4*)(base + (size_t)(row0 + ai * 128 + m * 16) * DM + col0 + bj * 128 + n * 16) = part ? d : old[mm][bj][n] + d; }
.LBB0_2564:
	v_pk_mul_f32 v[36:37], v[30:31], v[174:175]
	v_pk_mul_f32 v[38:39], v[28:29], v[172:173]
	s_waitcnt vmcnt(0)
	v_pk_fma_f32 v[30:31], v[30:31], v[174:175], v[158:159]
	v_pk_fma_f32 v[28:29], v[28:29], v[172:173], v[156:157]
	v_lshl_add_u64 v[34:35], v[202:203], 0, v[34:35]
	v_cndmask_b32_e64 v31, v37, v31, s[38:39]
	v_cndmask_b32_e64 v30, v36, v30, s[38:39]
	v_cndmask_b32_e64 v29, v39, v29, s[38:39]
	v_cndmask_b32_e64 v28, v38, v28, s[38:39]
	global_store_dwordx4 v[34:35], v[28:31], off sc0 sc1
	s_and_b64 vcc, exec, s[44:45]
	s_mov_b32 s40, s60
	v_pk_mul_f32 v[28:29], v[26:27], v[170:171]
	v_pk_mul_f32 v[30:31], v[24:25], v[168:169]
	v_pk_fma_f32 v[26:27], v[26:27], v[170:171], v[154:155]
	v_pk_fma_f32 v[24:25], v[24:25], v[168:169], v[152:153]
	v_cndmask_b32_e64 v27, v29, v27, s[38:39]
	v_cndmask_b32_e64 v26, v28, v26, s[38:39]
	v_cndmask_b32_e64 v25, v31, v25, s[38:39]
	v_cndmask_b32_e64 v24, v30, v24, s[38:39]
	global_store_dwordx4 v[34:35], v[24:27], off offset:64 sc0 sc1
	s_mov_b32 s41, s26
	s_mov_b32 s63, s62
	v_pk_mul_f32 v[24:25], v[22:23], v[166:167]
	v_pk_mul_f32 v[26:27], v[20:21], v[164:165]
	v_pk_fma_f32 v[22:23], v[22:23], v[166:167], v[150:151]
	v_pk_fma_f32 v[20:21], v[20:21], v[164:165], v[148:149]
	v_cndmask_b32_e64 v23, v25, v23, s[38:39]
	v_cndmask_b32_e64 v22, v24, v22, s[38:39]
	v_cndmask_b32_e64 v21, v27, v21, s[38:39]
	v_cndmask_b32_e64 v20, v26, v20, s[38:39]
	global_store_dwordx4 v[34:35], v[20:23], off offset:512 sc0 sc1
	s_mov_b32 s29, s27
	s_mov_b32 s28, s61
	v_pk_mul_f32 v[20:21], v[14:15], v[162:163]
	v_pk_mul_f32 v[22:23], v[12:13], v[160:161]
	v_pk_fma_f32 v[14:15], v[14:15], v[162:163], v[142:143]
	v_pk_fma_f32 v[12:13], v[12:13], v[160:161], v[140:141]
	v_cndmask_b32_e64 v15, v21, v15, s[38:39]
	v_cndmask_b32_e64 v14, v20, v14, s[38:39]
	v_cndmask_b32_e64 v13, v23, v13, s[38:39]
	v_cndmask_b32_e64 v12, v22, v12, s[38:39]
	global_store_dwordx4 v[34:35], v[12:15], off offset:576 sc0 sc1
	v_pk_mul_f32 v[22:23], v[16:17], v[172:173]
	v_pk_fma_f32 v[16:17], v[16:17], v[172:173], v[144:145]
	v_pk_mul_f32 v[12:13], v[18:19], v[174:175]
	v_pk_fma_f32 v[14:15], v[18:19], v[174:175], v[146:147]
	v_lshl_add_u64 v[20:21], v[202:203], 0, v[32:33]
	v_cndmask_b32_e64 v15, v13, v15, s[38:39]
	v_cndmask_b32_e64 v14, v12, v14, s[38:39]
	v_cndmask_b32_e64 v13, v23, v17, s[38:39]
	v_cndmask_b32_e64 v12, v22, v16, s[38:39]
	global_store_dwordx4 v[20:21], v[12:15], off sc0 sc1
	s_mov_b64 s[64:65], s[46:47]
	s_mov_b32 s11, s59
	v_pk_mul_f32 v[12:13], v[10:11], v[170:171]
	v_pk_mul_f32 v[14:15], v[8:9], v[168:169]
	v_pk_fma_f32 v[10:11], v[10:11], v[170:171], v[138:139]
	v_pk_fma_f32 v[8:9], v[8:9], v[168:169], v[136:137]
	v_cndmask_b32_e64 v11, v13, v11, s[38:39]
	v_cndmask_b32_e64 v10, v12, v10, s[38:39]
	v_cndmask_b32_e64 v9, v15, v9, s[38:39]
	v_cndmask_b32_e64 v8, v14, v8, s[38:39]
	global_store_dwordx4 v[20:21], v[8:11], off offset:64 sc0 sc1
	s_nop 1
	v_pk_mul_f32 v[8:9], v[6:7], v[166:167]
	v_pk_mul_f32 v[10:11], v[4:5], v[164:165]
	v_pk_fma_f32 v[6:7], v[6:7], v[166:167], v[134:135]
	v_pk_fma_f32 v[4:5], v[4:5], v[164:165], v[132:133]
	v_cndmask_b32_e64 v7, v9, v7, s[38:39]
	v_cndmask_b32_e64 v6, v8, v6, s[38:39]
	v_cndmask_b32_e64 v5, v11, v5, s[38:39]
	v_cndmask_b32_e64 v4, v10, v4, s[38:39]
	global_store_dwordx4 v[20:21], v[4:7], off offset:512 sc0 sc1
	s_nop 1
	v_pk_mul_f32 v[4:5], v[2:3], v[162:163]
	v_pk_mul_f32 v[6:7], v[0:1], v[160:161]
	v_pk_fma_f32 v[2:3], v[2:3], v[162:163], v[130:131]
	v_pk_fma_f32 v[0:1], v[0:1], v[160:161], v[128:129]
	v_cndmask_b32_e64 v3, v5, v3, s[38:39]
	v_cndmask_b32_e64 v2, v4, v2, s[38:39]
	v_cndmask_b32_e64 v1, v7, v1, s[38:39]
	v_cndmask_b32_e64 v0, v6, v0, s[38:39]
	s_mov_b64 s[38:39], s[42:43]
	global_store_dwordx4 v[20:21], v[0:3], off offset:576 sc0 sc1
	s_cbranch_vccnz .LBB0_2594

; #define PG8_STAGE(bufoff, gbase, voff) do { _Pragma("unroll") for (int _i = 0; _i < 2; ++_i) \
;         __builtin_amdgcn_global_load_lds((const unsigned*)((const char*)(gbase) + (voff)[_i]), (LAS unsigned*)(lds + (bufoff) + ldsw + _i * 8192), 16, 0, 0); } while (0)
; #define PG8_LDA(dst, b, h) do { _Pragma("unroll") for (int m = 0; m < 4; ++m) _Pragma("unroll") for (int k = 0; k < 2; ++k) dst[m][k] = *(const LAS bf16x8*)(lds + PG8_SA(b, h) + aoff + m * 2048 + k * 1024); } while (0)
; #define PG8_LDB(dst, b, h) do { _Pragma("unroll") for (int n = 0; n < 2; ++n) _Pragma("unroll") for (int k = 0; k < 2; ++k) dst[n][k] = *(const LAS bf16x8*)(lds + PG8_SB(b, h) + boff + n * 2048 + k * 1024); } while (0)
; #define PG8_MMA(ai, bj, At, Bt) do { __builtin_amdgcn_s_setprio(1); _Pragma("unroll") for (int m = 0; m < 4; ++m) _Pragma("unroll") for (int n = 0; n < 2; ++n) _Pragma("unroll") for (int k = 0; k < 2; ++k) \
;         acc[ai][bj][m][n] = __builtin_amdgcn_mfma_f32_16x16x32_bf16(Bt[n][k], At[m][k], acc[ai][bj][m][n], 0, 0, 0); __builtin_amdgcn_s_setprio(0); } while (0)
; #define PG8_WAIT_V(n) asm volatile("s_waitcnt vmcnt(" #n ")" ::: "memory")
; #define PG8_WAIT_L(n) asm volatile("s_waitcnt lgkmcnt(" #n ")" ::: "memory")
; #define PG8_BAR __builtin_amdgcn_s_barrier()
; #define PG8_SCHED __builtin_amdgcn_sched_barrier(0)
; template <class Epi>
; __device__ __forceinline__ void gemm_phase(LAS unsigned char* lds, const Gemm g, const StaticOrder S, const Epi E) {
;     ...
;             PG8_LDB(B0, 0, 0); PG8_SCHED; PG8_LDA(At, 0, 0); PG8_STAGE(PG8_SA(1, 1), a1 + hstep, voffA);
;             PG8_WAIT_L(8); PG8_BAR; PG8_WAIT_L(0); PG8_MMA(0, 0, At, B0); PG8_BAR; PG8_SCHED;
;             PG8_LDB(B1, 0, 1); PG8_STAGE(PG8_SB(0, 0), b2, voffA);
;             PG8_BAR; PG8_WAIT_L(0); PG8_MMA(0, 1, At, B1); PG8_BAR;
;             PG8_LDA(At, 0, 1); PG8_STAGE(PG8_SA(0, 0), a2, voffA);
;             PG8_BAR; PG8_WAIT_L(0); PG8_MMA(1, 0, At, B0); PG8_BAR; PG8_SCHED;
;             PG8_STAGE(PG8_SB(0, 1), b2 + hstep, voffA);
;             PG8_WAIT_V(6); PG8_BAR; PG8_MMA(1, 1, At, B1); PG8_BAR;
.LBB0_2573:
	s_add_i32 s66, s50, 2
	s_add_u32 s48, s38, 0x100
	s_addc_u32 s49, s39, 0
	s_add_i32 s30, 0, 0x10000
	v_add_u32_e32 v140, s30, v228
	ds_read_b128 v[128:131], v140
	ds_read_b128 v[132:135], v140 offset:1024
	ds_read_b128 v[136:139], v140 offset:2048
	ds_read_b128 v[140:143], v140 offset:3072
	s_cmp_eq_u32 s11, s50
	s_cselect_b32 s50, s46, s64
	s_cselect_b32 s53, s43, s49
	s_cselect_b32 s52, s42, s48
	s_cselect_b32 s51, s47, s65
	v_lshl_add_u64 v[200:201], s[38:39], 0, v[196:197]
	s_add_i32 m0, s23, 0xc000
	ds_read_b128 v[144:147], v230
	ds_read_b128 v[148:151], v230 offset:1024
	ds_read_b128 v[152:155], v230 offset:2048
	ds_read_b128 v[156:159], v230 offset:3072
	ds_read_b128 v[160:163], v230 offset:4096
	ds_read_b128 v[164:167], v230 offset:5120
	ds_read_b128 v[168:171], v230 offset:6144
	ds_read_b128 v[172:175], v230 offset:7168
	global_load_lds_dwordx4 v[200:201], off
	v_lshl_add_u64 v[200:201], s[38:39], 0, v[198:199]
	s_add_i32 m0, s23, 0xe000
	s_nop 0
	global_load_lds_dwordx4 v[200:201], off
	s_waitcnt lgkmcnt(8)
	s_barrier
	s_waitcnt lgkmcnt(0)
	s_setprio 1
	s_waitcnt lgkmcnt(0)
	v_mfma_f32_16x16x32_bf16 v[124:127], v[128:131], v[144:147], v[124:127]
	v_mfma_f32_16x16x32_bf16 v[120:123], v[136:139], v[144:147], v[120:123]
	v_mfma_f32_16x16x32_bf16 v[112:115], v[128:131], v[152:155], v[112:115]
	v_mfma_f32_16x16x32_bf16 v[104:107], v[136:139], v[152:155], v[104:107]
	v_mfma_f32_16x16x32_bf16 v[92:95], v[128:131], v[160:163], v[92:95]
	v_mfma_f32_16x16x32_bf16 v[88:91], v[136:139], v[160:163], v[88:91]
	v_mfma_f32_16x16x32_bf16 v[80:83], v[128:131], v[168:171], v[80:83]
	v_mfma_f32_16x16x32_bf16 v[72:75], v[136:139], v[168:171], v[72:75]
	v_mfma_f32_16x16x32_bf16 v[124:127], v[132:135], v[148:151], v[124:127]
	v_mfma_f32_16x16x32_bf16 v[120:123], v[140:143], v[148:151], v[120:123]
	v_mfma_f32_16x16x32_bf16 v[112:115], v[132:135], v[156:159], v[112:115]
	v_mfma_f32_16x16x32_bf16 v[104:107], v[140:143], v[156:159], v[104:107]
	v_mfma_f32_16x16x32_bf16 v[92:95], v[132:135], v[164:167], v[92:95]
	v_mfma_f32_16x16x32_bf16 v[88:91], v[140:143], v[164:167], v[88:91]
	v_mfma_f32_16x16x32_bf16 v[80:83], v[132:135], v[172:175], v[80:83]
	v_mfma_f32_16x16x32_bf16 v[72:75], v[140:143], v[172:175], v[72:75]
	s_setprio 0
	s_barrier
	s_add_i32 s38, 0, 0x14000
	v_add_u32_e32 v220, s38, v228
	s_add_i32 s30, s30, s22
	ds_read_b128 v[200:203], v220
	ds_read_b128 v[204:207], v220 offset:1024
	ds_read_b128 v[208:211], v220 offset:2048
	ds_read_b128 v[232:235], v220 offset:3072
	v_lshl_add_u64 v[220:221], s[50:51], 0, v[178:179]
	s_mov_b32 m0, s30
	v_lshl_add_u64 v[222:223], s[50:51], 0, v[194:195]
	global_load_lds_dwordx4 v[220:221], off
	s_add_i32 m0, s30, 0x2000
	s_nop 0
	global_load_lds_dwordx4 v[222:223], off
	s_barrier
	s_waitcnt lgkmcnt(0)
	s_setprio 1
	s_waitcnt lgkmcnt(0)
	v_mfma_f32_16x16x32_bf16 v[116:119], v[200:203], v[144:147], v[116:119]
	v_mfma_f32_16x16x32_bf16 v[108:111], v[208:211], v[144:147], v[108:111]
	v_mfma_f32_16x16x32_bf16 v[100:103], v[200:203], v[152:155], v[100:103]
	v_mfma_f32_16x16x32_bf16 v[96:99], v[208:211], v[152:155], v[96:99]
	v_mfma_f32_16x16x32_bf16 v[84:87], v[200:203], v[160:163], v[84:87]
	v_mfma_f32_16x16x32_bf16 v[76:79], v[208:211], v[160:163], v[76:79]
	v_mfma_f32_16x16x32_bf16 v[68:71], v[200:203], v[168:171], v[68:71]
	v_mfma_f32_16x16x32_bf16 v[64:67], v[208:211], v[168:171], v[64:67]
	v_mfma_f32_16x16x32_bf16 v[116:119], v[204:207], v[148:151], v[116:119]
	v_mfma_f32_16x16x32_bf16 v[108:111], v[232:235], v[148:151], v[108:111]
	v_mfma_f32_16x16x32_bf16 v[100:103], v[204:207], v[156:159], v[100:103]
	v_mfma_f32_16x16x32_bf16 v[96:99], v[232:235], v[156:159], v[96:99]
	v_mfma_f32_16x16x32_bf16 v[84:87], v[204:207], v[164:167], v[84:87]
	v_mfma_f32_16x16x32_bf16 v[76:79], v[232:235], v[164:167], v[76:79]
	v_mfma_f32_16x16x32_bf16 v[68:71], v[204:207], v[172:175], v[68:71]
	v_mfma_f32_16x16x32_bf16 v[64:67], v[232:235], v[172:175], v[64:67]
	s_setprio 0
	s_barrier
	s_mov_b32 m0, s23
	v_lshl_add_u64 v[236:237], s[52:53], 0, v[178:179]
	ds_read_b128 v[144:147], v230 offset:16384
	ds_read_b128 v[148:151], v230 offset:17408
	ds_read_b128 v[152:155], v230 offset:18432
	ds_read_b128 v[156:159], v230 offset:19456
	ds_read_b128 v[160:163], v230 offset:20480
	ds_read_b128 v[164:167], v230 offset:21504
	ds_read_b128 v[168:171], v230 offset:22528
	ds_read_b128 v[172:175], v230 offset:23552
	global_load_lds_dwordx4 v[236:237], off
	v_lshl_add_u64 v[238:239], s[52:53], 0, v[194:195]
	s_mov_b32 m0, s24
	s_nop 0
	global_load_lds_dwordx4 v[238:239], off
	s_barrier
	s_waitcnt lgkmcnt(0)
	s_setprio 1
	s_waitcnt lgkmcnt(0)
	v_mfma_f32_16x16x32_bf16 v[60:63], v[128:131], v[144:147], v[60:63]
	v_mfma_f32_16x16x32_bf16 v[56:59], v[136:139], v[144:147], v[56:59]
	v_mfma_f32_16x16x32_bf16 v[48:51], v[128:131], v[152:155], v[48:51]
	v_mfma_f32_16x16x32_bf16 v[40:43], v[136:139], v[152:155], v[40:43]
	v_mfma_f32_16x16x32_bf16 v[28:31], v[128:131], v[160:163], v[28:31]
	v_mfma_f32_16x16x32_bf16 v[24:27], v[136:139], v[160:163], v[24:27]
	v_mfma_f32_16x16x32_bf16 v[16:19], v[128:131], v[168:171], v[16:19]
	v_mfma_f32_16x16x32_bf16 v[8:11], v[136:139], v[168:171], v[8:11]
	v_mfma_f32_16x16x32_bf16 v[60:63], v[132:135], v[148:151], v[60:63]
	v_mfma_f32_16x16x32_bf16 v[56:59], v[140:143], v[148:151], v[56:59]
	v_mfma_f32_16x16x32_bf16 v[48:51], v[132:135], v[156:159], v[48:51]
	v_mfma_f32_16x16x32_bf16 v[40:43], v[140:143], v[156:159], v[40:43]
	v_mfma_f32_16x16x32_bf16 v[28:31], v[132:135], v[164:167], v[28:31]
	v_mfma_f32_16x16x32_bf16 v[24:27], v[140:143], v[164:167], v[24:27]
	v_mfma_f32_16x16x32_bf16 v[16:19], v[132:135], v[172:175], v[16:19]
	v_mfma_f32_16x16x32_bf16 v[8:11], v[140:143], v[172:175], v[8:11]
	s_setprio 0
	s_barrier
; #define PG8_STAGE(bufoff, gbase, voff) do { _Pragma("unroll") for (int _i = 0; _i < 2; ++_i) \
;         __builtin_amdgcn_global_load_lds((const unsigned*)((const char*)(gbase) + (voff)[_i]), (LAS unsigned*)(lds + (bufoff) + ldsw + _i * 8192), 16, 0, 0); } while (0)
; #define PG8_LDA(dst, b, h) do { _Pragma("unroll") for (int m = 0; m < 4; ++m) _Pragma("unroll") for (int k = 0; k < 2; ++k) dst[m][k] = *(const LAS bf16x8*)(lds + PG8_SA(b, h) + aoff + m * 2048 + k * 1024); } while (0)
; #define PG8_LDB(dst, b, h) do { _Pragma("unroll") for (int n = 0; n < 2; ++n) _Pragma("unroll") for (int k = 0; k < 2; ++k) dst[n][k] = *(const LAS bf16x8*)(lds + PG8_SB(b, h) + boff + n * 2048 + k * 1024); } while (0)
; #define PG8_MMA(ai, bj, At, Bt) do { __builtin_amdgcn_s_setprio(1); _Pragma("unroll") for (int m = 0; m < 4; ++m) _Pragma("unroll") for (int n = 0; n < 2; ++n) _Pragma("unroll") for (int k = 0; k < 2; ++k) \
;         acc[ai][bj][m][n] = __builtin_amdgcn_mfma_f32_16x16x32_bf16(Bt[n][k], At[m][k], acc[ai][bj][m][n], 0, 0, 0); __builtin_amdgcn_s_setprio(0); } while (0)
; #define PG8_WAIT_V(n) asm volatile("s_waitcnt vmcnt(" #n ")" ::: "memory")
; #define PG8_WAIT_L(n) asm volatile("s_waitcnt lgkmcnt(" #n ")" ::: "memory")
; #define PG8_BAR __builtin_amdgcn_s_barrier()
; #define PG8_SCHED __builtin_amdgcn_sched_barrier(0)
; template <class Epi>
; __device__ __forceinline__ void gemm_phase(LAS unsigned char* lds, const Gemm g, const StaticOrder S, const Epi E) {
;     ...
;             PG8_STAGE(PG8_SB(0, 1), b2 + hstep, voffA);
;             PG8_WAIT_V(6); PG8_BAR; PG8_MMA(1, 1, At, B1); PG8_BAR;
;             PG8_LDB(B0, 1, 0); PG8_SCHED; PG8_LDA(At, 1, 0); PG8_STAGE(PG8_SA(0, 1), a2 + hstep, voffA);
;             PG8_WAIT_L(8); PG8_BAR; PG8_WAIT_L(0); PG8_MMA(0, 0, At, B0); PG8_BAR; PG8_SCHED;
;             PG8_LDB(B1, 1, 1); PG8_STAGE(PG8_SB(1, 0), b3, voffA);
;             PG8_BAR; PG8_WAIT_L(0); PG8_MMA(0, 1, At, B1); PG8_BAR;
;             PG8_LDA(At, 1, 1); PG8_STAGE(PG8_SA(1, 0), a3, voffA);
	s_add_u32 s30, s50, 0x158000
	s_addc_u32 s31, s51, 0
	s_add_i32 s38, s38, s22
	v_lshl_add_u64 v[128:129], s[30:31], 0, v[178:179]
	s_mov_b32 m0, s38
	s_nop 0
	global_load_lds_dwordx4 v[128:129], off
	v_lshl_add_u64 v[128:129], s[30:31], 0, v[194:195]
	s_add_i32 m0, s38, 0x2000
	s_nop 0
	global_load_lds_dwordx4 v[128:129], off
	s_waitcnt vmcnt(6)
	s_barrier
	s_setprio 1
	v_mfma_f32_16x16x32_bf16 v[52:55], v[200:203], v[144:147], v[52:55]
	v_mfma_f32_16x16x32_bf16 v[44:47], v[208:211], v[144:147], v[44:47]
	v_mfma_f32_16x16x32_bf16 v[36:39], v[200:203], v[152:155], v[36:39]
	v_mfma_f32_16x16x32_bf16 v[32:35], v[208:211], v[152:155], v[32:35]
	v_mfma_f32_16x16x32_bf16 v[20:23], v[200:203], v[160:163], v[20:23]
	v_mfma_f32_16x16x32_bf16 v[12:15], v[208:211], v[160:163], v[12:15]
	v_mfma_f32_16x16x32_bf16 v[4:7], v[200:203], v[168:171], v[4:7]
	v_mfma_f32_16x16x32_bf16 v[0:3], v[208:211], v[168:171], v[0:3]
	v_mfma_f32_16x16x32_bf16 v[52:55], v[204:207], v[148:151], v[52:55]
	v_mfma_f32_16x16x32_bf16 v[44:47], v[232:235], v[148:151], v[44:47]
	v_mfma_f32_16x16x32_bf16 v[36:39], v[204:207], v[156:159], v[36:39]
	v_mfma_f32_16x16x32_bf16 v[32:35], v[232:235], v[156:159], v[32:35]
	v_mfma_f32_16x16x32_bf16 v[20:23], v[204:207], v[164:167], v[20:23]
	v_mfma_f32_16x16x32_bf16 v[12:15], v[232:235], v[164:167], v[12:15]
	v_mfma_f32_16x16x32_bf16 v[4:7], v[204:207], v[172:175], v[4:7]
	v_mfma_f32_16x16x32_bf16 v[0:3], v[232:235], v[172:175], v[0:3]
	s_setprio 0
	s_barrier
	s_add_i32 s38, 0, 0x18000
	v_add_u32_e32 v140, s38, v228
	ds_read_b128 v[128:131], v140
	ds_read_b128 v[132:135], v140 offset:1024
	ds_read_b128 v[136:139], v140 offset:2048
	ds_read_b128 v[140:143], v140 offset:3072
	s_add_u32 s30, s52, 0x158000
	s_addc_u32 s31, s53, 0
	s_mov_b32 m0, s25
	v_lshl_add_u64 v[200:201], s[30:31], 0, v[178:179]
	ds_read_b128 v[144:147], v230 offset:32768
	ds_read_b128 v[148:151], v230 offset:33792
	ds_read_b128 v[152:155], v230 offset:34816
	ds_read_b128 v[156:159], v230 offset:35840
	ds_read_b128 v[160:163], v230 offset:36864
	ds_read_b128 v[164:167], v230 offset:37888
	ds_read_b128 v[168:171], v230 offset:38912
	ds_read_b128 v[172:175], v230 offset:39936
	global_load_lds_dwordx4 v[200:201], off
	v_lshl_add_u64 v[200:201], s[30:31], 0, v[194:195]
	s_mov_b32 m0, s14
	s_nop 0
	global_load_lds_dwordx4 v[200:201], off
	s_waitcnt lgkmcnt(8)
	s_barrier
	s_waitcnt lgkmcnt(0)
	s_setprio 1
	s_waitcnt lgkmcnt(0)
	v_mfma_f32_16x16x32_bf16 v[124:127], v[128:131], v[144:147], v[124:127]
	v_mfma_f32_16x16x32_bf16 v[120:123], v[136:139], v[144:147], v[120:123]
	v_mfma_f32_16x16x32_bf16 v[112:115], v[128:131], v[152:155], v[112:115]
	v_mfma_f32_16x16x32_bf16 v[104:107], v[136:139], v[152:155], v[104:107]
	v_mfma_f32_16x16x32_bf16 v[92:95], v[128:131], v[160:163], v[92:95]
	v_mfma_f32_16x16x32_bf16 v[88:91], v[136:139], v[160:163], v[88:91]
	v_mfma_f32_16x16x32_bf16 v[80:83], v[128:131], v[168:171], v[80:83]
	v_mfma_f32_16x16x32_bf16 v[72:75], v[136:139], v[168:171], v[72:75]
	v_mfma_f32_16x16x32_bf16 v[124:127], v[132:135], v[148:151], v[124:127]
	v_mfma_f32_16x16x32_bf16 v[120:123], v[140:143], v[148:151], v[120:123]
	v_mfma_f32_16x16x32_bf16 v[112:115], v[132:135], v[156:159], v[112:115]
	v_mfma_f32_16x16x32_bf16 v[104:107], v[140:143], v[156:159], v[104:107]
	v_mfma_f32_16x16x32_bf16 v[92:95], v[132:135], v[164:167], v[92:95]
	v_mfma_f32_16x16x32_bf16 v[88:91], v[140:143], v[164:167], v[88:91]
	v_mfma_f32_16x16x32_bf16 v[80:83], v[132:135], v[172:175], v[80:83]
	v_mfma_f32_16x16x32_bf16 v[72:75], v[140:143], v[172:175], v[72:75]
	s_setprio 0
	s_barrier
	s_add_i32 s39, 0, 0x1c000
	s_add_i32 s30, s38, s22
	v_add_u32_e32 v231, s39, v228
	v_lshl_add_u64 v[220:221], v[220:221], 0, s[34:35]
	s_mov_b32 m0, s30
	ds_read_b128 v[200:203], v231
	ds_read_b128 v[204:207], v231 offset:1024
	ds_read_b128 v[208:211], v231 offset:2048
	ds_read_b128 v[232:235], v231 offset:3072
	global_load_lds_dwordx4 v[220:221], off
	v_lshl_add_u64 v[220:221], v[222:223], 0, s[34:35]
	s_add_i32 m0, s30, 0x2000
	s_nop 0
	global_load_lds_dwordx4 v[220:221], off
	s_barrier
; #define PG8_STAGE(bufoff, gbase, voff) do { _Pragma("unroll") for (int _i = 0; _i < 2; ++_i) \
;         __builtin_amdgcn_global_load_lds((const unsigned*)((const char*)(gbase) + (voff)[_i]), (LAS unsigned*)(lds + (bufoff) + ldsw + _i * 8192), 16, 0, 0); } while (0)
; #define PG8_LDA(dst, b, h) do { _Pragma("unroll") for (int m = 0; m < 4; ++m) _Pragma("unroll") for (int k = 0; k < 2; ++k) dst[m][k] = *(const LAS bf16x8*)(lds + PG8_SA(b, h) + aoff + m * 2048 + k * 1024); } while (0)
; #define PG8_MMA(ai, bj, At, Bt) do { __builtin_amdgcn_s_setprio(1); _Pragma("unroll") for (int m = 0; m < 4; ++m) _Pragma("unroll") for (int n = 0; n < 2; ++n) _Pragma("unroll") for (int k = 0; k < 2; ++k) \
;         acc[ai][bj][m][n] = __builtin_amdgcn_mfma_f32_16x16x32_bf16(Bt[n][k], At[m][k], acc[ai][bj][m][n], 0, 0, 0); __builtin_amdgcn_s_setprio(0); } while (0)
; #define PG8_WAIT_V(n) asm volatile("s_waitcnt vmcnt(" #n ")" ::: "memory")
; #define PG8_WAIT_L(n) asm volatile("s_waitcnt lgkmcnt(" #n ")" ::: "memory")
; #define PG8_BAR __builtin_amdgcn_s_barrier()
; #define PG8_SCHED __builtin_amdgcn_sched_barrier(0)
; template <class Epi>
; __device__ __forceinline__ void gemm_phase(LAS unsigned char* lds, const Gemm g, const StaticOrder S, const Epi E) {
;     ...
;             PG8_LDA(At, 1, 1); PG8_STAGE(PG8_SA(1, 0), a3, voffA);
;             PG8_BAR; PG8_WAIT_L(0); PG8_MMA(1, 0, At, B0); PG8_BAR; PG8_SCHED;
;             PG8_STAGE(PG8_SB(1, 1), b3 + hstep, voffA);
;             PG8_WAIT_V(6); PG8_BAR; PG8_MMA(1, 1, At, B1); PG8_BAR;
;         }
;     __device__ __forceinline__ void operator()(AccRef acc, const pg8::Unit& u, int wr, int wc, int fr, int fq) const {
;         const int row0 = u.pm * 256 + wr * 64 + fr, col0 = u.pn * 256 + wc * 32 + 4 * fq;
;         const int v = u.pm < 32 ? (u.pm >> 3) : 4;
	s_waitcnt lgkmcnt(0)
	s_setprio 1
	s_waitcnt lgkmcnt(0)
	v_mfma_f32_16x16x32_bf16 v[116:119], v[200:203], v[144:147], v[116:119]
	v_mfma_f32_16x16x32_bf16 v[108:111], v[208:211], v[144:147], v[108:111]
	v_mfma_f32_16x16x32_bf16 v[100:103], v[200:203], v[152:155], v[100:103]
	v_mfma_f32_16x16x32_bf16 v[96:99], v[208:211], v[152:155], v[96:99]
	v_mfma_f32_16x16x32_bf16 v[84:87], v[200:203], v[160:163], v[84:87]
	v_mfma_f32_16x16x32_bf16 v[76:79], v[208:211], v[160:163], v[76:79]
	v_mfma_f32_16x16x32_bf16 v[68:71], v[200:203], v[168:171], v[68:71]
	v_mfma_f32_16x16x32_bf16 v[64:67], v[208:211], v[168:171], v[64:67]
	v_mfma_f32_16x16x32_bf16 v[116:119], v[204:207], v[148:151], v[116:119]
	v_mfma_f32_16x16x32_bf16 v[108:111], v[232:235], v[148:151], v[108:111]
	v_mfma_f32_16x16x32_bf16 v[100:103], v[204:207], v[156:159], v[100:103]
	v_mfma_f32_16x16x32_bf16 v[96:99], v[232:235], v[156:159], v[96:99]
	v_mfma_f32_16x16x32_bf16 v[84:87], v[204:207], v[164:167], v[84:87]
	v_mfma_f32_16x16x32_bf16 v[76:79], v[232:235], v[164:167], v[76:79]
	v_mfma_f32_16x16x32_bf16 v[68:71], v[204:207], v[172:175], v[68:71]
	v_mfma_f32_16x16x32_bf16 v[64:67], v[232:235], v[172:175], v[64:67]
	s_setprio 0
	s_barrier
	s_mov_b32 m0, s57
	v_lshl_add_u64 v[220:221], v[236:237], 0, s[34:35]
	ds_read_b128 v[144:147], v230 offset:49152
	ds_read_b128 v[148:151], v230 offset:50176
	ds_read_b128 v[152:155], v230 offset:51200
	ds_read_b128 v[156:159], v230 offset:52224
	ds_read_b128 v[160:163], v230 offset:53248
	ds_read_b128 v[164:167], v230 offset:54272
	ds_read_b128 v[168:171], v230 offset:55296
	ds_read_b128 v[172:175], v230 offset:56320
	global_load_lds_dwordx4 v[220:221], off
	v_lshl_add_u64 v[220:221], v[238:239], 0, s[34:35]
	s_mov_b32 m0, s58
	s_nop 0
	global_load_lds_dwordx4 v[220:221], off
	s_barrier
	s_waitcnt lgkmcnt(0)
	s_setprio 1
	s_waitcnt lgkmcnt(0)
	v_mfma_f32_16x16x32_bf16 v[60:63], v[128:131], v[144:147], v[60:63]
	v_mfma_f32_16x16x32_bf16 v[56:59], v[136:139], v[144:147], v[56:59]
	v_mfma_f32_16x16x32_bf16 v[48:51], v[128:131], v[152:155], v[48:51]
	v_mfma_f32_16x16x32_bf16 v[40:43], v[136:139], v[152:155], v[40:43]
	v_mfma_f32_16x16x32_bf16 v[28:31], v[128:131], v[160:163], v[28:31]
	v_mfma_f32_16x16x32_bf16 v[24:27], v[136:139], v[160:163], v[24:27]
	v_mfma_f32_16x16x32_bf16 v[16:19], v[128:131], v[168:171], v[16:19]
	v_mfma_f32_16x16x32_bf16 v[8:11], v[136:139], v[168:171], v[8:11]
	v_mfma_f32_16x16x32_bf16 v[60:63], v[132:135], v[148:151], v[60:63]
	v_mfma_f32_16x16x32_bf16 v[56:59], v[140:143], v[148:151], v[56:59]
	v_mfma_f32_16x16x32_bf16 v[48:51], v[132:135], v[156:159], v[48:51]
	v_mfma_f32_16x16x32_bf16 v[40:43], v[140:143], v[156:159], v[40:43]
	v_mfma_f32_16x16x32_bf16 v[28:31], v[132:135], v[164:167], v[28:31]
	v_mfma_f32_16x16x32_bf16 v[24:27], v[140:143], v[164:167], v[24:27]
	v_mfma_f32_16x16x32_bf16 v[16:19], v[132:135], v[172:175], v[16:19]
	v_mfma_f32_16x16x32_bf16 v[8:11], v[140:143], v[172:175], v[8:11]
	s_setprio 0
	s_barrier
	s_add_u32 s30, s50, 0x158080
	s_addc_u32 s31, s51, 0
	s_add_i32 s38, s39, s22
	v_lshl_add_u64 v[128:129], s[30:31], 0, v[178:179]
	s_mov_b32 m0, s38
	s_nop 0
	global_load_lds_dwordx4 v[128:129], off
	v_lshl_add_u64 v[128:129], s[30:31], 0, v[194:195]
	s_add_i32 m0, s38, 0x2000
	s_nop 0
	global_load_lds_dwordx4 v[128:129], off
	s_waitcnt vmcnt(6)
	s_barrier
	s_setprio 1
	v_mfma_f32_16x16x32_bf16 v[52:55], v[200:203], v[144:147], v[52:55]
	v_mfma_f32_16x16x32_bf16 v[44:47], v[208:211], v[144:147], v[44:47]
	v_mfma_f32_16x16x32_bf16 v[36:39], v[200:203], v[152:155], v[36:39]
	v_mfma_f32_16x16x32_bf16 v[32:35], v[208:211], v[152:155], v[32:35]
	v_mfma_f32_16x16x32_bf16 v[20:23], v[200:203], v[160:163], v[20:23]
	v_mfma_f32_16x16x32_bf16 v[12:15], v[208:211], v[160:163], v[12:15]
	v_mfma_f32_16x16x32_bf16 v[4:7], v[200:203], v[168:171], v[4:7]
	v_mfma_f32_16x16x32_bf16 v[0:3], v[208:211], v[168:171], v[0:3]
	v_mfma_f32_16x16x32_bf16 v[52:55], v[204:207], v[148:151], v[52:55]
	v_mfma_f32_16x16x32_bf16 v[44:47], v[232:235], v[148:151], v[44:47]
	v_mfma_f32_16x16x32_bf16 v[36:39], v[204:207], v[156:159], v[36:39]
	v_mfma_f32_16x16x32_bf16 v[32:35], v[232:235], v[156:159], v[32:35]
	v_mfma_f32_16x16x32_bf16 v[20:23], v[204:207], v[164:167], v[20:23]
	v_mfma_f32_16x16x32_bf16 v[12:15], v[232:235], v[164:167], v[12:15]
	v_mfma_f32_16x16x32_bf16 v[4:7], v[204:207], v[172:175], v[4:7]
	v_mfma_f32_16x16x32_bf16 v[0:3], v[232:235], v[172:175], v[0:3]
	s_setprio 0
	s_barrier
	s_add_u32 s64, s64, 0x100
	s_addc_u32 s65, s65, 0
	s_cmp_ge_i32 s66, s63
	s_mov_b64 s[38:39], s[48:49]
	s_mov_b32 s50, s66
	s_cbranch_scc0 .LBB0_2573
	s_cmp_gt_i32 s28, 31
	s_mov_b64 s[38:39], 0x12000
	s_cbranch_scc1 .LBB0_2576
	s_ashr_i32 s11, s28, 3
	s_mul_hi_i32 s39, s11, 0x4800
	s_mul_i32 s38, s11, 0x4800

;     __device__ __forceinline__ void operator()(AccRef acc, const pg8::Unit& u, int wr, int wc, int fr, int fq) const {
;     ...
;         const int v = u.pm < 32 ? (u.pm >> 3) : 4;
;         f32x4 gv[2][2];
; #pragma unroll
;         for (int bj = 0; bj < 2; ++bj)
; #pragma unroll
;             for (int n = 0; n < 2; ++n) gv[bj][n] = *(const f32x4*)(gate + (size_t)v * MODW + col0 + bj * 128 + n * 16) * coef;
;         const bool part = u.part != 0;
;         float* base = part ? PART + ((size_t)u.ks * NCTX - NLAT) * DM : X;
; #pragma unroll
;         for (int ai = 0; ai < 2; ++ai)
; #pragma unroll
;             for (int mp = 0; mp < 2; ++mp) {
;                 f32x4 old[2][2][2];
;                 if (!part) {
; #pragma unroll
;                     for (int mm = 0; mm < 2; ++mm)
; #pragma unroll
;                         for (int bj = 0; bj < 2; ++bj)
; #pragma unroll
;                             for (int n = 0; n < 2; ++n) old[mm][bj][n] = *(const f32x4*)(SRC + (size_t)(row0 + ai * 128 + (2 * mp + mm) * 16) * DM + col0 + bj * 128 + n * 16);
;                 }
; #pragma unroll
;                 for (int mm = 0; mm < 2; ++mm)
; #pragma unroll
;                     for (int bj = 0; bj < 2; ++bj)
; #pragma unroll
;                         for (int n = 0; n < 2; ++n) { const int m = 2 * mp + mm; const f32x4 d = gv[bj][n] * acc[ai][bj][m][n];
;                             *(f32x4*)(base + (size_t)(row0 + ai * 128 + m * 16) * DM + col0 + bj * 128 + n * 16) = part ? d : old[mm][bj][n] + d; }
.LBB0_2580:
	s_ashr_i32 s41, s40, 31
	s_lshl_b64 s[28:29], s[40:41], 23
	v_readlane_b32 s30, v251, 46
	v_readlane_b32 s31, v251, 47
	s_add_u32 s11, s30, s28
	s_addc_u32 s28, s31, s29
	s_add_u32 s11, s11, 0xfc000000
	s_addc_u32 s30, s28, -1
	s_and_b64 s[28:29], exec, s[38:39]
	s_cselect_b32 s28, s83, s30
	s_cselect_b32 s11, s82, s11
	s_waitcnt vmcnt(0)
	v_pk_mul_f32 v[174:175], v[174:175], 0.5 op_sel_hi:[1,0]
	v_pk_mul_f32 v[172:173], v[172:173], 0.5 op_sel_hi:[1,0]
	v_mov_b32_e32 v210, s11
	v_mov_b32_e32 v211, s28
	v_lshl_add_u64 v[202:203], v[202:203], 2, v[210:211]
	v_pk_mul_f32 v[210:211], v[126:127], v[174:175]
	v_pk_mul_f32 v[220:221], v[124:125], v[172:173]
	v_pk_fma_f32 v[126:127], v[126:127], v[174:175], v[158:159]
	v_pk_fma_f32 v[124:125], v[124:125], v[172:173], v[156:157]
	v_pk_mul_f32 v[170:171], v[170:171], 0.5 op_sel_hi:[1,0]
	v_pk_mul_f32 v[168:169], v[168:169], 0.5 op_sel_hi:[1,0]
	v_lshl_add_u64 v[208:209], v[202:203], 0, v[208:209]
	v_cndmask_b32_e64 v127, v211, v127, s[38:39]
	v_cndmask_b32_e64 v126, v210, v126, s[38:39]
	v_cndmask_b32_e64 v125, v221, v125, s[38:39]
	v_cndmask_b32_e64 v124, v220, v124, s[38:39]
	global_store_dwordx4 v[208:209], v[124:127], off sc0 sc1
	v_pk_mul_f32 v[166:167], v[166:167], 0.5 op_sel_hi:[1,0]
	v_pk_mul_f32 v[164:165], v[164:165], 0.5 op_sel_hi:[1,0]
	v_pk_mul_f32 v[124:125], v[122:123], v[170:171]
	v_pk_mul_f32 v[126:127], v[120:121], v[168:169]
	v_pk_fma_f32 v[122:123], v[122:123], v[170:171], v[154:155]
	v_pk_fma_f32 v[120:121], v[120:121], v[168:169], v[152:153]
	v_cndmask_b32_e64 v123, v125, v123, s[38:39]
	v_cndmask_b32_e64 v122, v124, v122, s[38:39]
	v_cndmask_b32_e64 v121, v127, v121, s[38:39]
	v_cndmask_b32_e64 v120, v126, v120, s[38:39]
	global_store_dwordx4 v[208:209], v[120:123], off offset:64 sc0 sc1
	v_pk_mul_f32 v[162:163], v[162:163], 0.5 op_sel_hi:[1,0]
	v_pk_mul_f32 v[160:161], v[160:161], 0.5 op_sel_hi:[1,0]
	v_pk_mul_f32 v[120:121], v[118:119], v[166:167]
	v_pk_mul_f32 v[122:123], v[116:117], v[164:165]
	v_pk_fma_f32 v[118:119], v[118:119], v[166:167], v[150:151]
	v_pk_fma_f32 v[116:117], v[116:117], v[164:165], v[148:149]
	v_cndmask_b32_e64 v119, v121, v119, s[38:39]
	v_cndmask_b32_e64 v118, v120, v118, s[38:39]
	v_cndmask_b32_e64 v117, v123, v117, s[38:39]
	v_cndmask_b32_e64 v116, v122, v116, s[38:39]
	global_store_dwordx4 v[208:209], v[116:119], off offset:512 sc0 sc1
	s_mov_b64 s[50:51], -1
	s_andn2_b64 vcc, exec, s[48:49]
	v_pk_mul_f32 v[116:117], v[110:111], v[162:163]
	v_pk_mul_f32 v[118:119], v[108:109], v[160:161]
	v_pk_fma_f32 v[110:111], v[110:111], v[162:163], v[142:143]
	v_pk_fma_f32 v[108:109], v[108:109], v[160:161], v[140:141]
	v_cndmask_b32_e64 v111, v117, v111, s[38:39]
	v_cndmask_b32_e64 v110, v116, v110, s[38:39]
	v_cndmask_b32_e64 v109, v119, v109, s[38:39]
	v_cndmask_b32_e64 v108, v118, v108, s[38:39]
	global_store_dwordx4 v[208:209], v[108:111], off offset:576 sc0 sc1
	v_pk_mul_f32 v[118:119], v[112:113], v[172:173]
	v_pk_fma_f32 v[112:113], v[112:113], v[172:173], v[144:145]
	v_pk_mul_f32 v[108:109], v[114:115], v[174:175]
	v_pk_fma_f32 v[110:111], v[114:115], v[174:175], v[146:147]
	v_lshl_add_u64 v[116:117], v[202:203], 0, v[206:207]
	v_cndmask_b32_e64 v111, v109, v111, s[38:39]
	v_cndmask_b32_e64 v110, v108, v110, s[38:39]
	v_cndmask_b32_e64 v109, v119, v113, s[38:39]
	v_cndmask_b32_e64 v108, v118, v112, s[38:39]
	global_store_dwordx4 v[116:117], v[108:111], off sc0 sc1
	s_nop 1
	v_pk_mul_f32 v[108:109], v[106:107], v[170:171]
	v_pk_mul_f32 v[110:111], v[104:105], v[168:169]
	v_pk_fma_f32 v[106:107], v[106:107], v[170:171], v[138:139]
	v_pk_fma_f32 v[104:105], v[104:105], v[168:169], v[136:137]
	v_cndmask_b32_e64 v107, v109, v107, s[38:39]
	v_cndmask_b32_e64 v106, v108, v106, s[38:39]
	v_cndmask_b32_e64 v105, v111, v105, s[38:39]
	v_cndmask_b32_e64 v104, v110, v104, s[38:39]
	global_store_dwordx4 v[116:117], v[104:107], off offset:64 sc0 sc1
	s_nop 1
	v_pk_mul_f32 v[104:105], v[102:103], v[166:167]
	v_pk_mul_f32 v[106:107], v[100:101], v[164:165]
	v_pk_fma_f32 v[102:103], v[102:103], v[166:167], v[134:135]
	v_pk_fma_f32 v[100:101], v[100:101], v[164:165], v[132:133]
	v_cndmask_b32_e64 v103, v105, v103, s[38:39]
	v_cndmask_b32_e64 v102, v104, v102, s[38:39]
	v_cndmask_b32_e64 v101, v107, v101, s[38:39]
	v_cndmask_b32_e64 v100, v106, v100, s[38:39]
	global_store_dwordx4 v[116:117], v[100:103], off offset:512 sc0 sc1
	s_nop 1
	v_pk_mul_f32 v[100:101], v[98:99], v[162:163]
	v_pk_mul_f32 v[102:103], v[96:97], v[160:161]
	v_pk_fma_f32 v[98:99], v[98:99], v[162:163], v[130:131]
	v_pk_fma_f32 v[96:97], v[96:97], v[160:161], v[128:129]
	v_cndmask_b32_e64 v99, v101, v99, s[38:39]
	v_cndmask_b32_e64 v98, v100, v98, s[38:39]
	v_cndmask_b32_e64 v97, v103, v97, s[38:39]
	v_cndmask_b32_e64 v96, v102, v96, s[38:39]
	global_store_dwordx4 v[116:117], v[96:99], off offset:576 sc0 sc1
	v_or_b32_e32 v102, 32, v200
	v_or_b32_e32 v100, 48, v200
	v_cndmask_b32_e64 v96, 0, 1, s[48:49]
	v_cmp_ne_u32_e64 s[40:41], 1, v96
	v_ashrrev_i32_e32 v103, 31, v102
	v_ashrrev_i32_e32 v101, 31, v100
	s_cbranch_vccnz .LBB0_2582
	v_lshlrev_b64 v[98:99], 13, v[102:103]
	v_lshlrev_b64 v[96:97], 13, v[100:101]
	s_mov_b64 s[50:51], 0

;     __device__ __forceinline__ void operator()(AccRef acc, const pg8::Unit& u, int wr, int wc, int fr, int fq) const {
;     ...
;                 for (int mm = 0; mm < 2; ++mm)
; #pragma unroll
;                     for (int bj = 0; bj < 2; ++bj)
; #pragma unroll
;                         for (int n = 0; n < 2; ++n) { const int m = 2 * mp + mm; const f32x4 d = gv[bj][n] * acc[ai][bj][m][n];
;                             *(f32x4*)(base + (size_t)(row0 + ai * 128 + m * 16) * DM + col0 + bj * 128 + n * 16) = part ? d : old[mm][bj][n] + d; }
.LBB0_2584:
	v_pk_mul_f32 v[100:101], v[94:95], v[174:175]
	v_pk_mul_f32 v[102:103], v[92:93], v[172:173]
	s_waitcnt vmcnt(0)
	v_pk_fma_f32 v[94:95], v[94:95], v[174:175], v[158:159]
	v_pk_fma_f32 v[92:93], v[92:93], v[172:173], v[156:157]
	v_lshl_add_u64 v[98:99], v[202:203], 0, v[98:99]
	v_cndmask_b32_e64 v95, v101, v95, s[38:39]
	v_cndmask_b32_e64 v94, v100, v94, s[38:39]
	v_cndmask_b32_e64 v93, v103, v93, s[38:39]
	v_cndmask_b32_e64 v92, v102, v92, s[38:39]
	global_store_dwordx4 v[98:99], v[92:95], off sc0 sc1
	s_mov_b64 s[48:49], -1
	s_and_b64 vcc, exec, s[40:41]
	v_pk_mul_f32 v[92:93], v[90:91], v[170:171]
	v_pk_mul_f32 v[94:95], v[88:89], v[168:169]
	v_pk_fma_f32 v[90:91], v[90:91], v[170:171], v[154:155]
	v_pk_fma_f32 v[88:89], v[88:89], v[168:169], v[152:153]
	v_cndmask_b32_e64 v91, v93, v91, s[38:39]
	v_cndmask_b32_e64 v90, v92, v90, s[38:39]
	v_cndmask_b32_e64 v89, v95, v89, s[38:39]
	v_cndmask_b32_e64 v88, v94, v88, s[38:39]
	global_store_dwordx4 v[98:99], v[88:91], off offset:64 sc0 sc1
	s_nop 1
	v_pk_mul_f32 v[88:89], v[86:87], v[166:167]
	v_pk_mul_f32 v[90:91], v[84:85], v[164:165]
	v_pk_fma_f32 v[86:87], v[86:87], v[166:167], v[150:151]
	v_pk_fma_f32 v[84:85], v[84:85], v[164:165], v[148:149]
	v_cndmask_b32_e64 v87, v89, v87, s[38:39]
	v_cndmask_b32_e64 v86, v88, v86, s[38:39]
	v_cndmask_b32_e64 v85, v91, v85, s[38:39]
	v_cndmask_b32_e64 v84, v90, v84, s[38:39]
	global_store_dwordx4 v[98:99], v[84:87], off offset:512 sc0 sc1
	s_nop 1
	v_pk_mul_f32 v[84:85], v[78:79], v[162:163]
	v_pk_mul_f32 v[86:87], v[76:77], v[160:161]
	v_pk_fma_f32 v[78:79], v[78:79], v[162:163], v[142:143]
	v_pk_fma_f32 v[76:77], v[76:77], v[160:161], v[140:141]
	v_cndmask_b32_e64 v79, v85, v79, s[38:39]
	v_cndmask_b32_e64 v78, v84, v78, s[38:39]
	v_cndmask_b32_e64 v77, v87, v77, s[38:39]
	v_cndmask_b32_e64 v76, v86, v76, s[38:39]
	global_store_dwordx4 v[98:99], v[76:79], off offset:576 sc0 sc1
	v_pk_mul_f32 v[86:87], v[80:81], v[172:173]
	v_pk_fma_f32 v[80:81], v[80:81], v[172:173], v[144:145]
	v_pk_mul_f32 v[76:77], v[82:83], v[174:175]
	v_pk_fma_f32 v[78:79], v[82:83], v[174:175], v[146:147]
	v_lshl_add_u64 v[84:85], v[202:203], 0, v[96:97]
	v_cndmask_b32_e64 v79, v77, v79, s[38:39]
	v_cndmask_b32_e64 v78, v76, v78, s[38:39]
	v_cndmask_b32_e64 v77, v87, v81, s[38:39]
	v_cndmask_b32_e64 v76, v86, v80, s[38:39]
	global_store_dwordx4 v[84:85], v[76:79], off sc0 sc1
	s_nop 1
	v_pk_mul_f32 v[76:77], v[74:75], v[170:171]
	v_pk_mul_f32 v[78:79], v[72:73], v[168:169]
	v_pk_fma_f32 v[74:75], v[74:75], v[170:171], v[138:139]
	v_pk_fma_f32 v[72:73], v[72:73], v[168:169], v[136:137]
	v_cndmask_b32_e64 v75, v77, v75, s[38:39]
	v_cndmask_b32_e64 v74, v76, v74, s[38:39]
	v_cndmask_b32_e64 v73, v79, v73, s[38:39]
	v_cndmask_b32_e64 v72, v78, v72, s[38:39]
	global_store_dwordx4 v[84:85], v[72:75], off offset:64 sc0 sc1
	s_nop 1
	v_pk_mul_f32 v[72:73], v[70:71], v[166:167]
	v_pk_mul_f32 v[74:75], v[68:69], v[164:165]
	v_pk_fma_f32 v[70:71], v[70:71], v[166:167], v[134:135]
	v_pk_fma_f32 v[68:69], v[68:69], v[164:165], v[132:133]
	v_cndmask_b32_e64 v71, v73, v71, s[38:39]
	v_cndmask_b32_e64 v70, v72, v70, s[38:39]
	v_cndmask_b32_e64 v69, v75, v69, s[38:39]
	v_cndmask_b32_e64 v68, v74, v68, s[38:39]
	global_store_dwordx4 v[84:85], v[68:71], off offset:512 sc0 sc1
	s_nop 1
	v_pk_mul_f32 v[68:69], v[66:67], v[162:163]
	v_pk_fma_f32 v[66:67], v[66:67], v[162:163], v[130:131]
	v_pk_mul_f32 v[70:71], v[64:65], v[160:161]
	v_pk_fma_f32 v[64:65], v[64:65], v[160:161], v[128:129]
	v_cndmask_b32_e64 v66, v68, v66, s[38:39]
	v_add_u32_e32 v68, 0x80, v200
	v_cndmask_b32_e64 v67, v69, v67, s[38:39]
	v_cndmask_b32_e64 v65, v71, v65, s[38:39]
	v_cndmask_b32_e64 v64, v70, v64, s[38:39]
	v_ashrrev_i32_e32 v69, 31, v68
	global_store_dwordx4 v[84:85], v[64:67], off offset:576 sc0 sc1
	s_cbranch_vccnz .LBB0_2586
	s_nop 0
	v_lshlrev_b64 v[64:65], 13, v[200:201]
	s_mov_b64 s[28:29], 0x120000
	v_lshlrev_b64 v[66:67], 13, v[68:69]
	v_lshl_add_u64 v[64:65], v[64:65], 0, s[28:29]
	s_mov_b64 s[48:49], 0

;     __device__ __forceinline__ void operator()(AccRef acc, const pg8::Unit& u, int wr, int wc, int fr, int fq) const {
;     ...
;                 for (int mm = 0; mm < 2; ++mm)
; #pragma unroll
;                     for (int bj = 0; bj < 2; ++bj)
; #pragma unroll
;                         for (int n = 0; n < 2; ++n) { const int m = 2 * mp + mm; const f32x4 d = gv[bj][n] * acc[ai][bj][m][n];
;                             *(f32x4*)(base + (size_t)(row0 + ai * 128 + m * 16) * DM + col0 + bj * 128 + n * 16) = part ? d : old[mm][bj][n] + d; }
.LBB0_2588:
	v_pk_mul_f32 v[68:69], v[62:63], v[174:175]
	v_pk_mul_f32 v[70:71], v[60:61], v[172:173]
	s_waitcnt vmcnt(0)
	v_pk_fma_f32 v[62:63], v[62:63], v[174:175], v[158:159]
	v_pk_fma_f32 v[60:61], v[60:61], v[172:173], v[156:157]
	v_lshl_add_u64 v[66:67], v[202:203], 0, v[66:67]
	v_cndmask_b32_e64 v63, v69, v63, s[38:39]
	v_cndmask_b32_e64 v62, v68, v62, s[38:39]
	v_cndmask_b32_e64 v61, v71, v61, s[38:39]
	v_cndmask_b32_e64 v60, v70, v60, s[38:39]
	global_store_dwordx4 v[66:67], v[60:63], off sc0 sc1
	s_mov_b64 s[48:49], -1
	s_and_b64 vcc, exec, s[40:41]
	v_pk_mul_f32 v[60:61], v[58:59], v[170:171]
	v_pk_mul_f32 v[62:63], v[56:57], v[168:169]
	v_pk_fma_f32 v[58:59], v[58:59], v[170:171], v[154:155]
	v_pk_fma_f32 v[56:57], v[56:57], v[168:169], v[152:153]
	v_cndmask_b32_e64 v59, v61, v59, s[38:39]
	v_cndmask_b32_e64 v58, v60, v58, s[38:39]
	v_cndmask_b32_e64 v57, v63, v57, s[38:39]
	v_cndmask_b32_e64 v56, v62, v56, s[38:39]
	global_store_dwordx4 v[66:67], v[56:59], off offset:64 sc0 sc1
	s_nop 1
	v_pk_mul_f32 v[56:57], v[54:55], v[166:167]
	v_pk_mul_f32 v[58:59], v[52:53], v[164:165]
	v_pk_fma_f32 v[54:55], v[54:55], v[166:167], v[150:151]
	v_pk_fma_f32 v[52:53], v[52:53], v[164:165], v[148:149]
	v_cndmask_b32_e64 v55, v57, v55, s[38:39]
	v_cndmask_b32_e64 v54, v56, v54, s[38:39]
	v_cndmask_b32_e64 v53, v59, v53, s[38:39]
	v_cndmask_b32_e64 v52, v58, v52, s[38:39]
	global_store_dwordx4 v[66:67], v[52:55], off offset:512 sc0 sc1
	s_nop 1
	v_pk_mul_f32 v[52:53], v[46:47], v[162:163]
	v_pk_mul_f32 v[54:55], v[44:45], v[160:161]
	v_pk_fma_f32 v[46:47], v[46:47], v[162:163], v[142:143]
	v_pk_fma_f32 v[44:45], v[44:45], v[160:161], v[140:141]
	v_cndmask_b32_e64 v47, v53, v47, s[38:39]
	v_cndmask_b32_e64 v46, v52, v46, s[38:39]
	v_cndmask_b32_e64 v45, v55, v45, s[38:39]
	v_cndmask_b32_e64 v44, v54, v44, s[38:39]
	global_store_dwordx4 v[66:67], v[44:47], off offset:576 sc0 sc1
	v_pk_mul_f32 v[54:55], v[48:49], v[172:173]
	v_pk_fma_f32 v[48:49], v[48:49], v[172:173], v[144:145]
	v_pk_mul_f32 v[44:45], v[50:51], v[174:175]
	v_pk_fma_f32 v[46:47], v[50:51], v[174:175], v[146:147]
	v_lshl_add_u64 v[52:53], v[202:203], 0, v[64:65]
	v_cndmask_b32_e64 v47, v45, v47, s[38:39]
	v_cndmask_b32_e64 v46, v44, v46, s[38:39]
	v_cndmask_b32_e64 v45, v55, v49, s[38:39]
	v_cndmask_b32_e64 v44, v54, v48, s[38:39]
	global_store_dwordx4 v[52:53], v[44:47], off sc0 sc1
	s_nop 1
	v_pk_mul_f32 v[44:45], v[42:43], v[170:171]
	v_pk_mul_f32 v[46:47], v[40:41], v[168:169]
	v_pk_fma_f32 v[42:43], v[42:43], v[170:171], v[138:139]
	v_pk_fma_f32 v[40:41], v[40:41], v[168:169], v[136:137]
	v_cndmask_b32_e64 v43, v45, v43, s[38:39]
	v_cndmask_b32_e64 v42, v44, v42, s[38:39]
	v_cndmask_b32_e64 v41, v47, v41, s[38:39]
	v_cndmask_b32_e64 v40, v46, v40, s[38:39]
	global_store_dwordx4 v[52:53], v[40:43], off offset:64 sc0 sc1
	s_nop 1
	v_pk_mul_f32 v[40:41], v[38:39], v[166:167]
	v_pk_mul_f32 v[42:43], v[36:37], v[164:165]
	v_pk_fma_f32 v[38:39], v[38:39], v[166:167], v[134:135]
	v_pk_fma_f32 v[36:37], v[36:37], v[164:165], v[132:133]
	v_cndmask_b32_e64 v39, v41, v39, s[38:39]
	v_cndmask_b32_e64 v38, v40, v38, s[38:39]
	v_cndmask_b32_e64 v37, v43, v37, s[38:39]
	v_cndmask_b32_e64 v36, v42, v36, s[38:39]
	global_store_dwordx4 v[52:53], v[36:39], off offset:512 sc0 sc1
	s_nop 1
	v_pk_mul_f32 v[36:37], v[34:35], v[162:163]
	v_pk_fma_f32 v[34:35], v[34:35], v[162:163], v[130:131]
	v_pk_mul_f32 v[38:39], v[32:33], v[160:161]
	v_pk_fma_f32 v[32:33], v[32:33], v[160:161], v[128:129]
	v_cndmask_b32_e64 v34, v36, v34, s[38:39]
	v_add_u32_e32 v36, 0xa0, v200
	v_cndmask_b32_e64 v35, v37, v35, s[38:39]
	v_cndmask_b32_e64 v33, v39, v33, s[38:39]
	v_cndmask_b32_e64 v32, v38, v32, s[38:39]
	v_ashrrev_i32_e32 v37, 31, v36
	global_store_dwordx4 v[52:53], v[32:35], off offset:576 sc0 sc1
	s_cbranch_vccnz .LBB0_2590
	s_nop 0
	v_lshlrev_b64 v[32:33], 13, v[200:201]
	s_mov_b64 s[28:29], 0x160000
	v_lshlrev_b64 v[34:35], 13, v[36:37]
	v_lshl_add_u64 v[32:33], v[32:33], 0, s[28:29]
	s_mov_b64 s[48:49], 0

; __device__ __forceinline__ void norm_phase(float* __restrict__ X, bf16_t* __restrict__ H, const float* __restrict__ modl, int shiftIdx, int scaleIdx, int nrows, const float* __restrict__ PART, const float* __restrict__ XLAT) {
;     ...
;         const float* xs = (XLAT != nullptr && row < NLAT) ? XLAT + (size_t)row * DM : xr;
;         f32x4 x[8]; float ss = 0.f;
; #pragma unroll
;         for (int i = 0; i < 8; ++i) x[i] = *(const f32x4*)(xs + (i * 64 + lane) * 4);
;         if (PART != nullptr && row >= NLAT) {
; #pragma unroll
;             for (int s = 0; s < 8; ++s) { f32x4 pt[8];
; #pragma unroll
;                 for (int i = 0; i < 8; ++i) pt[i] = *(const f32x4*)(PART + ((size_t)s * NCTX + (row - NLAT)) * DM + (i * 64 + lane) * 4);
; #pragma unroll
;                 for (int i = 0; i < 8; ++i) x[i] += pt[i]; }
.LBB0_2655:
	v_lshl_add_u64 v[54:55], s[92:93], 0, v[38:39]
	v_add_co_u32_e32 v0, vcc, 0x142dd000, v54
	s_movk_i32 s4, 0x1fff
	s_nop 0
	v_addc_co_u32_e32 v1, vcc, 0, v55, vcc
	global_load_dwordx4 v[28:31], v[0:1], off
	global_load_dwordx4 v[24:27], v[0:1], off offset:1024
	global_load_dwordx4 v[20:23], v[0:1], off offset:2048
	global_load_dwordx4 v[16:19], v[0:1], off offset:3072
	v_add_co_u32_e32 v0, vcc, 0x142de000, v54
	v_readlane_b32 s6, v251, 26
	s_nop 0
	v_addc_co_u32_e32 v1, vcc, 0, v55, vcc
	global_load_dwordx4 v[12:15], v[0:1], off
	global_load_dwordx4 v[8:11], v[0:1], off offset:1024
	global_load_dwordx4 v[4:7], v[0:1], off offset:2048
	s_nop 0
	global_load_dwordx4 v[0:3], v[0:1], off offset:3072
	v_cmp_lt_i32_e32 vcc, s4, v32
	v_readlane_b32 s7, v251, 27
	s_and_b64 s[6:7], s[6:7], vcc
	v_lshlrev_b32_e32 v178, 2, v34
	s_and_saveexec_b64 s[38:39], s[6:7]
	s_cbranch_execz .LBB0_2654
	s_mov_b64 s[6:7], 0x142dd000
	v_lshl_add_u64 v[68:69], v[54:55], 0, s[6:7]
	s_mov_b64 s[6:7], 0x142dd400
	v_lshl_add_u64 v[66:67], v[54:55], 0, s[6:7]
	s_mov_b64 s[6:7], 0x142dd800
	v_lshl_add_u64 v[64:65], v[54:55], 0, s[6:7]
	s_mov_b64 s[6:7], 0x142ddc00
	v_lshl_add_u64 v[62:63], v[54:55], 0, s[6:7]
	s_mov_b64 s[6:7], 0x142de000
	v_lshl_add_u64 v[60:61], v[54:55], 0, s[6:7]
	s_mov_b64 s[6:7], 0x142de400
	v_lshl_add_u64 v[58:59], v[54:55], 0, s[6:7]
	s_mov_b64 s[6:7], 0x142de800
	v_lshl_add_u64 v[56:57], v[54:55], 0, s[6:7]
	s_mov_b64 s[6:7], 0x142dec00
	v_lshl_add_u64 v[54:55], v[54:55], 0, s[6:7]
	v_add_u32_e32 v70, 0xffffe000, v32
	v_mov_b32_e32 v71, v179
	v_readlane_b32 s6, v251, 46
	v_lshlrev_b64 v[70:71], 13, v[70:71]
	v_readlane_b32 s7, v251, 47
	v_mov_b32_e32 v47, v179
	v_mov_b32_e32 v49, v179
	v_lshl_add_u64 v[70:71], s[6:7], 0, v[70:71]
	v_lshl_add_u64 v[84:85], v[70:71], 0, v[178:179]
	global_load_dwordx4 v[72:75], v[84:85], off
	global_load_dwordx4 v[76:79], v[84:85], off offset:1024
	global_load_dwordx4 v[80:83], v[84:85], off offset:2048
	s_nop 0
	global_load_dwordx4 v[84:87], v[84:85], off offset:3072
	v_mov_b32_e32 v51, v179
	v_mov_b32_e32 v53, v179
	v_lshl_add_u64 v[88:89], v[70:71], 0, v[46:47]
	v_lshl_add_u64 v[92:93], v[70:71], 0, v[48:49]
	v_lshl_add_u64 v[96:97], v[70:71], 0, v[50:51]
	v_lshl_add_u64 v[100:101], v[70:71], 0, v[52:53]
	global_load_dwordx4 v[88:91], v[88:89], off
	s_mov_b64 s[6:7], 0x800000
	global_load_dwordx4 v[92:95], v[92:93], off
	v_mov_b32_e32 v41, v179
	global_load_dwordx4 v[96:99], v[96:97], off
	v_mov_b32_e32 v43, v179
	global_load_dwordx4 v[100:103], v[100:101], off
	v_mov_b32_e32 v45, v179
	s_waitcnt vmcnt(0)
	v_pk_add_f32 v[30:31], v[30:31], v[74:75]
	v_pk_add_f32 v[110:111], v[28:29], v[72:73]
	v_pk_add_f32 v[114:115], v[20:21], v[80:81]
	v_pk_add_f32 v[116:117], v[16:17], v[84:85]
	v_lshl_add_u64 v[16:17], v[70:71], 0, s[6:7]
	v_lshl_add_u64 v[20:21], v[16:17], 0, v[46:47]
	global_load_dwordx4 v[72:75], v[20:21], off
	v_lshl_add_u64 v[20:21], v[16:17], 0, v[48:49]
	v_pk_add_f32 v[26:27], v[26:27], v[78:79]
	v_pk_add_f32 v[112:113], v[24:25], v[76:77]
	v_pk_add_f32 v[88:89], v[12:13], v[88:89]
	v_lshl_add_u64 v[12:13], v[16:17], 0, v[44:45]
	global_load_dwordx4 v[76:79], v[20:21], off
	v_pk_add_f32 v[92:93], v[8:9], v[92:93]
	v_pk_add_f32 v[96:97], v[4:5], v[96:97]
	v_lshl_add_u64 v[4:5], v[16:17], 0, v[40:41]
	v_pk_add_f32 v[100:101], v[0:1], v[100:101]
	v_lshl_add_u64 v[0:1], v[16:17], 0, v[178:179]
	v_lshl_add_u64 v[8:9], v[16:17], 0, v[42:43]
	v_lshl_add_u64 v[20:21], v[16:17], 0, v[50:51]
	v_lshl_add_u64 v[16:17], v[16:17], 0, v[52:53]
	v_pk_add_f32 v[22:23], v[22:23], v[82:83]
	v_pk_add_f32 v[18:19], v[18:19], v[86:87]
	v_pk_add_f32 v[102:103], v[2:3], v[102:103]
	global_load_dwordx4 v[0:3], v[0:1], off
	v_pk_add_f32 v[90:91], v[14:15], v[90:91]
	global_load_dwordx4 v[80:83], v[20:21], off
	global_load_dwordx4 v[84:87], v[16:17], off
	v_pk_add_f32 v[94:95], v[10:11], v[94:95]
	global_load_dwordx4 v[8:11], v[8:9], off
	v_pk_add_f32 v[98:99], v[6:7], v[98:99]
	global_load_dwordx4 v[12:15], v[12:13], off
	s_mov_b64 s[6:7], 0x1000000
	global_load_dwordx4 v[4:7], v[4:5], off
	s_waitcnt vmcnt(0)
	v_pk_add_f32 v[28:29], v[30:31], v[2:3]
	v_pk_add_f32 v[30:31], v[110:111], v[0:1]
	v_pk_add_f32 v[2:3], v[100:101], v[84:85]
	v_lshl_add_u64 v[100:101], v[70:71], 0, s[6:7]
	v_pk_add_f32 v[20:21], v[22:23], v[10:11]
	v_pk_add_f32 v[10:11], v[92:93], v[76:77]
	v_pk_add_f32 v[16:17], v[18:19], v[14:15]
	v_pk_add_f32 v[14:15], v[88:89], v[72:73]
	v_lshl_add_u64 v[72:73], v[100:101], 0, v[178:179]
	v_pk_add_f32 v[24:25], v[26:27], v[6:7]
	v_pk_add_f32 v[18:19], v[116:117], v[12:13]
	v_pk_add_f32 v[12:13], v[90:91], v[74:75]
	v_pk_add_f32 v[6:7], v[96:97], v[80:81]
	global_load_dwordx4 v[72:75], v[72:73], off
	v_lshl_add_u64 v[76:77], v[100:101], 0, v[40:41]
	v_lshl_add_u64 v[80:81], v[100:101], 0, v[42:43]
	v_lshl_add_u64 v[84:85], v[100:101], 0, v[44:45]
	v_lshl_add_u64 v[88:89], v[100:101], 0, v[46:47]
	v_lshl_add_u64 v[92:93], v[100:101], 0, v[48:49]
	v_lshl_add_u64 v[96:97], v[100:101], 0, v[50:51]
	v_lshl_add_u64 v[100:101], v[100:101], 0, v[52:53]
	v_pk_add_f32 v[26:27], v[112:113], v[4:5]
	v_pk_add_f32 v[22:23], v[114:115], v[8:9]
	v_pk_add_f32 v[8:9], v[94:95], v[78:79]
	v_pk_add_f32 v[4:5], v[98:99], v[82:83]
	v_pk_add_f32 v[0:1], v[102:103], v[86:87]
	global_load_dwordx4 v[76:79], v[76:77], off
	s_mov_b64 s[6:7], 0x1800000
	global_load_dwordx4 v[80:83], v[80:81], off
	s_waitcnt vmcnt(0)
; __device__ __forceinline__ void norm_phase(float* __restrict__ X, bf16_t* __restrict__ H, const float* __restrict__ modl, int shiftIdx, int scaleIdx, int nrows, const float* __restrict__ PART, const float* __restrict__ XLAT) {
;     ...
;             for (int s = 0; s < 8; ++s) { f32x4 pt[8];
; #pragma unroll
;                 for (int i = 0; i < 8; ++i) pt[i] = *(const f32x4*)(PART + ((size_t)s * NCTX + (row - NLAT)) * DM + (i * 64 + lane) * 4);
; #pragma unroll
;                 for (int i = 0; i < 8; ++i) x[i] += pt[i]; }
	v_pk_add_f32 v[74:75], v[28:29], v[74:75]
	global_load_dwordx4 v[84:87], v[84:85], off
	v_lshl_add_u64 v[28:29], v[70:71], 0, s[6:7]
	global_load_dwordx4 v[88:91], v[88:89], off
	v_pk_add_f32 v[72:73], v[30:31], v[72:73]
	global_load_dwordx4 v[92:95], v[92:93], off
	s_mov_b64 s[6:7], 0x2000000
	global_load_dwordx4 v[96:99], v[96:97], off
	v_pk_add_f32 v[78:79], v[24:25], v[78:79]
	global_load_dwordx4 v[100:103], v[100:101], off
	v_pk_add_f32 v[82:83], v[20:21], v[82:83]
	v_lshl_add_u64 v[20:21], v[28:29], 0, v[48:49]
	v_lshl_add_u64 v[24:25], v[28:29], 0, v[50:51]
	v_pk_add_f32 v[76:77], v[26:27], v[76:77]
	global_load_dwordx4 v[24:27], v[24:25], off
	v_pk_add_f32 v[80:81], v[22:23], v[80:81]
	global_load_dwordx4 v[20:23], v[20:21], off
	s_waitcnt vmcnt(0)
	v_pk_add_f32 v[86:87], v[16:17], v[86:87]
	v_lshl_add_u64 v[16:17], v[28:29], 0, v[46:47]
	v_pk_add_f32 v[90:91], v[12:13], v[90:91]
	v_lshl_add_u64 v[12:13], v[28:29], 0, v[44:45]
	v_pk_add_f32 v[94:95], v[8:9], v[94:95]
	v_lshl_add_u64 v[8:9], v[28:29], 0, v[42:43]
	v_pk_add_f32 v[98:99], v[4:5], v[98:99]
	v_lshl_add_u64 v[4:5], v[28:29], 0, v[40:41]
	v_pk_add_f32 v[84:85], v[18:19], v[84:85]
	v_pk_add_f32 v[88:89], v[14:15], v[88:89]
	v_pk_add_f32 v[92:93], v[10:11], v[92:93]
	v_pk_add_f32 v[96:97], v[6:7], v[96:97]
	global_load_dwordx4 v[4:7], v[4:5], off
	v_pk_add_f32 v[102:103], v[0:1], v[102:103]
	v_lshl_add_u64 v[0:1], v[28:29], 0, v[178:179]
	v_lshl_add_u64 v[28:29], v[28:29], 0, v[52:53]
	global_load_dwordx4 v[28:31], v[28:29], off
	v_pk_add_f32 v[100:101], v[2:3], v[100:101]
	global_load_dwordx4 v[0:3], v[0:1], off
	v_pk_add_f32 v[96:97], v[96:97], v[24:25]
	global_load_dwordx4 v[8:11], v[8:9], off
	v_pk_add_f32 v[92:93], v[92:93], v[20:21]
	global_load_dwordx4 v[12:15], v[12:13], off
	v_pk_add_f32 v[98:99], v[98:99], v[26:27]
	global_load_dwordx4 v[16:19], v[16:17], off
	v_pk_add_f32 v[94:95], v[94:95], v[22:23]
	s_waitcnt vmcnt(0)
	v_pk_add_f32 v[76:77], v[76:77], v[4:5]
	v_pk_add_f32 v[78:79], v[78:79], v[6:7]
	v_pk_add_f32 v[100:101], v[100:101], v[28:29]
	v_lshl_add_u64 v[28:29], v[70:71], 0, s[6:7]
	v_pk_add_f32 v[72:73], v[72:73], v[0:1]
	v_lshl_add_u64 v[0:1], v[28:29], 0, v[178:179]
	v_pk_add_f32 v[80:81], v[80:81], v[8:9]
	v_lshl_add_u64 v[4:5], v[28:29], 0, v[40:41]
	v_pk_add_f32 v[84:85], v[84:85], v[12:13]
	v_lshl_add_u64 v[8:9], v[28:29], 0, v[42:43]
	v_pk_add_f32 v[88:89], v[88:89], v[16:17]
	v_lshl_add_u64 v[12:13], v[28:29], 0, v[44:45]
	v_lshl_add_u64 v[16:17], v[28:29], 0, v[46:47]
	v_lshl_add_u64 v[20:21], v[28:29], 0, v[48:49]
	v_lshl_add_u64 v[24:25], v[28:29], 0, v[50:51]
	v_lshl_add_u64 v[28:29], v[28:29], 0, v[52:53]
	v_pk_add_f32 v[102:103], v[102:103], v[30:31]
	global_load_dwordx4 v[24:27], v[24:25], off
	v_pk_add_f32 v[74:75], v[74:75], v[2:3]
	global_load_dwordx4 v[28:31], v[28:29], off
	v_pk_add_f32 v[82:83], v[82:83], v[10:11]
	v_pk_add_f32 v[86:87], v[86:87], v[14:15]
	v_pk_add_f32 v[90:91], v[90:91], v[18:19]
	global_load_dwordx4 v[0:3], v[0:1], off
	s_mov_b64 s[6:7], 0x2800000
	global_load_dwordx4 v[4:7], v[4:5], off
	s_waitcnt vmcnt(0)
	v_pk_add_f32 v[96:97], v[96:97], v[24:25]
	global_load_dwordx4 v[8:11], v[8:9], off
	v_pk_add_f32 v[100:101], v[100:101], v[28:29]
	global_load_dwordx4 v[12:15], v[12:13], off
	v_lshl_add_u64 v[28:29], v[70:71], 0, s[6:7]
	global_load_dwordx4 v[16:19], v[16:17], off
	v_pk_add_f32 v[72:73], v[72:73], v[0:1]
	global_load_dwordx4 v[20:23], v[20:21], off
	v_pk_add_f32 v[76:77], v[76:77], v[4:5]
	v_lshl_add_u64 v[0:1], v[28:29], 0, v[178:179]
	v_lshl_add_u64 v[4:5], v[28:29], 0, v[40:41]
	v_lshl_add_u64 v[24:25], v[28:29], 0, v[50:51]
	v_pk_add_f32 v[102:103], v[102:103], v[30:31]
	v_pk_add_f32 v[74:75], v[74:75], v[2:3]
	global_load_dwordx4 v[0:3], v[0:1], off
	v_pk_add_f32 v[78:79], v[78:79], v[6:7]
	v_pk_add_f32 v[98:99], v[98:99], v[26:27]
	global_load_dwordx4 v[4:7], v[4:5], off
	s_mov_b64 s[6:7], 0x3000000
	global_load_dwordx4 v[24:27], v[24:25], off
	s_waitcnt vmcnt(0)
; __device__ __forceinline__ void norm_phase(float* __restrict__ X, bf16_t* __restrict__ H, const float* __restrict__ modl, int shiftIdx, int scaleIdx, int nrows, const float* __restrict__ PART, const float* __restrict__ XLAT) {
;     ...
;         if (PART != nullptr && row >= NLAT) {
; #pragma unroll
;             for (int s = 0; s < 8; ++s) { f32x4 pt[8];
; #pragma unroll
;                 for (int i = 0; i < 8; ++i) pt[i] = *(const f32x4*)(PART + ((size_t)s * NCTX + (row - NLAT)) * DM + (i * 64 + lane) * 4);
; #pragma unroll
;                 for (int i = 0; i < 8; ++i) x[i] += pt[i]; }
; #pragma unroll
;             for (int i = 0; i < 8; ++i) *(f32x4*)(xr + (i * 64 + lane) * 4) = x[i];
	v_pk_add_f32 v[80:81], v[80:81], v[8:9]
	v_lshl_add_u64 v[8:9], v[28:29], 0, v[42:43]
	v_pk_add_f32 v[84:85], v[84:85], v[12:13]
	v_lshl_add_u64 v[12:13], v[28:29], 0, v[44:45]
	v_pk_add_f32 v[88:89], v[88:89], v[16:17]
	v_lshl_add_u64 v[16:17], v[28:29], 0, v[46:47]
	v_pk_add_f32 v[92:93], v[92:93], v[20:21]
	v_lshl_add_u64 v[20:21], v[28:29], 0, v[48:49]
	v_lshl_add_u64 v[28:29], v[28:29], 0, v[52:53]
	global_load_dwordx4 v[28:31], v[28:29], off
	v_pk_add_f32 v[90:91], v[90:91], v[18:19]
	v_pk_add_f32 v[94:95], v[94:95], v[22:23]
	global_load_dwordx4 v[16:19], v[16:17], off
	v_pk_add_f32 v[82:83], v[82:83], v[10:11]
	global_load_dwordx4 v[20:23], v[20:21], off
	v_pk_add_f32 v[86:87], v[86:87], v[14:15]
	global_load_dwordx4 v[8:11], v[8:9], off
	v_pk_add_f32 v[72:73], v[72:73], v[0:1]
	global_load_dwordx4 v[12:15], v[12:13], off
	v_pk_add_f32 v[74:75], v[74:75], v[2:3]
	v_pk_add_f32 v[76:77], v[76:77], v[4:5]
	v_pk_add_f32 v[78:79], v[78:79], v[6:7]
	s_waitcnt vmcnt(0)
	v_pk_add_f32 v[124:125], v[100:101], v[28:29]
	v_lshl_add_u64 v[28:29], v[70:71], 0, s[6:7]
	v_lshl_add_u64 v[0:1], v[28:29], 0, v[178:179]
	global_load_dwordx4 v[0:3], v[0:1], off
	v_pk_add_f32 v[112:113], v[88:89], v[16:17]
	v_pk_add_f32 v[116:117], v[92:93], v[20:21]
	v_lshl_add_u64 v[20:21], v[28:29], 0, v[48:49]
	v_pk_add_f32 v[80:81], v[80:81], v[8:9]
	v_pk_add_f32 v[114:115], v[94:95], v[22:23]
	v_pk_add_f32 v[84:85], v[84:85], v[12:13]
	v_lshl_add_u64 v[4:5], v[28:29], 0, v[40:41]
	v_lshl_add_u64 v[8:9], v[28:29], 0, v[42:43]
	v_lshl_add_u64 v[12:13], v[28:29], 0, v[44:45]
	v_lshl_add_u64 v[16:17], v[28:29], 0, v[46:47]
	global_load_dwordx4 v[20:23], v[20:21], off
	v_pk_add_f32 v[120:121], v[96:97], v[24:25]
	v_lshl_add_u64 v[24:25], v[28:29], 0, v[50:51]
	v_lshl_add_u64 v[28:29], v[28:29], 0, v[52:53]
	v_pk_add_f32 v[118:119], v[98:99], v[26:27]
	v_pk_add_f32 v[122:123], v[102:103], v[30:31]
	global_load_dwordx4 v[24:27], v[24:25], off
	v_pk_add_f32 v[82:83], v[82:83], v[10:11]
	global_load_dwordx4 v[28:31], v[28:29], off
	v_pk_add_f32 v[86:87], v[86:87], v[14:15]
	global_load_dwordx4 v[4:7], v[4:5], off
	v_pk_add_f32 v[110:111], v[90:91], v[18:19]
	global_load_dwordx4 v[8:11], v[8:9], off
	s_mov_b64 s[6:7], 0x3800000
	global_load_dwordx4 v[12:15], v[12:13], off
	s_waitcnt vmcnt(0)
	v_pk_add_f32 v[102:103], v[72:73], v[0:1]
	global_load_dwordx4 v[16:19], v[16:17], off
	v_lshl_add_u64 v[0:1], v[70:71], 0, s[6:7]
	v_pk_add_f32 v[100:101], v[74:75], v[2:3]
	v_lshl_add_u64 v[2:3], v[0:1], 0, v[178:179]
	v_pk_add_f32 v[72:73], v[122:123], v[30:31]
	v_pk_add_f32 v[74:75], v[124:125], v[28:29]
	global_load_dwordx4 v[28:31], v[2:3], off
	v_lshl_add_u64 v[2:3], v[0:1], 0, v[40:41]
	v_pk_add_f32 v[96:97], v[78:79], v[6:7]
	v_pk_add_f32 v[98:99], v[76:77], v[4:5]
	v_pk_add_f32 v[76:77], v[118:119], v[26:27]
	v_pk_add_f32 v[78:79], v[120:121], v[24:25]
	global_load_dwordx4 v[24:27], v[2:3], off
	v_lshl_add_u64 v[2:3], v[0:1], 0, v[42:43]
	v_pk_add_f32 v[92:93], v[82:83], v[10:11]
	v_pk_add_f32 v[94:95], v[80:81], v[8:9]
	v_pk_add_f32 v[80:81], v[114:115], v[22:23]
	v_pk_add_f32 v[82:83], v[116:117], v[20:21]
	global_load_dwordx4 v[20:23], v[2:3], off
	v_lshl_add_u64 v[2:3], v[0:1], 0, v[44:45]
	v_pk_add_f32 v[88:89], v[86:87], v[14:15]
	v_pk_add_f32 v[90:91], v[84:85], v[12:13]
	s_waitcnt vmcnt(0)
	v_pk_add_f32 v[84:85], v[110:111], v[18:19]
	v_pk_add_f32 v[86:87], v[112:113], v[16:17]
	global_load_dwordx4 v[16:19], v[2:3], off
	v_lshl_add_u64 v[2:3], v[0:1], 0, v[46:47]
	global_load_dwordx4 v[12:15], v[2:3], off
	v_lshl_add_u64 v[2:3], v[0:1], 0, v[48:49]
	global_load_dwordx4 v[8:11], v[2:3], off
	v_lshl_add_u64 v[2:3], v[0:1], 0, v[50:51]
	v_lshl_add_u64 v[0:1], v[0:1], 0, v[52:53]
	global_load_dwordx4 v[4:7], v[2:3], off
	v_pk_add_f32 v[30:31], v[100:101], v[30:31]
	global_load_dwordx4 v[0:3], v[0:1], off
	v_pk_add_f32 v[28:29], v[102:103], v[28:29]
	v_pk_add_f32 v[26:27], v[96:97], v[26:27]
	v_pk_add_f32 v[24:25], v[98:99], v[24:25]
	v_pk_add_f32 v[22:23], v[92:93], v[22:23]
	v_pk_add_f32 v[20:21], v[94:95], v[20:21]
	s_waitcnt vmcnt(0)
	v_pk_add_f32 v[18:19], v[88:89], v[18:19]
	v_pk_add_f32 v[16:17], v[90:91], v[16:17]
	v_pk_add_f32 v[14:15], v[84:85], v[14:15]
	v_pk_add_f32 v[12:13], v[86:87], v[12:13]
	v_pk_add_f32 v[10:11], v[80:81], v[10:11]
	v_pk_add_f32 v[8:9], v[82:83], v[8:9]
	v_pk_add_f32 v[6:7], v[76:77], v[6:7]
	v_pk_add_f32 v[4:5], v[78:79], v[4:5]
	v_pk_add_f32 v[2:3], v[72:73], v[2:3]
	v_pk_add_f32 v[0:1], v[74:75], v[0:1]
	global_store_dwordx4 v[68:69], v[28:31], off sc0 sc1
	global_store_dwordx4 v[66:67], v[24:27], off sc0 sc1
	global_store_dwordx4 v[64:65], v[20:23], off sc0 sc1
	global_store_dwordx4 v[62:63], v[16:19], off sc0 sc1
	global_store_dwordx4 v[60:61], v[12:15], off sc0 sc1
	global_store_dwordx4 v[58:59], v[8:11], off sc0 sc1
	global_store_dwordx4 v[56:57], v[4:7], off sc0 sc1
	global_store_dwordx4 v[54:55], v[0:3], off sc0 sc1
	s_branch .LBB0_2654

; #define PG8_STAGE(bufoff, gbase, voff) do { _Pragma("unroll") for (int _i = 0; _i < 2; ++_i) \
;         __builtin_amdgcn_global_load_lds((const unsigned*)((const char*)(gbase) + (voff)[_i]), (LAS unsigned*)(lds + (bufoff) + ldsw + _i * 8192), 16, 0, 0); } while (0)
; #define PG8_LDA(dst, b, h) do { _Pragma("unroll") for (int m = 0; m < 4; ++m) _Pragma("unroll") for (int k = 0; k < 2; ++k) dst[m][k] = *(const LAS bf16x8*)(lds + PG8_SA(b, h) + aoff + m * 2048 + k * 1024); } while (0)
; #define PG8_LDB(dst, b, h) do { _Pragma("unroll") for (int n = 0; n < 2; ++n) _Pragma("unroll") for (int k = 0; k < 2; ++k) dst[n][k] = *(const LAS bf16x8*)(lds + PG8_SB(b, h) + boff + n * 2048 + k * 1024); } while (0)
; #define PG8_MMA(ai, bj, At, Bt) do { __builtin_amdgcn_s_setprio(1); _Pragma("unroll") for (int m = 0; m < 4; ++m) _Pragma("unroll") for (int n = 0; n < 2; ++n) _Pragma("unroll") for (int k = 0; k < 2; ++k) \
;         acc[ai][bj][m][n] = __builtin_amdgcn_mfma_f32_16x16x32_bf16(Bt[n][k], At[m][k], acc[ai][bj][m][n], 0, 0, 0); __builtin_amdgcn_s_setprio(0); } while (0)
; #define PG8_WAIT_L(n) asm volatile("s_waitcnt lgkmcnt(" #n ")" ::: "memory")
; #define PG8_BAR __builtin_amdgcn_s_barrier()
; #define PG8_SCHED __builtin_amdgcn_sched_barrier(0)
; template <class Epi>
; __device__ __forceinline__ void gemm_phase(LAS unsigned char* lds, const Gemm g, const StaticOrder S, const Epi E) {
;     ...
;             PG8_LDB(B0, 0, 0); PG8_SCHED; PG8_LDA(At, 0, 0); PG8_STAGE(PG8_SA(1, 1), a1 + hstep, voffA);
;             PG8_WAIT_L(8); PG8_BAR; PG8_WAIT_L(0); PG8_MMA(0, 0, At, B0); PG8_BAR; PG8_SCHED;
;             PG8_LDB(B1, 0, 1); PG8_STAGE(PG8_SB(0, 0), b2, voffA);
;             PG8_BAR; PG8_WAIT_L(0); PG8_MMA(0, 1, At, B1); PG8_BAR;
;             PG8_LDA(At, 0, 1); PG8_STAGE(PG8_SA(0, 0), a2, voffA);
;             PG8_BAR; PG8_WAIT_L(0); PG8_MMA(1, 0, At, B0); PG8_BAR; PG8_SCHED;
.LBB0_2721:
	s_add_u32 s48, s42, 0x100
	s_addc_u32 s49, s43, 0
	s_add_i32 s30, 0, 0x10000
	v_add_u32_e32 v132, s30, v151
	ds_read_b128 v[128:131], v132
	ds_read_b128 v[142:145], v132 offset:1024
	ds_read_b128 v[146:149], v132 offset:2048
	ds_read_b128 v[158:161], v132 offset:3072
	s_cmp_eq_u32 s57, 28
	s_cselect_b32 s53, s45, s49
	s_cselect_b32 s52, s44, s48
	s_cselect_b32 s51, s47, s11
	s_cselect_b32 s50, s46, s3
	v_lshl_add_u64 v[132:133], s[42:43], 0, v[138:139]
	s_add_i32 m0, s23, 0xc000
	ds_read_b128 v[162:165], v156
	ds_read_b128 v[166:169], v156 offset:1024
	ds_read_b128 v[170:173], v156 offset:2048
	ds_read_b128 v[194:197], v156 offset:3072
	ds_read_b128 v[198:201], v156 offset:4096
	ds_read_b128 v[202:205], v156 offset:5120
	ds_read_b128 v[206:209], v156 offset:6144
	ds_read_b128 v[228:231], v156 offset:7168
	global_load_lds_dwordx4 v[132:133], off
	v_lshl_add_u64 v[132:133], s[42:43], 0, v[140:141]
	s_add_i32 m0, s23, 0xe000
	s_nop 0
	global_load_lds_dwordx4 v[132:133], off
	s_waitcnt lgkmcnt(8)
	s_barrier
	s_waitcnt lgkmcnt(0)
	s_setprio 1
	s_waitcnt lgkmcnt(0)
	v_mfma_f32_16x16x32_bf16 v[124:127], v[128:131], v[162:165], v[124:127]
	v_mfma_f32_16x16x32_bf16 v[120:123], v[146:149], v[162:165], v[120:123]
	v_mfma_f32_16x16x32_bf16 v[108:111], v[128:131], v[170:173], v[108:111]
	v_mfma_f32_16x16x32_bf16 v[104:107], v[146:149], v[170:173], v[104:107]
	v_mfma_f32_16x16x32_bf16 v[92:95], v[128:131], v[198:201], v[92:95]
	v_mfma_f32_16x16x32_bf16 v[88:91], v[146:149], v[198:201], v[88:91]
	v_mfma_f32_16x16x32_bf16 v[76:79], v[128:131], v[206:209], v[76:79]
	v_mfma_f32_16x16x32_bf16 v[72:75], v[146:149], v[206:209], v[72:75]
	v_mfma_f32_16x16x32_bf16 v[124:127], v[142:145], v[166:169], v[124:127]
	v_mfma_f32_16x16x32_bf16 v[120:123], v[158:161], v[166:169], v[120:123]
	v_mfma_f32_16x16x32_bf16 v[108:111], v[142:145], v[194:197], v[108:111]
	v_mfma_f32_16x16x32_bf16 v[104:107], v[158:161], v[194:197], v[104:107]
	v_mfma_f32_16x16x32_bf16 v[92:95], v[142:145], v[202:205], v[92:95]
	v_mfma_f32_16x16x32_bf16 v[88:91], v[158:161], v[202:205], v[88:91]
	v_mfma_f32_16x16x32_bf16 v[76:79], v[142:145], v[228:231], v[76:79]
	v_mfma_f32_16x16x32_bf16 v[72:75], v[158:161], v[228:231], v[72:75]
	s_setprio 0
	s_barrier
	s_add_i32 s42, 0, 0x14000
	v_add_u32_e32 v132, s42, v151
	s_add_i32 s30, s30, s22
	ds_read_b128 v[232:235], v132
	ds_read_b128 v[236:239], v132 offset:1024
	ds_read_b128 v[240:243], v132 offset:2048
	ds_read_b128 v[244:247], v132 offset:3072
	v_lshl_add_u64 v[132:133], s[50:51], 0, v[178:179]
	s_mov_b32 m0, s30
	v_lshl_add_u64 v[174:175], s[50:51], 0, v[134:135]
	global_load_lds_dwordx4 v[132:133], off
	s_add_i32 m0, s30, 0x2000
	s_nop 0
	global_load_lds_dwordx4 v[174:175], off
	s_barrier
	s_waitcnt lgkmcnt(0)
	s_setprio 1
	s_waitcnt lgkmcnt(0)
	v_mfma_f32_16x16x32_bf16 v[116:119], v[232:235], v[162:165], v[116:119]
	v_mfma_f32_16x16x32_bf16 v[112:115], v[240:243], v[162:165], v[112:115]
	v_mfma_f32_16x16x32_bf16 v[100:103], v[232:235], v[170:173], v[100:103]
	v_mfma_f32_16x16x32_bf16 v[96:99], v[240:243], v[170:173], v[96:99]
	v_mfma_f32_16x16x32_bf16 v[84:87], v[232:235], v[198:201], v[84:87]
	v_mfma_f32_16x16x32_bf16 v[80:83], v[240:243], v[198:201], v[80:83]
	v_mfma_f32_16x16x32_bf16 v[68:71], v[232:235], v[206:209], v[68:71]
	v_mfma_f32_16x16x32_bf16 v[64:67], v[240:243], v[206:209], v[64:67]
	v_mfma_f32_16x16x32_bf16 v[116:119], v[236:239], v[166:169], v[116:119]
	v_mfma_f32_16x16x32_bf16 v[112:115], v[244:247], v[166:169], v[112:115]
	v_mfma_f32_16x16x32_bf16 v[100:103], v[236:239], v[194:197], v[100:103]
	v_mfma_f32_16x16x32_bf16 v[96:99], v[244:247], v[194:197], v[96:99]
	v_mfma_f32_16x16x32_bf16 v[84:87], v[236:239], v[202:205], v[84:87]
	v_mfma_f32_16x16x32_bf16 v[80:83], v[244:247], v[202:205], v[80:83]
	v_mfma_f32_16x16x32_bf16 v[68:71], v[236:239], v[228:231], v[68:71]
	v_mfma_f32_16x16x32_bf16 v[64:67], v[244:247], v[228:231], v[64:67]
	s_setprio 0
	s_barrier
	s_mov_b32 m0, s23
	v_lshl_add_u64 v[210:211], s[52:53], 0, v[178:179]
	ds_read_b128 v[162:165], v156 offset:16384
	ds_read_b128 v[166:169], v156 offset:17408
	ds_read_b128 v[170:173], v156 offset:18432
	ds_read_b128 v[194:197], v156 offset:19456
	ds_read_b128 v[198:201], v156 offset:20480
	ds_read_b128 v[202:205], v156 offset:21504
	ds_read_b128 v[206:209], v156 offset:22528
	ds_read_b128 v[228:231], v156 offset:23552
	global_load_lds_dwordx4 v[210:211], off
	v_lshl_add_u64 v[220:221], s[52:53], 0, v[134:135]
	s_mov_b32 m0, s24
	s_nop 0
	global_load_lds_dwordx4 v[220:221], off
	s_barrier
	s_waitcnt lgkmcnt(0)
	s_setprio 1
	s_waitcnt lgkmcnt(0)
	v_mfma_f32_16x16x32_bf16 v[60:63], v[128:131], v[162:165], v[60:63]
	v_mfma_f32_16x16x32_bf16 v[56:59], v[146:149], v[162:165], v[56:59]
	v_mfma_f32_16x16x32_bf16 v[44:47], v[128:131], v[170:173], v[44:47]
	v_mfma_f32_16x16x32_bf16 v[40:43], v[146:149], v[170:173], v[40:43]
	v_mfma_f32_16x16x32_bf16 v[28:31], v[128:131], v[198:201], v[28:31]
	v_mfma_f32_16x16x32_bf16 v[24:27], v[146:149], v[198:201], v[24:27]
	v_mfma_f32_16x16x32_bf16 v[12:15], v[128:131], v[206:209], v[12:15]
	v_mfma_f32_16x16x32_bf16 v[8:11], v[146:149], v[206:209], v[8:11]
	v_mfma_f32_16x16x32_bf16 v[60:63], v[142:145], v[166:169], v[60:63]
	v_mfma_f32_16x16x32_bf16 v[56:59], v[158:161], v[166:169], v[56:59]
	v_mfma_f32_16x16x32_bf16 v[44:47], v[142:145], v[194:197], v[44:47]
	v_mfma_f32_16x16x32_bf16 v[40:43], v[158:161], v[194:197], v[40:43]
	v_mfma_f32_16x16x32_bf16 v[28:31], v[142:145], v[202:205], v[28:31]
	v_mfma_f32_16x16x32_bf16 v[24:27], v[158:161], v[202:205], v[24:27]
	v_mfma_f32_16x16x32_bf16 v[12:15], v[142:145], v[228:231], v[12:15]
	v_mfma_f32_16x16x32_bf16 v[8:11], v[158:161], v[228:231], v[8:11]
	s_setprio 0
	s_barrier
; #define PG8_STAGE(bufoff, gbase, voff) do { _Pragma("unroll") for (int _i = 0; _i < 2; ++_i) \
;         __builtin_amdgcn_global_load_lds((const unsigned*)((const char*)(gbase) + (voff)[_i]), (LAS unsigned*)(lds + (bufoff) + ldsw + _i * 8192), 16, 0, 0); } while (0)
; #define PG8_LDA(dst, b, h) do { _Pragma("unroll") for (int m = 0; m < 4; ++m) _Pragma("unroll") for (int k = 0; k < 2; ++k) dst[m][k] = *(const LAS bf16x8*)(lds + PG8_SA(b, h) + aoff + m * 2048 + k * 1024); } while (0)
; #define PG8_LDB(dst, b, h) do { _Pragma("unroll") for (int n = 0; n < 2; ++n) _Pragma("unroll") for (int k = 0; k < 2; ++k) dst[n][k] = *(const LAS bf16x8*)(lds + PG8_SB(b, h) + boff + n * 2048 + k * 1024); } while (0)
; #define PG8_MMA(ai, bj, At, Bt) do { __builtin_amdgcn_s_setprio(1); _Pragma("unroll") for (int m = 0; m < 4; ++m) _Pragma("unroll") for (int n = 0; n < 2; ++n) _Pragma("unroll") for (int k = 0; k < 2; ++k) \
;         acc[ai][bj][m][n] = __builtin_amdgcn_mfma_f32_16x16x32_bf16(Bt[n][k], At[m][k], acc[ai][bj][m][n], 0, 0, 0); __builtin_amdgcn_s_setprio(0); } while (0)
; #define PG8_WAIT_V(n) asm volatile("s_waitcnt vmcnt(" #n ")" ::: "memory")
; #define PG8_WAIT_L(n) asm volatile("s_waitcnt lgkmcnt(" #n ")" ::: "memory")
; #define PG8_BAR __builtin_amdgcn_s_barrier()
; #define PG8_SCHED __builtin_amdgcn_sched_barrier(0)
; template <class Epi>
; __device__ __forceinline__ void gemm_phase(LAS unsigned char* lds, const Gemm g, const StaticOrder S, const Epi E) {
;     ...
;             PG8_STAGE(PG8_SB(0, 1), b2 + hstep, voffA);
;             PG8_WAIT_V(6); PG8_BAR; PG8_MMA(1, 1, At, B1); PG8_BAR;
;             PG8_LDB(B0, 1, 0); PG8_SCHED; PG8_LDA(At, 1, 0); PG8_STAGE(PG8_SA(0, 1), a2 + hstep, voffA);
;             PG8_WAIT_L(8); PG8_BAR; PG8_WAIT_L(0); PG8_MMA(0, 0, At, B0); PG8_BAR; PG8_SCHED;
;             PG8_LDB(B1, 1, 1); PG8_STAGE(PG8_SB(1, 0), b3, voffA);
;             PG8_BAR; PG8_WAIT_L(0); PG8_MMA(0, 1, At, B1); PG8_BAR;
	s_add_u32 s30, s50, 0x80000
	s_addc_u32 s31, s51, 0
	s_add_i32 s42, s42, s22
	v_lshl_add_u64 v[128:129], s[30:31], 0, v[178:179]
	s_mov_b32 m0, s42
	s_nop 0
	global_load_lds_dwordx4 v[128:129], off
	v_lshl_add_u64 v[128:129], s[30:31], 0, v[134:135]
	s_add_i32 m0, s42, 0x2000
	s_nop 0
	global_load_lds_dwordx4 v[128:129], off
	s_waitcnt vmcnt(6)
	s_barrier
	s_setprio 1
	v_mfma_f32_16x16x32_bf16 v[52:55], v[232:235], v[162:165], v[52:55]
	v_mfma_f32_16x16x32_bf16 v[48:51], v[240:243], v[162:165], v[48:51]
	v_mfma_f32_16x16x32_bf16 v[36:39], v[232:235], v[170:173], v[36:39]
	v_mfma_f32_16x16x32_bf16 v[32:35], v[240:243], v[170:173], v[32:35]
	v_mfma_f32_16x16x32_bf16 v[20:23], v[232:235], v[198:201], v[20:23]
	v_mfma_f32_16x16x32_bf16 v[16:19], v[240:243], v[198:201], v[16:19]
	v_mfma_f32_16x16x32_bf16 v[4:7], v[232:235], v[206:209], v[4:7]
	v_mfma_f32_16x16x32_bf16 v[0:3], v[240:243], v[206:209], v[0:3]
	v_mfma_f32_16x16x32_bf16 v[52:55], v[236:239], v[166:169], v[52:55]
	v_mfma_f32_16x16x32_bf16 v[48:51], v[244:247], v[166:169], v[48:51]
	v_mfma_f32_16x16x32_bf16 v[36:39], v[236:239], v[194:197], v[36:39]
	v_mfma_f32_16x16x32_bf16 v[32:35], v[244:247], v[194:197], v[32:35]
	v_mfma_f32_16x16x32_bf16 v[20:23], v[236:239], v[202:205], v[20:23]
	v_mfma_f32_16x16x32_bf16 v[16:19], v[244:247], v[202:205], v[16:19]
	v_mfma_f32_16x16x32_bf16 v[4:7], v[236:239], v[228:231], v[4:7]
	v_mfma_f32_16x16x32_bf16 v[0:3], v[244:247], v[228:231], v[0:3]
	s_setprio 0
	s_barrier
	s_add_i32 s42, 0, 0x18000
	v_add_u32_e32 v157, s42, v151
	ds_read_b128 v[128:131], v157
	ds_read_b128 v[142:145], v157 offset:1024
	ds_read_b128 v[146:149], v157 offset:2048
	ds_read_b128 v[158:161], v157 offset:3072
	s_add_u32 s30, s52, 0x80000
	s_addc_u32 s31, s53, 0
	s_mov_b32 m0, s25
	v_lshl_add_u64 v[222:223], s[30:31], 0, v[178:179]
	ds_read_b128 v[162:165], v156 offset:32768
	ds_read_b128 v[166:169], v156 offset:33792
	ds_read_b128 v[170:173], v156 offset:34816
	ds_read_b128 v[194:197], v156 offset:35840
	ds_read_b128 v[198:201], v156 offset:36864
	ds_read_b128 v[202:205], v156 offset:37888
	ds_read_b128 v[206:209], v156 offset:38912
	ds_read_b128 v[228:231], v156 offset:39936
	global_load_lds_dwordx4 v[222:223], off
	v_lshl_add_u64 v[222:223], s[30:31], 0, v[134:135]
	s_mov_b32 m0, s26
	s_nop 0
	global_load_lds_dwordx4 v[222:223], off
	s_waitcnt lgkmcnt(8)
	s_barrier
	s_waitcnt lgkmcnt(0)
	s_setprio 1
	s_waitcnt lgkmcnt(0)
	v_mfma_f32_16x16x32_bf16 v[124:127], v[128:131], v[162:165], v[124:127]
	v_mfma_f32_16x16x32_bf16 v[120:123], v[146:149], v[162:165], v[120:123]
	v_mfma_f32_16x16x32_bf16 v[108:111], v[128:131], v[170:173], v[108:111]
	v_mfma_f32_16x16x32_bf16 v[104:107], v[146:149], v[170:173], v[104:107]
	v_mfma_f32_16x16x32_bf16 v[92:95], v[128:131], v[198:201], v[92:95]
	v_mfma_f32_16x16x32_bf16 v[88:91], v[146:149], v[198:201], v[88:91]
	v_mfma_f32_16x16x32_bf16 v[76:79], v[128:131], v[206:209], v[76:79]
	v_mfma_f32_16x16x32_bf16 v[72:75], v[146:149], v[206:209], v[72:75]
	v_mfma_f32_16x16x32_bf16 v[124:127], v[142:145], v[166:169], v[124:127]
	v_mfma_f32_16x16x32_bf16 v[120:123], v[158:161], v[166:169], v[120:123]
	v_mfma_f32_16x16x32_bf16 v[108:111], v[142:145], v[194:197], v[108:111]
	v_mfma_f32_16x16x32_bf16 v[104:107], v[158:161], v[194:197], v[104:107]
	v_mfma_f32_16x16x32_bf16 v[92:95], v[142:145], v[202:205], v[92:95]
	v_mfma_f32_16x16x32_bf16 v[88:91], v[158:161], v[202:205], v[88:91]
	v_mfma_f32_16x16x32_bf16 v[76:79], v[142:145], v[228:231], v[76:79]
	v_mfma_f32_16x16x32_bf16 v[72:75], v[158:161], v[228:231], v[72:75]
	s_setprio 0
	s_barrier
	s_add_i32 s43, 0, 0x1c000
	s_add_i32 s30, s42, s22
	v_add_u32_e32 v157, s43, v151
	v_lshl_add_u64 v[132:133], v[132:133], 0, s[34:35]
	s_mov_b32 m0, s30
	ds_read_b128 v[232:235], v157
	ds_read_b128 v[236:239], v157 offset:1024
	ds_read_b128 v[240:243], v157 offset:2048
	ds_read_b128 v[244:247], v157 offset:3072
	global_load_lds_dwordx4 v[132:133], off
	v_lshl_add_u64 v[132:133], v[174:175], 0, s[34:35]
	s_add_i32 m0, s30, 0x2000
	s_nop 0
	global_load_lds_dwordx4 v[132:133], off
	s_barrier
	s_waitcnt lgkmcnt(0)
	s_setprio 1
	s_waitcnt lgkmcnt(0)
	v_mfma_f32_16x16x32_bf16 v[116:119], v[232:235], v[162:165], v[116:119]
	v_mfma_f32_16x16x32_bf16 v[112:115], v[240:243], v[162:165], v[112:115]
	v_mfma_f32_16x16x32_bf16 v[100:103], v[232:235], v[170:173], v[100:103]
	v_mfma_f32_16x16x32_bf16 v[96:99], v[240:243], v[170:173], v[96:99]
	v_mfma_f32_16x16x32_bf16 v[84:87], v[232:235], v[198:201], v[84:87]
	v_mfma_f32_16x16x32_bf16 v[80:83], v[240:243], v[198:201], v[80:83]
	v_mfma_f32_16x16x32_bf16 v[68:71], v[232:235], v[206:209], v[68:71]
	v_mfma_f32_16x16x32_bf16 v[64:67], v[240:243], v[206:209], v[64:67]
	v_mfma_f32_16x16x32_bf16 v[116:119], v[236:239], v[166:169], v[116:119]
	v_mfma_f32_16x16x32_bf16 v[112:115], v[244:247], v[166:169], v[112:115]
	v_mfma_f32_16x16x32_bf16 v[100:103], v[236:239], v[194:197], v[100:103]
	v_mfma_f32_16x16x32_bf16 v[96:99], v[244:247], v[194:197], v[96:99]
	v_mfma_f32_16x16x32_bf16 v[84:87], v[236:239], v[202:205], v[84:87]
	v_mfma_f32_16x16x32_bf16 v[80:83], v[244:247], v[202:205], v[80:83]
	v_mfma_f32_16x16x32_bf16 v[68:71], v[236:239], v[228:231], v[68:71]
	v_mfma_f32_16x16x32_bf16 v[64:67], v[244:247], v[228:231], v[64:67]
	s_setprio 0
	s_barrier
; #define PG8_STAGE(bufoff, gbase, voff) do { _Pragma("unroll") for (int _i = 0; _i < 2; ++_i) \
;         __builtin_amdgcn_global_load_lds((const unsigned*)((const char*)(gbase) + (voff)[_i]), (LAS unsigned*)(lds + (bufoff) + ldsw + _i * 8192), 16, 0, 0); } while (0)
; #define PG8_LDA(dst, b, h) do { _Pragma("unroll") for (int m = 0; m < 4; ++m) _Pragma("unroll") for (int k = 0; k < 2; ++k) dst[m][k] = *(const LAS bf16x8*)(lds + PG8_SA(b, h) + aoff + m * 2048 + k * 1024); } while (0)
; #define PG8_MMA(ai, bj, At, Bt) do { __builtin_amdgcn_s_setprio(1); _Pragma("unroll") for (int m = 0; m < 4; ++m) _Pragma("unroll") for (int n = 0; n < 2; ++n) _Pragma("unroll") for (int k = 0; k < 2; ++k) \
;         acc[ai][bj][m][n] = __builtin_amdgcn_mfma_f32_16x16x32_bf16(Bt[n][k], At[m][k], acc[ai][bj][m][n], 0, 0, 0); __builtin_amdgcn_s_setprio(0); } while (0)
; #define PG8_WAIT_V(n) asm volatile("s_waitcnt vmcnt(" #n ")" ::: "memory")
; #define PG8_WAIT_L(n) asm volatile("s_waitcnt lgkmcnt(" #n ")" ::: "memory")
; #define PG8_BAR __builtin_amdgcn_s_barrier()
; #define PG8_SCHED __builtin_amdgcn_sched_barrier(0)
; template <class Epi>
; __device__ __forceinline__ void gemm_phase(LAS unsigned char* lds, const Gemm g, const StaticOrder S, const Epi E) {
;     ...
;             PG8_LDA(At, 1, 1); PG8_STAGE(PG8_SA(1, 0), a3, voffA);
;             PG8_BAR; PG8_WAIT_L(0); PG8_MMA(1, 0, At, B0); PG8_BAR; PG8_SCHED;
;             PG8_STAGE(PG8_SB(1, 1), b3 + hstep, voffA);
;             PG8_WAIT_V(6); PG8_BAR; PG8_MMA(1, 1, At, B1); PG8_BAR;
;     __device__ __forceinline__ void operator()(AccRef acc, const pg8::Unit& u, int wr, int wc, int fr, int fq) const {
;     ...
;         const bool rope = (u.pn == rope_pn) && (u.pm < 32);
; #pragma unroll
;         for (int ai = 0; ai < 2; ++ai)
; #pragma unroll
;             for (int m = 0; m < 4; ++m) { const int row = row0 + ai * 128 + m * 16; bf16_t* rowp = O + (size_t)row * ldc + col0;
;                 f32x4 cs = {1.f, 1.f, 1.f, 1.f}, sn = {0.f, 0.f, 0.f, 0.f};
;                 if (rope) { const int t = row & 2047; const int pos = (wc & 1) ? (t & 63) : (t >> 6); cs = *(const f32x4*)(cos64 + pos * 16 + 4 * fq); sn = *(const f32x4*)(sin64 + pos * 16 + 4 * fq); }
	s_mov_b32 m0, s28
	v_lshl_add_u64 v[132:133], v[210:211], 0, s[34:35]
	ds_read_b128 v[162:165], v156 offset:49152
	ds_read_b128 v[166:169], v156 offset:50176
	ds_read_b128 v[170:173], v156 offset:51200
	ds_read_b128 v[194:197], v156 offset:52224
	ds_read_b128 v[198:201], v156 offset:53248
	ds_read_b128 v[202:205], v156 offset:54272
	ds_read_b128 v[206:209], v156 offset:55296
	ds_read_b128 v[228:231], v156 offset:56320
	global_load_lds_dwordx4 v[132:133], off
	v_lshl_add_u64 v[132:133], v[220:221], 0, s[34:35]
	s_mov_b32 m0, s29
	s_nop 0
	global_load_lds_dwordx4 v[132:133], off
	s_barrier
	s_waitcnt lgkmcnt(0)
	s_setprio 1
	s_waitcnt lgkmcnt(0)
	v_mfma_f32_16x16x32_bf16 v[60:63], v[128:131], v[162:165], v[60:63]
	v_mfma_f32_16x16x32_bf16 v[56:59], v[146:149], v[162:165], v[56:59]
	v_mfma_f32_16x16x32_bf16 v[44:47], v[128:131], v[170:173], v[44:47]
	v_mfma_f32_16x16x32_bf16 v[40:43], v[146:149], v[170:173], v[40:43]
	v_mfma_f32_16x16x32_bf16 v[28:31], v[128:131], v[198:201], v[28:31]
	v_mfma_f32_16x16x32_bf16 v[24:27], v[146:149], v[198:201], v[24:27]
	v_mfma_f32_16x16x32_bf16 v[12:15], v[128:131], v[206:209], v[12:15]
	v_mfma_f32_16x16x32_bf16 v[8:11], v[146:149], v[206:209], v[8:11]
	v_mfma_f32_16x16x32_bf16 v[60:63], v[142:145], v[166:169], v[60:63]
	v_mfma_f32_16x16x32_bf16 v[56:59], v[158:161], v[166:169], v[56:59]
	v_mfma_f32_16x16x32_bf16 v[44:47], v[142:145], v[194:197], v[44:47]
	v_mfma_f32_16x16x32_bf16 v[40:43], v[158:161], v[194:197], v[40:43]
	v_mfma_f32_16x16x32_bf16 v[28:31], v[142:145], v[202:205], v[28:31]
	v_mfma_f32_16x16x32_bf16 v[24:27], v[158:161], v[202:205], v[24:27]
	v_mfma_f32_16x16x32_bf16 v[12:15], v[142:145], v[228:231], v[12:15]
	v_mfma_f32_16x16x32_bf16 v[8:11], v[158:161], v[228:231], v[8:11]
	s_setprio 0
	s_barrier
	s_add_u32 s30, s50, 0x80080
	s_addc_u32 s31, s51, 0
	s_add_i32 s42, s43, s22
	v_lshl_add_u64 v[128:129], s[30:31], 0, v[178:179]
	s_mov_b32 m0, s42
	s_nop 0
	global_load_lds_dwordx4 v[128:129], off
	v_lshl_add_u64 v[128:129], s[30:31], 0, v[134:135]
	s_add_i32 m0, s42, 0x2000
	s_nop 0
	global_load_lds_dwordx4 v[128:129], off
	s_waitcnt vmcnt(6)
	s_barrier
	s_setprio 1
	v_mfma_f32_16x16x32_bf16 v[52:55], v[232:235], v[162:165], v[52:55]
	v_mfma_f32_16x16x32_bf16 v[48:51], v[240:243], v[162:165], v[48:51]
	v_mfma_f32_16x16x32_bf16 v[36:39], v[232:235], v[170:173], v[36:39]
	v_mfma_f32_16x16x32_bf16 v[32:35], v[240:243], v[170:173], v[32:35]
	v_mfma_f32_16x16x32_bf16 v[20:23], v[232:235], v[198:201], v[20:23]
	v_mfma_f32_16x16x32_bf16 v[16:19], v[240:243], v[198:201], v[16:19]
	v_mfma_f32_16x16x32_bf16 v[4:7], v[232:235], v[206:209], v[4:7]
	v_mfma_f32_16x16x32_bf16 v[0:3], v[240:243], v[206:209], v[0:3]
	v_mfma_f32_16x16x32_bf16 v[52:55], v[236:239], v[166:169], v[52:55]
	v_mfma_f32_16x16x32_bf16 v[48:51], v[244:247], v[166:169], v[48:51]
	v_mfma_f32_16x16x32_bf16 v[36:39], v[236:239], v[194:197], v[36:39]
	v_mfma_f32_16x16x32_bf16 v[32:35], v[244:247], v[194:197], v[32:35]
	v_mfma_f32_16x16x32_bf16 v[20:23], v[236:239], v[202:205], v[20:23]
	v_mfma_f32_16x16x32_bf16 v[16:19], v[244:247], v[202:205], v[16:19]
	v_mfma_f32_16x16x32_bf16 v[4:7], v[236:239], v[228:231], v[4:7]
	v_mfma_f32_16x16x32_bf16 v[0:3], v[244:247], v[228:231], v[0:3]
	s_setprio 0
	s_barrier
	s_add_i32 s57, s57, 2
	s_add_u32 s3, s3, 0x100
	s_addc_u32 s11, s11, 0
	s_cmp_gt_u32 s57, 29
	s_mov_b64 s[42:43], s[48:49]
	s_cbranch_scc0 .LBB0_2721
	s_lshl_b32 s11, s56, 8
	s_add_i32 s11, s11, s27
	s_cmp_eq_u32 s55, -1
	s_cselect_b64 s[30:31], -1, 0
	s_cmp_lt_i32 s56, 32
	s_cselect_b64 s[42:43], -1, 0
	s_and_b64 s[30:31], s[30:31], s[42:43]
	v_cndmask_b32_e64 v129, 0, 1, s[30:31]
	s_bfe_u32 s3, s11, 0x50006
	v_mov_b32_e32 v144, 1.0
	v_mov_b32_e32 v128, 0
	v_cmp_ne_u32_e64 s[42:43], 1, v129
	s_andn2_b64 vcc, exec, s[30:31]
	v_mov_b32_e32 v130, 0
	v_mov_b32_e32 v131, 0
	v_mov_b32_e32 v132, 0
	v_mov_b32_e32 v133, 0
	v_mov_b32_e32 v146, 1.0
	v_mov_b32_e32 v147, 1.0
	v_mov_b32_e32 v148, 1.0
	v_mov_b32_e32 v149, 1.0
	s_cbranch_vccnz .LBB0_2724
	v_mov_b32_e32 v129, s3
	v_cndmask_b32_e64 v129, v150, v129, s[38:39]
	v_lshl_or_b32 v130, v129, 6, v136
	v_mov_b32_e32 v131, v137
	flat_load_dwordx4 v[130:133], v[130:131]
	s_waitcnt vmcnt(0) lgkmcnt(0)
	v_mov_b32_e32 v146, v130
	v_mov_b32_e32 v147, v131
	v_mov_b32_e32 v148, v132
	v_mov_b32_e32 v149, v133

; __device__ __forceinline__ bf16_t f2bf(float x) { return (bf16_t)(cvt_pk_bf16(x, 0.f) & 0xffffu); }
; __device__ __forceinline__ int otid() { int t = threadIdx.x; asm volatile("" : "+v"(t)); return t; }
; __device__ __forceinline__ void titem_store(const TItem& it, int tid, const f32x4 (&v)[4], bf16_t* T) {
; #pragma unroll
;     for (int i = 0; i < 4; ++i) { const int idx = tid + 512 * i, kk = idx >> 4, r4 = idx & 15;
; #pragma unroll
;         for (int j = 0; j < 4; ++j) T[(4 * r4 + j) * 136 + kk] = f2bf(v[i][j]); }
;     __syncthreads();
; #pragma unroll
;     for (int i = 0; i < 2; ++i) { const int c = tid + 512 * i, row = c >> 4, k8 = (c & 15) * 8;
;         const u32x4 w = *(const u32x4*)(T + row * 136 + k8);
;         *(u32x4*)(it.dst + (size_t)(it.r0 + row) * it.K + it.k0 + k8) = w; }
; }
; __device__ __forceinline__ int tset_item(int l, int which, int i) {
;     if (which == 0) return l * TT_LAYER + 2 * TT_FIN + 2 * TT_FOUT + i;
;     const int bin = (which == 1) ? 0 : TT_FIN, bout = 2 * TT_FIN + ((which == 1) ? 0 : TT_FOUT);
;     return l * TT_LAYER + (i < TT_FIN ? bin + i : bout + i - TT_FIN);
; }
;     const int nall = (which == 0) ? TT_WIN + TT_WOUT + TT_UQ + TT_UKV : TT_FIN + TT_FOUT;
;     const int n = (nall * hi4) / 4, start = (nall * lo4) / 4 + start0;
;     const int tid = otid();
;     if (start >= n) return;
;     TItem c0 = titem_decode(p, tset_item(l, which, start)), c1 = c0;
;     f32x4 v0[4], v1[4], v2[4];
;     titem_load(c0, tid, v0);
;     if (start + stride < n) { c1 = titem_decode(p, tset_item(l, which, start + stride)); titem_load(c1, tid, v1); }
;     int buf = 0;
;     for (int i = start; i < n; i += stride) {
;         TItem c2 = c1;
;         if (i + 2 * stride < n) { c2 = titem_decode(p, tset_item(l, which, i + 2 * stride)); titem_load(c2, tid, v2); }
;         titem_store(c0, tid, v0, (bf16_t*)(lds + buf * 17408));
;         buf ^= 1; c0 = c1; c1 = c2;
; #pragma unroll
;         for (int q = 0; q < 4; ++q) { v0[q] = v1[q]; v1[q] = v2[q]; }
;     }
.LBB0_2927:
	s_mul_i32 s11, s24, 0x4400
	s_add_i32 s11, s11, 0
	v_add_u32_e32 v32, s11, v43
	v_cvt_pk_bf16_f32 v0, v0, v179
	v_lshl_add_u32 v33, v35, 1, v32
	ds_write_b16 v33, v0
	v_cvt_pk_bf16_f32 v0, v1, v179
	ds_write_b16 v33, v0 offset:272
	v_cvt_pk_bf16_f32 v0, v2, v179
	ds_write_b16 v33, v0 offset:544
	v_cvt_pk_bf16_f32 v0, v3, v179
	ds_write_b16 v33, v0 offset:816
	v_cvt_pk_bf16_f32 v0, v4, v179
	v_lshl_add_u32 v1, v36, 1, v32
	ds_write_b16 v1, v0
	v_cvt_pk_bf16_f32 v0, v5, v179
	ds_write_b16 v1, v0 offset:272
	v_cvt_pk_bf16_f32 v0, v6, v179
	ds_write_b16 v1, v0 offset:544
	v_cvt_pk_bf16_f32 v0, v7, v179
	ds_write_b16 v1, v0 offset:816
	v_cvt_pk_bf16_f32 v0, v8, v179
	v_lshl_add_u32 v1, v37, 1, v32
	ds_write_b16 v1, v0
	v_cvt_pk_bf16_f32 v0, v9, v179
	ds_write_b16 v1, v0 offset:272
	v_cvt_pk_bf16_f32 v0, v10, v179
	ds_write_b16 v1, v0 offset:544
	v_cvt_pk_bf16_f32 v0, v11, v179
	ds_write_b16 v1, v0 offset:816
	v_cvt_pk_bf16_f32 v0, v12, v179
	v_lshl_add_u32 v1, v38, 1, v32
	ds_write_b16 v1, v0
	v_cvt_pk_bf16_f32 v0, v13, v179
	ds_write_b16 v1, v0 offset:272
	v_cvt_pk_bf16_f32 v0, v14, v179
	v_add_u32_e32 v4, s7, v35
	ds_write_b16 v1, v0 offset:544
	v_cvt_pk_bf16_f32 v0, v15, v179
	v_add_u32_e32 v10, s11, v178
	v_ashrrev_i32_e32 v7, 31, v4
	v_mad_u64_u32 v[4:5], s[30:31], v4, s6, 0
	ds_write_b16 v1, v0 offset:816
	v_add_u32_e32 v0, v10, v41
	v_mov_b32_e32 v6, v5
	s_waitcnt lgkmcnt(0)
	s_barrier
	ds_read_b128 v[0:3], v0
	v_mad_u64_u32 v[6:7], s[30:31], v7, s6, v[6:7]
	v_mov_b32_e32 v5, v6
	s_mov_b32 s11, s5
	v_lshl_add_u64 v[4:5], v[4:5], 1, s[2:3]
	s_lshl_b64 s[10:11], s[10:11], 1
	v_lshl_add_u64 v[4:5], v[4:5], 0, s[10:11]
	v_lshl_add_u64 v[8:9], v[4:5], 0, v[178:179]
	v_add_u32_e32 v4, v10, v42
	ds_read_b128 v[4:7], v4
	s_waitcnt lgkmcnt(1)
	global_store_dwordx4 v[8:9], v[0:3], off sc0 sc1
	s_xor_b32 s24, s24, 1
	s_add_i32 s25, s25, 48
	v_add_u32_e32 v0, s7, v36
	v_ashrrev_i32_e32 v3, 31, v0
	v_mad_u64_u32 v[0:1], s[30:31], v0, s6, 0
	v_mov_b32_e32 v2, v1
	v_mad_u64_u32 v[2:3], s[6:7], v3, s6, v[2:3]
	v_mov_b32_e32 v1, v2
	v_lshl_add_u64 v[0:1], v[0:1], 1, s[2:3]
	v_lshl_add_u64 v[0:1], v[0:1], 0, s[10:11]
	v_lshl_add_u64 v[0:1], v[0:1], 0, v[178:179]
	s_waitcnt lgkmcnt(0)
	global_store_dwordx4 v[0:1], v[4:7], off sc0 sc1
	s_cmpk_gt_i32 s29, 0xfef
	s_mov_b64 s[2:3], s[40:41]
	s_mov_b32 s6, s28
	s_mov_b32 s7, s27
	s_mov_b32 s10, s26
	v_mov_b32_e32 v0, v59
	v_mov_b32_e32 v1, v55
	v_mov_b32_e32 v2, v51
	v_mov_b32_e32 v3, v47
	v_mov_b32_e32 v4, v58
	v_mov_b32_e32 v5, v54
	v_mov_b32_e32 v6, v50
	v_mov_b32_e32 v7, v46
	v_mov_b32_e32 v8, v57
	v_mov_b32_e32 v9, v53
	v_mov_b32_e32 v10, v49
	v_mov_b32_e32 v11, v45
	v_mov_b32_e32 v12, v56
	v_mov_b32_e32 v13, v52
	v_mov_b32_e32 v14, v48
	v_mov_b32_e32 v15, v44
	s_waitcnt vmcnt(2)
	v_mov_b32_e32 v32, v16
	v_mov_b32_e32 v33, v17
	v_mov_b32_e32 v60, v18
	v_mov_b32_e32 v61, v19
	v_mov_b32_e32 v62, v20
	v_mov_b32_e32 v63, v21
	v_mov_b32_e32 v64, v22
	v_mov_b32_e32 v65, v23
	v_mov_b32_e32 v66, v24
	v_mov_b32_e32 v67, v25
	v_mov_b32_e32 v68, v26
	v_mov_b32_e32 v69, v27
	v_mov_b32_e32 v70, v28
	v_mov_b32_e32 v71, v29
	v_mov_b32_e32 v72, v30
	v_mov_b32_e32 v73, v31
	s_cbranch_scc1 .LBB0_3019

; #define PG8_STAGE(bufoff, gbase, voff) do { _Pragma("unroll") for (int _i = 0; _i < 2; ++_i) \
;         __builtin_amdgcn_global_load_lds((const unsigned*)((const char*)(gbase) + (voff)[_i]), (LAS unsigned*)(lds + (bufoff) + ldsw + _i * 8192), 16, 0, 0); } while (0)
; #define PG8_LDA(dst, b, h) do { _Pragma("unroll") for (int m = 0; m < 4; ++m) _Pragma("unroll") for (int k = 0; k < 2; ++k) dst[m][k] = *(const LAS bf16x8*)(lds + PG8_SA(b, h) + aoff + m * 2048 + k * 1024); } while (0)
; #define PG8_LDB(dst, b, h) do { _Pragma("unroll") for (int n = 0; n < 2; ++n) _Pragma("unroll") for (int k = 0; k < 2; ++k) dst[n][k] = *(const LAS bf16x8*)(lds + PG8_SB(b, h) + boff + n * 2048 + k * 1024); } while (0)
; #define PG8_MMA(ai, bj, At, Bt) do { __builtin_amdgcn_s_setprio(1); _Pragma("unroll") for (int m = 0; m < 4; ++m) _Pragma("unroll") for (int n = 0; n < 2; ++n) _Pragma("unroll") for (int k = 0; k < 2; ++k) \
;         acc[ai][bj][m][n] = __builtin_amdgcn_mfma_f32_16x16x32_bf16(Bt[n][k], At[m][k], acc[ai][bj][m][n], 0, 0, 0); __builtin_amdgcn_s_setprio(0); } while (0)
; #define PG8_WAIT_L(n) asm volatile("s_waitcnt lgkmcnt(" #n ")" ::: "memory")
; #define PG8_BAR __builtin_amdgcn_s_barrier()
; #define PG8_SCHED __builtin_amdgcn_sched_barrier(0)
; template <class Epi>
; __device__ __forceinline__ void gemm_phase(LAS unsigned char* lds, const Gemm g, const StaticOrder S, const Epi E) {
;     ...
;             PG8_LDB(B0, 0, 0); PG8_SCHED; PG8_LDA(At, 0, 0); PG8_STAGE(PG8_SA(1, 1), a1 + hstep, voffA);
;             PG8_WAIT_L(8); PG8_BAR; PG8_WAIT_L(0); PG8_MMA(0, 0, At, B0); PG8_BAR; PG8_SCHED;
;             PG8_LDB(B1, 0, 1); PG8_STAGE(PG8_SB(0, 0), b2, voffA);
;             PG8_BAR; PG8_WAIT_L(0); PG8_MMA(0, 1, At, B1); PG8_BAR;
;             PG8_LDA(At, 0, 1); PG8_STAGE(PG8_SA(0, 0), a2, voffA);
;             PG8_BAR; PG8_WAIT_L(0); PG8_MMA(1, 0, At, B0); PG8_BAR; PG8_SCHED;
.LBB0_3278:
	s_add_u32 s54, s52, 0x100
	s_addc_u32 s55, s53, 0
	s_add_i32 s28, 0, 0x10000
	v_add_u32_e32 v140, s28, v157
	ds_read_b128 v[128:131], v140
	ds_read_b128 v[132:135], v140 offset:1024
	ds_read_b128 v[136:139], v140 offset:2048
	ds_read_b128 v[164:167], v140 offset:3072
	s_cmp_eq_u32 s27, 4
	s_cselect_b32 s59, s47, s55
	s_cselect_b32 s58, s46, s54
	s_cselect_b32 s57, s49, s3
	s_cselect_b32 s56, s48, s1
	v_lshl_add_u64 v[140:141], s[52:53], 0, v[150:151]
	s_add_i32 m0, s23, 0xc000
	ds_read_b128 v[168:171], v162
	ds_read_b128 v[172:175], v162 offset:1024
	ds_read_b128 v[194:197], v162 offset:2048
	ds_read_b128 v[198:201], v162 offset:3072
	ds_read_b128 v[202:205], v162 offset:4096
	ds_read_b128 v[206:209], v162 offset:5120
	ds_read_b128 v[228:231], v162 offset:6144
	ds_read_b128 v[232:235], v162 offset:7168
	global_load_lds_dwordx4 v[140:141], off
	v_lshl_add_u64 v[140:141], s[52:53], 0, v[152:153]
	s_add_i32 m0, s23, 0xe000
	s_nop 0
	global_load_lds_dwordx4 v[140:141], off
	s_waitcnt lgkmcnt(8)
	s_barrier
	s_waitcnt lgkmcnt(0)
	s_setprio 1
	s_waitcnt lgkmcnt(0)
	v_mfma_f32_16x16x32_bf16 v[124:127], v[128:131], v[168:171], v[124:127]
	v_mfma_f32_16x16x32_bf16 v[120:123], v[136:139], v[168:171], v[120:123]
	v_mfma_f32_16x16x32_bf16 v[108:111], v[128:131], v[194:197], v[108:111]
	v_mfma_f32_16x16x32_bf16 v[104:107], v[136:139], v[194:197], v[104:107]
	v_mfma_f32_16x16x32_bf16 v[92:95], v[128:131], v[202:205], v[92:95]
	v_mfma_f32_16x16x32_bf16 v[88:91], v[136:139], v[202:205], v[88:91]
	v_mfma_f32_16x16x32_bf16 v[76:79], v[128:131], v[228:231], v[76:79]
	v_mfma_f32_16x16x32_bf16 v[72:75], v[136:139], v[228:231], v[72:75]
	v_mfma_f32_16x16x32_bf16 v[124:127], v[132:135], v[172:175], v[124:127]
	v_mfma_f32_16x16x32_bf16 v[120:123], v[164:167], v[172:175], v[120:123]
	v_mfma_f32_16x16x32_bf16 v[108:111], v[132:135], v[198:201], v[108:111]
	v_mfma_f32_16x16x32_bf16 v[104:107], v[164:167], v[198:201], v[104:107]
	v_mfma_f32_16x16x32_bf16 v[92:95], v[132:135], v[206:209], v[92:95]
	v_mfma_f32_16x16x32_bf16 v[88:91], v[164:167], v[206:209], v[88:91]
	v_mfma_f32_16x16x32_bf16 v[76:79], v[132:135], v[232:235], v[76:79]
	v_mfma_f32_16x16x32_bf16 v[72:75], v[164:167], v[232:235], v[72:75]
	s_setprio 0
	s_barrier
	s_add_i32 s30, 0, 0x14000
	v_add_u32_e32 v140, s30, v157
	s_add_i32 s28, s28, s22
	ds_read_b128 v[236:239], v140
	ds_read_b128 v[240:243], v140 offset:1024
	ds_read_b128 v[244:247], v140 offset:2048
	ds_read_b128 v[220:223], v140 offset:3072
	v_lshl_add_u64 v[140:141], s[56:57], 0, v[142:143]
	s_mov_b32 m0, s28
	v_lshl_add_u64 v[154:155], s[56:57], 0, v[144:145]
	global_load_lds_dwordx4 v[140:141], off
	s_add_i32 m0, s28, 0x2000
	s_nop 0
	global_load_lds_dwordx4 v[154:155], off
	s_barrier
	s_waitcnt lgkmcnt(0)
	s_setprio 1
	s_waitcnt lgkmcnt(0)
	v_mfma_f32_16x16x32_bf16 v[116:119], v[236:239], v[168:171], v[116:119]
	v_mfma_f32_16x16x32_bf16 v[112:115], v[244:247], v[168:171], v[112:115]
	v_mfma_f32_16x16x32_bf16 v[100:103], v[236:239], v[194:197], v[100:103]
	v_mfma_f32_16x16x32_bf16 v[96:99], v[244:247], v[194:197], v[96:99]
	v_mfma_f32_16x16x32_bf16 v[84:87], v[236:239], v[202:205], v[84:87]
	v_mfma_f32_16x16x32_bf16 v[80:83], v[244:247], v[202:205], v[80:83]
	v_mfma_f32_16x16x32_bf16 v[68:71], v[236:239], v[228:231], v[68:71]
	v_mfma_f32_16x16x32_bf16 v[64:67], v[244:247], v[228:231], v[64:67]
	v_mfma_f32_16x16x32_bf16 v[116:119], v[240:243], v[172:175], v[116:119]
	v_mfma_f32_16x16x32_bf16 v[112:115], v[220:223], v[172:175], v[112:115]
	v_mfma_f32_16x16x32_bf16 v[100:103], v[240:243], v[198:201], v[100:103]
	v_mfma_f32_16x16x32_bf16 v[96:99], v[220:223], v[198:201], v[96:99]
	v_mfma_f32_16x16x32_bf16 v[84:87], v[240:243], v[206:209], v[84:87]
	v_mfma_f32_16x16x32_bf16 v[80:83], v[220:223], v[206:209], v[80:83]
	v_mfma_f32_16x16x32_bf16 v[68:71], v[240:243], v[232:235], v[68:71]
	v_mfma_f32_16x16x32_bf16 v[64:67], v[220:223], v[232:235], v[64:67]
	s_setprio 0
	s_barrier
	s_mov_b32 m0, s23
	v_lshl_add_u64 v[210:211], s[58:59], 0, v[142:143]
	ds_read_b128 v[168:171], v162 offset:16384
	ds_read_b128 v[172:175], v162 offset:17408
	ds_read_b128 v[194:197], v162 offset:18432
	ds_read_b128 v[198:201], v162 offset:19456
	ds_read_b128 v[202:205], v162 offset:20480
	ds_read_b128 v[206:209], v162 offset:21504
	ds_read_b128 v[228:231], v162 offset:22528
	ds_read_b128 v[232:235], v162 offset:23552
	global_load_lds_dwordx4 v[210:211], off
	v_lshl_add_u64 v[248:249], s[58:59], 0, v[144:145]
	s_mov_b32 m0, s24
	s_nop 0
	global_load_lds_dwordx4 v[248:249], off
	s_barrier
	s_waitcnt lgkmcnt(0)
	s_setprio 1
	s_waitcnt lgkmcnt(0)
	v_mfma_f32_16x16x32_bf16 v[60:63], v[128:131], v[168:171], v[60:63]
	v_mfma_f32_16x16x32_bf16 v[56:59], v[136:139], v[168:171], v[56:59]
	v_mfma_f32_16x16x32_bf16 v[44:47], v[128:131], v[194:197], v[44:47]
	v_mfma_f32_16x16x32_bf16 v[40:43], v[136:139], v[194:197], v[40:43]
	v_mfma_f32_16x16x32_bf16 v[28:31], v[128:131], v[202:205], v[28:31]
	v_mfma_f32_16x16x32_bf16 v[24:27], v[136:139], v[202:205], v[24:27]
	v_mfma_f32_16x16x32_bf16 v[12:15], v[128:131], v[228:231], v[12:15]
	v_mfma_f32_16x16x32_bf16 v[8:11], v[136:139], v[228:231], v[8:11]
	v_mfma_f32_16x16x32_bf16 v[60:63], v[132:135], v[172:175], v[60:63]
	v_mfma_f32_16x16x32_bf16 v[56:59], v[164:167], v[172:175], v[56:59]
	v_mfma_f32_16x16x32_bf16 v[44:47], v[132:135], v[198:201], v[44:47]
	v_mfma_f32_16x16x32_bf16 v[40:43], v[164:167], v[198:201], v[40:43]
	v_mfma_f32_16x16x32_bf16 v[28:31], v[132:135], v[206:209], v[28:31]
	v_mfma_f32_16x16x32_bf16 v[24:27], v[164:167], v[206:209], v[24:27]
	v_mfma_f32_16x16x32_bf16 v[12:15], v[132:135], v[232:235], v[12:15]
	v_mfma_f32_16x16x32_bf16 v[8:11], v[164:167], v[232:235], v[8:11]
	s_setprio 0
	s_barrier
; #define PG8_STAGE(bufoff, gbase, voff) do { _Pragma("unroll") for (int _i = 0; _i < 2; ++_i) \
;         __builtin_amdgcn_global_load_lds((const unsigned*)((const char*)(gbase) + (voff)[_i]), (LAS unsigned*)(lds + (bufoff) + ldsw + _i * 8192), 16, 0, 0); } while (0)
; #define PG8_LDA(dst, b, h) do { _Pragma("unroll") for (int m = 0; m < 4; ++m) _Pragma("unroll") for (int k = 0; k < 2; ++k) dst[m][k] = *(const LAS bf16x8*)(lds + PG8_SA(b, h) + aoff + m * 2048 + k * 1024); } while (0)
; #define PG8_LDB(dst, b, h) do { _Pragma("unroll") for (int n = 0; n < 2; ++n) _Pragma("unroll") for (int k = 0; k < 2; ++k) dst[n][k] = *(const LAS bf16x8*)(lds + PG8_SB(b, h) + boff + n * 2048 + k * 1024); } while (0)
; #define PG8_MMA(ai, bj, At, Bt) do { __builtin_amdgcn_s_setprio(1); _Pragma("unroll") for (int m = 0; m < 4; ++m) _Pragma("unroll") for (int n = 0; n < 2; ++n) _Pragma("unroll") for (int k = 0; k < 2; ++k) \
;         acc[ai][bj][m][n] = __builtin_amdgcn_mfma_f32_16x16x32_bf16(Bt[n][k], At[m][k], acc[ai][bj][m][n], 0, 0, 0); __builtin_amdgcn_s_setprio(0); } while (0)
; #define PG8_WAIT_V(n) asm volatile("s_waitcnt vmcnt(" #n ")" ::: "memory")
; #define PG8_WAIT_L(n) asm volatile("s_waitcnt lgkmcnt(" #n ")" ::: "memory")
; #define PG8_BAR __builtin_amdgcn_s_barrier()
; #define PG8_SCHED __builtin_amdgcn_sched_barrier(0)
; template <class Epi>
; __device__ __forceinline__ void gemm_phase(LAS unsigned char* lds, const Gemm g, const StaticOrder S, const Epi E) {
;     ...
;             PG8_STAGE(PG8_SB(0, 1), b2 + hstep, voffA);
;             PG8_WAIT_V(6); PG8_BAR; PG8_MMA(1, 1, At, B1); PG8_BAR;
;             PG8_LDB(B0, 1, 0); PG8_SCHED; PG8_LDA(At, 1, 0); PG8_STAGE(PG8_SA(0, 1), a2 + hstep, voffA);
;             PG8_WAIT_L(8); PG8_BAR; PG8_WAIT_L(0); PG8_MMA(0, 0, At, B0); PG8_BAR; PG8_SCHED;
;             PG8_LDB(B1, 1, 1); PG8_STAGE(PG8_SB(1, 0), b3, voffA);
;             PG8_BAR; PG8_WAIT_L(0); PG8_MMA(0, 1, At, B1); PG8_BAR;
	s_add_u32 s28, s56, 0x20000
	s_addc_u32 s29, s57, 0
	s_add_i32 s30, s30, s22
	v_lshl_add_u64 v[128:129], s[28:29], 0, v[142:143]
	s_mov_b32 m0, s30
	s_nop 0
	global_load_lds_dwordx4 v[128:129], off
	v_lshl_add_u64 v[128:129], s[28:29], 0, v[144:145]
	s_add_i32 m0, s30, 0x2000
	s_nop 0
	global_load_lds_dwordx4 v[128:129], off
	s_waitcnt vmcnt(6)
	s_barrier
	s_setprio 1
	v_mfma_f32_16x16x32_bf16 v[52:55], v[236:239], v[168:171], v[52:55]
	v_mfma_f32_16x16x32_bf16 v[48:51], v[244:247], v[168:171], v[48:51]
	v_mfma_f32_16x16x32_bf16 v[36:39], v[236:239], v[194:197], v[36:39]
	v_mfma_f32_16x16x32_bf16 v[32:35], v[244:247], v[194:197], v[32:35]
	v_mfma_f32_16x16x32_bf16 v[20:23], v[236:239], v[202:205], v[20:23]
	v_mfma_f32_16x16x32_bf16 v[16:19], v[244:247], v[202:205], v[16:19]
	v_mfma_f32_16x16x32_bf16 v[4:7], v[236:239], v[228:231], v[4:7]
	v_mfma_f32_16x16x32_bf16 v[0:3], v[244:247], v[228:231], v[0:3]
	v_mfma_f32_16x16x32_bf16 v[52:55], v[240:243], v[172:175], v[52:55]
	v_mfma_f32_16x16x32_bf16 v[48:51], v[220:223], v[172:175], v[48:51]
	v_mfma_f32_16x16x32_bf16 v[36:39], v[240:243], v[198:201], v[36:39]
	v_mfma_f32_16x16x32_bf16 v[32:35], v[220:223], v[198:201], v[32:35]
	v_mfma_f32_16x16x32_bf16 v[20:23], v[240:243], v[206:209], v[20:23]
	v_mfma_f32_16x16x32_bf16 v[16:19], v[220:223], v[206:209], v[16:19]
	v_mfma_f32_16x16x32_bf16 v[4:7], v[240:243], v[232:235], v[4:7]
	v_mfma_f32_16x16x32_bf16 v[0:3], v[220:223], v[232:235], v[0:3]
	s_setprio 0
	s_barrier
	s_add_i32 s30, 0, 0x18000
	v_add_u32_e32 v163, s30, v157
	ds_read_b128 v[128:131], v163
	ds_read_b128 v[132:135], v163 offset:1024
	ds_read_b128 v[136:139], v163 offset:2048
	ds_read_b128 v[164:167], v163 offset:3072
	s_add_u32 s28, s58, 0x20000
	s_addc_u32 s29, s59, 0
	s_mov_b32 m0, s25
	v_lshl_add_u64 v[232:233], s[28:29], 0, v[142:143]
	ds_read_b128 v[168:171], v162 offset:32768
	ds_read_b128 v[172:175], v162 offset:33792
	ds_read_b128 v[194:197], v162 offset:34816
	ds_read_b128 v[198:201], v162 offset:35840
	ds_read_b128 v[202:205], v162 offset:36864
	ds_read_b128 v[206:209], v162 offset:37888
	ds_read_b128 v[220:223], v162 offset:38912
	ds_read_b128 v[228:231], v162 offset:39936
	global_load_lds_dwordx4 v[232:233], off
	v_lshl_add_u64 v[232:233], s[28:29], 0, v[144:145]
	s_mov_b32 m0, s51
	s_nop 0
	global_load_lds_dwordx4 v[232:233], off
	s_waitcnt lgkmcnt(8)
	s_barrier
	s_waitcnt lgkmcnt(0)
	s_setprio 1
	s_waitcnt lgkmcnt(0)
	v_mfma_f32_16x16x32_bf16 v[124:127], v[128:131], v[168:171], v[124:127]
	v_mfma_f32_16x16x32_bf16 v[120:123], v[136:139], v[168:171], v[120:123]
	v_mfma_f32_16x16x32_bf16 v[108:111], v[128:131], v[194:197], v[108:111]
	v_mfma_f32_16x16x32_bf16 v[104:107], v[136:139], v[194:197], v[104:107]
	v_mfma_f32_16x16x32_bf16 v[92:95], v[128:131], v[202:205], v[92:95]
	v_mfma_f32_16x16x32_bf16 v[88:91], v[136:139], v[202:205], v[88:91]
	v_mfma_f32_16x16x32_bf16 v[76:79], v[128:131], v[220:223], v[76:79]
	v_mfma_f32_16x16x32_bf16 v[72:75], v[136:139], v[220:223], v[72:75]
	v_mfma_f32_16x16x32_bf16 v[124:127], v[132:135], v[172:175], v[124:127]
	v_mfma_f32_16x16x32_bf16 v[120:123], v[164:167], v[172:175], v[120:123]
	v_mfma_f32_16x16x32_bf16 v[108:111], v[132:135], v[198:201], v[108:111]
	v_mfma_f32_16x16x32_bf16 v[104:107], v[164:167], v[198:201], v[104:107]
	v_mfma_f32_16x16x32_bf16 v[92:95], v[132:135], v[206:209], v[92:95]
	v_mfma_f32_16x16x32_bf16 v[88:91], v[164:167], v[206:209], v[88:91]
	v_mfma_f32_16x16x32_bf16 v[76:79], v[132:135], v[228:231], v[76:79]
	v_mfma_f32_16x16x32_bf16 v[72:75], v[164:167], v[228:231], v[72:75]
	s_setprio 0
	s_barrier
	s_add_i32 s31, 0, 0x1c000
	s_add_i32 s28, s30, s22
	v_add_u32_e32 v163, s31, v157
	v_lshl_add_u64 v[140:141], v[140:141], 0, s[34:35]
	s_mov_b32 m0, s28
	ds_read_b128 v[232:235], v163
	ds_read_b128 v[236:239], v163 offset:1024
	ds_read_b128 v[240:243], v163 offset:2048
	ds_read_b128 v[244:247], v163 offset:3072
	global_load_lds_dwordx4 v[140:141], off
	v_lshl_add_u64 v[140:141], v[154:155], 0, s[34:35]
	s_add_i32 m0, s28, 0x2000
	s_nop 0
	global_load_lds_dwordx4 v[140:141], off
	s_barrier
	s_waitcnt lgkmcnt(0)
	s_setprio 1
	s_waitcnt lgkmcnt(0)
	v_mfma_f32_16x16x32_bf16 v[116:119], v[232:235], v[168:171], v[116:119]
	v_mfma_f32_16x16x32_bf16 v[112:115], v[240:243], v[168:171], v[112:115]
	v_mfma_f32_16x16x32_bf16 v[100:103], v[232:235], v[194:197], v[100:103]
	v_mfma_f32_16x16x32_bf16 v[96:99], v[240:243], v[194:197], v[96:99]
	v_mfma_f32_16x16x32_bf16 v[84:87], v[232:235], v[202:205], v[84:87]
	v_mfma_f32_16x16x32_bf16 v[80:83], v[240:243], v[202:205], v[80:83]
	v_mfma_f32_16x16x32_bf16 v[68:71], v[232:235], v[220:223], v[68:71]
	v_mfma_f32_16x16x32_bf16 v[64:67], v[240:243], v[220:223], v[64:67]
	v_mfma_f32_16x16x32_bf16 v[116:119], v[236:239], v[172:175], v[116:119]
	v_mfma_f32_16x16x32_bf16 v[112:115], v[244:247], v[172:175], v[112:115]
	v_mfma_f32_16x16x32_bf16 v[100:103], v[236:239], v[198:201], v[100:103]
	v_mfma_f32_16x16x32_bf16 v[96:99], v[244:247], v[198:201], v[96:99]
	v_mfma_f32_16x16x32_bf16 v[84:87], v[236:239], v[206:209], v[84:87]
	v_mfma_f32_16x16x32_bf16 v[80:83], v[244:247], v[206:209], v[80:83]
	v_mfma_f32_16x16x32_bf16 v[68:71], v[236:239], v[228:231], v[68:71]
	v_mfma_f32_16x16x32_bf16 v[64:67], v[244:247], v[228:231], v[64:67]
	s_setprio 0
	s_barrier
; #define PG8_STAGE(bufoff, gbase, voff) do { _Pragma("unroll") for (int _i = 0; _i < 2; ++_i) \
;         __builtin_amdgcn_global_load_lds((const unsigned*)((const char*)(gbase) + (voff)[_i]), (LAS unsigned*)(lds + (bufoff) + ldsw + _i * 8192), 16, 0, 0); } while (0)
; #define PG8_LDA(dst, b, h) do { _Pragma("unroll") for (int m = 0; m < 4; ++m) _Pragma("unroll") for (int k = 0; k < 2; ++k) dst[m][k] = *(const LAS bf16x8*)(lds + PG8_SA(b, h) + aoff + m * 2048 + k * 1024); } while (0)
; #define PG8_MMA(ai, bj, At, Bt) do { __builtin_amdgcn_s_setprio(1); _Pragma("unroll") for (int m = 0; m < 4; ++m) _Pragma("unroll") for (int n = 0; n < 2; ++n) _Pragma("unroll") for (int k = 0; k < 2; ++k) \
;         acc[ai][bj][m][n] = __builtin_amdgcn_mfma_f32_16x16x32_bf16(Bt[n][k], At[m][k], acc[ai][bj][m][n], 0, 0, 0); __builtin_amdgcn_s_setprio(0); } while (0)
; #define PG8_WAIT_V(n) asm volatile("s_waitcnt vmcnt(" #n ")" ::: "memory")
; #define PG8_WAIT_L(n) asm volatile("s_waitcnt lgkmcnt(" #n ")" ::: "memory")
; #define PG8_BAR __builtin_amdgcn_s_barrier()
; #define PG8_SCHED __builtin_amdgcn_sched_barrier(0)
; template <class Epi>
; __device__ __forceinline__ void gemm_phase(LAS unsigned char* lds, const Gemm g, const StaticOrder S, const Epi E) {
;     ...
;             PG8_LDA(At, 1, 1); PG8_STAGE(PG8_SA(1, 0), a3, voffA);
;             PG8_BAR; PG8_WAIT_L(0); PG8_MMA(1, 0, At, B0); PG8_BAR; PG8_SCHED;
;             PG8_STAGE(PG8_SB(1, 1), b3 + hstep, voffA);
;             PG8_WAIT_V(6); PG8_BAR; PG8_MMA(1, 1, At, B1); PG8_BAR;
;     __device__ __forceinline__ void operator()(AccRef acc, const pg8::Unit& u, int wr, int wc, int fr, int fq) const {
;     ...
;         const bool rope = (u.pn == rope_pn) && (u.pm < 32);
; #pragma unroll
;         for (int ai = 0; ai < 2; ++ai)
; #pragma unroll
;             for (int m = 0; m < 4; ++m) { const int row = row0 + ai * 128 + m * 16; bf16_t* rowp = O + (size_t)row * ldc + col0;
;                 f32x4 cs = {1.f, 1.f, 1.f, 1.f}, sn = {0.f, 0.f, 0.f, 0.f};
;                 if (rope) { const int t = row & 2047; const int pos = (wc & 1) ? (t & 63) : (t >> 6); cs = *(const f32x4*)(cos64 + pos * 16 + 4 * fq); sn = *(const f32x4*)(sin64 + pos * 16 + 4 * fq); }
	s_mov_b32 m0, s61
	v_lshl_add_u64 v[140:141], v[210:211], 0, s[34:35]
	ds_read_b128 v[168:171], v162 offset:49152
	ds_read_b128 v[172:175], v162 offset:50176
	ds_read_b128 v[194:197], v162 offset:51200
	ds_read_b128 v[198:201], v162 offset:52224
	ds_read_b128 v[202:205], v162 offset:53248
	ds_read_b128 v[206:209], v162 offset:54272
	ds_read_b128 v[220:223], v162 offset:55296
	ds_read_b128 v[228:231], v162 offset:56320
	global_load_lds_dwordx4 v[140:141], off
	v_lshl_add_u64 v[140:141], v[248:249], 0, s[34:35]
	s_mov_b32 m0, s62
	s_nop 0
	global_load_lds_dwordx4 v[140:141], off
	s_barrier
	s_waitcnt lgkmcnt(0)
	s_setprio 1
	s_waitcnt lgkmcnt(0)
	v_mfma_f32_16x16x32_bf16 v[60:63], v[128:131], v[168:171], v[60:63]
	v_mfma_f32_16x16x32_bf16 v[56:59], v[136:139], v[168:171], v[56:59]
	v_mfma_f32_16x16x32_bf16 v[44:47], v[128:131], v[194:197], v[44:47]
	v_mfma_f32_16x16x32_bf16 v[40:43], v[136:139], v[194:197], v[40:43]
	v_mfma_f32_16x16x32_bf16 v[28:31], v[128:131], v[202:205], v[28:31]
	v_mfma_f32_16x16x32_bf16 v[24:27], v[136:139], v[202:205], v[24:27]
	v_mfma_f32_16x16x32_bf16 v[12:15], v[128:131], v[220:223], v[12:15]
	v_mfma_f32_16x16x32_bf16 v[8:11], v[136:139], v[220:223], v[8:11]
	v_mfma_f32_16x16x32_bf16 v[60:63], v[132:135], v[172:175], v[60:63]
	v_mfma_f32_16x16x32_bf16 v[56:59], v[164:167], v[172:175], v[56:59]
	v_mfma_f32_16x16x32_bf16 v[44:47], v[132:135], v[198:201], v[44:47]
	v_mfma_f32_16x16x32_bf16 v[40:43], v[164:167], v[198:201], v[40:43]
	v_mfma_f32_16x16x32_bf16 v[28:31], v[132:135], v[206:209], v[28:31]
	v_mfma_f32_16x16x32_bf16 v[24:27], v[164:167], v[206:209], v[24:27]
	v_mfma_f32_16x16x32_bf16 v[12:15], v[132:135], v[228:231], v[12:15]
	v_mfma_f32_16x16x32_bf16 v[8:11], v[164:167], v[228:231], v[8:11]
	s_setprio 0
	s_barrier
	s_add_u32 s28, s56, 0x20080
	s_addc_u32 s29, s57, 0
	s_add_i32 s30, s31, s22
	v_lshl_add_u64 v[128:129], s[28:29], 0, v[142:143]
	s_mov_b32 m0, s30
	s_nop 0
	global_load_lds_dwordx4 v[128:129], off
	v_lshl_add_u64 v[128:129], s[28:29], 0, v[144:145]
	s_add_i32 m0, s30, 0x2000
	s_nop 0
	global_load_lds_dwordx4 v[128:129], off
	s_waitcnt vmcnt(6)
	s_barrier
	s_setprio 1
	v_mfma_f32_16x16x32_bf16 v[52:55], v[232:235], v[168:171], v[52:55]
	v_mfma_f32_16x16x32_bf16 v[48:51], v[240:243], v[168:171], v[48:51]
	v_mfma_f32_16x16x32_bf16 v[36:39], v[232:235], v[194:197], v[36:39]
	v_mfma_f32_16x16x32_bf16 v[32:35], v[240:243], v[194:197], v[32:35]
	v_mfma_f32_16x16x32_bf16 v[20:23], v[232:235], v[202:205], v[20:23]
	v_mfma_f32_16x16x32_bf16 v[16:19], v[240:243], v[202:205], v[16:19]
	v_mfma_f32_16x16x32_bf16 v[4:7], v[232:235], v[220:223], v[4:7]
	v_mfma_f32_16x16x32_bf16 v[0:3], v[240:243], v[220:223], v[0:3]
	v_mfma_f32_16x16x32_bf16 v[52:55], v[236:239], v[172:175], v[52:55]
	v_mfma_f32_16x16x32_bf16 v[48:51], v[244:247], v[172:175], v[48:51]
	v_mfma_f32_16x16x32_bf16 v[36:39], v[236:239], v[198:201], v[36:39]
	v_mfma_f32_16x16x32_bf16 v[32:35], v[244:247], v[198:201], v[32:35]
	v_mfma_f32_16x16x32_bf16 v[20:23], v[236:239], v[206:209], v[20:23]
	v_mfma_f32_16x16x32_bf16 v[16:19], v[244:247], v[206:209], v[16:19]
	v_mfma_f32_16x16x32_bf16 v[4:7], v[236:239], v[228:231], v[4:7]
	v_mfma_f32_16x16x32_bf16 v[0:3], v[244:247], v[228:231], v[0:3]
	s_setprio 0
	s_barrier
	s_add_i32 s27, s27, 2
	s_add_u32 s1, s1, 0x100
	s_addc_u32 s3, s3, 0
	s_cmp_gt_u32 s27, 5
	s_mov_b64 s[52:53], s[54:55]
	s_cbranch_scc0 .LBB0_3278
	s_lshl_b32 s3, s42, 8
	s_add_i32 s3, s3, s60
	s_cmp_eq_u32 s50, 2
	s_cselect_b64 s[28:29], -1, 0
	s_cmp_lt_i32 s42, 32
	s_cselect_b64 s[30:31], -1, 0
	s_and_b64 s[28:29], s[28:29], s[30:31]
	v_cndmask_b32_e64 v129, 0, 1, s[28:29]
	s_bfe_u32 s1, s3, 0x50006
	v_mov_b32_e32 v128, 1.0
	v_mov_b32_e32 v132, 0
	v_cmp_ne_u32_e64 s[42:43], 1, v129
	s_andn2_b64 vcc, exec, s[28:29]
	v_mov_b32_e32 v134, 0
	v_mov_b32_e32 v135, 0
	v_mov_b32_e32 v136, 0
	v_mov_b32_e32 v137, 0
	v_mov_b32_e32 v138, 1.0
	v_mov_b32_e32 v139, 1.0
	v_mov_b32_e32 v140, 1.0
	v_mov_b32_e32 v141, 1.0
	s_cbranch_vccnz .LBB0_3281
	v_mov_b32_e32 v129, s1
	v_cndmask_b32_e64 v129, v156, v129, s[38:39]
	v_lshlrev_b32_e32 v178, 6, v129
	v_lshl_add_u64 v[130:131], v[148:149], 0, v[178:179]
	v_lshl_add_u64 v[134:135], v[146:147], 0, v[178:179]
	global_load_dwordx4 v[138:141], v[130:131], off
	s_nop 0
	global_load_dwordx4 v[134:137], v[134:135], off

; #define PG8_STAGE(bufoff, gbase, voff) do { _Pragma("unroll") for (int _i = 0; _i < 2; ++_i) \
;         __builtin_amdgcn_global_load_lds((const unsigned*)((const char*)(gbase) + (voff)[_i]), (LAS unsigned*)(lds + (bufoff) + ldsw + _i * 8192), 16, 0, 0); } while (0)
; #define PG8_LDA(dst, b, h) do { _Pragma("unroll") for (int m = 0; m < 4; ++m) _Pragma("unroll") for (int k = 0; k < 2; ++k) dst[m][k] = *(const LAS bf16x8*)(lds + PG8_SA(b, h) + aoff + m * 2048 + k * 1024); } while (0)
; #define PG8_LDB(dst, b, h) do { _Pragma("unroll") for (int n = 0; n < 2; ++n) _Pragma("unroll") for (int k = 0; k < 2; ++k) dst[n][k] = *(const LAS bf16x8*)(lds + PG8_SB(b, h) + boff + n * 2048 + k * 1024); } while (0)
; #define PG8_MMA(ai, bj, At, Bt) do { __builtin_amdgcn_s_setprio(1); _Pragma("unroll") for (int m = 0; m < 4; ++m) _Pragma("unroll") for (int n = 0; n < 2; ++n) _Pragma("unroll") for (int k = 0; k < 2; ++k) \
;         acc[ai][bj][m][n] = __builtin_amdgcn_mfma_f32_16x16x32_bf16(Bt[n][k], At[m][k], acc[ai][bj][m][n], 0, 0, 0); __builtin_amdgcn_s_setprio(0); } while (0)
; template <class Epi>
; __device__ __forceinline__ void gemm_phase(LAS unsigned char* lds, const Gemm g, const StaticOrder S, const Epi E) {
;     ...
;         const bool has_next = S.next(ui + 1, nxt);
;         const char* nA = has_next ? (const char*)g.A + (size_t)nxt.pm * tstep + (size_t)nxt.k0 * kstep : cA; const char* nB = has_next ? (const char*)g.Bt + (size_t)nxt.pn * tstep + (size_t)nxt.k0 * kstep : cB;
;         const int nt = cur.nk;
;         for (int t = 0; t < nt; t += 2) {
;             const bool last = (t == nt - 2);
;             const char* a1 = cA + (size_t)(t + 1) * kstep;
;             const char* a2 = last ? nA : cA + (size_t)(t + 2) * kstep; const char* b2 = last ? nB : cB + (size_t)(t + 2) * kstep;
;             const char* a3 = a2 + kstep; const char* b3 = b2 + kstep;
;             PG8_LDB(B0, 0, 0); PG8_SCHED; PG8_LDA(At, 0, 0); PG8_STAGE(PG8_SA(1, 1), a1 + hstep, voffA);
;             PG8_WAIT_L(8); PG8_BAR; PG8_WAIT_L(0); PG8_MMA(0, 0, At, B0); PG8_BAR; PG8_SCHED;
;             PG8_LDB(B1, 0, 1); PG8_STAGE(PG8_SB(0, 0), b2, voffA);
;             PG8_BAR; PG8_WAIT_L(0); PG8_MMA(0, 1, At, B1); PG8_BAR;
;             PG8_LDA(At, 0, 1); PG8_STAGE(PG8_SA(0, 0), a2, voffA);
;             PG8_BAR; PG8_WAIT_L(0); PG8_MMA(1, 0, At, B0); PG8_BAR; PG8_SCHED;
.LBB0_3306:
	s_add_u32 s3, s50, s1
	s_addc_u32 s29, s51, 0
	s_add_u32 s44, s3, 0x100
	s_addc_u32 s45, s29, 0
	s_and_b64 s[30:31], s[54:55], exec
	s_cselect_b32 s61, s47, s45
	s_cselect_b32 s60, s46, s44
	s_add_u32 s1, s42, s1
	s_addc_u32 s30, s43, 0
	s_add_u32 s1, s1, 0x100
	s_addc_u32 s44, s30, 0
	s_add_i32 s45, 0, 0x10000
	s_and_b64 s[30:31], s[54:55], exec
	s_cselect_b32 s63, s49, s44
	s_cselect_b32 s62, s48, s1
	s_add_u32 s64, s3, 0x10080
	s_addc_u32 s65, s29, 0
	s_add_i32 s73, s45, s22
	s_add_i32 m0, s14, 0xc000
	s_add_i32 s23, s14, 0xe000
	s_add_i32 vcc_hi, 0, 0x14000
	s_add_i32 s31, s73, 0x2000
	s_add_u32 s58, s62, 0x10000
	v_add_u32_e32 v140, s45, v155
	s_addc_u32 s59, s63, 0
	s_add_i32 s44, vcc_hi, s22
	ds_read_b128 v[128:131], v140
	ds_read_b128 v[132:135], v140 offset:1024
	ds_read_b128 v[136:139], v140 offset:2048
	ds_read_b128 v[150:153], v140 offset:3072
	s_add_i32 s72, s44, 0x2000
	s_add_i32 vcc_lo, 0, 0x18000
	s_add_u32 s56, s60, 0x10000
	s_addc_u32 s57, s61, 0
	s_add_i32 s29, vcc_lo, s22
	s_add_i32 s3, 0, 0x1c000
	s_add_i32 s1, s29, 0x2000
	s_add_u32 s54, s62, 0x10080
	s_addc_u32 s55, s63, 0
	s_add_i32 s45, s3, s22
	s_add_i32 s30, s45, 0x2000
	v_lshl_add_u64 v[140:141], s[64:65], 0, v[144:145]
	ds_read_b128 v[162:165], v160
	ds_read_b128 v[166:169], v160 offset:1024
	ds_read_b128 v[170:173], v160 offset:2048
	ds_read_b128 v[194:197], v160 offset:3072
	ds_read_b128 v[198:201], v160 offset:4096
	ds_read_b128 v[202:205], v160 offset:5120
	ds_read_b128 v[206:209], v160 offset:6144
	ds_read_b128 v[220:223], v160 offset:7168
	global_load_lds_dwordx4 v[140:141], off
	v_lshl_add_u64 v[140:141], s[64:65], 0, v[142:143]
	s_mov_b32 m0, s23
	s_nop 0
	global_load_lds_dwordx4 v[140:141], off
	s_waitcnt lgkmcnt(8)
	s_barrier
	s_waitcnt lgkmcnt(0)
	s_setprio 1
	s_waitcnt lgkmcnt(0)
	v_mfma_f32_16x16x32_bf16 v[124:127], v[128:131], v[162:165], v[124:127]
	v_mfma_f32_16x16x32_bf16 v[120:123], v[136:139], v[162:165], v[120:123]
	v_mfma_f32_16x16x32_bf16 v[108:111], v[128:131], v[170:173], v[108:111]
	v_mfma_f32_16x16x32_bf16 v[104:107], v[136:139], v[170:173], v[104:107]
	v_mfma_f32_16x16x32_bf16 v[92:95], v[128:131], v[198:201], v[92:95]
	v_mfma_f32_16x16x32_bf16 v[88:91], v[136:139], v[198:201], v[88:91]
	v_mfma_f32_16x16x32_bf16 v[76:79], v[128:131], v[206:209], v[76:79]
	v_mfma_f32_16x16x32_bf16 v[72:75], v[136:139], v[206:209], v[72:75]
	v_mfma_f32_16x16x32_bf16 v[124:127], v[132:135], v[166:169], v[124:127]
	v_mfma_f32_16x16x32_bf16 v[120:123], v[150:153], v[166:169], v[120:123]
	v_mfma_f32_16x16x32_bf16 v[108:111], v[132:135], v[194:197], v[108:111]
	v_mfma_f32_16x16x32_bf16 v[104:107], v[150:153], v[194:197], v[104:107]
	v_mfma_f32_16x16x32_bf16 v[92:95], v[132:135], v[202:205], v[92:95]
	v_mfma_f32_16x16x32_bf16 v[88:91], v[150:153], v[202:205], v[88:91]
	v_mfma_f32_16x16x32_bf16 v[76:79], v[132:135], v[220:223], v[76:79]
	v_mfma_f32_16x16x32_bf16 v[72:75], v[150:153], v[220:223], v[72:75]
	s_setprio 0
	s_barrier
	v_add_u32_e32 v140, vcc_hi, v155
	s_mov_b32 m0, s73
	ds_read_b128 v[228:231], v140
	ds_read_b128 v[232:235], v140 offset:1024
	ds_read_b128 v[236:239], v140 offset:2048
	ds_read_b128 v[240:243], v140 offset:3072
	v_lshl_add_u64 v[140:141], s[62:63], 0, v[144:145]
	global_load_lds_dwordx4 v[140:141], off
	v_lshl_add_u64 v[174:175], s[62:63], 0, v[142:143]
	s_mov_b32 m0, s31
	s_nop 0
	global_load_lds_dwordx4 v[174:175], off
	s_barrier
	s_waitcnt lgkmcnt(0)
	s_setprio 1
	s_waitcnt lgkmcnt(0)
	v_mfma_f32_16x16x32_bf16 v[116:119], v[228:231], v[162:165], v[116:119]
	v_mfma_f32_16x16x32_bf16 v[112:115], v[236:239], v[162:165], v[112:115]
	v_mfma_f32_16x16x32_bf16 v[100:103], v[228:231], v[170:173], v[100:103]
	v_mfma_f32_16x16x32_bf16 v[96:99], v[236:239], v[170:173], v[96:99]
	v_mfma_f32_16x16x32_bf16 v[84:87], v[228:231], v[198:201], v[84:87]
	v_mfma_f32_16x16x32_bf16 v[80:83], v[236:239], v[198:201], v[80:83]
	v_mfma_f32_16x16x32_bf16 v[68:71], v[228:231], v[206:209], v[68:71]
	v_mfma_f32_16x16x32_bf16 v[64:67], v[236:239], v[206:209], v[64:67]
	v_mfma_f32_16x16x32_bf16 v[116:119], v[232:235], v[166:169], v[116:119]
	v_mfma_f32_16x16x32_bf16 v[112:115], v[240:243], v[166:169], v[112:115]
	v_mfma_f32_16x16x32_bf16 v[100:103], v[232:235], v[194:197], v[100:103]
	v_mfma_f32_16x16x32_bf16 v[96:99], v[240:243], v[194:197], v[96:99]
	v_mfma_f32_16x16x32_bf16 v[84:87], v[232:235], v[202:205], v[84:87]
	v_mfma_f32_16x16x32_bf16 v[80:83], v[240:243], v[202:205], v[80:83]
	v_mfma_f32_16x16x32_bf16 v[68:71], v[232:235], v[220:223], v[68:71]
	v_mfma_f32_16x16x32_bf16 v[64:67], v[240:243], v[220:223], v[64:67]
	s_setprio 0
	s_barrier
	s_mov_b32 m0, s14
	v_lshl_add_u64 v[210:211], s[60:61], 0, v[144:145]
	ds_read_b128 v[162:165], v160 offset:16384
	ds_read_b128 v[166:169], v160 offset:17408
	ds_read_b128 v[170:173], v160 offset:18432
	ds_read_b128 v[194:197], v160 offset:19456
	ds_read_b128 v[198:201], v160 offset:20480
	ds_read_b128 v[202:205], v160 offset:21504
	ds_read_b128 v[206:209], v160 offset:22528
	ds_read_b128 v[220:223], v160 offset:23552
	global_load_lds_dwordx4 v[210:211], off
	v_lshl_add_u64 v[244:245], s[60:61], 0, v[142:143]
	s_mov_b32 m0, s24
	s_nop 0
	global_load_lds_dwordx4 v[244:245], off
	s_barrier
; #define PG8_STAGE(bufoff, gbase, voff) do { _Pragma("unroll") for (int _i = 0; _i < 2; ++_i) \
;         __builtin_amdgcn_global_load_lds((const unsigned*)((const char*)(gbase) + (voff)[_i]), (LAS unsigned*)(lds + (bufoff) + ldsw + _i * 8192), 16, 0, 0); } while (0)
; #define PG8_LDA(dst, b, h) do { _Pragma("unroll") for (int m = 0; m < 4; ++m) _Pragma("unroll") for (int k = 0; k < 2; ++k) dst[m][k] = *(const LAS bf16x8*)(lds + PG8_SA(b, h) + aoff + m * 2048 + k * 1024); } while (0)
; #define PG8_LDB(dst, b, h) do { _Pragma("unroll") for (int n = 0; n < 2; ++n) _Pragma("unroll") for (int k = 0; k < 2; ++k) dst[n][k] = *(const LAS bf16x8*)(lds + PG8_SB(b, h) + boff + n * 2048 + k * 1024); } while (0)
; #define PG8_MMA(ai, bj, At, Bt) do { __builtin_amdgcn_s_setprio(1); _Pragma("unroll") for (int m = 0; m < 4; ++m) _Pragma("unroll") for (int n = 0; n < 2; ++n) _Pragma("unroll") for (int k = 0; k < 2; ++k) \
;         acc[ai][bj][m][n] = __builtin_amdgcn_mfma_f32_16x16x32_bf16(Bt[n][k], At[m][k], acc[ai][bj][m][n], 0, 0, 0); __builtin_amdgcn_s_setprio(0); } while (0)
; #define PG8_WAIT_V(n) asm volatile("s_waitcnt vmcnt(" #n ")" ::: "memory")
; #define PG8_WAIT_L(n) asm volatile("s_waitcnt lgkmcnt(" #n ")" ::: "memory")
; #define PG8_BAR __builtin_amdgcn_s_barrier()
; #define PG8_SCHED __builtin_amdgcn_sched_barrier(0)
; template <class Epi>
; __device__ __forceinline__ void gemm_phase(LAS unsigned char* lds, const Gemm g, const StaticOrder S, const Epi E) {
;     ...
;             PG8_BAR; PG8_WAIT_L(0); PG8_MMA(1, 0, At, B0); PG8_BAR; PG8_SCHED;
;             PG8_STAGE(PG8_SB(0, 1), b2 + hstep, voffA);
;             PG8_WAIT_V(6); PG8_BAR; PG8_MMA(1, 1, At, B1); PG8_BAR;
;             PG8_LDB(B0, 1, 0); PG8_SCHED; PG8_LDA(At, 1, 0); PG8_STAGE(PG8_SA(0, 1), a2 + hstep, voffA);
;             PG8_WAIT_L(8); PG8_BAR; PG8_WAIT_L(0); PG8_MMA(0, 0, At, B0); PG8_BAR; PG8_SCHED;
;             PG8_LDB(B1, 1, 1); PG8_STAGE(PG8_SB(1, 0), b3, voffA);
;             PG8_BAR; PG8_WAIT_L(0); PG8_MMA(0, 1, At, B1); PG8_BAR;
	s_waitcnt lgkmcnt(0)
	s_setprio 1
	s_waitcnt lgkmcnt(0)
	v_mfma_f32_16x16x32_bf16 v[60:63], v[128:131], v[162:165], v[60:63]
	v_mfma_f32_16x16x32_bf16 v[56:59], v[136:139], v[162:165], v[56:59]
	v_mfma_f32_16x16x32_bf16 v[44:47], v[128:131], v[170:173], v[44:47]
	v_mfma_f32_16x16x32_bf16 v[40:43], v[136:139], v[170:173], v[40:43]
	v_mfma_f32_16x16x32_bf16 v[28:31], v[128:131], v[198:201], v[28:31]
	v_mfma_f32_16x16x32_bf16 v[24:27], v[136:139], v[198:201], v[24:27]
	v_mfma_f32_16x16x32_bf16 v[12:15], v[128:131], v[206:209], v[12:15]
	v_mfma_f32_16x16x32_bf16 v[8:11], v[136:139], v[206:209], v[8:11]
	v_mfma_f32_16x16x32_bf16 v[60:63], v[132:135], v[166:169], v[60:63]
	v_mfma_f32_16x16x32_bf16 v[56:59], v[150:153], v[166:169], v[56:59]
	v_mfma_f32_16x16x32_bf16 v[44:47], v[132:135], v[194:197], v[44:47]
	v_mfma_f32_16x16x32_bf16 v[40:43], v[150:153], v[194:197], v[40:43]
	v_mfma_f32_16x16x32_bf16 v[28:31], v[132:135], v[202:205], v[28:31]
	v_mfma_f32_16x16x32_bf16 v[24:27], v[150:153], v[202:205], v[24:27]
	v_mfma_f32_16x16x32_bf16 v[12:15], v[132:135], v[220:223], v[12:15]
	v_mfma_f32_16x16x32_bf16 v[8:11], v[150:153], v[220:223], v[8:11]
	s_setprio 0
	s_barrier
	s_mov_b32 m0, s44
	v_lshl_add_u64 v[128:129], s[58:59], 0, v[144:145]
	global_load_lds_dwordx4 v[128:129], off
	v_lshl_add_u64 v[128:129], s[58:59], 0, v[142:143]
	s_mov_b32 m0, s72
	s_nop 0
	global_load_lds_dwordx4 v[128:129], off
	s_waitcnt vmcnt(6)
	s_barrier
	s_setprio 1
	v_mfma_f32_16x16x32_bf16 v[52:55], v[228:231], v[162:165], v[52:55]
	v_mfma_f32_16x16x32_bf16 v[48:51], v[236:239], v[162:165], v[48:51]
	v_mfma_f32_16x16x32_bf16 v[36:39], v[228:231], v[170:173], v[36:39]
	v_mfma_f32_16x16x32_bf16 v[32:35], v[236:239], v[170:173], v[32:35]
	v_mfma_f32_16x16x32_bf16 v[20:23], v[228:231], v[198:201], v[20:23]
	v_mfma_f32_16x16x32_bf16 v[16:19], v[236:239], v[198:201], v[16:19]
	v_mfma_f32_16x16x32_bf16 v[4:7], v[228:231], v[206:209], v[4:7]
	v_mfma_f32_16x16x32_bf16 v[0:3], v[236:239], v[206:209], v[0:3]
	v_mfma_f32_16x16x32_bf16 v[52:55], v[232:235], v[166:169], v[52:55]
	v_mfma_f32_16x16x32_bf16 v[48:51], v[240:243], v[166:169], v[48:51]
	v_mfma_f32_16x16x32_bf16 v[36:39], v[232:235], v[194:197], v[36:39]
	v_mfma_f32_16x16x32_bf16 v[32:35], v[240:243], v[194:197], v[32:35]
	v_mfma_f32_16x16x32_bf16 v[20:23], v[232:235], v[202:205], v[20:23]
	v_mfma_f32_16x16x32_bf16 v[16:19], v[240:243], v[202:205], v[16:19]
	v_mfma_f32_16x16x32_bf16 v[4:7], v[232:235], v[220:223], v[4:7]
	v_mfma_f32_16x16x32_bf16 v[0:3], v[240:243], v[220:223], v[0:3]
	s_setprio 0
	s_barrier
	v_add_u32_e32 v150, vcc_lo, v155
	ds_read_b128 v[128:131], v150
	ds_read_b128 v[132:135], v150 offset:1024
	ds_read_b128 v[136:139], v150 offset:2048
	ds_read_b128 v[150:153], v150 offset:3072
	s_mov_b32 m0, s25
	v_lshl_add_u64 v[228:229], s[56:57], 0, v[144:145]
	ds_read_b128 v[162:165], v160 offset:32768
	ds_read_b128 v[166:169], v160 offset:33792
	ds_read_b128 v[170:173], v160 offset:34816
	ds_read_b128 v[194:197], v160 offset:35840
	ds_read_b128 v[198:201], v160 offset:36864
	ds_read_b128 v[202:205], v160 offset:37888
	ds_read_b128 v[206:209], v160 offset:38912
	ds_read_b128 v[220:223], v160 offset:39936
	global_load_lds_dwordx4 v[228:229], off
	v_lshl_add_u64 v[228:229], s[56:57], 0, v[142:143]
	s_mov_b32 m0, s66
	s_nop 0
	global_load_lds_dwordx4 v[228:229], off
	s_waitcnt lgkmcnt(8)
	s_barrier
	s_waitcnt lgkmcnt(0)
	s_setprio 1
	s_waitcnt lgkmcnt(0)
	v_mfma_f32_16x16x32_bf16 v[124:127], v[128:131], v[162:165], v[124:127]
	v_mfma_f32_16x16x32_bf16 v[120:123], v[136:139], v[162:165], v[120:123]
	v_mfma_f32_16x16x32_bf16 v[108:111], v[128:131], v[170:173], v[108:111]
	v_mfma_f32_16x16x32_bf16 v[104:107], v[136:139], v[170:173], v[104:107]
	v_mfma_f32_16x16x32_bf16 v[92:95], v[128:131], v[198:201], v[92:95]
	v_mfma_f32_16x16x32_bf16 v[88:91], v[136:139], v[198:201], v[88:91]
	v_mfma_f32_16x16x32_bf16 v[76:79], v[128:131], v[206:209], v[76:79]
	v_mfma_f32_16x16x32_bf16 v[72:75], v[136:139], v[206:209], v[72:75]
	v_mfma_f32_16x16x32_bf16 v[124:127], v[132:135], v[166:169], v[124:127]
	v_mfma_f32_16x16x32_bf16 v[120:123], v[150:153], v[166:169], v[120:123]
	v_mfma_f32_16x16x32_bf16 v[108:111], v[132:135], v[194:197], v[108:111]
	v_mfma_f32_16x16x32_bf16 v[104:107], v[150:153], v[194:197], v[104:107]
	v_mfma_f32_16x16x32_bf16 v[92:95], v[132:135], v[202:205], v[92:95]
	v_mfma_f32_16x16x32_bf16 v[88:91], v[150:153], v[202:205], v[88:91]
	v_mfma_f32_16x16x32_bf16 v[76:79], v[132:135], v[220:223], v[76:79]
	v_mfma_f32_16x16x32_bf16 v[72:75], v[150:153], v[220:223], v[72:75]
	s_setprio 0
	s_barrier
	s_mov_b32 m0, s29
	v_add_u32_e32 v161, s3, v155
	v_lshl_add_u64 v[140:141], v[140:141], 0, s[34:35]
	ds_read_b128 v[228:231], v161
	ds_read_b128 v[232:235], v161 offset:1024
	ds_read_b128 v[236:239], v161 offset:2048
	ds_read_b128 v[240:243], v161 offset:3072
	global_load_lds_dwordx4 v[140:141], off
	v_lshl_add_u64 v[140:141], v[174:175], 0, s[34:35]
	s_mov_b32 m0, s1
	s_nop 0
	global_load_lds_dwordx4 v[140:141], off
	s_barrier
; #define PG8_STAGE(bufoff, gbase, voff) do { _Pragma("unroll") for (int _i = 0; _i < 2; ++_i) \
;         __builtin_amdgcn_global_load_lds((const unsigned*)((const char*)(gbase) + (voff)[_i]), (LAS unsigned*)(lds + (bufoff) + ldsw + _i * 8192), 16, 0, 0); } while (0)
; #define PG8_LDA(dst, b, h) do { _Pragma("unroll") for (int m = 0; m < 4; ++m) _Pragma("unroll") for (int k = 0; k < 2; ++k) dst[m][k] = *(const LAS bf16x8*)(lds + PG8_SA(b, h) + aoff + m * 2048 + k * 1024); } while (0)
; #define PG8_MMA(ai, bj, At, Bt) do { __builtin_amdgcn_s_setprio(1); _Pragma("unroll") for (int m = 0; m < 4; ++m) _Pragma("unroll") for (int n = 0; n < 2; ++n) _Pragma("unroll") for (int k = 0; k < 2; ++k) \
;         acc[ai][bj][m][n] = __builtin_amdgcn_mfma_f32_16x16x32_bf16(Bt[n][k], At[m][k], acc[ai][bj][m][n], 0, 0, 0); __builtin_amdgcn_s_setprio(0); } while (0)
; #define PG8_WAIT_V(n) asm volatile("s_waitcnt vmcnt(" #n ")" ::: "memory")
; #define PG8_WAIT_L(n) asm volatile("s_waitcnt lgkmcnt(" #n ")" ::: "memory")
; #define PG8_BAR __builtin_amdgcn_s_barrier()
; #define PG8_SCHED __builtin_amdgcn_sched_barrier(0)
; template <class Epi>
; __device__ __forceinline__ void gemm_phase(LAS unsigned char* lds, const Gemm g, const StaticOrder S, const Epi E) {
;     ...
;             PG8_BAR; PG8_WAIT_L(0); PG8_MMA(0, 1, At, B1); PG8_BAR;
;             PG8_LDA(At, 1, 1); PG8_STAGE(PG8_SA(1, 0), a3, voffA);
;             PG8_BAR; PG8_WAIT_L(0); PG8_MMA(1, 0, At, B0); PG8_BAR; PG8_SCHED;
;             PG8_STAGE(PG8_SB(1, 1), b3 + hstep, voffA);
;             PG8_WAIT_V(6); PG8_BAR; PG8_MMA(1, 1, At, B1); PG8_BAR;
;     __device__ __forceinline__ void operator()(AccRef acc, const pg8::Unit& u, int wr, int wc, int fr, int fq) const {
;     ...
;         const bool rope = (u.pn == rope_pn) && (u.pm < 32);
; #pragma unroll
;         for (int ai = 0; ai < 2; ++ai)
; #pragma unroll
;             for (int m = 0; m < 4; ++m) { const int row = row0 + ai * 128 + m * 16; bf16_t* rowp = O + (size_t)row * ldc + col0;
;                 f32x4 cs = {1.f, 1.f, 1.f, 1.f}, sn = {0.f, 0.f, 0.f, 0.f};
;                 if (rope) { const int t = row & 2047; const int pos = (wc & 1) ? (t & 63) : (t >> 6); cs = *(const f32x4*)(cos64 + pos * 16 + 4 * fq); sn = *(const f32x4*)(sin64 + pos * 16 + 4 * fq); }
	s_waitcnt lgkmcnt(0)
	s_setprio 1
	s_waitcnt lgkmcnt(0)
	v_mfma_f32_16x16x32_bf16 v[116:119], v[228:231], v[162:165], v[116:119]
	v_mfma_f32_16x16x32_bf16 v[112:115], v[236:239], v[162:165], v[112:115]
	v_mfma_f32_16x16x32_bf16 v[100:103], v[228:231], v[170:173], v[100:103]
	v_mfma_f32_16x16x32_bf16 v[96:99], v[236:239], v[170:173], v[96:99]
	v_mfma_f32_16x16x32_bf16 v[84:87], v[228:231], v[198:201], v[84:87]
	v_mfma_f32_16x16x32_bf16 v[80:83], v[236:239], v[198:201], v[80:83]
	v_mfma_f32_16x16x32_bf16 v[68:71], v[228:231], v[206:209], v[68:71]
	v_mfma_f32_16x16x32_bf16 v[64:67], v[236:239], v[206:209], v[64:67]
	v_mfma_f32_16x16x32_bf16 v[116:119], v[232:235], v[166:169], v[116:119]
	v_mfma_f32_16x16x32_bf16 v[112:115], v[240:243], v[166:169], v[112:115]
	v_mfma_f32_16x16x32_bf16 v[100:103], v[232:235], v[194:197], v[100:103]
	v_mfma_f32_16x16x32_bf16 v[96:99], v[240:243], v[194:197], v[96:99]
	v_mfma_f32_16x16x32_bf16 v[84:87], v[232:235], v[202:205], v[84:87]
	v_mfma_f32_16x16x32_bf16 v[80:83], v[240:243], v[202:205], v[80:83]
	v_mfma_f32_16x16x32_bf16 v[68:71], v[232:235], v[220:223], v[68:71]
	v_mfma_f32_16x16x32_bf16 v[64:67], v[240:243], v[220:223], v[64:67]
	s_setprio 0
	s_barrier
	s_mov_b32 m0, s68
	v_lshl_add_u64 v[140:141], v[210:211], 0, s[34:35]
	ds_read_b128 v[162:165], v160 offset:49152
	ds_read_b128 v[166:169], v160 offset:50176
	ds_read_b128 v[170:173], v160 offset:51200
	ds_read_b128 v[194:197], v160 offset:52224
	ds_read_b128 v[198:201], v160 offset:53248
	ds_read_b128 v[202:205], v160 offset:54272
	ds_read_b128 v[206:209], v160 offset:55296
	ds_read_b128 v[220:223], v160 offset:56320
	global_load_lds_dwordx4 v[140:141], off
	v_lshl_add_u64 v[140:141], v[244:245], 0, s[34:35]
	s_mov_b32 m0, s69
	s_nop 0
	global_load_lds_dwordx4 v[140:141], off
	s_barrier
	s_waitcnt lgkmcnt(0)
	s_setprio 1
	s_waitcnt lgkmcnt(0)
	v_mfma_f32_16x16x32_bf16 v[60:63], v[128:131], v[162:165], v[60:63]
	v_mfma_f32_16x16x32_bf16 v[56:59], v[136:139], v[162:165], v[56:59]
	v_mfma_f32_16x16x32_bf16 v[44:47], v[128:131], v[170:173], v[44:47]
	v_mfma_f32_16x16x32_bf16 v[40:43], v[136:139], v[170:173], v[40:43]
	v_mfma_f32_16x16x32_bf16 v[28:31], v[128:131], v[198:201], v[28:31]
	v_mfma_f32_16x16x32_bf16 v[24:27], v[136:139], v[198:201], v[24:27]
	v_mfma_f32_16x16x32_bf16 v[12:15], v[128:131], v[206:209], v[12:15]
	v_mfma_f32_16x16x32_bf16 v[8:11], v[136:139], v[206:209], v[8:11]
	v_mfma_f32_16x16x32_bf16 v[60:63], v[132:135], v[166:169], v[60:63]
	v_mfma_f32_16x16x32_bf16 v[56:59], v[150:153], v[166:169], v[56:59]
	v_mfma_f32_16x16x32_bf16 v[44:47], v[132:135], v[194:197], v[44:47]
	v_mfma_f32_16x16x32_bf16 v[40:43], v[150:153], v[194:197], v[40:43]
	v_mfma_f32_16x16x32_bf16 v[28:31], v[132:135], v[202:205], v[28:31]
	v_mfma_f32_16x16x32_bf16 v[24:27], v[150:153], v[202:205], v[24:27]
	v_mfma_f32_16x16x32_bf16 v[12:15], v[132:135], v[220:223], v[12:15]
	v_mfma_f32_16x16x32_bf16 v[8:11], v[150:153], v[220:223], v[8:11]
	s_setprio 0
	s_barrier
	s_mov_b32 m0, s45
	v_lshl_add_u64 v[128:129], s[54:55], 0, v[144:145]
	global_load_lds_dwordx4 v[128:129], off
	v_lshl_add_u64 v[128:129], s[54:55], 0, v[142:143]
	s_mov_b32 m0, s30
	s_nop 0
	global_load_lds_dwordx4 v[128:129], off
	s_waitcnt vmcnt(6)
	s_barrier
	s_setprio 1
	v_mfma_f32_16x16x32_bf16 v[52:55], v[228:231], v[162:165], v[52:55]
	v_mfma_f32_16x16x32_bf16 v[48:51], v[236:239], v[162:165], v[48:51]
	v_mfma_f32_16x16x32_bf16 v[36:39], v[228:231], v[170:173], v[36:39]
	v_mfma_f32_16x16x32_bf16 v[32:35], v[236:239], v[170:173], v[32:35]
	v_mfma_f32_16x16x32_bf16 v[20:23], v[228:231], v[198:201], v[20:23]
	v_mfma_f32_16x16x32_bf16 v[16:19], v[236:239], v[198:201], v[16:19]
	v_mfma_f32_16x16x32_bf16 v[4:7], v[228:231], v[206:209], v[4:7]
	v_mfma_f32_16x16x32_bf16 v[0:3], v[236:239], v[206:209], v[0:3]
	v_mfma_f32_16x16x32_bf16 v[52:55], v[232:235], v[166:169], v[52:55]
	v_mfma_f32_16x16x32_bf16 v[48:51], v[240:243], v[166:169], v[48:51]
	v_mfma_f32_16x16x32_bf16 v[36:39], v[232:235], v[194:197], v[36:39]
	v_mfma_f32_16x16x32_bf16 v[32:35], v[240:243], v[194:197], v[32:35]
	v_mfma_f32_16x16x32_bf16 v[20:23], v[232:235], v[202:205], v[20:23]
	v_mfma_f32_16x16x32_bf16 v[16:19], v[240:243], v[202:205], v[16:19]
	v_mfma_f32_16x16x32_bf16 v[4:7], v[232:235], v[220:223], v[4:7]
	v_mfma_f32_16x16x32_bf16 v[0:3], v[240:243], v[220:223], v[0:3]
	s_setprio 0
	s_barrier
	s_movk_i32 s1, 0x100
	s_andn2_b64 vcc, exec, s[52:53]
	s_mov_b64 s[54:55], -1
	s_mov_b64 s[52:53], 0
	s_cbranch_vccz .LBB0_3306
	s_lshl_b32 s3, s28, 8
	s_add_i32 s3, s3, s67
	s_cmp_eq_u32 s27, -1
	s_cselect_b64 s[30:31], -1, 0
	s_cmp_lt_i32 s28, 32
	s_cselect_b64 s[28:29], -1, 0
	s_and_b64 s[28:29], s[30:31], s[28:29]
	v_cndmask_b32_e64 v129, 0, 1, s[28:29]
	s_bfe_u32 s1, s3, 0x50006
	v_mov_b32_e32 v128, 1.0
	v_mov_b32_e32 v132, 0
	v_cmp_ne_u32_e64 s[42:43], 1, v129
	s_andn2_b64 vcc, exec, s[28:29]
	v_mov_b32_e32 v134, 0
	v_mov_b32_e32 v135, 0
	v_mov_b32_e32 v136, 0
	v_mov_b32_e32 v137, 0
	v_mov_b32_e32 v138, 1.0
	v_mov_b32_e32 v139, 1.0
	v_mov_b32_e32 v140, 1.0
	v_mov_b32_e32 v141, 1.0
	s_cbranch_vccnz .LBB0_3309
	v_mov_b32_e32 v129, s1
	v_cndmask_b32_e64 v129, v154, v129, s[38:39]
	v_lshlrev_b32_e32 v178, 6, v129
	v_lshl_add_u64 v[130:131], v[148:149], 0, v[178:179]
	v_lshl_add_u64 v[134:135], v[146:147], 0, v[178:179]
	global_load_dwordx4 v[138:141], v[130:131], off
	s_nop 0
	global_load_dwordx4 v[134:137], v[134:135], off

;     __device__ __forceinline__ void operator()(AccRef acc, const pg8::Unit& u, int wr, int wc, int fr, int fq) const {
;     ...
; #pragma unroll
;                 for (int mm = 0; mm < 2; ++mm)
; #pragma unroll
;                     for (int bj = 0; bj < 2; ++bj)
; #pragma unroll
;                         for (int n = 0; n < 2; ++n) { const int m = 2 * mp + mm; const f32x4 d = gv[bj][n] * acc[ai][bj][m][n];
;                             *(f32x4*)(base + (size_t)(row0 + ai * 128 + m * 16) * DM + col0 + bj * 128 + n * 16) = part ? d : old[mm][bj][n] + d; }
.LBB0_3559:
	v_pk_mul_f32 v[36:37], v[30:31], v[134:135]
	v_pk_mul_f32 v[38:39], v[28:29], v[132:133]
	s_waitcnt vmcnt(0)
	v_pk_fma_f32 v[30:31], v[30:31], v[134:135], v[174:175]
	v_pk_fma_f32 v[28:29], v[28:29], v[132:133], v[172:173]
	v_lshl_add_u64 v[34:35], v[200:201], 0, v[34:35]
	v_cndmask_b32_e64 v31, v37, v31, s[38:39]
	v_cndmask_b32_e64 v30, v36, v30, s[38:39]
	v_cndmask_b32_e64 v29, v39, v29, s[38:39]
	v_cndmask_b32_e64 v28, v38, v28, s[38:39]
	global_store_dwordx4 v[34:35], v[28:31], off sc0 sc1
	s_and_b64 vcc, exec, s[48:49]
	s_mov_b32 s54, s27
	v_pk_mul_f32 v[28:29], v[26:27], v[130:131]
	v_pk_mul_f32 v[30:31], v[24:25], v[128:129]
	v_pk_fma_f32 v[26:27], v[26:27], v[130:131], v[170:171]
	v_pk_fma_f32 v[24:25], v[24:25], v[128:129], v[168:169]
	v_cndmask_b32_e64 v27, v29, v27, s[38:39]
	v_cndmask_b32_e64 v26, v28, v26, s[38:39]
	v_cndmask_b32_e64 v25, v31, v25, s[38:39]
	v_cndmask_b32_e64 v24, v30, v24, s[38:39]
	global_store_dwordx4 v[34:35], v[24:27], off offset:64 sc0 sc1
	s_mov_b32 s41, s28
	s_mov_b32 s40, s42
	v_pk_mul_f32 v[24:25], v[22:23], v[126:127]
	v_pk_mul_f32 v[26:27], v[20:21], v[124:125]
	v_pk_fma_f32 v[22:23], v[22:23], v[126:127], v[166:167]
	v_pk_fma_f32 v[20:21], v[20:21], v[124:125], v[164:165]
	v_cndmask_b32_e64 v23, v25, v23, s[38:39]
	v_cndmask_b32_e64 v22, v24, v22, s[38:39]
	v_cndmask_b32_e64 v21, v27, v21, s[38:39]
	v_cndmask_b32_e64 v20, v26, v20, s[38:39]
	global_store_dwordx4 v[34:35], v[20:23], off offset:512 sc0 sc1
	s_mov_b64 s[58:59], s[52:53]
	s_mov_b64 s[56:57], s[50:51]
	v_pk_mul_f32 v[20:21], v[14:15], v[118:119]
	v_pk_mul_f32 v[22:23], v[12:13], v[116:117]
	v_pk_fma_f32 v[14:15], v[14:15], v[118:119], v[158:159]
	v_pk_fma_f32 v[12:13], v[12:13], v[116:117], v[156:157]
	v_cndmask_b32_e64 v15, v21, v15, s[38:39]
	v_cndmask_b32_e64 v14, v20, v14, s[38:39]
	v_cndmask_b32_e64 v13, v23, v13, s[38:39]
	v_cndmask_b32_e64 v12, v22, v12, s[38:39]
	global_store_dwordx4 v[34:35], v[12:15], off offset:576 sc0 sc1
	v_pk_mul_f32 v[22:23], v[16:17], v[132:133]
	v_pk_fma_f32 v[16:17], v[16:17], v[132:133], v[160:161]
	v_pk_mul_f32 v[12:13], v[18:19], v[134:135]
	v_pk_fma_f32 v[14:15], v[18:19], v[134:135], v[162:163]
	v_lshl_add_u64 v[20:21], v[200:201], 0, v[32:33]
	v_cndmask_b32_e64 v15, v13, v15, s[38:39]
	v_cndmask_b32_e64 v14, v12, v14, s[38:39]
	v_cndmask_b32_e64 v13, v23, v17, s[38:39]
	v_cndmask_b32_e64 v12, v22, v16, s[38:39]
	global_store_dwordx4 v[20:21], v[12:15], off sc0 sc1
	s_mov_b32 s30, s26
	s_nop 0
	v_pk_mul_f32 v[12:13], v[10:11], v[130:131]
	v_pk_mul_f32 v[14:15], v[8:9], v[128:129]
	v_pk_fma_f32 v[10:11], v[10:11], v[130:131], v[154:155]
	v_pk_fma_f32 v[8:9], v[8:9], v[128:129], v[152:153]
	v_cndmask_b32_e64 v11, v13, v11, s[38:39]
	v_cndmask_b32_e64 v10, v12, v10, s[38:39]
	v_cndmask_b32_e64 v9, v15, v9, s[38:39]
	v_cndmask_b32_e64 v8, v14, v8, s[38:39]
	global_store_dwordx4 v[20:21], v[8:11], off offset:64 sc0 sc1
	s_nop 1
	v_pk_mul_f32 v[8:9], v[6:7], v[126:127]
	v_pk_mul_f32 v[10:11], v[4:5], v[124:125]
	v_pk_fma_f32 v[6:7], v[6:7], v[126:127], v[150:151]
	v_pk_fma_f32 v[4:5], v[4:5], v[124:125], v[148:149]
	v_cndmask_b32_e64 v7, v9, v7, s[38:39]
	v_cndmask_b32_e64 v6, v8, v6, s[38:39]
	v_cndmask_b32_e64 v5, v11, v5, s[38:39]
	v_cndmask_b32_e64 v4, v10, v4, s[38:39]
	global_store_dwordx4 v[20:21], v[4:7], off offset:512 sc0 sc1
	s_nop 1
	v_pk_mul_f32 v[4:5], v[2:3], v[118:119]
	v_pk_mul_f32 v[6:7], v[0:1], v[116:117]
	v_pk_fma_f32 v[2:3], v[2:3], v[118:119], v[146:147]
	v_pk_fma_f32 v[0:1], v[0:1], v[116:117], v[144:145]
	v_cndmask_b32_e64 v3, v5, v3, s[38:39]
	v_cndmask_b32_e64 v2, v4, v2, s[38:39]
	v_cndmask_b32_e64 v1, v7, v1, s[38:39]
	v_cndmask_b32_e64 v0, v6, v0, s[38:39]
	s_mov_b32 s39, s29
	s_mov_b32 s38, s44
	global_store_dwordx4 v[20:21], v[0:3], off offset:576 sc0 sc1
	s_cbranch_vccnz .LBB0_3589

; #define PG8_STAGE(bufoff, gbase, voff) do { _Pragma("unroll") for (int _i = 0; _i < 2; ++_i) \
;         __builtin_amdgcn_global_load_lds((const unsigned*)((const char*)(gbase) + (voff)[_i]), (LAS unsigned*)(lds + (bufoff) + ldsw + _i * 8192), 16, 0, 0); } while (0)
; #define PG8_LDA(dst, b, h) do { _Pragma("unroll") for (int m = 0; m < 4; ++m) _Pragma("unroll") for (int k = 0; k < 2; ++k) dst[m][k] = *(const LAS bf16x8*)(lds + PG8_SA(b, h) + aoff + m * 2048 + k * 1024); } while (0)
; #define PG8_LDB(dst, b, h) do { _Pragma("unroll") for (int n = 0; n < 2; ++n) _Pragma("unroll") for (int k = 0; k < 2; ++k) dst[n][k] = *(const LAS bf16x8*)(lds + PG8_SB(b, h) + boff + n * 2048 + k * 1024); } while (0)
; #define PG8_MMA(ai, bj, At, Bt) do { __builtin_amdgcn_s_setprio(1); _Pragma("unroll") for (int m = 0; m < 4; ++m) _Pragma("unroll") for (int n = 0; n < 2; ++n) _Pragma("unroll") for (int k = 0; k < 2; ++k) \
;         acc[ai][bj][m][n] = __builtin_amdgcn_mfma_f32_16x16x32_bf16(Bt[n][k], At[m][k], acc[ai][bj][m][n], 0, 0, 0); __builtin_amdgcn_s_setprio(0); } while (0)
; #define PG8_WAIT_L(n) asm volatile("s_waitcnt lgkmcnt(" #n ")" ::: "memory")
; #define PG8_BAR __builtin_amdgcn_s_barrier()
; #define PG8_SCHED __builtin_amdgcn_sched_barrier(0)
; template <class Epi>
; __device__ __forceinline__ void gemm_phase(LAS unsigned char* lds, const Gemm g, const StaticOrder S, const Epi E) {
;     ...
;         for (int t = 0; t < nt; t += 2) {
;             const bool last = (t == nt - 2);
;             const char* a1 = cA + (size_t)(t + 1) * kstep;
;             const char* a2 = last ? nA : cA + (size_t)(t + 2) * kstep; const char* b2 = last ? nB : cB + (size_t)(t + 2) * kstep;
;             const char* a3 = a2 + kstep; const char* b3 = b2 + kstep;
;             PG8_LDB(B0, 0, 0); PG8_SCHED; PG8_LDA(At, 0, 0); PG8_STAGE(PG8_SA(1, 1), a1 + hstep, voffA);
;             PG8_WAIT_L(8); PG8_BAR; PG8_WAIT_L(0); PG8_MMA(0, 0, At, B0); PG8_BAR; PG8_SCHED;
;             PG8_LDB(B1, 0, 1); PG8_STAGE(PG8_SB(0, 0), b2, voffA);
;             PG8_BAR; PG8_WAIT_L(0); PG8_MMA(0, 1, At, B1); PG8_BAR;
;             PG8_LDA(At, 0, 1); PG8_STAGE(PG8_SA(0, 0), a2, voffA);
;             PG8_BAR; PG8_WAIT_L(0); PG8_MMA(1, 0, At, B0); PG8_BAR; PG8_SCHED;
.LBB0_3568:
	s_add_i32 vcc_lo, s55, 2
	s_add_u32 s58, s56, 0x100
	s_addc_u32 s59, s57, 0
	s_add_i32 s14, 0, 0x10000
	v_add_u32_e32 v132, s14, v228
	ds_read_b128 v[116:119], v132
	ds_read_b128 v[124:127], v132 offset:1024
	ds_read_b128 v[128:131], v132 offset:2048
	ds_read_b128 v[132:135], v132 offset:3072
	s_cmp_eq_u32 s43, s55
	s_cselect_b32 s63, s51, s59
	s_cselect_b32 s62, s50, s58
	s_cselect_b32 s61, s53, s47
	s_cselect_b32 s60, s52, s45
	v_lshl_add_u64 v[200:201], s[56:57], 0, v[196:197]
	s_add_i32 m0, s25, 0xc000
	ds_read_b128 v[144:147], v230
	ds_read_b128 v[148:151], v230 offset:1024
	ds_read_b128 v[152:155], v230 offset:2048
	ds_read_b128 v[156:159], v230 offset:3072
	ds_read_b128 v[160:163], v230 offset:4096
	ds_read_b128 v[164:167], v230 offset:5120
	ds_read_b128 v[168:171], v230 offset:6144
	ds_read_b128 v[172:175], v230 offset:7168
	global_load_lds_dwordx4 v[200:201], off
	v_lshl_add_u64 v[200:201], s[56:57], 0, v[198:199]
	s_add_i32 m0, s25, 0xe000
	s_nop 0
	global_load_lds_dwordx4 v[200:201], off
	s_waitcnt lgkmcnt(8)
	s_barrier
	s_waitcnt lgkmcnt(0)
	s_setprio 1
	s_waitcnt lgkmcnt(0)
	v_mfma_f32_16x16x32_bf16 v[140:143], v[116:119], v[144:147], v[140:143]
	v_mfma_f32_16x16x32_bf16 v[136:139], v[128:131], v[144:147], v[136:139]
	v_mfma_f32_16x16x32_bf16 v[112:115], v[116:119], v[152:155], v[112:115]
	v_mfma_f32_16x16x32_bf16 v[104:107], v[128:131], v[152:155], v[104:107]
	v_mfma_f32_16x16x32_bf16 v[92:95], v[116:119], v[160:163], v[92:95]
	v_mfma_f32_16x16x32_bf16 v[88:91], v[128:131], v[160:163], v[88:91]
	v_mfma_f32_16x16x32_bf16 v[80:83], v[116:119], v[168:171], v[80:83]
	v_mfma_f32_16x16x32_bf16 v[72:75], v[128:131], v[168:171], v[72:75]
	v_mfma_f32_16x16x32_bf16 v[140:143], v[124:127], v[148:151], v[140:143]
	v_mfma_f32_16x16x32_bf16 v[136:139], v[132:135], v[148:151], v[136:139]
	v_mfma_f32_16x16x32_bf16 v[112:115], v[124:127], v[156:159], v[112:115]
	v_mfma_f32_16x16x32_bf16 v[104:107], v[132:135], v[156:159], v[104:107]
	v_mfma_f32_16x16x32_bf16 v[92:95], v[124:127], v[164:167], v[92:95]
	v_mfma_f32_16x16x32_bf16 v[88:91], v[132:135], v[164:167], v[88:91]
	v_mfma_f32_16x16x32_bf16 v[80:83], v[124:127], v[172:175], v[80:83]
	v_mfma_f32_16x16x32_bf16 v[72:75], v[132:135], v[172:175], v[72:75]
	s_setprio 0
	s_barrier
	s_add_i32 s55, 0, 0x14000
	s_add_i32 s14, s14, s24
	v_add_u32_e32 v220, s55, v228
	v_lshl_add_u64 v[232:233], s[60:61], 0, v[178:179]
	s_mov_b32 m0, s14
	ds_read_b128 v[200:203], v220
	ds_read_b128 v[204:207], v220 offset:1024
	ds_read_b128 v[208:211], v220 offset:2048
	ds_read_b128 v[220:223], v220 offset:3072
	global_load_lds_dwordx4 v[232:233], off
	v_lshl_add_u64 v[234:235], s[60:61], 0, v[194:195]
	s_add_i32 m0, s14, 0x2000
	s_nop 0
	global_load_lds_dwordx4 v[234:235], off
	s_barrier
	s_waitcnt lgkmcnt(0)
	s_setprio 1
	s_waitcnt lgkmcnt(0)
	v_mfma_f32_16x16x32_bf16 v[120:123], v[200:203], v[144:147], v[120:123]
	v_mfma_f32_16x16x32_bf16 v[108:111], v[208:211], v[144:147], v[108:111]
	v_mfma_f32_16x16x32_bf16 v[100:103], v[200:203], v[152:155], v[100:103]
	v_mfma_f32_16x16x32_bf16 v[96:99], v[208:211], v[152:155], v[96:99]
	v_mfma_f32_16x16x32_bf16 v[84:87], v[200:203], v[160:163], v[84:87]
	v_mfma_f32_16x16x32_bf16 v[76:79], v[208:211], v[160:163], v[76:79]
	v_mfma_f32_16x16x32_bf16 v[68:71], v[200:203], v[168:171], v[68:71]
	v_mfma_f32_16x16x32_bf16 v[64:67], v[208:211], v[168:171], v[64:67]
	v_mfma_f32_16x16x32_bf16 v[120:123], v[204:207], v[148:151], v[120:123]
	v_mfma_f32_16x16x32_bf16 v[108:111], v[220:223], v[148:151], v[108:111]
	v_mfma_f32_16x16x32_bf16 v[100:103], v[204:207], v[156:159], v[100:103]
	v_mfma_f32_16x16x32_bf16 v[96:99], v[220:223], v[156:159], v[96:99]
	v_mfma_f32_16x16x32_bf16 v[84:87], v[204:207], v[164:167], v[84:87]
	v_mfma_f32_16x16x32_bf16 v[76:79], v[220:223], v[164:167], v[76:79]
	v_mfma_f32_16x16x32_bf16 v[68:71], v[204:207], v[172:175], v[68:71]
	v_mfma_f32_16x16x32_bf16 v[64:67], v[220:223], v[172:175], v[64:67]
	s_setprio 0
	s_barrier
	s_mov_b32 m0, s25
	v_lshl_add_u64 v[236:237], s[62:63], 0, v[178:179]
	ds_read_b128 v[144:147], v230 offset:16384
	ds_read_b128 v[148:151], v230 offset:17408
	ds_read_b128 v[152:155], v230 offset:18432
	ds_read_b128 v[156:159], v230 offset:19456
	ds_read_b128 v[160:163], v230 offset:20480
	ds_read_b128 v[164:167], v230 offset:21504
	ds_read_b128 v[168:171], v230 offset:22528
	ds_read_b128 v[172:175], v230 offset:23552
	global_load_lds_dwordx4 v[236:237], off
	v_lshl_add_u64 v[238:239], s[62:63], 0, v[194:195]
	s_mov_b32 m0, s64
	s_nop 0
	global_load_lds_dwordx4 v[238:239], off
	s_barrier
	s_waitcnt lgkmcnt(0)
	s_setprio 1
	s_waitcnt lgkmcnt(0)
	v_mfma_f32_16x16x32_bf16 v[60:63], v[116:119], v[144:147], v[60:63]
	v_mfma_f32_16x16x32_bf16 v[56:59], v[128:131], v[144:147], v[56:59]
	v_mfma_f32_16x16x32_bf16 v[48:51], v[116:119], v[152:155], v[48:51]
	v_mfma_f32_16x16x32_bf16 v[40:43], v[128:131], v[152:155], v[40:43]
	v_mfma_f32_16x16x32_bf16 v[28:31], v[116:119], v[160:163], v[28:31]
	v_mfma_f32_16x16x32_bf16 v[24:27], v[128:131], v[160:163], v[24:27]
	v_mfma_f32_16x16x32_bf16 v[16:19], v[116:119], v[168:171], v[16:19]
	v_mfma_f32_16x16x32_bf16 v[8:11], v[128:131], v[168:171], v[8:11]
	v_mfma_f32_16x16x32_bf16 v[60:63], v[124:127], v[148:151], v[60:63]
	v_mfma_f32_16x16x32_bf16 v[56:59], v[132:135], v[148:151], v[56:59]
	v_mfma_f32_16x16x32_bf16 v[48:51], v[124:127], v[156:159], v[48:51]
	v_mfma_f32_16x16x32_bf16 v[40:43], v[132:135], v[156:159], v[40:43]
	v_mfma_f32_16x16x32_bf16 v[28:31], v[124:127], v[164:167], v[28:31]
	v_mfma_f32_16x16x32_bf16 v[24:27], v[132:135], v[164:167], v[24:27]
	v_mfma_f32_16x16x32_bf16 v[16:19], v[124:127], v[172:175], v[16:19]
	v_mfma_f32_16x16x32_bf16 v[8:11], v[132:135], v[172:175], v[8:11]
	s_setprio 0
	s_barrier
; #define PG8_STAGE(bufoff, gbase, voff) do { _Pragma("unroll") for (int _i = 0; _i < 2; ++_i) \
;         __builtin_amdgcn_global_load_lds((const unsigned*)((const char*)(gbase) + (voff)[_i]), (LAS unsigned*)(lds + (bufoff) + ldsw + _i * 8192), 16, 0, 0); } while (0)
; #define PG8_LDA(dst, b, h) do { _Pragma("unroll") for (int m = 0; m < 4; ++m) _Pragma("unroll") for (int k = 0; k < 2; ++k) dst[m][k] = *(const LAS bf16x8*)(lds + PG8_SA(b, h) + aoff + m * 2048 + k * 1024); } while (0)
; #define PG8_LDB(dst, b, h) do { _Pragma("unroll") for (int n = 0; n < 2; ++n) _Pragma("unroll") for (int k = 0; k < 2; ++k) dst[n][k] = *(const LAS bf16x8*)(lds + PG8_SB(b, h) + boff + n * 2048 + k * 1024); } while (0)
; #define PG8_MMA(ai, bj, At, Bt) do { __builtin_amdgcn_s_setprio(1); _Pragma("unroll") for (int m = 0; m < 4; ++m) _Pragma("unroll") for (int n = 0; n < 2; ++n) _Pragma("unroll") for (int k = 0; k < 2; ++k) \
;         acc[ai][bj][m][n] = __builtin_amdgcn_mfma_f32_16x16x32_bf16(Bt[n][k], At[m][k], acc[ai][bj][m][n], 0, 0, 0); __builtin_amdgcn_s_setprio(0); } while (0)
; #define PG8_WAIT_V(n) asm volatile("s_waitcnt vmcnt(" #n ")" ::: "memory")
; #define PG8_WAIT_L(n) asm volatile("s_waitcnt lgkmcnt(" #n ")" ::: "memory")
; #define PG8_BAR __builtin_amdgcn_s_barrier()
; #define PG8_SCHED __builtin_amdgcn_sched_barrier(0)
; template <class Epi>
; __device__ __forceinline__ void gemm_phase(LAS unsigned char* lds, const Gemm g, const StaticOrder S, const Epi E) {
;     ...
;             PG8_STAGE(PG8_SB(0, 1), b2 + hstep, voffA);
;             PG8_WAIT_V(6); PG8_BAR; PG8_MMA(1, 1, At, B1); PG8_BAR;
;             PG8_LDB(B0, 1, 0); PG8_SCHED; PG8_LDA(At, 1, 0); PG8_STAGE(PG8_SA(0, 1), a2 + hstep, voffA);
;             PG8_WAIT_L(8); PG8_BAR; PG8_WAIT_L(0); PG8_MMA(0, 0, At, B0); PG8_BAR; PG8_SCHED;
;             PG8_LDB(B1, 1, 1); PG8_STAGE(PG8_SB(1, 0), b3, voffA);
;             PG8_BAR; PG8_WAIT_L(0); PG8_MMA(0, 1, At, B1); PG8_BAR;
	s_add_u32 s30, s60, 0x80000
	s_addc_u32 s31, s61, 0
	s_add_i32 s14, s55, s24
	v_lshl_add_u64 v[116:117], s[30:31], 0, v[178:179]
	s_mov_b32 m0, s14
	s_nop 0
	global_load_lds_dwordx4 v[116:117], off
	v_lshl_add_u64 v[116:117], s[30:31], 0, v[194:195]
	s_add_i32 m0, s14, 0x2000
	s_nop 0
	global_load_lds_dwordx4 v[116:117], off
	s_waitcnt vmcnt(6)
	s_barrier
	s_setprio 1
	v_mfma_f32_16x16x32_bf16 v[52:55], v[200:203], v[144:147], v[52:55]
	v_mfma_f32_16x16x32_bf16 v[44:47], v[208:211], v[144:147], v[44:47]
	v_mfma_f32_16x16x32_bf16 v[36:39], v[200:203], v[152:155], v[36:39]
	v_mfma_f32_16x16x32_bf16 v[32:35], v[208:211], v[152:155], v[32:35]
	v_mfma_f32_16x16x32_bf16 v[20:23], v[200:203], v[160:163], v[20:23]
	v_mfma_f32_16x16x32_bf16 v[12:15], v[208:211], v[160:163], v[12:15]
	v_mfma_f32_16x16x32_bf16 v[4:7], v[200:203], v[168:171], v[4:7]
	v_mfma_f32_16x16x32_bf16 v[0:3], v[208:211], v[168:171], v[0:3]
	v_mfma_f32_16x16x32_bf16 v[52:55], v[204:207], v[148:151], v[52:55]
	v_mfma_f32_16x16x32_bf16 v[44:47], v[220:223], v[148:151], v[44:47]
	v_mfma_f32_16x16x32_bf16 v[36:39], v[204:207], v[156:159], v[36:39]
	v_mfma_f32_16x16x32_bf16 v[32:35], v[220:223], v[156:159], v[32:35]
	v_mfma_f32_16x16x32_bf16 v[20:23], v[204:207], v[164:167], v[20:23]
	v_mfma_f32_16x16x32_bf16 v[12:15], v[220:223], v[164:167], v[12:15]
	v_mfma_f32_16x16x32_bf16 v[4:7], v[204:207], v[172:175], v[4:7]
	v_mfma_f32_16x16x32_bf16 v[0:3], v[220:223], v[172:175], v[0:3]
	s_setprio 0
	s_barrier
	s_add_i32 s14, 0, 0x18000
	v_add_u32_e32 v132, s14, v228
	ds_read_b128 v[116:119], v132
	ds_read_b128 v[124:127], v132 offset:1024
	ds_read_b128 v[128:131], v132 offset:2048
	ds_read_b128 v[132:135], v132 offset:3072
	s_add_u32 s30, s62, 0x80000
	s_addc_u32 s31, s63, 0
	s_mov_b32 m0, s65
	v_lshl_add_u64 v[200:201], s[30:31], 0, v[178:179]
	ds_read_b128 v[144:147], v230 offset:32768
	ds_read_b128 v[148:151], v230 offset:33792
	ds_read_b128 v[152:155], v230 offset:34816
	ds_read_b128 v[156:159], v230 offset:35840
	ds_read_b128 v[160:163], v230 offset:36864
	ds_read_b128 v[164:167], v230 offset:37888
	ds_read_b128 v[168:171], v230 offset:38912
	ds_read_b128 v[172:175], v230 offset:39936
	global_load_lds_dwordx4 v[200:201], off
	v_lshl_add_u64 v[200:201], s[30:31], 0, v[194:195]
	s_mov_b32 m0, s66
	s_nop 0
	global_load_lds_dwordx4 v[200:201], off
	s_waitcnt lgkmcnt(8)
	s_barrier
	s_waitcnt lgkmcnt(0)
	s_setprio 1
	s_waitcnt lgkmcnt(0)
	v_mfma_f32_16x16x32_bf16 v[140:143], v[116:119], v[144:147], v[140:143]
	v_mfma_f32_16x16x32_bf16 v[136:139], v[128:131], v[144:147], v[136:139]
	v_mfma_f32_16x16x32_bf16 v[112:115], v[116:119], v[152:155], v[112:115]
	v_mfma_f32_16x16x32_bf16 v[104:107], v[128:131], v[152:155], v[104:107]
	v_mfma_f32_16x16x32_bf16 v[92:95], v[116:119], v[160:163], v[92:95]
	v_mfma_f32_16x16x32_bf16 v[88:91], v[128:131], v[160:163], v[88:91]
	v_mfma_f32_16x16x32_bf16 v[80:83], v[116:119], v[168:171], v[80:83]
	v_mfma_f32_16x16x32_bf16 v[72:75], v[128:131], v[168:171], v[72:75]
	v_mfma_f32_16x16x32_bf16 v[140:143], v[124:127], v[148:151], v[140:143]
	v_mfma_f32_16x16x32_bf16 v[136:139], v[132:135], v[148:151], v[136:139]
	v_mfma_f32_16x16x32_bf16 v[112:115], v[124:127], v[156:159], v[112:115]
	v_mfma_f32_16x16x32_bf16 v[104:107], v[132:135], v[156:159], v[104:107]
	v_mfma_f32_16x16x32_bf16 v[92:95], v[124:127], v[164:167], v[92:95]
	v_mfma_f32_16x16x32_bf16 v[88:91], v[132:135], v[164:167], v[88:91]
	v_mfma_f32_16x16x32_bf16 v[80:83], v[124:127], v[172:175], v[80:83]
	v_mfma_f32_16x16x32_bf16 v[72:75], v[132:135], v[172:175], v[72:75]
	s_setprio 0
	s_barrier
	s_add_i32 s55, 0, 0x1c000
	s_add_i32 s14, s14, s24
	v_add_u32_e32 v220, s55, v228
	v_lshl_add_u64 v[232:233], v[232:233], 0, s[34:35]
	s_mov_b32 m0, s14
	ds_read_b128 v[200:203], v220
	ds_read_b128 v[204:207], v220 offset:1024
	ds_read_b128 v[208:211], v220 offset:2048
	ds_read_b128 v[220:223], v220 offset:3072
	global_load_lds_dwordx4 v[232:233], off
	v_lshl_add_u64 v[232:233], v[234:235], 0, s[34:35]
	s_add_i32 m0, s14, 0x2000
	s_nop 0
	global_load_lds_dwordx4 v[232:233], off
	s_barrier
; #define PG8_STAGE(bufoff, gbase, voff) do { _Pragma("unroll") for (int _i = 0; _i < 2; ++_i) \
;         __builtin_amdgcn_global_load_lds((const unsigned*)((const char*)(gbase) + (voff)[_i]), (LAS unsigned*)(lds + (bufoff) + ldsw + _i * 8192), 16, 0, 0); } while (0)
; #define PG8_LDA(dst, b, h) do { _Pragma("unroll") for (int m = 0; m < 4; ++m) _Pragma("unroll") for (int k = 0; k < 2; ++k) dst[m][k] = *(const LAS bf16x8*)(lds + PG8_SA(b, h) + aoff + m * 2048 + k * 1024); } while (0)
; #define PG8_MMA(ai, bj, At, Bt) do { __builtin_amdgcn_s_setprio(1); _Pragma("unroll") for (int m = 0; m < 4; ++m) _Pragma("unroll") for (int n = 0; n < 2; ++n) _Pragma("unroll") for (int k = 0; k < 2; ++k) \
;         acc[ai][bj][m][n] = __builtin_amdgcn_mfma_f32_16x16x32_bf16(Bt[n][k], At[m][k], acc[ai][bj][m][n], 0, 0, 0); __builtin_amdgcn_s_setprio(0); } while (0)
; #define PG8_WAIT_V(n) asm volatile("s_waitcnt vmcnt(" #n ")" ::: "memory")
; #define PG8_WAIT_L(n) asm volatile("s_waitcnt lgkmcnt(" #n ")" ::: "memory")
; #define PG8_BAR __builtin_amdgcn_s_barrier()
; #define PG8_SCHED __builtin_amdgcn_sched_barrier(0)
; template <class Epi>
; __device__ __forceinline__ void gemm_phase(LAS unsigned char* lds, const Gemm g, const StaticOrder S, const Epi E) {
;     ...
;             PG8_LDA(At, 1, 1); PG8_STAGE(PG8_SA(1, 0), a3, voffA);
;             PG8_BAR; PG8_WAIT_L(0); PG8_MMA(1, 0, At, B0); PG8_BAR; PG8_SCHED;
;             PG8_STAGE(PG8_SB(1, 1), b3 + hstep, voffA);
;             PG8_WAIT_V(6); PG8_BAR; PG8_MMA(1, 1, At, B1); PG8_BAR;
;     __device__ __forceinline__ void operator()(AccRef acc, const pg8::Unit& u, int wr, int wc, int fr, int fq) const {
;     ...
;         const int v = u.pm < 32 ? (u.pm >> 3) : 4;
;         f32x4 gv[2][2];
; #pragma unroll
;         for (int bj = 0; bj < 2; ++bj)
; #pragma unroll
;             for (int n = 0; n < 2; ++n) gv[bj][n] = *(const f32x4*)(gate + (size_t)v * MODW + col0 + bj * 128 + n * 16) * coef;
	s_waitcnt lgkmcnt(0)
	s_setprio 1
	s_waitcnt lgkmcnt(0)
	v_mfma_f32_16x16x32_bf16 v[120:123], v[200:203], v[144:147], v[120:123]
	v_mfma_f32_16x16x32_bf16 v[108:111], v[208:211], v[144:147], v[108:111]
	v_mfma_f32_16x16x32_bf16 v[100:103], v[200:203], v[152:155], v[100:103]
	v_mfma_f32_16x16x32_bf16 v[96:99], v[208:211], v[152:155], v[96:99]
	v_mfma_f32_16x16x32_bf16 v[84:87], v[200:203], v[160:163], v[84:87]
	v_mfma_f32_16x16x32_bf16 v[76:79], v[208:211], v[160:163], v[76:79]
	v_mfma_f32_16x16x32_bf16 v[68:71], v[200:203], v[168:171], v[68:71]
	v_mfma_f32_16x16x32_bf16 v[64:67], v[208:211], v[168:171], v[64:67]
	v_mfma_f32_16x16x32_bf16 v[120:123], v[204:207], v[148:151], v[120:123]
	v_mfma_f32_16x16x32_bf16 v[108:111], v[220:223], v[148:151], v[108:111]
	v_mfma_f32_16x16x32_bf16 v[100:103], v[204:207], v[156:159], v[100:103]
	v_mfma_f32_16x16x32_bf16 v[96:99], v[220:223], v[156:159], v[96:99]
	v_mfma_f32_16x16x32_bf16 v[84:87], v[204:207], v[164:167], v[84:87]
	v_mfma_f32_16x16x32_bf16 v[76:79], v[220:223], v[164:167], v[76:79]
	v_mfma_f32_16x16x32_bf16 v[68:71], v[204:207], v[172:175], v[68:71]
	v_mfma_f32_16x16x32_bf16 v[64:67], v[220:223], v[172:175], v[64:67]
	s_setprio 0
	s_barrier
	s_mov_b32 m0, s69
	v_lshl_add_u64 v[232:233], v[236:237], 0, s[34:35]
	ds_read_b128 v[144:147], v230 offset:49152
	ds_read_b128 v[148:151], v230 offset:50176
	ds_read_b128 v[152:155], v230 offset:51200
	ds_read_b128 v[156:159], v230 offset:52224
	ds_read_b128 v[160:163], v230 offset:53248
	ds_read_b128 v[164:167], v230 offset:54272
	ds_read_b128 v[168:171], v230 offset:55296
	ds_read_b128 v[172:175], v230 offset:56320
	global_load_lds_dwordx4 v[232:233], off
	v_lshl_add_u64 v[232:233], v[238:239], 0, s[34:35]
	s_mov_b32 m0, s7
	s_nop 0
	global_load_lds_dwordx4 v[232:233], off
	s_barrier
	s_waitcnt lgkmcnt(0)
	s_setprio 1
	s_waitcnt lgkmcnt(0)
	v_mfma_f32_16x16x32_bf16 v[60:63], v[116:119], v[144:147], v[60:63]
	v_mfma_f32_16x16x32_bf16 v[56:59], v[128:131], v[144:147], v[56:59]
	v_mfma_f32_16x16x32_bf16 v[48:51], v[116:119], v[152:155], v[48:51]
	v_mfma_f32_16x16x32_bf16 v[40:43], v[128:131], v[152:155], v[40:43]
	v_mfma_f32_16x16x32_bf16 v[28:31], v[116:119], v[160:163], v[28:31]
	v_mfma_f32_16x16x32_bf16 v[24:27], v[128:131], v[160:163], v[24:27]
	v_mfma_f32_16x16x32_bf16 v[16:19], v[116:119], v[168:171], v[16:19]
	v_mfma_f32_16x16x32_bf16 v[8:11], v[128:131], v[168:171], v[8:11]
	v_mfma_f32_16x16x32_bf16 v[60:63], v[124:127], v[148:151], v[60:63]
	v_mfma_f32_16x16x32_bf16 v[56:59], v[132:135], v[148:151], v[56:59]
	v_mfma_f32_16x16x32_bf16 v[48:51], v[124:127], v[156:159], v[48:51]
	v_mfma_f32_16x16x32_bf16 v[40:43], v[132:135], v[156:159], v[40:43]
	v_mfma_f32_16x16x32_bf16 v[28:31], v[124:127], v[164:167], v[28:31]
	v_mfma_f32_16x16x32_bf16 v[24:27], v[132:135], v[164:167], v[24:27]
	v_mfma_f32_16x16x32_bf16 v[16:19], v[124:127], v[172:175], v[16:19]
	v_mfma_f32_16x16x32_bf16 v[8:11], v[132:135], v[172:175], v[8:11]
	s_setprio 0
	s_barrier
	s_add_u32 s30, s60, 0x80080
	s_addc_u32 s31, s61, 0
	s_add_i32 s14, s55, s24
	v_lshl_add_u64 v[116:117], s[30:31], 0, v[178:179]
	s_mov_b32 m0, s14
	s_nop 0
	global_load_lds_dwordx4 v[116:117], off
	v_lshl_add_u64 v[116:117], s[30:31], 0, v[194:195]
	s_add_i32 m0, s14, 0x2000
	s_nop 0
	global_load_lds_dwordx4 v[116:117], off
	s_waitcnt vmcnt(6)
	s_barrier
	s_setprio 1
	v_mfma_f32_16x16x32_bf16 v[52:55], v[200:203], v[144:147], v[52:55]
	v_mfma_f32_16x16x32_bf16 v[44:47], v[208:211], v[144:147], v[44:47]
	v_mfma_f32_16x16x32_bf16 v[36:39], v[200:203], v[152:155], v[36:39]
	v_mfma_f32_16x16x32_bf16 v[32:35], v[208:211], v[152:155], v[32:35]
	v_mfma_f32_16x16x32_bf16 v[20:23], v[200:203], v[160:163], v[20:23]
	v_mfma_f32_16x16x32_bf16 v[12:15], v[208:211], v[160:163], v[12:15]
	v_mfma_f32_16x16x32_bf16 v[4:7], v[200:203], v[168:171], v[4:7]
	v_mfma_f32_16x16x32_bf16 v[0:3], v[208:211], v[168:171], v[0:3]
	v_mfma_f32_16x16x32_bf16 v[52:55], v[204:207], v[148:151], v[52:55]
	v_mfma_f32_16x16x32_bf16 v[44:47], v[220:223], v[148:151], v[44:47]
	v_mfma_f32_16x16x32_bf16 v[36:39], v[204:207], v[156:159], v[36:39]
	v_mfma_f32_16x16x32_bf16 v[32:35], v[220:223], v[156:159], v[32:35]
	v_mfma_f32_16x16x32_bf16 v[20:23], v[204:207], v[164:167], v[20:23]
	v_mfma_f32_16x16x32_bf16 v[12:15], v[220:223], v[164:167], v[12:15]
	v_mfma_f32_16x16x32_bf16 v[4:7], v[204:207], v[172:175], v[4:7]
	v_mfma_f32_16x16x32_bf16 v[0:3], v[220:223], v[172:175], v[0:3]
	s_setprio 0
	s_barrier
	s_add_u32 s45, s45, 0x100
	s_addc_u32 s47, s47, 0
	s_cmp_ge_i32 vcc_lo, s39
	s_mov_b64 s[56:57], s[58:59]
	s_mov_b32 s55, vcc_lo
	s_cbranch_scc0 .LBB0_3568
	s_cmp_gt_i32 s38, 31
	s_mov_b64 s[56:57], 0x12000
	s_cbranch_scc1 .LBB0_3571
	s_ashr_i32 s14, s38, 3
	s_mul_hi_i32 s57, s14, 0x4800
	s_mul_i32 s56, s14, 0x4800

;     __device__ __forceinline__ void operator()(AccRef acc, const pg8::Unit& u, int wr, int wc, int fr, int fq) const {
;     ...
;         const bool part = u.part != 0;
;         float* base = part ? PART + ((size_t)u.ks * NCTX - NLAT) * DM : X;
; #pragma unroll
;         for (int ai = 0; ai < 2; ++ai)
; #pragma unroll
;             for (int mp = 0; mp < 2; ++mp) {
;                 f32x4 old[2][2][2];
;                 if (!part) {
; #pragma unroll
;                     for (int mm = 0; mm < 2; ++mm)
; #pragma unroll
;                         for (int bj = 0; bj < 2; ++bj)
; #pragma unroll
;                             for (int n = 0; n < 2; ++n) old[mm][bj][n] = *(const f32x4*)(SRC + (size_t)(row0 + ai * 128 + (2 * mp + mm) * 16) * DM + col0 + bj * 128 + n * 16);
;                 }
; #pragma unroll
;                 for (int mm = 0; mm < 2; ++mm)
; #pragma unroll
;                     for (int bj = 0; bj < 2; ++bj)
; #pragma unroll
;                         for (int n = 0; n < 2; ++n) { const int m = 2 * mp + mm; const f32x4 d = gv[bj][n] * acc[ai][bj][m][n];
;                             *(f32x4*)(base + (size_t)(row0 + ai * 128 + m * 16) * DM + col0 + bj * 128 + n * 16) = part ? d : old[mm][bj][n] + d; }
.LBB0_3575:
	s_ashr_i32 s55, s54, 31
	s_lshl_b64 s[30:31], s[54:55], 23
	v_readlane_b32 s40, v251, 46
	v_readlane_b32 s41, v251, 47
	s_add_u32 s14, s40, s30
	s_addc_u32 s30, s41, s31
	s_add_u32 s14, s14, 0xfc000000
	s_addc_u32 s40, s30, -1
	s_and_b64 s[30:31], exec, s[38:39]
	s_cselect_b32 s30, s83, s40
	s_cselect_b32 s14, s82, s14
	v_mov_b32_e32 v210, s14
	v_mov_b32_e32 v211, s30
	v_lshl_add_u64 v[200:201], v[200:201], 2, v[210:211]
	s_waitcnt vmcnt(0)
	v_pk_mul_f32 v[210:211], v[142:143], v[134:135]
	v_pk_mul_f32 v[220:221], v[140:141], v[132:133]
	v_pk_fma_f32 v[142:143], v[142:143], v[134:135], v[174:175]
	v_pk_fma_f32 v[140:141], v[140:141], v[132:133], v[172:173]
	v_lshl_add_u64 v[208:209], v[200:201], 0, v[208:209]
	v_cndmask_b32_e64 v143, v211, v143, s[38:39]
	v_cndmask_b32_e64 v142, v210, v142, s[38:39]
	v_cndmask_b32_e64 v141, v221, v141, s[38:39]
	v_cndmask_b32_e64 v140, v220, v140, s[38:39]
	global_store_dwordx4 v[208:209], v[140:143], off sc0 sc1
	s_mov_b64 s[54:55], -1
	s_andn2_b64 vcc, exec, s[56:57]
	v_pk_mul_f32 v[140:141], v[138:139], v[130:131]
	v_pk_mul_f32 v[142:143], v[136:137], v[128:129]
	v_pk_fma_f32 v[138:139], v[138:139], v[130:131], v[170:171]
	v_pk_fma_f32 v[136:137], v[136:137], v[128:129], v[168:169]
	v_cndmask_b32_e64 v139, v141, v139, s[38:39]
	v_cndmask_b32_e64 v138, v140, v138, s[38:39]
	v_cndmask_b32_e64 v137, v143, v137, s[38:39]
	v_cndmask_b32_e64 v136, v142, v136, s[38:39]
	global_store_dwordx4 v[208:209], v[136:139], off offset:64 sc0 sc1
	v_readlane_b32 s63, v255, 55
	s_nop 0
	v_pk_mul_f32 v[136:137], v[122:123], v[126:127]
	v_pk_mul_f32 v[138:139], v[120:121], v[124:125]
	v_pk_fma_f32 v[122:123], v[122:123], v[126:127], v[166:167]
	v_pk_fma_f32 v[120:121], v[120:121], v[124:125], v[164:165]
	v_cndmask_b32_e64 v123, v137, v123, s[38:39]
	v_cndmask_b32_e64 v122, v136, v122, s[38:39]
	v_cndmask_b32_e64 v121, v139, v121, s[38:39]
	v_cndmask_b32_e64 v120, v138, v120, s[38:39]
	global_store_dwordx4 v[208:209], v[120:123], off offset:512 sc0 sc1
	s_nop 1
	v_pk_mul_f32 v[120:121], v[110:111], v[118:119]
	v_pk_mul_f32 v[122:123], v[108:109], v[116:117]
	v_pk_fma_f32 v[110:111], v[110:111], v[118:119], v[158:159]
	v_pk_fma_f32 v[108:109], v[108:109], v[116:117], v[156:157]
	v_cndmask_b32_e64 v111, v121, v111, s[38:39]
	v_cndmask_b32_e64 v110, v120, v110, s[38:39]
	v_cndmask_b32_e64 v109, v123, v109, s[38:39]
	v_cndmask_b32_e64 v108, v122, v108, s[38:39]
	global_store_dwordx4 v[208:209], v[108:111], off offset:576 sc0 sc1
	v_pk_mul_f32 v[122:123], v[112:113], v[132:133]
	v_pk_fma_f32 v[112:113], v[112:113], v[132:133], v[160:161]
	v_pk_mul_f32 v[108:109], v[114:115], v[134:135]
	v_pk_fma_f32 v[110:111], v[114:115], v[134:135], v[162:163]
	v_lshl_add_u64 v[120:121], v[200:201], 0, v[206:207]
	v_cndmask_b32_e64 v111, v109, v111, s[38:39]
	v_cndmask_b32_e64 v110, v108, v110, s[38:39]
	v_cndmask_b32_e64 v109, v123, v113, s[38:39]
	v_cndmask_b32_e64 v108, v122, v112, s[38:39]
	global_store_dwordx4 v[120:121], v[108:111], off sc0 sc1
	s_nop 1
	v_pk_mul_f32 v[108:109], v[106:107], v[130:131]
	v_pk_mul_f32 v[110:111], v[104:105], v[128:129]
	v_pk_fma_f32 v[106:107], v[106:107], v[130:131], v[154:155]
	v_pk_fma_f32 v[104:105], v[104:105], v[128:129], v[152:153]
	v_cndmask_b32_e64 v107, v109, v107, s[38:39]
	v_cndmask_b32_e64 v106, v108, v106, s[38:39]
	v_cndmask_b32_e64 v105, v111, v105, s[38:39]
	v_cndmask_b32_e64 v104, v110, v104, s[38:39]
	global_store_dwordx4 v[120:121], v[104:107], off offset:64 sc0 sc1
	s_nop 1
	v_pk_mul_f32 v[104:105], v[102:103], v[126:127]
	v_pk_mul_f32 v[106:107], v[100:101], v[124:125]
	v_pk_fma_f32 v[102:103], v[102:103], v[126:127], v[150:151]
	v_pk_fma_f32 v[100:101], v[100:101], v[124:125], v[148:149]
	v_cndmask_b32_e64 v103, v105, v103, s[38:39]
	v_cndmask_b32_e64 v102, v104, v102, s[38:39]
	v_cndmask_b32_e64 v101, v107, v101, s[38:39]
	v_cndmask_b32_e64 v100, v106, v100, s[38:39]
	global_store_dwordx4 v[120:121], v[100:103], off offset:512 sc0 sc1
	s_nop 1
	v_pk_mul_f32 v[100:101], v[98:99], v[118:119]
	v_pk_mul_f32 v[102:103], v[96:97], v[116:117]
	v_pk_fma_f32 v[98:99], v[98:99], v[118:119], v[146:147]
	v_pk_fma_f32 v[96:97], v[96:97], v[116:117], v[144:145]
	v_cndmask_b32_e64 v99, v101, v99, s[38:39]
	v_cndmask_b32_e64 v98, v100, v98, s[38:39]
	v_cndmask_b32_e64 v97, v103, v97, s[38:39]
	v_cndmask_b32_e64 v96, v102, v96, s[38:39]
	global_store_dwordx4 v[120:121], v[96:99], off offset:576 sc0 sc1
	v_or_b32_e32 v102, 32, v202
	v_or_b32_e32 v100, 48, v202
	v_cndmask_b32_e64 v96, 0, 1, s[56:57]
	v_cmp_ne_u32_e64 s[40:41], 1, v96
	v_ashrrev_i32_e32 v103, 31, v102
	v_ashrrev_i32_e32 v101, 31, v100
	s_cbranch_vccnz .LBB0_3577
	v_lshlrev_b64 v[98:99], 13, v[102:103]
	v_lshlrev_b64 v[96:97], 13, v[100:101]
	s_mov_b64 s[54:55], 0

;     __device__ __forceinline__ void operator()(AccRef acc, const pg8::Unit& u, int wr, int wc, int fr, int fq) const {
;     ...
; #pragma unroll
;                 for (int mm = 0; mm < 2; ++mm)
; #pragma unroll
;                     for (int bj = 0; bj < 2; ++bj)
; #pragma unroll
;                         for (int n = 0; n < 2; ++n) { const int m = 2 * mp + mm; const f32x4 d = gv[bj][n] * acc[ai][bj][m][n];
;                             *(f32x4*)(base + (size_t)(row0 + ai * 128 + m * 16) * DM + col0 + bj * 128 + n * 16) = part ? d : old[mm][bj][n] + d; }
.LBB0_3579:
	v_pk_mul_f32 v[100:101], v[94:95], v[134:135]
	v_pk_mul_f32 v[102:103], v[92:93], v[132:133]
	s_waitcnt vmcnt(0)
	v_pk_fma_f32 v[94:95], v[94:95], v[134:135], v[174:175]
	v_pk_fma_f32 v[92:93], v[92:93], v[132:133], v[172:173]
	v_lshl_add_u64 v[98:99], v[200:201], 0, v[98:99]
	v_cndmask_b32_e64 v95, v101, v95, s[38:39]
	v_cndmask_b32_e64 v94, v100, v94, s[38:39]
	v_cndmask_b32_e64 v93, v103, v93, s[38:39]
	v_cndmask_b32_e64 v92, v102, v92, s[38:39]
	global_store_dwordx4 v[98:99], v[92:95], off sc0 sc1
	s_mov_b64 s[54:55], -1
	s_and_b64 vcc, exec, s[40:41]
	v_pk_mul_f32 v[92:93], v[90:91], v[130:131]
	v_pk_mul_f32 v[94:95], v[88:89], v[128:129]
	v_pk_fma_f32 v[90:91], v[90:91], v[130:131], v[170:171]
	v_pk_fma_f32 v[88:89], v[88:89], v[128:129], v[168:169]
	v_cndmask_b32_e64 v91, v93, v91, s[38:39]
	v_cndmask_b32_e64 v90, v92, v90, s[38:39]
	v_cndmask_b32_e64 v89, v95, v89, s[38:39]
	v_cndmask_b32_e64 v88, v94, v88, s[38:39]
	global_store_dwordx4 v[98:99], v[88:91], off offset:64 sc0 sc1
	s_nop 1
	v_pk_mul_f32 v[88:89], v[86:87], v[126:127]
	v_pk_mul_f32 v[90:91], v[84:85], v[124:125]
	v_pk_fma_f32 v[86:87], v[86:87], v[126:127], v[166:167]
	v_pk_fma_f32 v[84:85], v[84:85], v[124:125], v[164:165]
	v_cndmask_b32_e64 v87, v89, v87, s[38:39]
	v_cndmask_b32_e64 v86, v88, v86, s[38:39]
	v_cndmask_b32_e64 v85, v91, v85, s[38:39]
	v_cndmask_b32_e64 v84, v90, v84, s[38:39]
	global_store_dwordx4 v[98:99], v[84:87], off offset:512 sc0 sc1
	s_nop 1
	v_pk_mul_f32 v[84:85], v[78:79], v[118:119]
	v_pk_mul_f32 v[86:87], v[76:77], v[116:117]
	v_pk_fma_f32 v[78:79], v[78:79], v[118:119], v[158:159]
	v_pk_fma_f32 v[76:77], v[76:77], v[116:117], v[156:157]
	v_cndmask_b32_e64 v79, v85, v79, s[38:39]
	v_cndmask_b32_e64 v78, v84, v78, s[38:39]
	v_cndmask_b32_e64 v77, v87, v77, s[38:39]
	v_cndmask_b32_e64 v76, v86, v76, s[38:39]
	global_store_dwordx4 v[98:99], v[76:79], off offset:576 sc0 sc1
	v_pk_mul_f32 v[86:87], v[80:81], v[132:133]
	v_pk_fma_f32 v[80:81], v[80:81], v[132:133], v[160:161]
	v_pk_mul_f32 v[76:77], v[82:83], v[134:135]
	v_pk_fma_f32 v[78:79], v[82:83], v[134:135], v[162:163]
	v_lshl_add_u64 v[84:85], v[200:201], 0, v[96:97]
	v_cndmask_b32_e64 v79, v77, v79, s[38:39]
	v_cndmask_b32_e64 v78, v76, v78, s[38:39]
	v_cndmask_b32_e64 v77, v87, v81, s[38:39]
	v_cndmask_b32_e64 v76, v86, v80, s[38:39]
	global_store_dwordx4 v[84:85], v[76:79], off sc0 sc1
	s_nop 1
	v_pk_mul_f32 v[76:77], v[74:75], v[130:131]
	v_pk_mul_f32 v[78:79], v[72:73], v[128:129]
	v_pk_fma_f32 v[74:75], v[74:75], v[130:131], v[154:155]
	v_pk_fma_f32 v[72:73], v[72:73], v[128:129], v[152:153]
	v_cndmask_b32_e64 v75, v77, v75, s[38:39]
	v_cndmask_b32_e64 v74, v76, v74, s[38:39]
	v_cndmask_b32_e64 v73, v79, v73, s[38:39]
	v_cndmask_b32_e64 v72, v78, v72, s[38:39]
	global_store_dwordx4 v[84:85], v[72:75], off offset:64 sc0 sc1
	s_nop 1
	v_pk_mul_f32 v[72:73], v[70:71], v[126:127]
	v_pk_mul_f32 v[74:75], v[68:69], v[124:125]
	v_pk_fma_f32 v[70:71], v[70:71], v[126:127], v[150:151]
	v_pk_fma_f32 v[68:69], v[68:69], v[124:125], v[148:149]
	v_cndmask_b32_e64 v71, v73, v71, s[38:39]
	v_cndmask_b32_e64 v70, v72, v70, s[38:39]
	v_cndmask_b32_e64 v69, v75, v69, s[38:39]
	v_cndmask_b32_e64 v68, v74, v68, s[38:39]
	global_store_dwordx4 v[84:85], v[68:71], off offset:512 sc0 sc1
	s_nop 1
	v_pk_mul_f32 v[68:69], v[66:67], v[118:119]
	v_pk_fma_f32 v[66:67], v[66:67], v[118:119], v[146:147]
	v_pk_mul_f32 v[70:71], v[64:65], v[116:117]
	v_pk_fma_f32 v[64:65], v[64:65], v[116:117], v[144:145]
	v_cndmask_b32_e64 v66, v68, v66, s[38:39]
	v_add_u32_e32 v68, 0x80, v202
	v_cndmask_b32_e64 v67, v69, v67, s[38:39]
	v_cndmask_b32_e64 v65, v71, v65, s[38:39]
	v_cndmask_b32_e64 v64, v70, v64, s[38:39]
	v_ashrrev_i32_e32 v69, 31, v68
	global_store_dwordx4 v[84:85], v[64:67], off offset:576 sc0 sc1
	s_cbranch_vccnz .LBB0_3581
	s_nop 0
	v_lshlrev_b64 v[64:65], 13, v[202:203]
	s_mov_b64 s[30:31], 0x120000
	v_lshlrev_b64 v[66:67], 13, v[68:69]
	v_lshl_add_u64 v[64:65], v[64:65], 0, s[30:31]
	s_mov_b64 s[54:55], 0

;     __device__ __forceinline__ void operator()(AccRef acc, const pg8::Unit& u, int wr, int wc, int fr, int fq) const {
;     ...
; #pragma unroll
;                 for (int mm = 0; mm < 2; ++mm)
; #pragma unroll
;                     for (int bj = 0; bj < 2; ++bj)
; #pragma unroll
;                         for (int n = 0; n < 2; ++n) { const int m = 2 * mp + mm; const f32x4 d = gv[bj][n] * acc[ai][bj][m][n];
;                             *(f32x4*)(base + (size_t)(row0 + ai * 128 + m * 16) * DM + col0 + bj * 128 + n * 16) = part ? d : old[mm][bj][n] + d; }
.LBB0_3583:
	v_pk_mul_f32 v[68:69], v[62:63], v[134:135]
	v_pk_mul_f32 v[70:71], v[60:61], v[132:133]
	s_waitcnt vmcnt(0)
	v_pk_fma_f32 v[62:63], v[62:63], v[134:135], v[174:175]
	v_pk_fma_f32 v[60:61], v[60:61], v[132:133], v[172:173]
	v_lshl_add_u64 v[66:67], v[200:201], 0, v[66:67]
	v_cndmask_b32_e64 v63, v69, v63, s[38:39]
	v_cndmask_b32_e64 v62, v68, v62, s[38:39]
	v_cndmask_b32_e64 v61, v71, v61, s[38:39]
	v_cndmask_b32_e64 v60, v70, v60, s[38:39]
	global_store_dwordx4 v[66:67], v[60:63], off sc0 sc1
	s_mov_b64 s[54:55], -1
	s_and_b64 vcc, exec, s[40:41]
	v_pk_mul_f32 v[60:61], v[58:59], v[130:131]
	v_pk_mul_f32 v[62:63], v[56:57], v[128:129]
	v_pk_fma_f32 v[58:59], v[58:59], v[130:131], v[170:171]
	v_pk_fma_f32 v[56:57], v[56:57], v[128:129], v[168:169]
	v_cndmask_b32_e64 v59, v61, v59, s[38:39]
	v_cndmask_b32_e64 v58, v60, v58, s[38:39]
	v_cndmask_b32_e64 v57, v63, v57, s[38:39]
	v_cndmask_b32_e64 v56, v62, v56, s[38:39]
	global_store_dwordx4 v[66:67], v[56:59], off offset:64 sc0 sc1
	s_nop 1
	v_pk_mul_f32 v[56:57], v[54:55], v[126:127]
	v_pk_mul_f32 v[58:59], v[52:53], v[124:125]
	v_pk_fma_f32 v[54:55], v[54:55], v[126:127], v[166:167]
	v_pk_fma_f32 v[52:53], v[52:53], v[124:125], v[164:165]
	v_cndmask_b32_e64 v55, v57, v55, s[38:39]
	v_cndmask_b32_e64 v54, v56, v54, s[38:39]
	v_cndmask_b32_e64 v53, v59, v53, s[38:39]
	v_cndmask_b32_e64 v52, v58, v52, s[38:39]
	global_store_dwordx4 v[66:67], v[52:55], off offset:512 sc0 sc1
	s_nop 1
	v_pk_mul_f32 v[52:53], v[46:47], v[118:119]
	v_pk_mul_f32 v[54:55], v[44:45], v[116:117]
	v_pk_fma_f32 v[46:47], v[46:47], v[118:119], v[158:159]
	v_pk_fma_f32 v[44:45], v[44:45], v[116:117], v[156:157]
	v_cndmask_b32_e64 v47, v53, v47, s[38:39]
	v_cndmask_b32_e64 v46, v52, v46, s[38:39]
	v_cndmask_b32_e64 v45, v55, v45, s[38:39]
	v_cndmask_b32_e64 v44, v54, v44, s[38:39]
	global_store_dwordx4 v[66:67], v[44:47], off offset:576 sc0 sc1
	v_pk_mul_f32 v[54:55], v[48:49], v[132:133]
	v_pk_fma_f32 v[48:49], v[48:49], v[132:133], v[160:161]
	v_pk_mul_f32 v[44:45], v[50:51], v[134:135]
	v_pk_fma_f32 v[46:47], v[50:51], v[134:135], v[162:163]
	v_lshl_add_u64 v[52:53], v[200:201], 0, v[64:65]
	v_cndmask_b32_e64 v47, v45, v47, s[38:39]
	v_cndmask_b32_e64 v46, v44, v46, s[38:39]
	v_cndmask_b32_e64 v45, v55, v49, s[38:39]
	v_cndmask_b32_e64 v44, v54, v48, s[38:39]
	global_store_dwordx4 v[52:53], v[44:47], off sc0 sc1
	s_nop 1
	v_pk_mul_f32 v[44:45], v[42:43], v[130:131]
	v_pk_mul_f32 v[46:47], v[40:41], v[128:129]
	v_pk_fma_f32 v[42:43], v[42:43], v[130:131], v[154:155]
	v_pk_fma_f32 v[40:41], v[40:41], v[128:129], v[152:153]
	v_cndmask_b32_e64 v43, v45, v43, s[38:39]
	v_cndmask_b32_e64 v42, v44, v42, s[38:39]
	v_cndmask_b32_e64 v41, v47, v41, s[38:39]
	v_cndmask_b32_e64 v40, v46, v40, s[38:39]
	global_store_dwordx4 v[52:53], v[40:43], off offset:64 sc0 sc1
	s_nop 1
	v_pk_mul_f32 v[40:41], v[38:39], v[126:127]
	v_pk_mul_f32 v[42:43], v[36:37], v[124:125]
	v_pk_fma_f32 v[38:39], v[38:39], v[126:127], v[150:151]
	v_pk_fma_f32 v[36:37], v[36:37], v[124:125], v[148:149]
	v_cndmask_b32_e64 v39, v41, v39, s[38:39]
	v_cndmask_b32_e64 v38, v40, v38, s[38:39]
	v_cndmask_b32_e64 v37, v43, v37, s[38:39]
	v_cndmask_b32_e64 v36, v42, v36, s[38:39]
	global_store_dwordx4 v[52:53], v[36:39], off offset:512 sc0 sc1
	s_nop 1
	v_pk_mul_f32 v[36:37], v[34:35], v[118:119]
	v_pk_fma_f32 v[34:35], v[34:35], v[118:119], v[146:147]
	v_pk_mul_f32 v[38:39], v[32:33], v[116:117]
	v_pk_fma_f32 v[32:33], v[32:33], v[116:117], v[144:145]
	v_cndmask_b32_e64 v34, v36, v34, s[38:39]
	v_add_u32_e32 v36, 0xa0, v202
	v_cndmask_b32_e64 v35, v37, v35, s[38:39]
	v_cndmask_b32_e64 v33, v39, v33, s[38:39]
	v_cndmask_b32_e64 v32, v38, v32, s[38:39]
	v_ashrrev_i32_e32 v37, 31, v36
	global_store_dwordx4 v[52:53], v[32:35], off offset:576 sc0 sc1
	s_cbranch_vccnz .LBB0_3585
	s_nop 0
	v_lshlrev_b64 v[32:33], 13, v[202:203]
	s_mov_b64 s[30:31], 0x160000
	v_lshlrev_b64 v[34:35], 13, v[36:37]
	v_lshl_add_u64 v[32:33], v[32:33], 0, s[30:31]
	s_mov_b64 s[54:55], 0

; __device__ __forceinline__ void norm_phase(float* __restrict__ X, bf16_t* __restrict__ H, const float* __restrict__ modl, int shiftIdx, int scaleIdx, int nrows, const float* __restrict__ PART, const float* __restrict__ XLAT) {
;     ...
;     for (int row = gw; row < nrows; row += nw) {
;         float* xr = X + (size_t)row * DM;
;         const float* xs = (XLAT != nullptr && row < NLAT) ? XLAT + (size_t)row * DM : xr;
;         f32x4 x[8]; float ss = 0.f;
; #pragma unroll
;         for (int i = 0; i < 8; ++i) x[i] = *(const f32x4*)(xs + (i * 64 + lane) * 4);
;         if (PART != nullptr && row >= NLAT) {
; #pragma unroll
;             for (int s = 0; s < 8; ++s) { f32x4 pt[8];
; #pragma unroll
;                 for (int i = 0; i < 8; ++i) pt[i] = *(const f32x4*)(PART + ((size_t)s * NCTX + (row - NLAT)) * DM + (i * 64 + lane) * 4);
; #pragma unroll
;                 for (int i = 0; i < 8; ++i) x[i] += pt[i]; }
.LBB0_3650:
	v_lshl_add_u64 v[54:55], s[92:93], 0, v[38:39]
	v_add_co_u32_e32 v0, vcc, 0x142dd000, v54
	s_movk_i32 s6, 0x1fff
	s_nop 0
	v_addc_co_u32_e32 v1, vcc, 0, v55, vcc
	global_load_dwordx4 v[28:31], v[0:1], off
	global_load_dwordx4 v[24:27], v[0:1], off offset:1024
	global_load_dwordx4 v[20:23], v[0:1], off offset:2048
	global_load_dwordx4 v[16:19], v[0:1], off offset:3072
	v_add_co_u32_e32 v0, vcc, 0x142de000, v54
	v_lshlrev_b32_e32 v178, 2, v34
	s_nop 0
	v_addc_co_u32_e32 v1, vcc, 0, v55, vcc
	global_load_dwordx4 v[12:15], v[0:1], off
	global_load_dwordx4 v[8:11], v[0:1], off offset:1024
	global_load_dwordx4 v[4:7], v[0:1], off offset:2048
	s_nop 0
	global_load_dwordx4 v[0:3], v[0:1], off offset:3072
	v_cmp_lt_i32_e32 vcc, s6, v32
	s_and_b64 s[6:7], s[38:39], vcc
	s_and_saveexec_b64 s[44:45], s[6:7]
	s_cbranch_execz .LBB0_3649
	v_add_u32_e32 v70, 0xffffe000, v32
	v_mov_b32_e32 v71, v179
	v_lshlrev_b64 v[70:71], 13, v[70:71]
	v_lshl_add_u64 v[70:71], s[40:41], 0, v[70:71]
	v_lshl_add_u64 v[84:85], v[70:71], 0, v[178:179]
	global_load_dwordx4 v[72:75], v[84:85], off
	global_load_dwordx4 v[76:79], v[84:85], off offset:1024
	global_load_dwordx4 v[80:83], v[84:85], off offset:2048
	s_nop 0
	global_load_dwordx4 v[84:87], v[84:85], off offset:3072
	v_mov_b32_e32 v47, v179
	v_mov_b32_e32 v49, v179
	v_mov_b32_e32 v51, v179
	v_mov_b32_e32 v53, v179
	v_lshl_add_u64 v[88:89], v[70:71], 0, v[46:47]
	v_lshl_add_u64 v[92:93], v[70:71], 0, v[48:49]
	v_lshl_add_u64 v[96:97], v[70:71], 0, v[50:51]
	v_lshl_add_u64 v[100:101], v[70:71], 0, v[52:53]
	global_load_dwordx4 v[88:91], v[88:89], off
	s_mov_b64 s[6:7], 0x142dd000
	global_load_dwordx4 v[92:95], v[92:93], off
	v_lshl_add_u64 v[68:69], v[54:55], 0, s[6:7]
	global_load_dwordx4 v[96:99], v[96:97], off
	s_mov_b64 s[6:7], 0x142dd400
	global_load_dwordx4 v[100:103], v[100:101], off
	v_lshl_add_u64 v[66:67], v[54:55], 0, s[6:7]
	s_mov_b64 s[6:7], 0x142dd800
	v_lshl_add_u64 v[64:65], v[54:55], 0, s[6:7]
	s_mov_b64 s[6:7], 0x142ddc00
	v_lshl_add_u64 v[62:63], v[54:55], 0, s[6:7]
	s_mov_b64 s[6:7], 0x142de000
	v_lshl_add_u64 v[60:61], v[54:55], 0, s[6:7]
	s_mov_b64 s[6:7], 0x142de400
	v_lshl_add_u64 v[58:59], v[54:55], 0, s[6:7]
	s_mov_b64 s[6:7], 0x142de800
	v_lshl_add_u64 v[56:57], v[54:55], 0, s[6:7]
	s_mov_b64 s[6:7], 0x142dec00
	v_lshl_add_u64 v[54:55], v[54:55], 0, s[6:7]
	s_mov_b64 s[6:7], 0x800000
	v_mov_b32_e32 v41, v179
	v_mov_b32_e32 v43, v179
	v_mov_b32_e32 v45, v179
	s_waitcnt vmcnt(0)
	v_pk_add_f32 v[30:31], v[30:31], v[74:75]
	v_pk_add_f32 v[110:111], v[28:29], v[72:73]
	v_pk_add_f32 v[114:115], v[20:21], v[80:81]
	v_pk_add_f32 v[116:117], v[16:17], v[84:85]
	v_lshl_add_u64 v[16:17], v[70:71], 0, s[6:7]
	v_lshl_add_u64 v[20:21], v[16:17], 0, v[46:47]
	global_load_dwordx4 v[72:75], v[20:21], off
	v_lshl_add_u64 v[20:21], v[16:17], 0, v[48:49]
	v_pk_add_f32 v[26:27], v[26:27], v[78:79]
	v_pk_add_f32 v[112:113], v[24:25], v[76:77]
	global_load_dwordx4 v[76:79], v[20:21], off
	v_lshl_add_u64 v[20:21], v[16:17], 0, v[50:51]
	v_pk_add_f32 v[88:89], v[12:13], v[88:89]
	v_lshl_add_u64 v[12:13], v[16:17], 0, v[44:45]
	v_pk_add_f32 v[92:93], v[8:9], v[92:93]
	v_lshl_add_u64 v[8:9], v[16:17], 0, v[42:43]
	v_pk_add_f32 v[96:97], v[4:5], v[96:97]
	v_lshl_add_u64 v[4:5], v[16:17], 0, v[40:41]
	v_pk_add_f32 v[100:101], v[0:1], v[100:101]
	v_lshl_add_u64 v[0:1], v[16:17], 0, v[178:179]
	v_lshl_add_u64 v[16:17], v[16:17], 0, v[52:53]
	v_pk_add_f32 v[22:23], v[22:23], v[82:83]
	v_pk_add_f32 v[18:19], v[18:19], v[86:87]
	v_pk_add_f32 v[102:103], v[2:3], v[102:103]
	global_load_dwordx4 v[0:3], v[0:1], off
	v_pk_add_f32 v[90:91], v[14:15], v[90:91]
	global_load_dwordx4 v[80:83], v[20:21], off
	global_load_dwordx4 v[84:87], v[16:17], off
	v_pk_add_f32 v[94:95], v[10:11], v[94:95]
	global_load_dwordx4 v[8:11], v[8:9], off
	v_pk_add_f32 v[98:99], v[6:7], v[98:99]
	global_load_dwordx4 v[12:15], v[12:13], off
	s_mov_b64 s[6:7], 0x1000000
	global_load_dwordx4 v[4:7], v[4:5], off
	s_waitcnt vmcnt(0)
	v_pk_add_f32 v[28:29], v[30:31], v[2:3]
	v_pk_add_f32 v[30:31], v[110:111], v[0:1]
	v_pk_add_f32 v[2:3], v[100:101], v[84:85]
	v_lshl_add_u64 v[100:101], v[70:71], 0, s[6:7]
	v_pk_add_f32 v[20:21], v[22:23], v[10:11]
	v_pk_add_f32 v[10:11], v[92:93], v[76:77]
	v_pk_add_f32 v[16:17], v[18:19], v[14:15]
	v_pk_add_f32 v[14:15], v[88:89], v[72:73]
	v_lshl_add_u64 v[72:73], v[100:101], 0, v[178:179]
	v_pk_add_f32 v[24:25], v[26:27], v[6:7]
	v_pk_add_f32 v[18:19], v[116:117], v[12:13]
	v_pk_add_f32 v[12:13], v[90:91], v[74:75]
	v_pk_add_f32 v[6:7], v[96:97], v[80:81]
	global_load_dwordx4 v[72:75], v[72:73], off
	v_lshl_add_u64 v[76:77], v[100:101], 0, v[40:41]
	v_lshl_add_u64 v[80:81], v[100:101], 0, v[42:43]
	v_lshl_add_u64 v[84:85], v[100:101], 0, v[44:45]
	v_lshl_add_u64 v[88:89], v[100:101], 0, v[46:47]
	v_lshl_add_u64 v[92:93], v[100:101], 0, v[48:49]
	v_lshl_add_u64 v[96:97], v[100:101], 0, v[50:51]
	v_lshl_add_u64 v[100:101], v[100:101], 0, v[52:53]
	v_pk_add_f32 v[26:27], v[112:113], v[4:5]
	v_pk_add_f32 v[22:23], v[114:115], v[8:9]
	v_pk_add_f32 v[8:9], v[94:95], v[78:79]
	v_pk_add_f32 v[4:5], v[98:99], v[82:83]
	v_pk_add_f32 v[0:1], v[102:103], v[86:87]
	global_load_dwordx4 v[76:79], v[76:77], off
	s_mov_b64 s[6:7], 0x1800000
	global_load_dwordx4 v[80:83], v[80:81], off
	s_waitcnt vmcnt(0)
; __device__ __forceinline__ void norm_phase(float* __restrict__ X, bf16_t* __restrict__ H, const float* __restrict__ modl, int shiftIdx, int scaleIdx, int nrows, const float* __restrict__ PART, const float* __restrict__ XLAT) {
;     ...
;             for (int s = 0; s < 8; ++s) { f32x4 pt[8];
; #pragma unroll
;                 for (int i = 0; i < 8; ++i) pt[i] = *(const f32x4*)(PART + ((size_t)s * NCTX + (row - NLAT)) * DM + (i * 64 + lane) * 4);
; #pragma unroll
;                 for (int i = 0; i < 8; ++i) x[i] += pt[i]; }
	v_pk_add_f32 v[74:75], v[28:29], v[74:75]
	global_load_dwordx4 v[84:87], v[84:85], off
	v_lshl_add_u64 v[28:29], v[70:71], 0, s[6:7]
	global_load_dwordx4 v[88:91], v[88:89], off
	v_pk_add_f32 v[72:73], v[30:31], v[72:73]
	global_load_dwordx4 v[92:95], v[92:93], off
	s_mov_b64 s[6:7], 0x2000000
	global_load_dwordx4 v[96:99], v[96:97], off
	v_pk_add_f32 v[78:79], v[24:25], v[78:79]
	global_load_dwordx4 v[100:103], v[100:101], off
	v_pk_add_f32 v[82:83], v[20:21], v[82:83]
	v_lshl_add_u64 v[20:21], v[28:29], 0, v[48:49]
	v_lshl_add_u64 v[24:25], v[28:29], 0, v[50:51]
	v_pk_add_f32 v[76:77], v[26:27], v[76:77]
	global_load_dwordx4 v[24:27], v[24:25], off
	v_pk_add_f32 v[80:81], v[22:23], v[80:81]
	global_load_dwordx4 v[20:23], v[20:21], off
	s_waitcnt vmcnt(0)
	v_pk_add_f32 v[86:87], v[16:17], v[86:87]
	v_lshl_add_u64 v[16:17], v[28:29], 0, v[46:47]
	v_pk_add_f32 v[90:91], v[12:13], v[90:91]
	v_lshl_add_u64 v[12:13], v[28:29], 0, v[44:45]
	v_pk_add_f32 v[94:95], v[8:9], v[94:95]
	v_lshl_add_u64 v[8:9], v[28:29], 0, v[42:43]
	v_pk_add_f32 v[98:99], v[4:5], v[98:99]
	v_lshl_add_u64 v[4:5], v[28:29], 0, v[40:41]
	v_pk_add_f32 v[84:85], v[18:19], v[84:85]
	v_pk_add_f32 v[88:89], v[14:15], v[88:89]
	v_pk_add_f32 v[92:93], v[10:11], v[92:93]
	v_pk_add_f32 v[96:97], v[6:7], v[96:97]
	global_load_dwordx4 v[4:7], v[4:5], off
	v_pk_add_f32 v[102:103], v[0:1], v[102:103]
	v_lshl_add_u64 v[0:1], v[28:29], 0, v[178:179]
	v_lshl_add_u64 v[28:29], v[28:29], 0, v[52:53]
	global_load_dwordx4 v[28:31], v[28:29], off
	v_pk_add_f32 v[100:101], v[2:3], v[100:101]
	global_load_dwordx4 v[0:3], v[0:1], off
	v_pk_add_f32 v[96:97], v[96:97], v[24:25]
	global_load_dwordx4 v[8:11], v[8:9], off
	v_pk_add_f32 v[92:93], v[92:93], v[20:21]
	global_load_dwordx4 v[12:15], v[12:13], off
	v_pk_add_f32 v[98:99], v[98:99], v[26:27]
	global_load_dwordx4 v[16:19], v[16:17], off
	v_pk_add_f32 v[94:95], v[94:95], v[22:23]
	s_waitcnt vmcnt(0)
	v_pk_add_f32 v[76:77], v[76:77], v[4:5]
	v_pk_add_f32 v[78:79], v[78:79], v[6:7]
	v_pk_add_f32 v[100:101], v[100:101], v[28:29]
	v_lshl_add_u64 v[28:29], v[70:71], 0, s[6:7]
	v_pk_add_f32 v[72:73], v[72:73], v[0:1]
	v_lshl_add_u64 v[0:1], v[28:29], 0, v[178:179]
	v_pk_add_f32 v[80:81], v[80:81], v[8:9]
	v_lshl_add_u64 v[4:5], v[28:29], 0, v[40:41]
	v_pk_add_f32 v[84:85], v[84:85], v[12:13]
	v_lshl_add_u64 v[8:9], v[28:29], 0, v[42:43]
	v_pk_add_f32 v[88:89], v[88:89], v[16:17]
	v_lshl_add_u64 v[12:13], v[28:29], 0, v[44:45]
	v_lshl_add_u64 v[16:17], v[28:29], 0, v[46:47]
	v_lshl_add_u64 v[20:21], v[28:29], 0, v[48:49]
	v_lshl_add_u64 v[24:25], v[28:29], 0, v[50:51]
	v_lshl_add_u64 v[28:29], v[28:29], 0, v[52:53]
	v_pk_add_f32 v[102:103], v[102:103], v[30:31]
	global_load_dwordx4 v[24:27], v[24:25], off
	v_pk_add_f32 v[74:75], v[74:75], v[2:3]
	global_load_dwordx4 v[28:31], v[28:29], off
	v_pk_add_f32 v[82:83], v[82:83], v[10:11]
	v_pk_add_f32 v[86:87], v[86:87], v[14:15]
	v_pk_add_f32 v[90:91], v[90:91], v[18:19]
	global_load_dwordx4 v[0:3], v[0:1], off
	s_mov_b64 s[6:7], 0x2800000
	global_load_dwordx4 v[4:7], v[4:5], off
	s_waitcnt vmcnt(0)
	v_pk_add_f32 v[96:97], v[96:97], v[24:25]
	global_load_dwordx4 v[8:11], v[8:9], off
	v_pk_add_f32 v[100:101], v[100:101], v[28:29]
	global_load_dwordx4 v[12:15], v[12:13], off
	v_lshl_add_u64 v[28:29], v[70:71], 0, s[6:7]
	global_load_dwordx4 v[16:19], v[16:17], off
	v_pk_add_f32 v[72:73], v[72:73], v[0:1]
	global_load_dwordx4 v[20:23], v[20:21], off
	v_pk_add_f32 v[76:77], v[76:77], v[4:5]
	v_lshl_add_u64 v[0:1], v[28:29], 0, v[178:179]
	v_lshl_add_u64 v[4:5], v[28:29], 0, v[40:41]
	v_lshl_add_u64 v[24:25], v[28:29], 0, v[50:51]
	v_pk_add_f32 v[102:103], v[102:103], v[30:31]
	v_pk_add_f32 v[74:75], v[74:75], v[2:3]
	global_load_dwordx4 v[0:3], v[0:1], off
	v_pk_add_f32 v[78:79], v[78:79], v[6:7]
	v_pk_add_f32 v[98:99], v[98:99], v[26:27]
	global_load_dwordx4 v[4:7], v[4:5], off
	s_mov_b64 s[6:7], 0x3000000
	global_load_dwordx4 v[24:27], v[24:25], off
	s_waitcnt vmcnt(0)
; __device__ __forceinline__ void norm_phase(float* __restrict__ X, bf16_t* __restrict__ H, const float* __restrict__ modl, int shiftIdx, int scaleIdx, int nrows, const float* __restrict__ PART, const float* __restrict__ XLAT) {
;     ...
;             for (int s = 0; s < 8; ++s) { f32x4 pt[8];
; #pragma unroll
;                 for (int i = 0; i < 8; ++i) pt[i] = *(const f32x4*)(PART + ((size_t)s * NCTX + (row - NLAT)) * DM + (i * 64 + lane) * 4);
; #pragma unroll
;                 for (int i = 0; i < 8; ++i) x[i] += pt[i]; }
; #pragma unroll
;             for (int i = 0; i < 8; ++i) *(f32x4*)(xr + (i * 64 + lane) * 4) = x[i];
	v_pk_add_f32 v[80:81], v[80:81], v[8:9]
	v_lshl_add_u64 v[8:9], v[28:29], 0, v[42:43]
	v_pk_add_f32 v[84:85], v[84:85], v[12:13]
	v_lshl_add_u64 v[12:13], v[28:29], 0, v[44:45]
	v_pk_add_f32 v[88:89], v[88:89], v[16:17]
	v_lshl_add_u64 v[16:17], v[28:29], 0, v[46:47]
	v_pk_add_f32 v[92:93], v[92:93], v[20:21]
	v_lshl_add_u64 v[20:21], v[28:29], 0, v[48:49]
	v_lshl_add_u64 v[28:29], v[28:29], 0, v[52:53]
	global_load_dwordx4 v[28:31], v[28:29], off
	v_pk_add_f32 v[90:91], v[90:91], v[18:19]
	v_pk_add_f32 v[94:95], v[94:95], v[22:23]
	global_load_dwordx4 v[16:19], v[16:17], off
	v_pk_add_f32 v[82:83], v[82:83], v[10:11]
	global_load_dwordx4 v[20:23], v[20:21], off
	v_pk_add_f32 v[86:87], v[86:87], v[14:15]
	global_load_dwordx4 v[8:11], v[8:9], off
	v_pk_add_f32 v[72:73], v[72:73], v[0:1]
	global_load_dwordx4 v[12:15], v[12:13], off
	v_pk_add_f32 v[74:75], v[74:75], v[2:3]
	v_pk_add_f32 v[76:77], v[76:77], v[4:5]
	v_pk_add_f32 v[78:79], v[78:79], v[6:7]
	s_waitcnt vmcnt(0)
	v_pk_add_f32 v[124:125], v[100:101], v[28:29]
	v_lshl_add_u64 v[28:29], v[70:71], 0, s[6:7]
	v_lshl_add_u64 v[0:1], v[28:29], 0, v[178:179]
	global_load_dwordx4 v[0:3], v[0:1], off
	v_pk_add_f32 v[112:113], v[88:89], v[16:17]
	v_pk_add_f32 v[116:117], v[92:93], v[20:21]
	v_lshl_add_u64 v[20:21], v[28:29], 0, v[48:49]
	v_pk_add_f32 v[80:81], v[80:81], v[8:9]
	v_pk_add_f32 v[114:115], v[94:95], v[22:23]
	v_pk_add_f32 v[84:85], v[84:85], v[12:13]
	v_lshl_add_u64 v[4:5], v[28:29], 0, v[40:41]
	v_lshl_add_u64 v[8:9], v[28:29], 0, v[42:43]
	v_lshl_add_u64 v[12:13], v[28:29], 0, v[44:45]
	v_lshl_add_u64 v[16:17], v[28:29], 0, v[46:47]
	global_load_dwordx4 v[20:23], v[20:21], off
	v_pk_add_f32 v[120:121], v[96:97], v[24:25]
	v_lshl_add_u64 v[24:25], v[28:29], 0, v[50:51]
	v_lshl_add_u64 v[28:29], v[28:29], 0, v[52:53]
	v_pk_add_f32 v[118:119], v[98:99], v[26:27]
	v_pk_add_f32 v[122:123], v[102:103], v[30:31]
	global_load_dwordx4 v[24:27], v[24:25], off
	v_pk_add_f32 v[82:83], v[82:83], v[10:11]
	global_load_dwordx4 v[28:31], v[28:29], off
	v_pk_add_f32 v[86:87], v[86:87], v[14:15]
	global_load_dwordx4 v[4:7], v[4:5], off
	v_pk_add_f32 v[110:111], v[90:91], v[18:19]
	global_load_dwordx4 v[8:11], v[8:9], off
	s_mov_b64 s[6:7], 0x3800000
	global_load_dwordx4 v[12:15], v[12:13], off
	s_waitcnt vmcnt(0)
	v_pk_add_f32 v[102:103], v[72:73], v[0:1]
	global_load_dwordx4 v[16:19], v[16:17], off
	v_lshl_add_u64 v[0:1], v[70:71], 0, s[6:7]
	v_pk_add_f32 v[100:101], v[74:75], v[2:3]
	v_lshl_add_u64 v[2:3], v[0:1], 0, v[178:179]
	v_pk_add_f32 v[72:73], v[122:123], v[30:31]
	v_pk_add_f32 v[74:75], v[124:125], v[28:29]
	global_load_dwordx4 v[28:31], v[2:3], off
	v_lshl_add_u64 v[2:3], v[0:1], 0, v[40:41]
	v_pk_add_f32 v[96:97], v[78:79], v[6:7]
	v_pk_add_f32 v[98:99], v[76:77], v[4:5]
	v_pk_add_f32 v[76:77], v[118:119], v[26:27]
	v_pk_add_f32 v[78:79], v[120:121], v[24:25]
	global_load_dwordx4 v[24:27], v[2:3], off
	v_lshl_add_u64 v[2:3], v[0:1], 0, v[42:43]
	v_pk_add_f32 v[92:93], v[82:83], v[10:11]
	v_pk_add_f32 v[94:95], v[80:81], v[8:9]
	v_pk_add_f32 v[80:81], v[114:115], v[22:23]
	v_pk_add_f32 v[82:83], v[116:117], v[20:21]
	global_load_dwordx4 v[20:23], v[2:3], off
	v_lshl_add_u64 v[2:3], v[0:1], 0, v[44:45]
	v_pk_add_f32 v[88:89], v[86:87], v[14:15]
	v_pk_add_f32 v[90:91], v[84:85], v[12:13]
	s_waitcnt vmcnt(0)
	v_pk_add_f32 v[84:85], v[110:111], v[18:19]
	v_pk_add_f32 v[86:87], v[112:113], v[16:17]
	global_load_dwordx4 v[16:19], v[2:3], off
	v_lshl_add_u64 v[2:3], v[0:1], 0, v[46:47]
	global_load_dwordx4 v[12:15], v[2:3], off
	v_lshl_add_u64 v[2:3], v[0:1], 0, v[48:49]
	global_load_dwordx4 v[8:11], v[2:3], off
	v_lshl_add_u64 v[2:3], v[0:1], 0, v[50:51]
	v_lshl_add_u64 v[0:1], v[0:1], 0, v[52:53]
	global_load_dwordx4 v[4:7], v[2:3], off
	v_pk_add_f32 v[30:31], v[100:101], v[30:31]
	global_load_dwordx4 v[0:3], v[0:1], off
	v_pk_add_f32 v[28:29], v[102:103], v[28:29]
	v_pk_add_f32 v[26:27], v[96:97], v[26:27]
	v_pk_add_f32 v[24:25], v[98:99], v[24:25]
	v_pk_add_f32 v[22:23], v[92:93], v[22:23]
	v_pk_add_f32 v[20:21], v[94:95], v[20:21]
	s_waitcnt vmcnt(0)
	v_pk_add_f32 v[18:19], v[88:89], v[18:19]
	v_pk_add_f32 v[16:17], v[90:91], v[16:17]
	v_pk_add_f32 v[14:15], v[84:85], v[14:15]
	v_pk_add_f32 v[12:13], v[86:87], v[12:13]
	v_pk_add_f32 v[10:11], v[80:81], v[10:11]
	v_pk_add_f32 v[8:9], v[82:83], v[8:9]
	v_pk_add_f32 v[6:7], v[76:77], v[6:7]
	v_pk_add_f32 v[4:5], v[78:79], v[4:5]
	v_pk_add_f32 v[2:3], v[72:73], v[2:3]
	v_pk_add_f32 v[0:1], v[74:75], v[0:1]
	global_store_dwordx4 v[68:69], v[28:31], off sc0 sc1
	global_store_dwordx4 v[66:67], v[24:27], off sc0 sc1
	global_store_dwordx4 v[64:65], v[20:23], off sc0 sc1
	global_store_dwordx4 v[62:63], v[16:19], off sc0 sc1
	global_store_dwordx4 v[60:61], v[12:15], off sc0 sc1
	global_store_dwordx4 v[58:59], v[8:11], off sc0 sc1
	global_store_dwordx4 v[56:57], v[4:7], off sc0 sc1
	global_store_dwordx4 v[54:55], v[0:3], off sc0 sc1
	s_branch .LBB0_3649

; #define PG8_STAGE(bufoff, gbase, voff) do { _Pragma("unroll") for (int _i = 0; _i < 2; ++_i) \
;         __builtin_amdgcn_global_load_lds((const unsigned*)((const char*)(gbase) + (voff)[_i]), (LAS unsigned*)(lds + (bufoff) + ldsw + _i * 8192), 16, 0, 0); } while (0)
; #define PG8_LDA(dst, b, h) do { _Pragma("unroll") for (int m = 0; m < 4; ++m) _Pragma("unroll") for (int k = 0; k < 2; ++k) dst[m][k] = *(const LAS bf16x8*)(lds + PG8_SA(b, h) + aoff + m * 2048 + k * 1024); } while (0)
; #define PG8_LDB(dst, b, h) do { _Pragma("unroll") for (int n = 0; n < 2; ++n) _Pragma("unroll") for (int k = 0; k < 2; ++k) dst[n][k] = *(const LAS bf16x8*)(lds + PG8_SB(b, h) + boff + n * 2048 + k * 1024); } while (0)
; #define PG8_MMA(ai, bj, At, Bt) do { __builtin_amdgcn_s_setprio(1); _Pragma("unroll") for (int m = 0; m < 4; ++m) _Pragma("unroll") for (int n = 0; n < 2; ++n) _Pragma("unroll") for (int k = 0; k < 2; ++k) \
;         acc[ai][bj][m][n] = __builtin_amdgcn_mfma_f32_16x16x32_bf16(Bt[n][k], At[m][k], acc[ai][bj][m][n], 0, 0, 0); __builtin_amdgcn_s_setprio(0); } while (0)
; #define PG8_WAIT_L(n) asm volatile("s_waitcnt lgkmcnt(" #n ")" ::: "memory")
; #define PG8_BAR __builtin_amdgcn_s_barrier()
; #define PG8_SCHED __builtin_amdgcn_sched_barrier(0)
; template <class Epi>
; __device__ __forceinline__ void gemm_phase(LAS unsigned char* lds, const Gemm g, const StaticOrder S, const Epi E) {
;     ...
;             PG8_LDB(B0, 0, 0); PG8_SCHED; PG8_LDA(At, 0, 0); PG8_STAGE(PG8_SA(1, 1), a1 + hstep, voffA);
;             PG8_WAIT_L(8); PG8_BAR; PG8_WAIT_L(0); PG8_MMA(0, 0, At, B0); PG8_BAR; PG8_SCHED;
;             PG8_LDB(B1, 0, 1); PG8_STAGE(PG8_SB(0, 0), b2, voffA);
;             PG8_BAR; PG8_WAIT_L(0); PG8_MMA(0, 1, At, B1); PG8_BAR;
;             PG8_LDA(At, 0, 1); PG8_STAGE(PG8_SA(0, 0), a2, voffA);
;             PG8_BAR; PG8_WAIT_L(0); PG8_MMA(1, 0, At, B0); PG8_BAR; PG8_SCHED;
.LBB0_3723:
	s_add_u32 s14, s50, 0xfff80080
	s_addc_u32 s30, s51, -1
	s_add_i32 s31, 0, 0x10000
	v_add_u32_e32 v134, s31, v137
	ds_read_b128 v[140:143], v134
	ds_read_b128 v[144:147], v134 offset:1024
	ds_read_b128 v[148:151], v134 offset:2048
	ds_read_b128 v[152:155], v134 offset:3072
	s_cmp_eq_u32 s64, 28
	s_cselect_b32 s55, s3, s30
	s_cselect_b32 s54, s26, s14
	s_cselect_b32 s53, s1, s29
	s_cselect_b32 s52, s27, s28
	v_lshl_add_u64 v[134:135], s[50:51], 0, v[130:131]
	s_add_i32 m0, s47, 0xc000
	ds_read_b128 v[156:159], v139
	ds_read_b128 v[160:163], v139 offset:1024
	ds_read_b128 v[164:167], v139 offset:2048
	ds_read_b128 v[168:171], v139 offset:3072
	ds_read_b128 v[172:175], v139 offset:4096
	ds_read_b128 v[194:197], v139 offset:5120
	ds_read_b128 v[198:201], v139 offset:6144
	ds_read_b128 v[202:205], v139 offset:7168
	global_load_lds_dwordx4 v[134:135], off
	v_lshl_add_u64 v[134:135], s[50:51], 0, v[132:133]
	s_add_i32 m0, s47, 0xe000
	s_nop 0
	global_load_lds_dwordx4 v[134:135], off
	s_waitcnt lgkmcnt(8)
	s_barrier
	s_waitcnt lgkmcnt(0)
	s_setprio 1
	s_waitcnt lgkmcnt(0)
	v_mfma_f32_16x16x32_bf16 v[120:123], v[140:143], v[156:159], v[120:123]
	v_mfma_f32_16x16x32_bf16 v[124:127], v[148:151], v[156:159], v[124:127]
	v_mfma_f32_16x16x32_bf16 v[104:107], v[140:143], v[164:167], v[104:107]
	v_mfma_f32_16x16x32_bf16 v[108:111], v[148:151], v[164:167], v[108:111]
	v_mfma_f32_16x16x32_bf16 v[88:91], v[140:143], v[172:175], v[88:91]
	v_mfma_f32_16x16x32_bf16 v[92:95], v[148:151], v[172:175], v[92:95]
	v_mfma_f32_16x16x32_bf16 v[72:75], v[140:143], v[198:201], v[72:75]
	v_mfma_f32_16x16x32_bf16 v[76:79], v[148:151], v[198:201], v[76:79]
	v_mfma_f32_16x16x32_bf16 v[120:123], v[144:147], v[160:163], v[120:123]
	v_mfma_f32_16x16x32_bf16 v[124:127], v[152:155], v[160:163], v[124:127]
	v_mfma_f32_16x16x32_bf16 v[104:107], v[144:147], v[168:171], v[104:107]
	v_mfma_f32_16x16x32_bf16 v[108:111], v[152:155], v[168:171], v[108:111]
	v_mfma_f32_16x16x32_bf16 v[88:91], v[144:147], v[194:197], v[88:91]
	v_mfma_f32_16x16x32_bf16 v[92:95], v[152:155], v[194:197], v[92:95]
	v_mfma_f32_16x16x32_bf16 v[72:75], v[144:147], v[202:205], v[72:75]
	v_mfma_f32_16x16x32_bf16 v[76:79], v[152:155], v[202:205], v[76:79]
	s_setprio 0
	s_barrier
	s_add_i32 s14, 0, 0x14000
	v_add_u32_e32 v134, s14, v137
	s_add_i32 s30, s31, s58
	ds_read_b128 v[206:209], v134
	ds_read_b128 v[220:223], v134 offset:1024
	ds_read_b128 v[228:231], v134 offset:2048
	ds_read_b128 v[232:235], v134 offset:3072
	v_lshl_add_u64 v[134:135], s[52:53], 0, v[178:179]
	s_mov_b32 m0, s30
	v_lshl_add_u64 v[210:211], s[52:53], 0, v[128:129]
	global_load_lds_dwordx4 v[134:135], off
	s_add_i32 m0, s30, 0x2000
	s_nop 0
	global_load_lds_dwordx4 v[210:211], off
	s_barrier
	s_waitcnt lgkmcnt(0)
	s_setprio 1
	s_waitcnt lgkmcnt(0)
	v_mfma_f32_16x16x32_bf16 v[112:115], v[206:209], v[156:159], v[112:115]
	v_mfma_f32_16x16x32_bf16 v[116:119], v[228:231], v[156:159], v[116:119]
	v_mfma_f32_16x16x32_bf16 v[96:99], v[206:209], v[164:167], v[96:99]
	v_mfma_f32_16x16x32_bf16 v[100:103], v[228:231], v[164:167], v[100:103]
	v_mfma_f32_16x16x32_bf16 v[80:83], v[206:209], v[172:175], v[80:83]
	v_mfma_f32_16x16x32_bf16 v[84:87], v[228:231], v[172:175], v[84:87]
	v_mfma_f32_16x16x32_bf16 v[64:67], v[206:209], v[198:201], v[64:67]
	v_mfma_f32_16x16x32_bf16 v[68:71], v[228:231], v[198:201], v[68:71]
	v_mfma_f32_16x16x32_bf16 v[112:115], v[220:223], v[160:163], v[112:115]
	v_mfma_f32_16x16x32_bf16 v[116:119], v[232:235], v[160:163], v[116:119]
	v_mfma_f32_16x16x32_bf16 v[96:99], v[220:223], v[168:171], v[96:99]
	v_mfma_f32_16x16x32_bf16 v[100:103], v[232:235], v[168:171], v[100:103]
	v_mfma_f32_16x16x32_bf16 v[80:83], v[220:223], v[194:197], v[80:83]
	v_mfma_f32_16x16x32_bf16 v[84:87], v[232:235], v[194:197], v[84:87]
	v_mfma_f32_16x16x32_bf16 v[64:67], v[220:223], v[202:205], v[64:67]
	v_mfma_f32_16x16x32_bf16 v[68:71], v[232:235], v[202:205], v[68:71]
	s_setprio 0
	s_barrier
	s_mov_b32 m0, s47
	v_lshl_add_u64 v[236:237], s[54:55], 0, v[178:179]
	ds_read_b128 v[156:159], v139 offset:16384
	ds_read_b128 v[160:163], v139 offset:17408
	ds_read_b128 v[164:167], v139 offset:18432
	ds_read_b128 v[168:171], v139 offset:19456
	ds_read_b128 v[172:175], v139 offset:20480
	ds_read_b128 v[194:197], v139 offset:21504
	ds_read_b128 v[198:201], v139 offset:22528
	ds_read_b128 v[202:205], v139 offset:23552
	global_load_lds_dwordx4 v[236:237], off
	v_lshl_add_u64 v[238:239], s[54:55], 0, v[128:129]
	s_mov_b32 m0, s49
	s_nop 0
	global_load_lds_dwordx4 v[238:239], off
	s_barrier
	s_waitcnt lgkmcnt(0)
	s_setprio 1
	s_waitcnt lgkmcnt(0)
	v_mfma_f32_16x16x32_bf16 v[56:59], v[140:143], v[156:159], v[56:59]
	v_mfma_f32_16x16x32_bf16 v[60:63], v[148:151], v[156:159], v[60:63]
	v_mfma_f32_16x16x32_bf16 v[40:43], v[140:143], v[164:167], v[40:43]
	v_mfma_f32_16x16x32_bf16 v[44:47], v[148:151], v[164:167], v[44:47]
	v_mfma_f32_16x16x32_bf16 v[24:27], v[140:143], v[172:175], v[24:27]
	v_mfma_f32_16x16x32_bf16 v[28:31], v[148:151], v[172:175], v[28:31]
	v_mfma_f32_16x16x32_bf16 v[8:11], v[140:143], v[198:201], v[8:11]
	v_mfma_f32_16x16x32_bf16 v[12:15], v[148:151], v[198:201], v[12:15]
	v_mfma_f32_16x16x32_bf16 v[56:59], v[144:147], v[160:163], v[56:59]
	v_mfma_f32_16x16x32_bf16 v[60:63], v[152:155], v[160:163], v[60:63]
	v_mfma_f32_16x16x32_bf16 v[40:43], v[144:147], v[168:171], v[40:43]
	v_mfma_f32_16x16x32_bf16 v[44:47], v[152:155], v[168:171], v[44:47]
	v_mfma_f32_16x16x32_bf16 v[24:27], v[144:147], v[194:197], v[24:27]
	v_mfma_f32_16x16x32_bf16 v[28:31], v[152:155], v[194:197], v[28:31]
	v_mfma_f32_16x16x32_bf16 v[8:11], v[144:147], v[202:205], v[8:11]
	v_mfma_f32_16x16x32_bf16 v[12:15], v[152:155], v[202:205], v[12:15]
	s_setprio 0
	s_barrier
; #define PG8_STAGE(bufoff, gbase, voff) do { _Pragma("unroll") for (int _i = 0; _i < 2; ++_i) \
;         __builtin_amdgcn_global_load_lds((const unsigned*)((const char*)(gbase) + (voff)[_i]), (LAS unsigned*)(lds + (bufoff) + ldsw + _i * 8192), 16, 0, 0); } while (0)
; #define PG8_LDA(dst, b, h) do { _Pragma("unroll") for (int m = 0; m < 4; ++m) _Pragma("unroll") for (int k = 0; k < 2; ++k) dst[m][k] = *(const LAS bf16x8*)(lds + PG8_SA(b, h) + aoff + m * 2048 + k * 1024); } while (0)
; #define PG8_LDB(dst, b, h) do { _Pragma("unroll") for (int n = 0; n < 2; ++n) _Pragma("unroll") for (int k = 0; k < 2; ++k) dst[n][k] = *(const LAS bf16x8*)(lds + PG8_SB(b, h) + boff + n * 2048 + k * 1024); } while (0)
; #define PG8_MMA(ai, bj, At, Bt) do { __builtin_amdgcn_s_setprio(1); _Pragma("unroll") for (int m = 0; m < 4; ++m) _Pragma("unroll") for (int n = 0; n < 2; ++n) _Pragma("unroll") for (int k = 0; k < 2; ++k) \
;         acc[ai][bj][m][n] = __builtin_amdgcn_mfma_f32_16x16x32_bf16(Bt[n][k], At[m][k], acc[ai][bj][m][n], 0, 0, 0); __builtin_amdgcn_s_setprio(0); } while (0)
; #define PG8_WAIT_V(n) asm volatile("s_waitcnt vmcnt(" #n ")" ::: "memory")
; #define PG8_WAIT_L(n) asm volatile("s_waitcnt lgkmcnt(" #n ")" ::: "memory")
; #define PG8_BAR __builtin_amdgcn_s_barrier()
; #define PG8_SCHED __builtin_amdgcn_sched_barrier(0)
; template <class Epi>
; __device__ __forceinline__ void gemm_phase(LAS unsigned char* lds, const Gemm g, const StaticOrder S, const Epi E) {
;     ...
;             PG8_STAGE(PG8_SB(0, 1), b2 + hstep, voffA);
;             PG8_WAIT_V(6); PG8_BAR; PG8_MMA(1, 1, At, B1); PG8_BAR;
;             PG8_LDB(B0, 1, 0); PG8_SCHED; PG8_LDA(At, 1, 0); PG8_STAGE(PG8_SA(0, 1), a2 + hstep, voffA);
;             PG8_WAIT_L(8); PG8_BAR; PG8_WAIT_L(0); PG8_MMA(0, 0, At, B0); PG8_BAR; PG8_SCHED;
;             PG8_LDB(B1, 1, 1); PG8_STAGE(PG8_SB(1, 0), b3, voffA);
;             PG8_BAR; PG8_WAIT_L(0); PG8_MMA(0, 1, At, B1); PG8_BAR;
;             PG8_LDA(At, 1, 1); PG8_STAGE(PG8_SA(1, 0), a3, voffA);
	s_add_u32 s30, s52, 0x80000
	s_addc_u32 s31, s53, 0
	s_add_i32 s14, s14, s58
	v_lshl_add_u64 v[140:141], s[30:31], 0, v[178:179]
	s_mov_b32 m0, s14
	s_nop 0
	global_load_lds_dwordx4 v[140:141], off
	v_lshl_add_u64 v[140:141], s[30:31], 0, v[128:129]
	s_add_i32 m0, s14, 0x2000
	s_nop 0
	global_load_lds_dwordx4 v[140:141], off
	s_waitcnt vmcnt(6)
	s_barrier
	s_setprio 1
	v_mfma_f32_16x16x32_bf16 v[48:51], v[206:209], v[156:159], v[48:51]
	v_mfma_f32_16x16x32_bf16 v[52:55], v[228:231], v[156:159], v[52:55]
	v_mfma_f32_16x16x32_bf16 v[32:35], v[206:209], v[164:167], v[32:35]
	v_mfma_f32_16x16x32_bf16 v[36:39], v[228:231], v[164:167], v[36:39]
	v_mfma_f32_16x16x32_bf16 v[16:19], v[206:209], v[172:175], v[16:19]
	v_mfma_f32_16x16x32_bf16 v[20:23], v[228:231], v[172:175], v[20:23]
	v_mfma_f32_16x16x32_bf16 v[0:3], v[206:209], v[198:201], v[0:3]
	v_mfma_f32_16x16x32_bf16 v[4:7], v[228:231], v[198:201], v[4:7]
	v_mfma_f32_16x16x32_bf16 v[48:51], v[220:223], v[160:163], v[48:51]
	v_mfma_f32_16x16x32_bf16 v[52:55], v[232:235], v[160:163], v[52:55]
	v_mfma_f32_16x16x32_bf16 v[32:35], v[220:223], v[168:171], v[32:35]
	v_mfma_f32_16x16x32_bf16 v[36:39], v[232:235], v[168:171], v[36:39]
	v_mfma_f32_16x16x32_bf16 v[16:19], v[220:223], v[194:197], v[16:19]
	v_mfma_f32_16x16x32_bf16 v[20:23], v[232:235], v[194:197], v[20:23]
	v_mfma_f32_16x16x32_bf16 v[0:3], v[220:223], v[202:205], v[0:3]
	v_mfma_f32_16x16x32_bf16 v[4:7], v[232:235], v[202:205], v[4:7]
	s_setprio 0
	s_barrier
	s_add_i32 s14, 0, 0x18000
	v_add_u32_e32 v152, s14, v137
	ds_read_b128 v[140:143], v152
	ds_read_b128 v[144:147], v152 offset:1024
	ds_read_b128 v[148:151], v152 offset:2048
	ds_read_b128 v[152:155], v152 offset:3072
	s_add_u32 s30, s54, 0x80000
	s_addc_u32 s31, s55, 0
	s_mov_b32 m0, s59
	v_lshl_add_u64 v[206:207], s[30:31], 0, v[178:179]
	ds_read_b128 v[156:159], v139 offset:32768
	ds_read_b128 v[160:163], v139 offset:33792
	ds_read_b128 v[164:167], v139 offset:34816
	ds_read_b128 v[168:171], v139 offset:35840
	ds_read_b128 v[172:175], v139 offset:36864
	ds_read_b128 v[194:197], v139 offset:37888
	ds_read_b128 v[198:201], v139 offset:38912
	ds_read_b128 v[202:205], v139 offset:39936
	global_load_lds_dwordx4 v[206:207], off
	v_lshl_add_u64 v[206:207], s[30:31], 0, v[128:129]
	s_mov_b32 m0, s60
	s_nop 0
	global_load_lds_dwordx4 v[206:207], off
	s_waitcnt lgkmcnt(8)
	s_barrier
	s_waitcnt lgkmcnt(0)
	s_setprio 1
	s_waitcnt lgkmcnt(0)
	v_mfma_f32_16x16x32_bf16 v[120:123], v[140:143], v[156:159], v[120:123]
	v_mfma_f32_16x16x32_bf16 v[124:127], v[148:151], v[156:159], v[124:127]
	v_mfma_f32_16x16x32_bf16 v[104:107], v[140:143], v[164:167], v[104:107]
	v_mfma_f32_16x16x32_bf16 v[108:111], v[148:151], v[164:167], v[108:111]
	v_mfma_f32_16x16x32_bf16 v[88:91], v[140:143], v[172:175], v[88:91]
	v_mfma_f32_16x16x32_bf16 v[92:95], v[148:151], v[172:175], v[92:95]
	v_mfma_f32_16x16x32_bf16 v[72:75], v[140:143], v[198:201], v[72:75]
	v_mfma_f32_16x16x32_bf16 v[76:79], v[148:151], v[198:201], v[76:79]
	v_mfma_f32_16x16x32_bf16 v[120:123], v[144:147], v[160:163], v[120:123]
	v_mfma_f32_16x16x32_bf16 v[124:127], v[152:155], v[160:163], v[124:127]
	v_mfma_f32_16x16x32_bf16 v[104:107], v[144:147], v[168:171], v[104:107]
	v_mfma_f32_16x16x32_bf16 v[108:111], v[152:155], v[168:171], v[108:111]
	v_mfma_f32_16x16x32_bf16 v[88:91], v[144:147], v[194:197], v[88:91]
	v_mfma_f32_16x16x32_bf16 v[92:95], v[152:155], v[194:197], v[92:95]
	v_mfma_f32_16x16x32_bf16 v[72:75], v[144:147], v[202:205], v[72:75]
	v_mfma_f32_16x16x32_bf16 v[76:79], v[152:155], v[202:205], v[76:79]
	s_setprio 0
	s_barrier
	s_add_i32 s54, 0, 0x1c000
	s_add_i32 s14, s14, s58
	v_add_u32_e32 v227, s54, v137
	v_lshl_add_u64 v[134:135], v[134:135], 0, s[34:35]
	s_mov_b32 m0, s14
	ds_read_b128 v[206:209], v227
	ds_read_b128 v[220:223], v227 offset:1024
	ds_read_b128 v[228:231], v227 offset:2048
	ds_read_b128 v[232:235], v227 offset:3072
	global_load_lds_dwordx4 v[134:135], off
	v_lshl_add_u64 v[134:135], v[210:211], 0, s[34:35]
	s_add_i32 m0, s14, 0x2000
	s_nop 0
	global_load_lds_dwordx4 v[134:135], off
	s_barrier
	s_waitcnt lgkmcnt(0)
	s_setprio 1
	s_waitcnt lgkmcnt(0)
	v_mfma_f32_16x16x32_bf16 v[112:115], v[206:209], v[156:159], v[112:115]
	v_mfma_f32_16x16x32_bf16 v[116:119], v[228:231], v[156:159], v[116:119]
	v_mfma_f32_16x16x32_bf16 v[96:99], v[206:209], v[164:167], v[96:99]
	v_mfma_f32_16x16x32_bf16 v[100:103], v[228:231], v[164:167], v[100:103]
	v_mfma_f32_16x16x32_bf16 v[80:83], v[206:209], v[172:175], v[80:83]
	v_mfma_f32_16x16x32_bf16 v[84:87], v[228:231], v[172:175], v[84:87]
	v_mfma_f32_16x16x32_bf16 v[64:67], v[206:209], v[198:201], v[64:67]
	v_mfma_f32_16x16x32_bf16 v[68:71], v[228:231], v[198:201], v[68:71]
	v_mfma_f32_16x16x32_bf16 v[112:115], v[220:223], v[160:163], v[112:115]
	v_mfma_f32_16x16x32_bf16 v[116:119], v[232:235], v[160:163], v[116:119]
	v_mfma_f32_16x16x32_bf16 v[96:99], v[220:223], v[168:171], v[96:99]
	v_mfma_f32_16x16x32_bf16 v[100:103], v[232:235], v[168:171], v[100:103]
	v_mfma_f32_16x16x32_bf16 v[80:83], v[220:223], v[194:197], v[80:83]
	v_mfma_f32_16x16x32_bf16 v[84:87], v[232:235], v[194:197], v[84:87]
	v_mfma_f32_16x16x32_bf16 v[64:67], v[220:223], v[202:205], v[64:67]
	v_mfma_f32_16x16x32_bf16 v[68:71], v[232:235], v[202:205], v[68:71]
	s_setprio 0
	s_barrier
	s_mov_b32 m0, s61
	v_lshl_add_u64 v[134:135], v[236:237], 0, s[34:35]
	ds_read_b128 v[156:159], v139 offset:49152
	ds_read_b128 v[160:163], v139 offset:50176
	ds_read_b128 v[164:167], v139 offset:51200
	ds_read_b128 v[168:171], v139 offset:52224
	ds_read_b128 v[172:175], v139 offset:53248
	ds_read_b128 v[194:197], v139 offset:54272
	ds_read_b128 v[198:201], v139 offset:55296
	ds_read_b128 v[202:205], v139 offset:56320
	global_load_lds_dwordx4 v[134:135], off
	v_lshl_add_u64 v[134:135], v[238:239], 0, s[34:35]
	s_mov_b32 m0, s62
	s_nop 0
	global_load_lds_dwordx4 v[134:135], off
	s_barrier
; #define PG8_STAGE(bufoff, gbase, voff) do { _Pragma("unroll") for (int _i = 0; _i < 2; ++_i) \
;         __builtin_amdgcn_global_load_lds((const unsigned*)((const char*)(gbase) + (voff)[_i]), (LAS unsigned*)(lds + (bufoff) + ldsw + _i * 8192), 16, 0, 0); } while (0)
; #define PG8_LDA(dst, b, h) do { _Pragma("unroll") for (int m = 0; m < 4; ++m) _Pragma("unroll") for (int k = 0; k < 2; ++k) dst[m][k] = *(const LAS bf16x8*)(lds + PG8_SA(b, h) + aoff + m * 2048 + k * 1024); } while (0)
; #define PG8_MMA(ai, bj, At, Bt) do { __builtin_amdgcn_s_setprio(1); _Pragma("unroll") for (int m = 0; m < 4; ++m) _Pragma("unroll") for (int n = 0; n < 2; ++n) _Pragma("unroll") for (int k = 0; k < 2; ++k) \
;         acc[ai][bj][m][n] = __builtin_amdgcn_mfma_f32_16x16x32_bf16(Bt[n][k], At[m][k], acc[ai][bj][m][n], 0, 0, 0); __builtin_amdgcn_s_setprio(0); } while (0)
; #define PG8_WAIT_V(n) asm volatile("s_waitcnt vmcnt(" #n ")" ::: "memory")
; #define PG8_WAIT_L(n) asm volatile("s_waitcnt lgkmcnt(" #n ")" ::: "memory")
; #define PG8_BAR __builtin_amdgcn_s_barrier()
; #define PG8_SCHED __builtin_amdgcn_sched_barrier(0)
; template <class Epi>
; __device__ __forceinline__ void gemm_phase(LAS unsigned char* lds, const Gemm g, const StaticOrder S, const Epi E) {
;     ...
;             PG8_LDA(At, 1, 1); PG8_STAGE(PG8_SA(1, 0), a3, voffA);
;             PG8_BAR; PG8_WAIT_L(0); PG8_MMA(1, 0, At, B0); PG8_BAR; PG8_SCHED;
;             PG8_STAGE(PG8_SB(1, 1), b3 + hstep, voffA);
;             PG8_WAIT_V(6); PG8_BAR; PG8_MMA(1, 1, At, B1); PG8_BAR;
;     __device__ __forceinline__ void operator()(AccRef acc, const pg8::Unit& u, int wr, int wc, int fr, int fq) const {
;     ...
;             for (int m = 0; m < 4; ++m) { bf16_t* rowp = G + (size_t)(row0 + ai * 128 + m * 16) * FH + col0;
; #pragma unroll
;                 for (int bj = 0; bj < 2; ++bj) { const f32x4 gq = acc[ai][bj][m][0], uq = acc[ai][bj][m][1]; float v[4];
; #pragma unroll
;                     for (int i = 0; i < 4; ++i) v[i] = gq[i] * uq[i] * __builtin_amdgcn_rcpf(1.f + __builtin_amdgcn_exp2f(-gq[i] * LOG2E));
	s_waitcnt lgkmcnt(0)
	s_setprio 1
	s_waitcnt lgkmcnt(0)
	v_mfma_f32_16x16x32_bf16 v[56:59], v[140:143], v[156:159], v[56:59]
	v_mfma_f32_16x16x32_bf16 v[60:63], v[148:151], v[156:159], v[60:63]
	v_mfma_f32_16x16x32_bf16 v[40:43], v[140:143], v[164:167], v[40:43]
	v_mfma_f32_16x16x32_bf16 v[44:47], v[148:151], v[164:167], v[44:47]
	v_mfma_f32_16x16x32_bf16 v[24:27], v[140:143], v[172:175], v[24:27]
	v_mfma_f32_16x16x32_bf16 v[28:31], v[148:151], v[172:175], v[28:31]
	v_mfma_f32_16x16x32_bf16 v[8:11], v[140:143], v[198:201], v[8:11]
	v_mfma_f32_16x16x32_bf16 v[12:15], v[148:151], v[198:201], v[12:15]
	v_mfma_f32_16x16x32_bf16 v[56:59], v[144:147], v[160:163], v[56:59]
	v_mfma_f32_16x16x32_bf16 v[60:63], v[152:155], v[160:163], v[60:63]
	v_mfma_f32_16x16x32_bf16 v[40:43], v[144:147], v[168:171], v[40:43]
	v_mfma_f32_16x16x32_bf16 v[44:47], v[152:155], v[168:171], v[44:47]
	v_mfma_f32_16x16x32_bf16 v[24:27], v[144:147], v[194:197], v[24:27]
	v_mfma_f32_16x16x32_bf16 v[28:31], v[152:155], v[194:197], v[28:31]
	v_mfma_f32_16x16x32_bf16 v[8:11], v[144:147], v[202:205], v[8:11]
	v_mfma_f32_16x16x32_bf16 v[12:15], v[152:155], v[202:205], v[12:15]
	s_setprio 0
	s_barrier
	s_add_u32 s30, s52, 0x80080
	s_addc_u32 s31, s53, 0
	s_add_i32 s14, s54, s58
	v_lshl_add_u64 v[134:135], s[30:31], 0, v[178:179]
	s_mov_b32 m0, s14
	s_nop 0
	global_load_lds_dwordx4 v[134:135], off
	v_lshl_add_u64 v[134:135], s[30:31], 0, v[128:129]
	s_add_i32 m0, s14, 0x2000
	s_nop 0
	global_load_lds_dwordx4 v[134:135], off
	s_waitcnt vmcnt(6)
	s_barrier
	s_setprio 1
	v_mfma_f32_16x16x32_bf16 v[48:51], v[206:209], v[156:159], v[48:51]
	v_mfma_f32_16x16x32_bf16 v[52:55], v[228:231], v[156:159], v[52:55]
	v_mfma_f32_16x16x32_bf16 v[32:35], v[206:209], v[164:167], v[32:35]
	v_mfma_f32_16x16x32_bf16 v[36:39], v[228:231], v[164:167], v[36:39]
	v_mfma_f32_16x16x32_bf16 v[16:19], v[206:209], v[172:175], v[16:19]
	v_mfma_f32_16x16x32_bf16 v[20:23], v[228:231], v[172:175], v[20:23]
	v_mfma_f32_16x16x32_bf16 v[0:3], v[206:209], v[198:201], v[0:3]
	v_mfma_f32_16x16x32_bf16 v[4:7], v[228:231], v[198:201], v[4:7]
	v_mfma_f32_16x16x32_bf16 v[48:51], v[220:223], v[160:163], v[48:51]
	v_mfma_f32_16x16x32_bf16 v[52:55], v[232:235], v[160:163], v[52:55]
	v_mfma_f32_16x16x32_bf16 v[32:35], v[220:223], v[168:171], v[32:35]
	v_mfma_f32_16x16x32_bf16 v[36:39], v[232:235], v[168:171], v[36:39]
	v_mfma_f32_16x16x32_bf16 v[16:19], v[220:223], v[194:197], v[16:19]
	v_mfma_f32_16x16x32_bf16 v[20:23], v[232:235], v[194:197], v[20:23]
	v_mfma_f32_16x16x32_bf16 v[0:3], v[220:223], v[202:205], v[0:3]
	v_mfma_f32_16x16x32_bf16 v[4:7], v[232:235], v[202:205], v[4:7]
	s_setprio 0
	s_barrier
	s_add_i32 s64, s64, 2
	s_add_u32 s50, s50, 0x100
	s_addc_u32 s51, s51, 0
	s_add_u32 s28, s28, 0x100
	s_addc_u32 s29, s29, 0
	s_cmp_gt_u32 s64, 29
	s_cbranch_scc0 .LBB0_3723
	v_mul_f32_e32 v116, v116, v112
	v_mul_f32_e32 v112, 0xbfb8aa3b, v112
	v_exp_f32_e32 v112, v112
	v_mul_f32_e32 v100, v100, v96
	v_mul_f32_e32 v96, 0xbfb8aa3b, v96
	v_exp_f32_e32 v96, v96
	v_mul_f32_e32 v84, v84, v80
	v_mul_f32_e32 v80, 0xbfb8aa3b, v80
	v_add_f32_e32 v112, 1.0, v112
	v_exp_f32_e32 v80, v80
	v_rcp_f32_e32 v112, v112
	v_mul_f32_e32 v68, v68, v64
	v_mul_f32_e32 v64, 0xbfb8aa3b, v64
	v_add_f32_e32 v96, 1.0, v96
	v_exp_f32_e32 v64, v64
	v_rcp_f32_e32 v96, v96
	v_mul_f32_e32 v52, v52, v48
	v_mul_f32_e32 v48, 0xbfb8aa3b, v48
	v_add_f32_e32 v80, 1.0, v80
	v_exp_f32_e32 v48, v48
	v_mul_f32_e32 v112, v116, v112
	v_mul_f32_e32 v116, v117, v113
	v_mul_f32_e32 v113, 0xbfb8aa3b, v113
	v_rcp_f32_e32 v80, v80
	v_mul_f32_e32 v36, v36, v32
	v_mul_f32_e32 v32, 0xbfb8aa3b, v32
	v_exp_f32_e32 v113, v113
	v_add_f32_e32 v64, 1.0, v64
	v_exp_f32_e32 v32, v32
	v_mul_f32_e32 v96, v100, v96
	v_mul_f32_e32 v100, v101, v97
	v_mul_f32_e32 v97, 0xbfb8aa3b, v97
	v_rcp_f32_e32 v64, v64
	v_mul_f32_e32 v20, v20, v16
	v_mul_f32_e32 v16, 0xbfb8aa3b, v16
	v_exp_f32_e32 v97, v97
	v_add_f32_e32 v48, 1.0, v48
	v_exp_f32_e32 v16, v16
	v_mul_f32_e32 v124, v124, v120
	v_mul_f32_e32 v120, 0xbfb8aa3b, v120
	v_mul_f32_e32 v108, v108, v104
	v_mul_f32_e32 v104, 0xbfb8aa3b, v104
	v_mul_f32_e32 v92, v92, v88
	v_mul_f32_e32 v88, 0xbfb8aa3b, v88
	v_mul_f32_e32 v80, v84, v80
	v_mul_f32_e32 v84, v85, v81
	v_mul_f32_e32 v81, 0xbfb8aa3b, v81
	v_mul_f32_e32 v76, v76, v72
	v_mul_f32_e32 v72, 0xbfb8aa3b, v72
	v_mul_f32_e32 v60, v60, v56
	v_mul_f32_e32 v56, 0xbfb8aa3b, v56
	v_rcp_f32_e32 v48, v48
	v_mul_f32_e32 v44, v44, v40
	v_mul_f32_e32 v40, 0xbfb8aa3b, v40
	v_mul_f32_e32 v28, v28, v24
	v_mul_f32_e32 v24, 0xbfb8aa3b, v24
	v_mul_f32_e32 v12, v12, v8
	v_mul_f32_e32 v8, 0xbfb8aa3b, v8
	v_mul_f32_e32 v4, v4, v0
	v_mul_f32_e32 v0, 0xbfb8aa3b, v0
	v_exp_f32_e32 v120, v120
	v_add_f32_e32 v113, 1.0, v113
	v_exp_f32_e32 v104, v104
	v_exp_f32_e32 v88, v88
	v_exp_f32_e32 v81, v81
	v_exp_f32_e32 v72, v72
	v_exp_f32_e32 v56, v56
	v_exp_f32_e32 v40, v40
	v_add_f32_e32 v32, 1.0, v32
	v_exp_f32_e32 v24, v24
	v_exp_f32_e32 v8, v8
	v_exp_f32_e32 v0, v0
	v_rcp_f32_e32 v113, v113
	v_mul_f32_e32 v64, v68, v64
	v_mul_f32_e32 v68, v69, v65
	v_mul_f32_e32 v65, 0xbfb8aa3b, v65
	v_rcp_f32_e32 v32, v32
	v_add_f32_e32 v97, 1.0, v97
	v_exp_f32_e32 v65, v65
	v_add_f32_e32 v16, 1.0, v16
	v_rcp_f32_e32 v97, v97
	v_mul_f32_e32 v48, v52, v48
	v_mul_f32_e32 v52, v53, v49
	v_mul_f32_e32 v49, 0xbfb8aa3b, v49
	v_rcp_f32_e32 v16, v16
	v_add_f32_e32 v120, 1.0, v120
	v_add_f32_e32 v104, 1.0, v104
	v_add_f32_e32 v88, 1.0, v88
	v_add_f32_e32 v81, 1.0, v81
	v_add_f32_e32 v72, 1.0, v72
	v_add_f32_e32 v56, 1.0, v56
	v_exp_f32_e32 v49, v49
	v_add_f32_e32 v40, 1.0, v40
	v_add_f32_e32 v24, 1.0, v24
	v_add_f32_e32 v8, 1.0, v8
	v_add_f32_e32 v0, 1.0, v0
; __device__ __forceinline__ unsigned cvt_pk_bf16(float lo, float hi) { unsigned r; asm("v_cvt_pk_bf16_f32 %0, %1, %2" : "=v"(r) : "v"(lo), "v"(hi)); return r; }
;     __device__ __forceinline__ void operator()(AccRef acc, const pg8::Unit& u, int wr, int wc, int fr, int fq) const {
;     ...
;             for (int m = 0; m < 4; ++m) { bf16_t* rowp = G + (size_t)(row0 + ai * 128 + m * 16) * FH + col0;
; #pragma unroll
;                 for (int bj = 0; bj < 2; ++bj) { const f32x4 gq = acc[ai][bj][m][0], uq = acc[ai][bj][m][1]; float v[4];
; #pragma unroll
;                     for (int i = 0; i < 4; ++i) v[i] = gq[i] * uq[i] * __builtin_amdgcn_rcpf(1.f + __builtin_amdgcn_exp2f(-gq[i] * LOG2E));
;                     u32x2 w; w.x = cvt_pk_bf16(v[0], v[1]); w.y = cvt_pk_bf16(v[2], v[3]);
;                     *(u32x2*)(rowp + bj * 64) = w; } }
	v_rcp_f32_e32 v120, v120
	v_mul_f32_e32 v113, v116, v113
	v_mul_f32_e32 v116, v118, v114
	v_mul_f32_e32 v114, 0xbfb8aa3b, v114
	v_rcp_f32_e32 v104, v104
	v_rcp_f32_e32 v88, v88
	v_rcp_f32_e32 v81, v81
	v_rcp_f32_e32 v72, v72
	v_rcp_f32_e32 v56, v56
	v_rcp_f32_e32 v40, v40
	v_mul_f32_e32 v32, v36, v32
	v_mul_f32_e32 v36, v37, v33
	v_mul_f32_e32 v33, 0xbfb8aa3b, v33
	v_rcp_f32_e32 v24, v24
	v_rcp_f32_e32 v8, v8
	v_rcp_f32_e32 v0, v0
	v_exp_f32_e32 v114, v114
	v_add_f32_e32 v65, 1.0, v65
	v_exp_f32_e32 v33, v33
	v_mul_f32_e32 v97, v100, v97
	v_mul_f32_e32 v100, v102, v98
	v_mul_f32_e32 v98, 0xbfb8aa3b, v98
	v_rcp_f32_e32 v65, v65
	v_mul_f32_e32 v16, v20, v16
	v_mul_f32_e32 v20, v21, v17
	v_mul_f32_e32 v17, 0xbfb8aa3b, v17
	v_exp_f32_e32 v98, v98
	v_add_f32_e32 v49, 1.0, v49
	v_exp_f32_e32 v17, v17
	v_mul_f32_e32 v120, v124, v120
	v_mul_f32_e32 v124, v125, v121
	v_mul_f32_e32 v121, 0xbfb8aa3b, v121
	v_mul_f32_e32 v104, v108, v104
	v_mul_f32_e32 v108, v109, v105
	v_mul_f32_e32 v105, 0xbfb8aa3b, v105
	v_mul_f32_e32 v88, v92, v88
	v_mul_f32_e32 v92, v93, v89
	v_mul_f32_e32 v89, 0xbfb8aa3b, v89
	v_mul_f32_e32 v81, v84, v81
	v_mul_f32_e32 v84, v86, v82
	v_mul_f32_e32 v82, 0xbfb8aa3b, v82
	v_mul_f32_e32 v72, v76, v72
	v_mul_f32_e32 v76, v77, v73
	v_mul_f32_e32 v73, 0xbfb8aa3b, v73
	v_mul_f32_e32 v56, v60, v56
	v_mul_f32_e32 v60, v61, v57
	v_mul_f32_e32 v57, 0xbfb8aa3b, v57
	v_rcp_f32_e32 v49, v49
	v_mul_f32_e32 v40, v44, v40
	v_mul_f32_e32 v44, v45, v41
	v_mul_f32_e32 v41, 0xbfb8aa3b, v41
	v_mul_f32_e32 v24, v28, v24
	v_mul_f32_e32 v28, v29, v25
	v_mul_f32_e32 v25, 0xbfb8aa3b, v25
	v_mul_f32_e32 v8, v12, v8
	v_mul_f32_e32 v12, v13, v9
	v_mul_f32_e32 v9, 0xbfb8aa3b, v9
	v_mul_f32_e32 v0, v4, v0
	v_mul_f32_e32 v4, v5, v1
	v_mul_f32_e32 v1, 0xbfb8aa3b, v1
	v_exp_f32_e32 v121, v121
	v_add_f32_e32 v114, 1.0, v114
	v_exp_f32_e32 v105, v105
	v_exp_f32_e32 v89, v89
	v_exp_f32_e32 v82, v82
	v_exp_f32_e32 v73, v73
	v_exp_f32_e32 v57, v57
	v_exp_f32_e32 v41, v41
	v_add_f32_e32 v33, 1.0, v33
	v_exp_f32_e32 v25, v25
	v_exp_f32_e32 v9, v9
	v_exp_f32_e32 v1, v1
	v_rcp_f32_e32 v114, v114
	v_mul_f32_e32 v65, v68, v65
	v_mul_f32_e32 v68, v70, v66
	v_mul_f32_e32 v66, 0xbfb8aa3b, v66
	v_rcp_f32_e32 v33, v33
	v_add_f32_e32 v98, 1.0, v98
	v_exp_f32_e32 v66, v66
	v_add_f32_e32 v17, 1.0, v17
	v_rcp_f32_e32 v98, v98
	v_mul_f32_e32 v49, v52, v49
	v_mul_f32_e32 v52, v54, v50
	v_mul_f32_e32 v50, 0xbfb8aa3b, v50
	v_rcp_f32_e32 v17, v17
	v_add_f32_e32 v121, 1.0, v121
	v_add_f32_e32 v105, 1.0, v105
	v_add_f32_e32 v89, 1.0, v89
	v_add_f32_e32 v82, 1.0, v82
	v_add_f32_e32 v73, 1.0, v73
	v_add_f32_e32 v57, 1.0, v57
	v_exp_f32_e32 v50, v50
	v_add_f32_e32 v41, 1.0, v41
	v_add_f32_e32 v25, 1.0, v25
	v_add_f32_e32 v9, 1.0, v9
	v_add_f32_e32 v1, 1.0, v1
	v_rcp_f32_e32 v121, v121
	v_mul_f32_e32 v114, v116, v114
	v_mul_f32_e32 v116, v119, v115
	v_mul_f32_e32 v115, 0xbfb8aa3b, v115
	v_rcp_f32_e32 v105, v105
	v_rcp_f32_e32 v89, v89
	v_rcp_f32_e32 v82, v82
	v_rcp_f32_e32 v73, v73
	v_rcp_f32_e32 v57, v57
	v_rcp_f32_e32 v41, v41
	v_mul_f32_e32 v33, v36, v33
	v_mul_f32_e32 v36, v38, v34
	v_mul_f32_e32 v34, 0xbfb8aa3b, v34
	v_rcp_f32_e32 v25, v25
	v_rcp_f32_e32 v9, v9
	v_rcp_f32_e32 v1, v1
	v_exp_f32_e32 v115, v115
	v_add_f32_e32 v66, 1.0, v66
	v_exp_f32_e32 v34, v34
	v_mul_f32_e32 v98, v100, v98
	v_mul_f32_e32 v100, v103, v99
	v_mul_f32_e32 v99, 0xbfb8aa3b, v99
	v_rcp_f32_e32 v66, v66
	v_mul_f32_e32 v17, v20, v17
	v_mul_f32_e32 v20, v22, v18
	v_mul_f32_e32 v18, 0xbfb8aa3b, v18
	v_exp_f32_e32 v99, v99
	v_add_f32_e32 v50, 1.0, v50
	v_exp_f32_e32 v18, v18
	v_mul_f32_e32 v121, v124, v121
	v_mul_f32_e32 v124, v126, v122
	v_mul_f32_e32 v122, 0xbfb8aa3b, v122
	v_mul_f32_e32 v105, v108, v105
	v_mul_f32_e32 v108, v110, v106
	v_mul_f32_e32 v106, 0xbfb8aa3b, v106
	v_mul_f32_e32 v89, v92, v89
	v_mul_f32_e32 v92, v94, v90
	v_mul_f32_e32 v90, 0xbfb8aa3b, v90
	v_mul_f32_e32 v82, v84, v82
	v_mul_f32_e32 v84, v87, v83
	v_mul_f32_e32 v83, 0xbfb8aa3b, v83
	v_mul_f32_e32 v73, v76, v73
	v_mul_f32_e32 v76, v78, v74
	v_mul_f32_e32 v74, 0xbfb8aa3b, v74
	v_mul_f32_e32 v57, v60, v57
	v_mul_f32_e32 v60, v62, v58
	v_mul_f32_e32 v58, 0xbfb8aa3b, v58
	v_rcp_f32_e32 v50, v50
	v_mul_f32_e32 v41, v44, v41
	v_mul_f32_e32 v44, v46, v42
	v_mul_f32_e32 v42, 0xbfb8aa3b, v42
	v_mul_f32_e32 v25, v28, v25
	v_mul_f32_e32 v28, v30, v26
	v_mul_f32_e32 v26, 0xbfb8aa3b, v26
	v_mul_f32_e32 v9, v12, v9
	v_mul_f32_e32 v12, v14, v10
	v_mul_f32_e32 v10, 0xbfb8aa3b, v10
	v_mul_f32_e32 v1, v4, v1
	v_mul_f32_e32 v4, v6, v2
	v_mul_f32_e32 v2, 0xbfb8aa3b, v2
	v_exp_f32_e32 v122, v122
	v_add_f32_e32 v115, 1.0, v115
	v_exp_f32_e32 v106, v106
	v_exp_f32_e32 v90, v90
	v_exp_f32_e32 v83, v83
	v_exp_f32_e32 v74, v74
	v_exp_f32_e32 v58, v58
	v_exp_f32_e32 v42, v42
	v_add_f32_e32 v34, 1.0, v34
	v_exp_f32_e32 v26, v26
	v_exp_f32_e32 v10, v10
	v_exp_f32_e32 v2, v2
	v_lshl_or_b32 v134, s46, 7, v138
	v_rcp_f32_e32 v115, v115
	v_mul_f32_e32 v66, v68, v66
	v_mul_f32_e32 v68, v71, v67
	v_mul_f32_e32 v67, 0xbfb8aa3b, v67
	v_rcp_f32_e32 v34, v34
	v_ashrrev_i32_e32 v135, 31, v134
	v_add_f32_e32 v99, 1.0, v99
	v_exp_f32_e32 v67, v67
	v_add_f32_e32 v18, 1.0, v18
	v_lshl_add_u32 v140, s48, 8, v136
	v_lshl_add_u64 v[134:135], v[134:135], 1, s[74:75]
	v_rcp_f32_e32 v99, v99
	v_mul_f32_e32 v50, v52, v50
	v_mul_f32_e32 v52, v55, v51
	v_mul_f32_e32 v51, 0xbfb8aa3b, v51
	v_rcp_f32_e32 v18, v18
	v_mad_i64_i32 v[142:143], s[26:27], v140, s33, v[134:135]
	v_add_f32_e32 v122, 1.0, v122
	v_cvt_pk_bf16_f32 v112, v112, v113
	v_add_f32_e32 v106, 1.0, v106
	v_add_f32_e32 v90, 1.0, v90
	v_add_f32_e32 v83, 1.0, v83
	v_add_f32_e32 v74, 1.0, v74
	v_add_f32_e32 v58, 1.0, v58
; __device__ __forceinline__ unsigned cvt_pk_bf16(float lo, float hi) { unsigned r; asm("v_cvt_pk_bf16_f32 %0, %1, %2" : "=v"(r) : "v"(lo), "v"(hi)); return r; }
; #define PG8_WAIT_V(n) asm volatile("s_waitcnt vmcnt(" #n ")" ::: "memory")
; #define PG8_BAR __builtin_amdgcn_s_barrier()
; template <class Epi>
; __device__ __forceinline__ void gemm_phase(LAS unsigned char* lds, const Gemm g, const StaticOrder S, const Epi E) {
;     ...
;     PG8_WAIT_V(0);
;     if (wr == 0) PG8_BAR;
;     PG8_BAR;
;     __device__ __forceinline__ void operator()(AccRef acc, const pg8::Unit& u, int wr, int wc, int fr, int fq) const {
;     ...
;             for (int m = 0; m < 4; ++m) { bf16_t* rowp = G + (size_t)(row0 + ai * 128 + m * 16) * FH + col0;
; #pragma unroll
;                 for (int bj = 0; bj < 2; ++bj) { const f32x4 gq = acc[ai][bj][m][0], uq = acc[ai][bj][m][1]; float v[4];
; #pragma unroll
;                     for (int i = 0; i < 4; ++i) v[i] = gq[i] * uq[i] * __builtin_amdgcn_rcpf(1.f + __builtin_amdgcn_exp2f(-gq[i] * LOG2E));
;                     u32x2 w; w.x = cvt_pk_bf16(v[0], v[1]); w.y = cvt_pk_bf16(v[2], v[3]);
;                     *(u32x2*)(rowp + bj * 64) = w; } }
	v_exp_f32_e32 v51, v51
	v_add_f32_e32 v42, 1.0, v42
	v_add_f32_e32 v26, 1.0, v26
	v_add_f32_e32 v10, 1.0, v10
	v_add_f32_e32 v2, 1.0, v2
	v_rcp_f32_e32 v122, v122
	v_mul_f32_e32 v115, v116, v115
	v_cvt_pk_bf16_f32 v113, v114, v115
	global_store_dwordx2 v[142:143], v[112:113], off offset:128
	v_or_b32_e32 v112, 16, v140
	v_rcp_f32_e32 v106, v106
	v_rcp_f32_e32 v90, v90
	v_rcp_f32_e32 v83, v83
	v_rcp_f32_e32 v74, v74
	v_rcp_f32_e32 v58, v58
	v_rcp_f32_e32 v42, v42
	v_mul_f32_e32 v34, v36, v34
	v_mul_f32_e32 v36, v39, v35
	v_mul_f32_e32 v35, 0xbfb8aa3b, v35
	v_rcp_f32_e32 v26, v26
	v_rcp_f32_e32 v10, v10
	v_rcp_f32_e32 v2, v2
	v_mad_i64_i32 v[112:113], s[26:27], v112, s33, v[134:135]
	v_cvt_pk_bf16_f32 v96, v96, v97
	v_add_f32_e32 v67, 1.0, v67
	v_exp_f32_e32 v35, v35
	v_mul_f32_e32 v99, v100, v99
	v_cvt_pk_bf16_f32 v97, v98, v99
	global_store_dwordx2 v[112:113], v[96:97], off offset:128
	v_or_b32_e32 v96, 32, v140
	v_rcp_f32_e32 v67, v67
	v_mul_f32_e32 v18, v20, v18
	v_mul_f32_e32 v20, v23, v19
	v_mul_f32_e32 v19, 0xbfb8aa3b, v19
	v_mad_i64_i32 v[96:97], s[26:27], v96, s33, v[134:135]
	v_cvt_pk_bf16_f32 v80, v80, v81
	v_add_f32_e32 v51, 1.0, v51
	v_exp_f32_e32 v19, v19
	v_mul_f32_e32 v122, v124, v122
	v_mul_f32_e32 v124, v127, v123
	v_mul_f32_e32 v123, 0xbfb8aa3b, v123
	v_mul_f32_e32 v106, v108, v106
	v_mul_f32_e32 v108, v111, v107
	v_mul_f32_e32 v107, 0xbfb8aa3b, v107
	v_mul_f32_e32 v90, v92, v90
	v_mul_f32_e32 v92, v95, v91
	v_mul_f32_e32 v91, 0xbfb8aa3b, v91
	v_mul_f32_e32 v83, v84, v83
	v_cvt_pk_bf16_f32 v81, v82, v83
	global_store_dwordx2 v[96:97], v[80:81], off offset:128
	v_or_b32_e32 v80, 48, v140
	v_mul_f32_e32 v74, v76, v74
	v_mul_f32_e32 v76, v79, v75
	v_mul_f32_e32 v75, 0xbfb8aa3b, v75
	v_mul_f32_e32 v58, v60, v58
	v_mul_f32_e32 v60, v63, v59
	v_mul_f32_e32 v59, 0xbfb8aa3b, v59
	v_rcp_f32_e32 v51, v51
	v_mul_f32_e32 v42, v44, v42
	v_mul_f32_e32 v44, v47, v43
	v_mul_f32_e32 v43, 0xbfb8aa3b, v43
	v_mul_f32_e32 v26, v28, v26
	v_mul_f32_e32 v28, v31, v27
	v_mul_f32_e32 v27, 0xbfb8aa3b, v27
	v_mul_f32_e32 v10, v12, v10
	v_mul_f32_e32 v12, v15, v11
	v_mul_f32_e32 v11, 0xbfb8aa3b, v11
	v_mul_f32_e32 v2, v4, v2
	v_mul_f32_e32 v4, v7, v3
	v_mul_f32_e32 v3, 0xbfb8aa3b, v3
	v_exp_f32_e32 v123, v123
	v_exp_f32_e32 v107, v107
	v_exp_f32_e32 v91, v91
	v_mad_i64_i32 v[80:81], s[26:27], v80, s33, v[134:135]
	v_exp_f32_e32 v75, v75
	v_cvt_pk_bf16_f32 v64, v64, v65
	v_exp_f32_e32 v59, v59
	v_exp_f32_e32 v43, v43
	v_add_f32_e32 v35, 1.0, v35
	v_exp_f32_e32 v27, v27
	v_exp_f32_e32 v11, v11
	v_exp_f32_e32 v3, v3
	v_mul_f32_e32 v67, v68, v67
	v_cvt_pk_bf16_f32 v65, v66, v67
	global_store_dwordx2 v[80:81], v[64:65], off offset:128
	v_add_u32_e32 v64, 0x80, v140
	v_rcp_f32_e32 v35, v35
	v_mad_i64_i32 v[64:65], s[26:27], v64, s33, v[134:135]
	v_cvt_pk_bf16_f32 v48, v48, v49
	v_add_f32_e32 v19, 1.0, v19
	v_mul_f32_e32 v51, v52, v51
	v_cvt_pk_bf16_f32 v49, v50, v51
	global_store_dwordx2 v[64:65], v[48:49], off offset:128
	v_add_u32_e32 v48, 0x90, v140
	v_rcp_f32_e32 v19, v19
	v_add_f32_e32 v123, 1.0, v123
	v_add_f32_e32 v107, 1.0, v107
	v_add_f32_e32 v91, 1.0, v91
	v_add_f32_e32 v75, 1.0, v75
	v_add_f32_e32 v59, 1.0, v59
	v_mad_i64_i32 v[48:49], s[26:27], v48, s33, v[134:135]
	v_add_f32_e32 v43, 1.0, v43
	v_cvt_pk_bf16_f32 v32, v32, v33
	v_add_f32_e32 v27, 1.0, v27
	v_add_f32_e32 v11, 1.0, v11
	v_add_f32_e32 v3, 1.0, v3
	v_rcp_f32_e32 v123, v123
	v_rcp_f32_e32 v107, v107
	v_rcp_f32_e32 v91, v91
	v_rcp_f32_e32 v75, v75
	v_rcp_f32_e32 v59, v59
	v_rcp_f32_e32 v43, v43
	v_mul_f32_e32 v35, v36, v35
	v_cvt_pk_bf16_f32 v33, v34, v35
	global_store_dwordx2 v[48:49], v[32:33], off offset:128
	v_add_u32_e32 v32, 0xa0, v140
	v_rcp_f32_e32 v27, v27
	v_rcp_f32_e32 v11, v11
	v_rcp_f32_e32 v3, v3
	v_mad_i64_i32 v[32:33], s[26:27], v32, s33, v[134:135]
	v_cvt_pk_bf16_f32 v16, v16, v17
	v_mul_f32_e32 v19, v20, v19
	v_cvt_pk_bf16_f32 v17, v18, v19
	global_store_dwordx2 v[32:33], v[16:17], off offset:128
	v_add_u32_e32 v16, 0xb0, v140
	v_mad_i64_i32 v[16:17], s[26:27], v16, s33, v[134:135]
	s_and_b64 vcc, exec, s[38:39]
	s_mov_b32 s46, s0
	s_mov_b32 s48, s2
	s_mov_b64 s[52:53], s[44:45]
	s_mov_b64 s[50:51], s[42:43]
	v_readlane_b32 s64, v255, 53
	v_mul_f32_e32 v123, v124, v123
	v_cvt_pk_bf16_f32 v120, v120, v121
	v_cvt_pk_bf16_f32 v121, v122, v123
	global_store_dwordx2 v[142:143], v[120:121], off
	v_mul_f32_e32 v107, v108, v107
	v_cvt_pk_bf16_f32 v104, v104, v105
	v_cvt_pk_bf16_f32 v105, v106, v107
	global_store_dwordx2 v[112:113], v[104:105], off
	v_mul_f32_e32 v91, v92, v91
	v_cvt_pk_bf16_f32 v88, v88, v89
	v_cvt_pk_bf16_f32 v89, v90, v91
	global_store_dwordx2 v[96:97], v[88:89], off
	v_mul_f32_e32 v75, v76, v75
	v_cvt_pk_bf16_f32 v72, v72, v73
	v_cvt_pk_bf16_f32 v73, v74, v75
	global_store_dwordx2 v[80:81], v[72:73], off
	v_mul_f32_e32 v59, v60, v59
	v_cvt_pk_bf16_f32 v56, v56, v57
	v_cvt_pk_bf16_f32 v57, v58, v59
	global_store_dwordx2 v[64:65], v[56:57], off
	v_mul_f32_e32 v43, v44, v43
	v_cvt_pk_bf16_f32 v40, v40, v41
	v_cvt_pk_bf16_f32 v41, v42, v43
	global_store_dwordx2 v[48:49], v[40:41], off
	v_mul_f32_e32 v27, v28, v27
	v_cvt_pk_bf16_f32 v24, v24, v25
	v_cvt_pk_bf16_f32 v25, v26, v27
	global_store_dwordx2 v[32:33], v[24:25], off
	v_mul_f32_e32 v11, v12, v11
	v_cvt_pk_bf16_f32 v8, v8, v9
	v_cvt_pk_bf16_f32 v9, v10, v11
	global_store_dwordx2 v[16:17], v[8:9], off
	v_mul_f32_e32 v3, v4, v3
	v_cvt_pk_bf16_f32 v0, v0, v1
	v_cvt_pk_bf16_f32 v1, v2, v3
	global_store_dwordx2 v[16:17], v[0:1], off offset:128
	v_readlane_b32 s65, v255, 54
	s_cbranch_vccz .LBB0_3716
	s_waitcnt vmcnt(0)
	s_cmpk_gt_u32 s7, 0xff
	s_cbranch_scc1 .LBB0_3727
	s_barrier

; __device__ __forceinline__ bf16_t f2bf(float x) { return (bf16_t)(cvt_pk_bf16(x, 0.f) & 0xffffu); }
; __device__ __forceinline__ int otid() { int t = threadIdx.x; asm volatile("" : "+v"(t)); return t; }
; __device__ __forceinline__ void titem_store(const TItem& it, int tid, const f32x4 (&v)[4], bf16_t* T) {
; #pragma unroll
;     for (int i = 0; i < 4; ++i) { const int idx = tid + 512 * i, kk = idx >> 4, r4 = idx & 15;
; #pragma unroll
;         for (int j = 0; j < 4; ++j) T[(4 * r4 + j) * 136 + kk] = f2bf(v[i][j]); }
;     __syncthreads();
; #pragma unroll
;     for (int i = 0; i < 2; ++i) { const int c = tid + 512 * i, row = c >> 4, k8 = (c & 15) * 8;
;         const u32x4 w = *(const u32x4*)(T + row * 136 + k8);
;         *(u32x4*)(it.dst + (size_t)(it.r0 + row) * it.K + it.k0 + k8) = w; }
; }
; __device__ __forceinline__ int tset_item(int l, int which, int i) {
;     if (which == 0) return l * TT_LAYER + 2 * TT_FIN + 2 * TT_FOUT + i;
;     const int bin = (which == 1) ? 0 : TT_FIN, bout = 2 * TT_FIN + ((which == 1) ? 0 : TT_FOUT);
;     return l * TT_LAYER + (i < TT_FIN ? bin + i : bout + i - TT_FIN);
; }
;     const int nall = (which == 0) ? TT_WIN + TT_WOUT + TT_UQ + TT_UKV : TT_FIN + TT_FOUT;
;     const int n = (nall * hi4) / 4, start = (nall * lo4) / 4 + start0;
;     const int tid = otid();
;     if (start >= n) return;
;     TItem c0 = titem_decode(p, tset_item(l, which, start)), c1 = c0;
;     f32x4 v0[4], v1[4], v2[4];
;     titem_load(c0, tid, v0);
;     if (start + stride < n) { c1 = titem_decode(p, tset_item(l, which, start + stride)); titem_load(c1, tid, v1); }
;     int buf = 0;
;     for (int i = start; i < n; i += stride) {
;         TItem c2 = c1;
;         if (i + 2 * stride < n) { c2 = titem_decode(p, tset_item(l, which, i + 2 * stride)); titem_load(c2, tid, v2); }
;         titem_store(c0, tid, v0, (bf16_t*)(lds + buf * 17408));
;         buf ^= 1; c0 = c1; c1 = c2;
; #pragma unroll
;         for (int q = 0; q < 4; ++q) { v0[q] = v1[q]; v1[q] = v2[q]; }
.LBB0_3756:
	s_mul_i32 s14, s22, 0x4400
	s_add_i32 s14, s14, 0
	v_add_u32_e32 v32, s14, v43
	v_cvt_pk_bf16_f32 v0, v0, v179
	v_lshl_add_u32 v33, v36, 1, v32
	ds_write_b16 v33, v0
	v_cvt_pk_bf16_f32 v0, v1, v179
	ds_write_b16 v33, v0 offset:272
	v_cvt_pk_bf16_f32 v0, v2, v179
	ds_write_b16 v33, v0 offset:544
	v_cvt_pk_bf16_f32 v0, v3, v179
	ds_write_b16 v33, v0 offset:816
	v_cvt_pk_bf16_f32 v0, v4, v179
	v_lshl_add_u32 v1, v37, 1, v32
	ds_write_b16 v1, v0
	v_cvt_pk_bf16_f32 v0, v5, v179
	ds_write_b16 v1, v0 offset:272
	v_cvt_pk_bf16_f32 v0, v6, v179
	ds_write_b16 v1, v0 offset:544
	v_cvt_pk_bf16_f32 v0, v7, v179
	ds_write_b16 v1, v0 offset:816
	v_cvt_pk_bf16_f32 v0, v8, v179
	v_lshl_add_u32 v1, v38, 1, v32
	ds_write_b16 v1, v0
	v_cvt_pk_bf16_f32 v0, v9, v179
	ds_write_b16 v1, v0 offset:272
	v_cvt_pk_bf16_f32 v0, v10, v179
	ds_write_b16 v1, v0 offset:544
	v_cvt_pk_bf16_f32 v0, v11, v179
	ds_write_b16 v1, v0 offset:816
	v_cvt_pk_bf16_f32 v0, v12, v179
	v_lshl_add_u32 v1, v39, 1, v32
	ds_write_b16 v1, v0
	v_cvt_pk_bf16_f32 v0, v13, v179
	ds_write_b16 v1, v0 offset:272
	v_cvt_pk_bf16_f32 v0, v14, v179
	v_add_u32_e32 v4, s6, v36
	ds_write_b16 v1, v0 offset:544
	v_cvt_pk_bf16_f32 v0, v15, v179
	v_add_u32_e32 v10, s14, v178
	v_ashrrev_i32_e32 v7, 31, v4
	v_mad_u64_u32 v[4:5], s[30:31], v4, s4, 0
	ds_write_b16 v1, v0 offset:816
	v_add_u32_e32 v0, v10, v41
	v_mov_b32_e32 v6, v5
	s_waitcnt lgkmcnt(0)
	s_barrier
	ds_read_b128 v[0:3], v0
	v_mad_u64_u32 v[6:7], s[30:31], v7, s4, v[6:7]
	v_mov_b32_e32 v5, v6
	s_ashr_i32 s39, s38, 31
	v_lshl_add_u64 v[4:5], v[4:5], 1, s[2:3]
	s_lshl_b64 s[30:31], s[38:39], 1
	v_lshl_add_u64 v[4:5], v[4:5], 0, s[30:31]
	v_lshl_add_u64 v[8:9], v[4:5], 0, v[178:179]
	v_add_u32_e32 v4, v10, v42
	ds_read_b128 v[4:7], v4
	s_waitcnt lgkmcnt(1)
	global_store_dwordx4 v[8:9], v[0:3], off sc0 sc1
	s_xor_b32 s22, s22, 1
	v_mov_b32_e32 v8, v57
	v_add_u32_e32 v0, s6, v37
	v_ashrrev_i32_e32 v3, 31, v0
	v_mad_u64_u32 v[0:1], s[38:39], v0, s4, 0
	v_mov_b32_e32 v2, v1
	v_mad_u64_u32 v[2:3], s[38:39], v3, s4, v[2:3]
	v_mov_b32_e32 v1, v2
	v_lshl_add_u64 v[0:1], v[0:1], 1, s[2:3]
	v_readlane_b32 s2, v253, 3
	v_lshl_add_u64 v[0:1], v[0:1], 0, s[30:31]
	s_add_i32 s23, s23, s2
	v_lshl_add_u64 v[0:1], v[0:1], 0, v[178:179]
	s_add_i32 s2, s23, 24
	s_waitcnt lgkmcnt(0)
	global_store_dwordx4 v[0:1], v[4:7], off sc0 sc1
	s_cmpk_gt_i32 s2, 0x101f
	s_mov_b64 s[2:3], s[0:1]
	s_mov_b32 s4, s26
	s_mov_b32 s6, s25
	s_mov_b32 s38, s24
	v_mov_b32_e32 v0, v59
	v_mov_b32_e32 v1, v55
	v_mov_b32_e32 v2, v51
	v_mov_b32_e32 v3, v47
	v_mov_b32_e32 v4, v58
	v_mov_b32_e32 v5, v54
	v_mov_b32_e32 v6, v50
	v_mov_b32_e32 v7, v46
	v_mov_b32_e32 v9, v53
	v_mov_b32_e32 v10, v49
	v_mov_b32_e32 v11, v45
	v_mov_b32_e32 v12, v56
	v_mov_b32_e32 v13, v52
	v_mov_b32_e32 v14, v48
	v_mov_b32_e32 v15, v44
	s_waitcnt vmcnt(2)
	v_mov_b32_e32 v32, v16
	v_mov_b32_e32 v33, v17
	v_mov_b32_e32 v60, v18
	v_mov_b32_e32 v61, v19
	v_mov_b32_e32 v62, v20
	v_mov_b32_e32 v63, v21
	v_mov_b32_e32 v64, v22
	v_mov_b32_e32 v65, v23
	v_mov_b32_e32 v66, v24
	v_mov_b32_e32 v67, v25
	v_mov_b32_e32 v68, v26
	v_mov_b32_e32 v69, v27
	v_mov_b32_e32 v70, v28
	v_mov_b32_e32 v71, v29
	v_mov_b32_e32 v72, v30
	v_mov_b32_e32 v73, v31
	s_cbranch_scc1 .LBB0_3848

;     __device__ __forceinline__ void operator()(AccRef acc, const pg8::Unit& u, int wr, int wc, int fr, int fq) const {
;     ...
; #pragma unroll
;                 for (int mm = 0; mm < 2; ++mm)
; #pragma unroll
;                     for (int bj = 0; bj < 2; ++bj)
; #pragma unroll
;                         for (int n = 0; n < 2; ++n) { const int m = 2 * mp + mm; const f32x4 d = gv[bj][n] * acc[ai][bj][m][n];
;                             *(f32x4*)(base + (size_t)(row0 + ai * 128 + m * 16) * DM + col0 + bj * 128 + n * 16) = part ? d : old[mm][bj][n] + d; }
;             }
.LBB0_3910:
	v_pk_mul_f32 v[36:37], v[30:31], v[174:175]
	v_pk_mul_f32 v[38:39], v[28:29], v[172:173]
	s_waitcnt vmcnt(0)
	v_pk_fma_f32 v[30:31], v[30:31], v[174:175], v[158:159]
	v_pk_fma_f32 v[28:29], v[28:29], v[172:173], v[156:157]
	v_lshl_add_u64 v[34:35], v[202:203], 0, v[34:35]
	v_cndmask_b32_e64 v31, v37, v31, s[38:39]
	v_cndmask_b32_e64 v30, v36, v30, s[38:39]
	v_cndmask_b32_e64 v29, v39, v29, s[38:39]
	v_cndmask_b32_e64 v28, v38, v28, s[38:39]
	global_store_dwordx4 v[34:35], v[28:31], off sc0 sc1
	s_and_b64 vcc, exec, s[46:47]
	s_mov_b32 s40, s64
	v_pk_mul_f32 v[28:29], v[26:27], v[170:171]
	v_pk_mul_f32 v[30:31], v[24:25], v[168:169]
	v_pk_fma_f32 v[26:27], v[26:27], v[170:171], v[154:155]
	v_pk_fma_f32 v[24:25], v[24:25], v[168:169], v[152:153]
	v_cndmask_b32_e64 v27, v29, v27, s[38:39]
	v_cndmask_b32_e64 v26, v28, v26, s[38:39]
	v_cndmask_b32_e64 v25, v31, v25, s[38:39]
	v_cndmask_b32_e64 v24, v30, v24, s[38:39]
	global_store_dwordx4 v[34:35], v[24:27], off offset:64 sc0 sc1
	s_mov_b32 s41, s26
	s_mov_b32 s67, s66
	v_pk_mul_f32 v[24:25], v[22:23], v[166:167]
	v_pk_mul_f32 v[26:27], v[20:21], v[164:165]
	v_pk_fma_f32 v[22:23], v[22:23], v[166:167], v[150:151]
	v_pk_fma_f32 v[20:21], v[20:21], v[164:165], v[148:149]
	v_cndmask_b32_e64 v23, v25, v23, s[38:39]
	v_cndmask_b32_e64 v22, v24, v22, s[38:39]
	v_cndmask_b32_e64 v21, v27, v21, s[38:39]
	v_cndmask_b32_e64 v20, v26, v20, s[38:39]
	global_store_dwordx4 v[34:35], v[20:23], off offset:512 sc0 sc1
	s_mov_b32 s29, s27
	s_mov_b32 s28, s65
	v_pk_mul_f32 v[20:21], v[14:15], v[162:163]
	v_pk_mul_f32 v[22:23], v[12:13], v[160:161]
	v_pk_fma_f32 v[14:15], v[14:15], v[162:163], v[142:143]
	v_pk_fma_f32 v[12:13], v[12:13], v[160:161], v[140:141]
	v_cndmask_b32_e64 v15, v21, v15, s[38:39]
	v_cndmask_b32_e64 v14, v20, v14, s[38:39]
	v_cndmask_b32_e64 v13, v23, v13, s[38:39]
	v_cndmask_b32_e64 v12, v22, v12, s[38:39]
	global_store_dwordx4 v[34:35], v[12:15], off offset:576 sc0 sc1
	v_pk_mul_f32 v[22:23], v[16:17], v[172:173]
	v_pk_fma_f32 v[16:17], v[16:17], v[172:173], v[144:145]
	v_pk_mul_f32 v[12:13], v[18:19], v[174:175]
	v_pk_fma_f32 v[14:15], v[18:19], v[174:175], v[146:147]
	v_lshl_add_u64 v[20:21], v[202:203], 0, v[32:33]
	v_cndmask_b32_e64 v15, v13, v15, s[38:39]
	v_cndmask_b32_e64 v14, v12, v14, s[38:39]
	v_cndmask_b32_e64 v13, v23, v17, s[38:39]
	v_cndmask_b32_e64 v12, v22, v16, s[38:39]
	global_store_dwordx4 v[20:21], v[12:15], off sc0 sc1
	s_mov_b64 s[50:51], s[48:49]
	s_mov_b32 s30, s63
	v_pk_mul_f32 v[12:13], v[10:11], v[170:171]
	v_pk_mul_f32 v[14:15], v[8:9], v[168:169]
	v_pk_fma_f32 v[10:11], v[10:11], v[170:171], v[138:139]
	v_pk_fma_f32 v[8:9], v[8:9], v[168:169], v[136:137]
	v_cndmask_b32_e64 v11, v13, v11, s[38:39]
	v_cndmask_b32_e64 v10, v12, v10, s[38:39]
	v_cndmask_b32_e64 v9, v15, v9, s[38:39]
	v_cndmask_b32_e64 v8, v14, v8, s[38:39]
	global_store_dwordx4 v[20:21], v[8:11], off offset:64 sc0 sc1
	s_nop 1
	v_pk_mul_f32 v[8:9], v[6:7], v[166:167]
	v_pk_mul_f32 v[10:11], v[4:5], v[164:165]
	v_pk_fma_f32 v[6:7], v[6:7], v[166:167], v[134:135]
	v_pk_fma_f32 v[4:5], v[4:5], v[164:165], v[132:133]
	v_cndmask_b32_e64 v7, v9, v7, s[38:39]
	v_cndmask_b32_e64 v6, v8, v6, s[38:39]
	v_cndmask_b32_e64 v5, v11, v5, s[38:39]
	v_cndmask_b32_e64 v4, v10, v4, s[38:39]
	global_store_dwordx4 v[20:21], v[4:7], off offset:512 sc0 sc1
	s_nop 1
	v_pk_mul_f32 v[4:5], v[2:3], v[162:163]
	v_pk_mul_f32 v[6:7], v[0:1], v[160:161]
	v_pk_fma_f32 v[2:3], v[2:3], v[162:163], v[130:131]
	v_pk_fma_f32 v[0:1], v[0:1], v[160:161], v[128:129]
	v_cndmask_b32_e64 v3, v5, v3, s[38:39]
	v_cndmask_b32_e64 v2, v4, v2, s[38:39]
	v_cndmask_b32_e64 v1, v7, v1, s[38:39]
	v_cndmask_b32_e64 v0, v6, v0, s[38:39]
	s_mov_b64 s[38:39], s[44:45]
	global_store_dwordx4 v[20:21], v[0:3], off offset:576 sc0 sc1
	s_cbranch_vccnz .LBB0_3940

; #define PG8_STAGE(bufoff, gbase, voff) do { _Pragma("unroll") for (int _i = 0; _i < 2; ++_i) \
;         __builtin_amdgcn_global_load_lds((const unsigned*)((const char*)(gbase) + (voff)[_i]), (LAS unsigned*)(lds + (bufoff) + ldsw + _i * 8192), 16, 0, 0); } while (0)
; #define PG8_LDA(dst, b, h) do { _Pragma("unroll") for (int m = 0; m < 4; ++m) _Pragma("unroll") for (int k = 0; k < 2; ++k) dst[m][k] = *(const LAS bf16x8*)(lds + PG8_SA(b, h) + aoff + m * 2048 + k * 1024); } while (0)
; #define PG8_LDB(dst, b, h) do { _Pragma("unroll") for (int n = 0; n < 2; ++n) _Pragma("unroll") for (int k = 0; k < 2; ++k) dst[n][k] = *(const LAS bf16x8*)(lds + PG8_SB(b, h) + boff + n * 2048 + k * 1024); } while (0)
; #define PG8_MMA(ai, bj, At, Bt) do { __builtin_amdgcn_s_setprio(1); _Pragma("unroll") for (int m = 0; m < 4; ++m) _Pragma("unroll") for (int n = 0; n < 2; ++n) _Pragma("unroll") for (int k = 0; k < 2; ++k) \
;         acc[ai][bj][m][n] = __builtin_amdgcn_mfma_f32_16x16x32_bf16(Bt[n][k], At[m][k], acc[ai][bj][m][n], 0, 0, 0); __builtin_amdgcn_s_setprio(0); } while (0)
; #define PG8_WAIT_L(n) asm volatile("s_waitcnt lgkmcnt(" #n ")" ::: "memory")
; #define PG8_BAR __builtin_amdgcn_s_barrier()
; #define PG8_SCHED __builtin_amdgcn_sched_barrier(0)
; template <class Epi>
; __device__ __forceinline__ void gemm_phase(LAS unsigned char* lds, const Gemm g, const StaticOrder S, const Epi E) {
;     ...
;             const char* a1 = cA + (size_t)(t + 1) * kstep;
;             const char* a2 = last ? nA : cA + (size_t)(t + 2) * kstep; const char* b2 = last ? nB : cB + (size_t)(t + 2) * kstep;
;             const char* a3 = a2 + kstep; const char* b3 = b2 + kstep;
;             PG8_LDB(B0, 0, 0); PG8_SCHED; PG8_LDA(At, 0, 0); PG8_STAGE(PG8_SA(1, 1), a1 + hstep, voffA);
;             PG8_WAIT_L(8); PG8_BAR; PG8_WAIT_L(0); PG8_MMA(0, 0, At, B0); PG8_BAR; PG8_SCHED;
;             PG8_LDB(B1, 0, 1); PG8_STAGE(PG8_SB(0, 0), b2, voffA);
;             PG8_BAR; PG8_WAIT_L(0); PG8_MMA(0, 1, At, B1); PG8_BAR;
;             PG8_LDA(At, 0, 1); PG8_STAGE(PG8_SA(0, 0), a2, voffA);
;             PG8_BAR; PG8_WAIT_L(0); PG8_MMA(1, 0, At, B0); PG8_BAR; PG8_SCHED;
.LBB0_3919:
	s_add_i32 vcc_lo, s52, 2
	s_add_u32 s50, s38, 0x100
	s_addc_u32 s51, s39, 0
	s_add_i32 s14, 0, 0x10000
	v_add_u32_e32 v140, s14, v228
	ds_read_b128 v[128:131], v140
	ds_read_b128 v[132:135], v140 offset:1024
	ds_read_b128 v[136:139], v140 offset:2048
	ds_read_b128 v[140:143], v140 offset:3072
	s_cmp_eq_u32 s43, s52
	s_cselect_b32 s52, s48, s68
	s_cselect_b32 s55, s45, s51
	s_cselect_b32 s54, s44, s50
	s_cselect_b32 s53, s49, s69
	v_lshl_add_u64 v[200:201], s[38:39], 0, v[196:197]
	s_add_i32 m0, s25, 0xc000
	ds_read_b128 v[144:147], v230
	ds_read_b128 v[148:151], v230 offset:1024
	ds_read_b128 v[152:155], v230 offset:2048
	ds_read_b128 v[156:159], v230 offset:3072
	ds_read_b128 v[160:163], v230 offset:4096
	ds_read_b128 v[164:167], v230 offset:5120
	ds_read_b128 v[168:171], v230 offset:6144
	ds_read_b128 v[172:175], v230 offset:7168
	global_load_lds_dwordx4 v[200:201], off
	v_lshl_add_u64 v[200:201], s[38:39], 0, v[198:199]
	s_add_i32 m0, s25, 0xe000
	s_nop 0
	global_load_lds_dwordx4 v[200:201], off
	s_waitcnt lgkmcnt(8)
	s_barrier
	s_waitcnt lgkmcnt(0)
	s_setprio 1
	s_waitcnt lgkmcnt(0)
	v_mfma_f32_16x16x32_bf16 v[124:127], v[128:131], v[144:147], v[124:127]
	v_mfma_f32_16x16x32_bf16 v[120:123], v[136:139], v[144:147], v[120:123]
	v_mfma_f32_16x16x32_bf16 v[112:115], v[128:131], v[152:155], v[112:115]
	v_mfma_f32_16x16x32_bf16 v[104:107], v[136:139], v[152:155], v[104:107]
	v_mfma_f32_16x16x32_bf16 v[92:95], v[128:131], v[160:163], v[92:95]
	v_mfma_f32_16x16x32_bf16 v[88:91], v[136:139], v[160:163], v[88:91]
	v_mfma_f32_16x16x32_bf16 v[80:83], v[128:131], v[168:171], v[80:83]
	v_mfma_f32_16x16x32_bf16 v[72:75], v[136:139], v[168:171], v[72:75]
	v_mfma_f32_16x16x32_bf16 v[124:127], v[132:135], v[148:151], v[124:127]
	v_mfma_f32_16x16x32_bf16 v[120:123], v[140:143], v[148:151], v[120:123]
	v_mfma_f32_16x16x32_bf16 v[112:115], v[132:135], v[156:159], v[112:115]
	v_mfma_f32_16x16x32_bf16 v[104:107], v[140:143], v[156:159], v[104:107]
	v_mfma_f32_16x16x32_bf16 v[92:95], v[132:135], v[164:167], v[92:95]
	v_mfma_f32_16x16x32_bf16 v[88:91], v[140:143], v[164:167], v[88:91]
	v_mfma_f32_16x16x32_bf16 v[80:83], v[132:135], v[172:175], v[80:83]
	v_mfma_f32_16x16x32_bf16 v[72:75], v[140:143], v[172:175], v[72:75]
	s_setprio 0
	s_barrier
	s_add_i32 s38, 0, 0x14000
	s_add_i32 s14, s14, s24
	v_add_u32_e32 v220, s38, v228
	v_lshl_add_u64 v[232:233], s[52:53], 0, v[178:179]
	s_mov_b32 m0, s14
	ds_read_b128 v[200:203], v220
	ds_read_b128 v[204:207], v220 offset:1024
	ds_read_b128 v[208:211], v220 offset:2048
	ds_read_b128 v[220:223], v220 offset:3072
	global_load_lds_dwordx4 v[232:233], off
	v_lshl_add_u64 v[234:235], s[52:53], 0, v[194:195]
	s_add_i32 m0, s14, 0x2000
	s_nop 0
	global_load_lds_dwordx4 v[234:235], off
	s_barrier
	s_waitcnt lgkmcnt(0)
	s_setprio 1
	s_waitcnt lgkmcnt(0)
	v_mfma_f32_16x16x32_bf16 v[116:119], v[200:203], v[144:147], v[116:119]
	v_mfma_f32_16x16x32_bf16 v[108:111], v[208:211], v[144:147], v[108:111]
	v_mfma_f32_16x16x32_bf16 v[100:103], v[200:203], v[152:155], v[100:103]
	v_mfma_f32_16x16x32_bf16 v[96:99], v[208:211], v[152:155], v[96:99]
	v_mfma_f32_16x16x32_bf16 v[84:87], v[200:203], v[160:163], v[84:87]
	v_mfma_f32_16x16x32_bf16 v[76:79], v[208:211], v[160:163], v[76:79]
	v_mfma_f32_16x16x32_bf16 v[68:71], v[200:203], v[168:171], v[68:71]
	v_mfma_f32_16x16x32_bf16 v[64:67], v[208:211], v[168:171], v[64:67]
	v_mfma_f32_16x16x32_bf16 v[116:119], v[204:207], v[148:151], v[116:119]
	v_mfma_f32_16x16x32_bf16 v[108:111], v[220:223], v[148:151], v[108:111]
	v_mfma_f32_16x16x32_bf16 v[100:103], v[204:207], v[156:159], v[100:103]
	v_mfma_f32_16x16x32_bf16 v[96:99], v[220:223], v[156:159], v[96:99]
	v_mfma_f32_16x16x32_bf16 v[84:87], v[204:207], v[164:167], v[84:87]
	v_mfma_f32_16x16x32_bf16 v[76:79], v[220:223], v[164:167], v[76:79]
	v_mfma_f32_16x16x32_bf16 v[68:71], v[204:207], v[172:175], v[68:71]
	v_mfma_f32_16x16x32_bf16 v[64:67], v[220:223], v[172:175], v[64:67]
	s_setprio 0
	s_barrier
	s_mov_b32 m0, s25
	v_lshl_add_u64 v[236:237], s[54:55], 0, v[178:179]
	ds_read_b128 v[144:147], v230 offset:16384
	ds_read_b128 v[148:151], v230 offset:17408
	ds_read_b128 v[152:155], v230 offset:18432
	ds_read_b128 v[156:159], v230 offset:19456
	ds_read_b128 v[160:163], v230 offset:20480
	ds_read_b128 v[164:167], v230 offset:21504
	ds_read_b128 v[168:171], v230 offset:22528
	ds_read_b128 v[172:175], v230 offset:23552
	global_load_lds_dwordx4 v[236:237], off
	v_lshl_add_u64 v[238:239], s[54:55], 0, v[194:195]
	s_mov_b32 m0, s56
	s_nop 0
	global_load_lds_dwordx4 v[238:239], off
	s_barrier
	s_waitcnt lgkmcnt(0)
	s_setprio 1
	s_waitcnt lgkmcnt(0)
	v_mfma_f32_16x16x32_bf16 v[60:63], v[128:131], v[144:147], v[60:63]
	v_mfma_f32_16x16x32_bf16 v[56:59], v[136:139], v[144:147], v[56:59]
	v_mfma_f32_16x16x32_bf16 v[48:51], v[128:131], v[152:155], v[48:51]
	v_mfma_f32_16x16x32_bf16 v[40:43], v[136:139], v[152:155], v[40:43]
	v_mfma_f32_16x16x32_bf16 v[28:31], v[128:131], v[160:163], v[28:31]
	v_mfma_f32_16x16x32_bf16 v[24:27], v[136:139], v[160:163], v[24:27]
	v_mfma_f32_16x16x32_bf16 v[16:19], v[128:131], v[168:171], v[16:19]
	v_mfma_f32_16x16x32_bf16 v[8:11], v[136:139], v[168:171], v[8:11]
	v_mfma_f32_16x16x32_bf16 v[60:63], v[132:135], v[148:151], v[60:63]
	v_mfma_f32_16x16x32_bf16 v[56:59], v[140:143], v[148:151], v[56:59]
	v_mfma_f32_16x16x32_bf16 v[48:51], v[132:135], v[156:159], v[48:51]
	v_mfma_f32_16x16x32_bf16 v[40:43], v[140:143], v[156:159], v[40:43]
	v_mfma_f32_16x16x32_bf16 v[28:31], v[132:135], v[164:167], v[28:31]
	v_mfma_f32_16x16x32_bf16 v[24:27], v[140:143], v[164:167], v[24:27]
	v_mfma_f32_16x16x32_bf16 v[16:19], v[132:135], v[172:175], v[16:19]
	v_mfma_f32_16x16x32_bf16 v[8:11], v[140:143], v[172:175], v[8:11]
	s_setprio 0
	s_barrier
; #define PG8_STAGE(bufoff, gbase, voff) do { _Pragma("unroll") for (int _i = 0; _i < 2; ++_i) \
;         __builtin_amdgcn_global_load_lds((const unsigned*)((const char*)(gbase) + (voff)[_i]), (LAS unsigned*)(lds + (bufoff) + ldsw + _i * 8192), 16, 0, 0); } while (0)
; #define PG8_LDA(dst, b, h) do { _Pragma("unroll") for (int m = 0; m < 4; ++m) _Pragma("unroll") for (int k = 0; k < 2; ++k) dst[m][k] = *(const LAS bf16x8*)(lds + PG8_SA(b, h) + aoff + m * 2048 + k * 1024); } while (0)
; #define PG8_LDB(dst, b, h) do { _Pragma("unroll") for (int n = 0; n < 2; ++n) _Pragma("unroll") for (int k = 0; k < 2; ++k) dst[n][k] = *(const LAS bf16x8*)(lds + PG8_SB(b, h) + boff + n * 2048 + k * 1024); } while (0)
; #define PG8_MMA(ai, bj, At, Bt) do { __builtin_amdgcn_s_setprio(1); _Pragma("unroll") for (int m = 0; m < 4; ++m) _Pragma("unroll") for (int n = 0; n < 2; ++n) _Pragma("unroll") for (int k = 0; k < 2; ++k) \
;         acc[ai][bj][m][n] = __builtin_amdgcn_mfma_f32_16x16x32_bf16(Bt[n][k], At[m][k], acc[ai][bj][m][n], 0, 0, 0); __builtin_amdgcn_s_setprio(0); } while (0)
; #define PG8_WAIT_V(n) asm volatile("s_waitcnt vmcnt(" #n ")" ::: "memory")
; #define PG8_WAIT_L(n) asm volatile("s_waitcnt lgkmcnt(" #n ")" ::: "memory")
; #define PG8_BAR __builtin_amdgcn_s_barrier()
; #define PG8_SCHED __builtin_amdgcn_sched_barrier(0)
; template <class Epi>
; __device__ __forceinline__ void gemm_phase(LAS unsigned char* lds, const Gemm g, const StaticOrder S, const Epi E) {
;     ...
;             PG8_BAR; PG8_WAIT_L(0); PG8_MMA(1, 0, At, B0); PG8_BAR; PG8_SCHED;
;             PG8_STAGE(PG8_SB(0, 1), b2 + hstep, voffA);
;             PG8_WAIT_V(6); PG8_BAR; PG8_MMA(1, 1, At, B1); PG8_BAR;
;             PG8_LDB(B0, 1, 0); PG8_SCHED; PG8_LDA(At, 1, 0); PG8_STAGE(PG8_SA(0, 1), a2 + hstep, voffA);
;             PG8_WAIT_L(8); PG8_BAR; PG8_WAIT_L(0); PG8_MMA(0, 0, At, B0); PG8_BAR; PG8_SCHED;
;             PG8_LDB(B1, 1, 1); PG8_STAGE(PG8_SB(1, 0), b3, voffA);
;             PG8_BAR; PG8_WAIT_L(0); PG8_MMA(0, 1, At, B1); PG8_BAR;
	s_add_u32 s30, s52, 0x158000
	s_addc_u32 s31, s53, 0
	s_add_i32 s14, s38, s24
	v_lshl_add_u64 v[128:129], s[30:31], 0, v[178:179]
	s_mov_b32 m0, s14
	s_nop 0
	global_load_lds_dwordx4 v[128:129], off
	v_lshl_add_u64 v[128:129], s[30:31], 0, v[194:195]
	s_add_i32 m0, s14, 0x2000
	s_nop 0
	global_load_lds_dwordx4 v[128:129], off
	s_waitcnt vmcnt(6)
	s_barrier
	s_setprio 1
	v_mfma_f32_16x16x32_bf16 v[52:55], v[200:203], v[144:147], v[52:55]
	v_mfma_f32_16x16x32_bf16 v[44:47], v[208:211], v[144:147], v[44:47]
	v_mfma_f32_16x16x32_bf16 v[36:39], v[200:203], v[152:155], v[36:39]
	v_mfma_f32_16x16x32_bf16 v[32:35], v[208:211], v[152:155], v[32:35]
	v_mfma_f32_16x16x32_bf16 v[20:23], v[200:203], v[160:163], v[20:23]
	v_mfma_f32_16x16x32_bf16 v[12:15], v[208:211], v[160:163], v[12:15]
	v_mfma_f32_16x16x32_bf16 v[4:7], v[200:203], v[168:171], v[4:7]
	v_mfma_f32_16x16x32_bf16 v[0:3], v[208:211], v[168:171], v[0:3]
	v_mfma_f32_16x16x32_bf16 v[52:55], v[204:207], v[148:151], v[52:55]
	v_mfma_f32_16x16x32_bf16 v[44:47], v[220:223], v[148:151], v[44:47]
	v_mfma_f32_16x16x32_bf16 v[36:39], v[204:207], v[156:159], v[36:39]
	v_mfma_f32_16x16x32_bf16 v[32:35], v[220:223], v[156:159], v[32:35]
	v_mfma_f32_16x16x32_bf16 v[20:23], v[204:207], v[164:167], v[20:23]
	v_mfma_f32_16x16x32_bf16 v[12:15], v[220:223], v[164:167], v[12:15]
	v_mfma_f32_16x16x32_bf16 v[4:7], v[204:207], v[172:175], v[4:7]
	v_mfma_f32_16x16x32_bf16 v[0:3], v[220:223], v[172:175], v[0:3]
	s_setprio 0
	s_barrier
	s_add_i32 s14, 0, 0x18000
	v_add_u32_e32 v140, s14, v228
	ds_read_b128 v[128:131], v140
	ds_read_b128 v[132:135], v140 offset:1024
	ds_read_b128 v[136:139], v140 offset:2048
	ds_read_b128 v[140:143], v140 offset:3072
	s_add_u32 s30, s54, 0x158000
	s_addc_u32 s31, s55, 0
	s_mov_b32 m0, s57
	v_lshl_add_u64 v[200:201], s[30:31], 0, v[178:179]
	ds_read_b128 v[144:147], v230 offset:32768
	ds_read_b128 v[148:151], v230 offset:33792
	ds_read_b128 v[152:155], v230 offset:34816
	ds_read_b128 v[156:159], v230 offset:35840
	ds_read_b128 v[160:163], v230 offset:36864
	ds_read_b128 v[164:167], v230 offset:37888
	ds_read_b128 v[168:171], v230 offset:38912
	ds_read_b128 v[172:175], v230 offset:39936
	global_load_lds_dwordx4 v[200:201], off
	v_lshl_add_u64 v[200:201], s[30:31], 0, v[194:195]
	s_mov_b32 m0, s58
	s_nop 0
	global_load_lds_dwordx4 v[200:201], off
	s_waitcnt lgkmcnt(8)
	s_barrier
	s_waitcnt lgkmcnt(0)
	s_setprio 1
	s_waitcnt lgkmcnt(0)
	v_mfma_f32_16x16x32_bf16 v[124:127], v[128:131], v[144:147], v[124:127]
	v_mfma_f32_16x16x32_bf16 v[120:123], v[136:139], v[144:147], v[120:123]
	v_mfma_f32_16x16x32_bf16 v[112:115], v[128:131], v[152:155], v[112:115]
	v_mfma_f32_16x16x32_bf16 v[104:107], v[136:139], v[152:155], v[104:107]
	v_mfma_f32_16x16x32_bf16 v[92:95], v[128:131], v[160:163], v[92:95]
	v_mfma_f32_16x16x32_bf16 v[88:91], v[136:139], v[160:163], v[88:91]
	v_mfma_f32_16x16x32_bf16 v[80:83], v[128:131], v[168:171], v[80:83]
	v_mfma_f32_16x16x32_bf16 v[72:75], v[136:139], v[168:171], v[72:75]
	v_mfma_f32_16x16x32_bf16 v[124:127], v[132:135], v[148:151], v[124:127]
	v_mfma_f32_16x16x32_bf16 v[120:123], v[140:143], v[148:151], v[120:123]
	v_mfma_f32_16x16x32_bf16 v[112:115], v[132:135], v[156:159], v[112:115]
	v_mfma_f32_16x16x32_bf16 v[104:107], v[140:143], v[156:159], v[104:107]
	v_mfma_f32_16x16x32_bf16 v[92:95], v[132:135], v[164:167], v[92:95]
	v_mfma_f32_16x16x32_bf16 v[88:91], v[140:143], v[164:167], v[88:91]
	v_mfma_f32_16x16x32_bf16 v[80:83], v[132:135], v[172:175], v[80:83]
	v_mfma_f32_16x16x32_bf16 v[72:75], v[140:143], v[172:175], v[72:75]
	s_setprio 0
	s_barrier
	s_add_i32 s38, 0, 0x1c000
	s_add_i32 s14, s14, s24
	v_add_u32_e32 v220, s38, v228
	v_lshl_add_u64 v[232:233], v[232:233], 0, s[34:35]
	s_mov_b32 m0, s14
	ds_read_b128 v[200:203], v220
	ds_read_b128 v[204:207], v220 offset:1024
	ds_read_b128 v[208:211], v220 offset:2048
	ds_read_b128 v[220:223], v220 offset:3072
	global_load_lds_dwordx4 v[232:233], off
	v_lshl_add_u64 v[232:233], v[234:235], 0, s[34:35]
	s_add_i32 m0, s14, 0x2000
	s_nop 0
	global_load_lds_dwordx4 v[232:233], off
	s_barrier
; #define PG8_STAGE(bufoff, gbase, voff) do { _Pragma("unroll") for (int _i = 0; _i < 2; ++_i) \
;         __builtin_amdgcn_global_load_lds((const unsigned*)((const char*)(gbase) + (voff)[_i]), (LAS unsigned*)(lds + (bufoff) + ldsw + _i * 8192), 16, 0, 0); } while (0)
; #define PG8_LDA(dst, b, h) do { _Pragma("unroll") for (int m = 0; m < 4; ++m) _Pragma("unroll") for (int k = 0; k < 2; ++k) dst[m][k] = *(const LAS bf16x8*)(lds + PG8_SA(b, h) + aoff + m * 2048 + k * 1024); } while (0)
; #define PG8_LDB(dst, b, h) do { _Pragma("unroll") for (int n = 0; n < 2; ++n) _Pragma("unroll") for (int k = 0; k < 2; ++k) dst[n][k] = *(const LAS bf16x8*)(lds + PG8_SB(b, h) + boff + n * 2048 + k * 1024); } while (0)
; #define PG8_MMA(ai, bj, At, Bt) do { __builtin_amdgcn_s_setprio(1); _Pragma("unroll") for (int m = 0; m < 4; ++m) _Pragma("unroll") for (int n = 0; n < 2; ++n) _Pragma("unroll") for (int k = 0; k < 2; ++k) \
;         acc[ai][bj][m][n] = __builtin_amdgcn_mfma_f32_16x16x32_bf16(Bt[n][k], At[m][k], acc[ai][bj][m][n], 0, 0, 0); __builtin_amdgcn_s_setprio(0); } while (0)
; #define PG8_WAIT_V(n) asm volatile("s_waitcnt vmcnt(" #n ")" ::: "memory")
; #define PG8_WAIT_L(n) asm volatile("s_waitcnt lgkmcnt(" #n ")" ::: "memory")
; #define PG8_BAR __builtin_amdgcn_s_barrier()
; #define PG8_SCHED __builtin_amdgcn_sched_barrier(0)
; template <class Epi>
; __device__ __forceinline__ void gemm_phase(LAS unsigned char* lds, const Gemm g, const StaticOrder S, const Epi E) {
;     ...
;             PG8_WAIT_L(8); PG8_BAR; PG8_WAIT_L(0); PG8_MMA(0, 0, At, B0); PG8_BAR; PG8_SCHED;
;             PG8_LDB(B1, 1, 1); PG8_STAGE(PG8_SB(1, 0), b3, voffA);
;             PG8_BAR; PG8_WAIT_L(0); PG8_MMA(0, 1, At, B1); PG8_BAR;
;             PG8_LDA(At, 1, 1); PG8_STAGE(PG8_SA(1, 0), a3, voffA);
;             PG8_BAR; PG8_WAIT_L(0); PG8_MMA(1, 0, At, B0); PG8_BAR; PG8_SCHED;
;             PG8_STAGE(PG8_SB(1, 1), b3 + hstep, voffA);
;             PG8_WAIT_V(6); PG8_BAR; PG8_MMA(1, 1, At, B1); PG8_BAR;
;         }
	s_waitcnt lgkmcnt(0)
	s_setprio 1
	s_waitcnt lgkmcnt(0)
	v_mfma_f32_16x16x32_bf16 v[116:119], v[200:203], v[144:147], v[116:119]
	v_mfma_f32_16x16x32_bf16 v[108:111], v[208:211], v[144:147], v[108:111]
	v_mfma_f32_16x16x32_bf16 v[100:103], v[200:203], v[152:155], v[100:103]
	v_mfma_f32_16x16x32_bf16 v[96:99], v[208:211], v[152:155], v[96:99]
	v_mfma_f32_16x16x32_bf16 v[84:87], v[200:203], v[160:163], v[84:87]
	v_mfma_f32_16x16x32_bf16 v[76:79], v[208:211], v[160:163], v[76:79]
	v_mfma_f32_16x16x32_bf16 v[68:71], v[200:203], v[168:171], v[68:71]
	v_mfma_f32_16x16x32_bf16 v[64:67], v[208:211], v[168:171], v[64:67]
	v_mfma_f32_16x16x32_bf16 v[116:119], v[204:207], v[148:151], v[116:119]
	v_mfma_f32_16x16x32_bf16 v[108:111], v[220:223], v[148:151], v[108:111]
	v_mfma_f32_16x16x32_bf16 v[100:103], v[204:207], v[156:159], v[100:103]
	v_mfma_f32_16x16x32_bf16 v[96:99], v[220:223], v[156:159], v[96:99]
	v_mfma_f32_16x16x32_bf16 v[84:87], v[204:207], v[164:167], v[84:87]
	v_mfma_f32_16x16x32_bf16 v[76:79], v[220:223], v[164:167], v[76:79]
	v_mfma_f32_16x16x32_bf16 v[68:71], v[204:207], v[172:175], v[68:71]
	v_mfma_f32_16x16x32_bf16 v[64:67], v[220:223], v[172:175], v[64:67]
	s_setprio 0
	s_barrier
	s_mov_b32 m0, s61
	v_lshl_add_u64 v[232:233], v[236:237], 0, s[34:35]
	ds_read_b128 v[144:147], v230 offset:49152
	ds_read_b128 v[148:151], v230 offset:50176
	ds_read_b128 v[152:155], v230 offset:51200
	ds_read_b128 v[156:159], v230 offset:52224
	ds_read_b128 v[160:163], v230 offset:53248
	ds_read_b128 v[164:167], v230 offset:54272
	ds_read_b128 v[168:171], v230 offset:55296
	ds_read_b128 v[172:175], v230 offset:56320
	global_load_lds_dwordx4 v[232:233], off
	v_lshl_add_u64 v[232:233], v[238:239], 0, s[34:35]
	s_mov_b32 m0, s62
	s_nop 0
	global_load_lds_dwordx4 v[232:233], off
	s_barrier
	s_waitcnt lgkmcnt(0)
	s_setprio 1
	s_waitcnt lgkmcnt(0)
	v_mfma_f32_16x16x32_bf16 v[60:63], v[128:131], v[144:147], v[60:63]
	v_mfma_f32_16x16x32_bf16 v[56:59], v[136:139], v[144:147], v[56:59]
	v_mfma_f32_16x16x32_bf16 v[48:51], v[128:131], v[152:155], v[48:51]
	v_mfma_f32_16x16x32_bf16 v[40:43], v[136:139], v[152:155], v[40:43]
	v_mfma_f32_16x16x32_bf16 v[28:31], v[128:131], v[160:163], v[28:31]
	v_mfma_f32_16x16x32_bf16 v[24:27], v[136:139], v[160:163], v[24:27]
	v_mfma_f32_16x16x32_bf16 v[16:19], v[128:131], v[168:171], v[16:19]
	v_mfma_f32_16x16x32_bf16 v[8:11], v[136:139], v[168:171], v[8:11]
	v_mfma_f32_16x16x32_bf16 v[60:63], v[132:135], v[148:151], v[60:63]
	v_mfma_f32_16x16x32_bf16 v[56:59], v[140:143], v[148:151], v[56:59]
	v_mfma_f32_16x16x32_bf16 v[48:51], v[132:135], v[156:159], v[48:51]
	v_mfma_f32_16x16x32_bf16 v[40:43], v[140:143], v[156:159], v[40:43]
	v_mfma_f32_16x16x32_bf16 v[28:31], v[132:135], v[164:167], v[28:31]
	v_mfma_f32_16x16x32_bf16 v[24:27], v[140:143], v[164:167], v[24:27]
	v_mfma_f32_16x16x32_bf16 v[16:19], v[132:135], v[172:175], v[16:19]
	v_mfma_f32_16x16x32_bf16 v[8:11], v[140:143], v[172:175], v[8:11]
	s_setprio 0
	s_barrier
	s_add_u32 s30, s52, 0x158080
	s_addc_u32 s31, s53, 0
	s_add_i32 s14, s38, s24
	v_lshl_add_u64 v[128:129], s[30:31], 0, v[178:179]
	s_mov_b32 m0, s14
	s_nop 0
	global_load_lds_dwordx4 v[128:129], off
	v_lshl_add_u64 v[128:129], s[30:31], 0, v[194:195]
	s_add_i32 m0, s14, 0x2000
	s_nop 0
	global_load_lds_dwordx4 v[128:129], off
	s_waitcnt vmcnt(6)
	s_barrier
	s_setprio 1
	v_mfma_f32_16x16x32_bf16 v[52:55], v[200:203], v[144:147], v[52:55]
	v_mfma_f32_16x16x32_bf16 v[44:47], v[208:211], v[144:147], v[44:47]
	v_mfma_f32_16x16x32_bf16 v[36:39], v[200:203], v[152:155], v[36:39]
	v_mfma_f32_16x16x32_bf16 v[32:35], v[208:211], v[152:155], v[32:35]
	v_mfma_f32_16x16x32_bf16 v[20:23], v[200:203], v[160:163], v[20:23]
	v_mfma_f32_16x16x32_bf16 v[12:15], v[208:211], v[160:163], v[12:15]
	v_mfma_f32_16x16x32_bf16 v[4:7], v[200:203], v[168:171], v[4:7]
	v_mfma_f32_16x16x32_bf16 v[0:3], v[208:211], v[168:171], v[0:3]
	v_mfma_f32_16x16x32_bf16 v[52:55], v[204:207], v[148:151], v[52:55]
	v_mfma_f32_16x16x32_bf16 v[44:47], v[220:223], v[148:151], v[44:47]
	v_mfma_f32_16x16x32_bf16 v[36:39], v[204:207], v[156:159], v[36:39]
	v_mfma_f32_16x16x32_bf16 v[32:35], v[220:223], v[156:159], v[32:35]
	v_mfma_f32_16x16x32_bf16 v[20:23], v[204:207], v[164:167], v[20:23]
	v_mfma_f32_16x16x32_bf16 v[12:15], v[220:223], v[164:167], v[12:15]
	v_mfma_f32_16x16x32_bf16 v[4:7], v[204:207], v[172:175], v[4:7]
	v_mfma_f32_16x16x32_bf16 v[0:3], v[220:223], v[172:175], v[0:3]
	s_setprio 0
	s_barrier
	s_add_u32 s68, s68, 0x100
	s_addc_u32 s69, s69, 0
	s_cmp_ge_i32 vcc_lo, s67
	s_mov_b64 s[38:39], s[50:51]
	s_mov_b32 s52, vcc_lo
	s_cbranch_scc0 .LBB0_3919
	s_cmp_gt_i32 s28, 31
	s_mov_b64 s[38:39], 0x12000
	s_cbranch_scc1 .LBB0_3922
	s_ashr_i32 s14, s28, 3
	s_mul_hi_i32 s39, s14, 0x4800
	s_mul_i32 s38, s14, 0x4800

;     __device__ __forceinline__ void operator()(AccRef acc, const pg8::Unit& u, int wr, int wc, int fr, int fq) const {
;     ...
;         const int v = u.pm < 32 ? (u.pm >> 3) : 4;
;         f32x4 gv[2][2];
; #pragma unroll
;         for (int bj = 0; bj < 2; ++bj)
; #pragma unroll
;             for (int n = 0; n < 2; ++n) gv[bj][n] = *(const f32x4*)(gate + (size_t)v * MODW + col0 + bj * 128 + n * 16) * coef;
;         const bool part = u.part != 0;
;         float* base = part ? PART + ((size_t)u.ks * NCTX - NLAT) * DM : X;
; #pragma unroll
;         for (int ai = 0; ai < 2; ++ai)
; #pragma unroll
;             for (int mp = 0; mp < 2; ++mp) {
;                 f32x4 old[2][2][2];
;                 if (!part) {
; #pragma unroll
;                     for (int mm = 0; mm < 2; ++mm)
; #pragma unroll
;                         for (int bj = 0; bj < 2; ++bj)
; #pragma unroll
;                             for (int n = 0; n < 2; ++n) old[mm][bj][n] = *(const f32x4*)(SRC + (size_t)(row0 + ai * 128 + (2 * mp + mm) * 16) * DM + col0 + bj * 128 + n * 16);
;                 }
; #pragma unroll
;                 for (int mm = 0; mm < 2; ++mm)
; #pragma unroll
;                     for (int bj = 0; bj < 2; ++bj)
; #pragma unroll
;                         for (int n = 0; n < 2; ++n) { const int m = 2 * mp + mm; const f32x4 d = gv[bj][n] * acc[ai][bj][m][n];
;                             *(f32x4*)(base + (size_t)(row0 + ai * 128 + m * 16) * DM + col0 + bj * 128 + n * 16) = part ? d : old[mm][bj][n] + d; }
;             }
.LBB0_3926:
	s_ashr_i32 s41, s40, 31
	s_lshl_b64 s[28:29], s[40:41], 23
	v_readlane_b32 s30, v251, 46
	v_readlane_b32 s31, v251, 47
	s_add_u32 s14, s30, s28
	s_addc_u32 s28, s31, s29
	s_add_u32 s14, s14, 0xfc000000
	s_addc_u32 s30, s28, -1
	s_and_b64 s[28:29], exec, s[38:39]
	s_cselect_b32 s28, s83, s30
	s_cselect_b32 s14, s82, s14
	s_waitcnt vmcnt(0)
	v_pk_mul_f32 v[174:175], v[174:175], 0.5 op_sel_hi:[1,0]
	v_pk_mul_f32 v[172:173], v[172:173], 0.5 op_sel_hi:[1,0]
	v_mov_b32_e32 v210, s14
	v_mov_b32_e32 v211, s28
	v_lshl_add_u64 v[202:203], v[202:203], 2, v[210:211]
	v_pk_mul_f32 v[210:211], v[126:127], v[174:175]
	v_pk_mul_f32 v[220:221], v[124:125], v[172:173]
	v_pk_fma_f32 v[126:127], v[126:127], v[174:175], v[158:159]
	v_pk_fma_f32 v[124:125], v[124:125], v[172:173], v[156:157]
	v_pk_mul_f32 v[170:171], v[170:171], 0.5 op_sel_hi:[1,0]
	v_pk_mul_f32 v[168:169], v[168:169], 0.5 op_sel_hi:[1,0]
	v_lshl_add_u64 v[208:209], v[202:203], 0, v[208:209]
	v_cndmask_b32_e64 v127, v211, v127, s[38:39]
	v_cndmask_b32_e64 v126, v210, v126, s[38:39]
	v_cndmask_b32_e64 v125, v221, v125, s[38:39]
	v_cndmask_b32_e64 v124, v220, v124, s[38:39]
	global_store_dwordx4 v[208:209], v[124:127], off sc0 sc1
	v_pk_mul_f32 v[166:167], v[166:167], 0.5 op_sel_hi:[1,0]
	v_pk_mul_f32 v[164:165], v[164:165], 0.5 op_sel_hi:[1,0]
	v_pk_mul_f32 v[124:125], v[122:123], v[170:171]
	v_pk_mul_f32 v[126:127], v[120:121], v[168:169]
	v_pk_fma_f32 v[122:123], v[122:123], v[170:171], v[154:155]
	v_pk_fma_f32 v[120:121], v[120:121], v[168:169], v[152:153]
	v_cndmask_b32_e64 v123, v125, v123, s[38:39]
	v_cndmask_b32_e64 v122, v124, v122, s[38:39]
	v_cndmask_b32_e64 v121, v127, v121, s[38:39]
	v_cndmask_b32_e64 v120, v126, v120, s[38:39]
	global_store_dwordx4 v[208:209], v[120:123], off offset:64 sc0 sc1
	v_pk_mul_f32 v[162:163], v[162:163], 0.5 op_sel_hi:[1,0]
	v_pk_mul_f32 v[160:161], v[160:161], 0.5 op_sel_hi:[1,0]
	v_pk_mul_f32 v[120:121], v[118:119], v[166:167]
	v_pk_mul_f32 v[122:123], v[116:117], v[164:165]
	v_pk_fma_f32 v[118:119], v[118:119], v[166:167], v[150:151]
	v_pk_fma_f32 v[116:117], v[116:117], v[164:165], v[148:149]
	v_cndmask_b32_e64 v119, v121, v119, s[38:39]
	v_cndmask_b32_e64 v118, v120, v118, s[38:39]
	v_cndmask_b32_e64 v117, v123, v117, s[38:39]
	v_cndmask_b32_e64 v116, v122, v116, s[38:39]
	global_store_dwordx4 v[208:209], v[116:119], off offset:512 sc0 sc1
	s_mov_b64 s[52:53], -1
	s_andn2_b64 vcc, exec, s[50:51]
	v_pk_mul_f32 v[116:117], v[110:111], v[162:163]
	v_pk_mul_f32 v[118:119], v[108:109], v[160:161]
	v_pk_fma_f32 v[110:111], v[110:111], v[162:163], v[142:143]
	v_pk_fma_f32 v[108:109], v[108:109], v[160:161], v[140:141]
	v_cndmask_b32_e64 v111, v117, v111, s[38:39]
	v_cndmask_b32_e64 v110, v116, v110, s[38:39]
	v_cndmask_b32_e64 v109, v119, v109, s[38:39]
	v_cndmask_b32_e64 v108, v118, v108, s[38:39]
	global_store_dwordx4 v[208:209], v[108:111], off offset:576 sc0 sc1
	v_pk_mul_f32 v[118:119], v[112:113], v[172:173]
	v_pk_fma_f32 v[112:113], v[112:113], v[172:173], v[144:145]
	v_pk_mul_f32 v[108:109], v[114:115], v[174:175]
	v_pk_fma_f32 v[110:111], v[114:115], v[174:175], v[146:147]
	v_lshl_add_u64 v[116:117], v[202:203], 0, v[206:207]
	v_cndmask_b32_e64 v111, v109, v111, s[38:39]
	v_cndmask_b32_e64 v110, v108, v110, s[38:39]
	v_cndmask_b32_e64 v109, v119, v113, s[38:39]
	v_cndmask_b32_e64 v108, v118, v112, s[38:39]
	global_store_dwordx4 v[116:117], v[108:111], off sc0 sc1
	s_nop 1
	v_pk_mul_f32 v[108:109], v[106:107], v[170:171]
	v_pk_mul_f32 v[110:111], v[104:105], v[168:169]
	v_pk_fma_f32 v[106:107], v[106:107], v[170:171], v[138:139]
	v_pk_fma_f32 v[104:105], v[104:105], v[168:169], v[136:137]
	v_cndmask_b32_e64 v107, v109, v107, s[38:39]
	v_cndmask_b32_e64 v106, v108, v106, s[38:39]
	v_cndmask_b32_e64 v105, v111, v105, s[38:39]
	v_cndmask_b32_e64 v104, v110, v104, s[38:39]
	global_store_dwordx4 v[116:117], v[104:107], off offset:64 sc0 sc1
	s_nop 1
	v_pk_mul_f32 v[104:105], v[102:103], v[166:167]
	v_pk_mul_f32 v[106:107], v[100:101], v[164:165]
	v_pk_fma_f32 v[102:103], v[102:103], v[166:167], v[134:135]
	v_pk_fma_f32 v[100:101], v[100:101], v[164:165], v[132:133]
	v_cndmask_b32_e64 v103, v105, v103, s[38:39]
	v_cndmask_b32_e64 v102, v104, v102, s[38:39]
	v_cndmask_b32_e64 v101, v107, v101, s[38:39]
	v_cndmask_b32_e64 v100, v106, v100, s[38:39]
	global_store_dwordx4 v[116:117], v[100:103], off offset:512 sc0 sc1
	s_nop 1
	v_pk_mul_f32 v[100:101], v[98:99], v[162:163]
	v_pk_mul_f32 v[102:103], v[96:97], v[160:161]
	v_pk_fma_f32 v[98:99], v[98:99], v[162:163], v[130:131]
	v_pk_fma_f32 v[96:97], v[96:97], v[160:161], v[128:129]
	v_cndmask_b32_e64 v99, v101, v99, s[38:39]
	v_cndmask_b32_e64 v98, v100, v98, s[38:39]
	v_cndmask_b32_e64 v97, v103, v97, s[38:39]
	v_cndmask_b32_e64 v96, v102, v96, s[38:39]
	global_store_dwordx4 v[116:117], v[96:99], off offset:576 sc0 sc1
	v_or_b32_e32 v102, 32, v200
	v_or_b32_e32 v100, 48, v200
	v_cndmask_b32_e64 v96, 0, 1, s[50:51]
	v_cmp_ne_u32_e64 s[40:41], 1, v96
	v_ashrrev_i32_e32 v103, 31, v102
	v_ashrrev_i32_e32 v101, 31, v100
	s_cbranch_vccnz .LBB0_3928
	v_lshlrev_b64 v[98:99], 13, v[102:103]
	v_lshlrev_b64 v[96:97], 13, v[100:101]
	s_mov_b64 s[52:53], 0

;     __device__ __forceinline__ void operator()(AccRef acc, const pg8::Unit& u, int wr, int wc, int fr, int fq) const {
;     ...
; #pragma unroll
;                 for (int mm = 0; mm < 2; ++mm)
; #pragma unroll
;                     for (int bj = 0; bj < 2; ++bj)
; #pragma unroll
;                         for (int n = 0; n < 2; ++n) { const int m = 2 * mp + mm; const f32x4 d = gv[bj][n] * acc[ai][bj][m][n];
;                             *(f32x4*)(base + (size_t)(row0 + ai * 128 + m * 16) * DM + col0 + bj * 128 + n * 16) = part ? d : old[mm][bj][n] + d; }
;             }
.LBB0_3930:
	v_pk_mul_f32 v[100:101], v[94:95], v[174:175]
	v_pk_mul_f32 v[102:103], v[92:93], v[172:173]
	s_waitcnt vmcnt(0)
	v_pk_fma_f32 v[94:95], v[94:95], v[174:175], v[158:159]
	v_pk_fma_f32 v[92:93], v[92:93], v[172:173], v[156:157]
	v_lshl_add_u64 v[98:99], v[202:203], 0, v[98:99]
	v_cndmask_b32_e64 v95, v101, v95, s[38:39]
	v_cndmask_b32_e64 v94, v100, v94, s[38:39]
	v_cndmask_b32_e64 v93, v103, v93, s[38:39]
	v_cndmask_b32_e64 v92, v102, v92, s[38:39]
	global_store_dwordx4 v[98:99], v[92:95], off sc0 sc1
	s_mov_b64 s[50:51], -1
	s_and_b64 vcc, exec, s[40:41]
	v_pk_mul_f32 v[92:93], v[90:91], v[170:171]
	v_pk_mul_f32 v[94:95], v[88:89], v[168:169]
	v_pk_fma_f32 v[90:91], v[90:91], v[170:171], v[154:155]
	v_pk_fma_f32 v[88:89], v[88:89], v[168:169], v[152:153]
	v_cndmask_b32_e64 v91, v93, v91, s[38:39]
	v_cndmask_b32_e64 v90, v92, v90, s[38:39]
	v_cndmask_b32_e64 v89, v95, v89, s[38:39]
	v_cndmask_b32_e64 v88, v94, v88, s[38:39]
	global_store_dwordx4 v[98:99], v[88:91], off offset:64 sc0 sc1
	s_nop 1
	v_pk_mul_f32 v[88:89], v[86:87], v[166:167]
	v_pk_mul_f32 v[90:91], v[84:85], v[164:165]
	v_pk_fma_f32 v[86:87], v[86:87], v[166:167], v[150:151]
	v_pk_fma_f32 v[84:85], v[84:85], v[164:165], v[148:149]
	v_cndmask_b32_e64 v87, v89, v87, s[38:39]
	v_cndmask_b32_e64 v86, v88, v86, s[38:39]
	v_cndmask_b32_e64 v85, v91, v85, s[38:39]
	v_cndmask_b32_e64 v84, v90, v84, s[38:39]
	global_store_dwordx4 v[98:99], v[84:87], off offset:512 sc0 sc1
	s_nop 1
	v_pk_mul_f32 v[84:85], v[78:79], v[162:163]
	v_pk_mul_f32 v[86:87], v[76:77], v[160:161]
	v_pk_fma_f32 v[78:79], v[78:79], v[162:163], v[142:143]
	v_pk_fma_f32 v[76:77], v[76:77], v[160:161], v[140:141]
	v_cndmask_b32_e64 v79, v85, v79, s[38:39]
	v_cndmask_b32_e64 v78, v84, v78, s[38:39]
	v_cndmask_b32_e64 v77, v87, v77, s[38:39]
	v_cndmask_b32_e64 v76, v86, v76, s[38:39]
	global_store_dwordx4 v[98:99], v[76:79], off offset:576 sc0 sc1
	v_pk_mul_f32 v[86:87], v[80:81], v[172:173]
	v_pk_fma_f32 v[80:81], v[80:81], v[172:173], v[144:145]
	v_pk_mul_f32 v[76:77], v[82:83], v[174:175]
	v_pk_fma_f32 v[78:79], v[82:83], v[174:175], v[146:147]
	v_lshl_add_u64 v[84:85], v[202:203], 0, v[96:97]
	v_cndmask_b32_e64 v79, v77, v79, s[38:39]
	v_cndmask_b32_e64 v78, v76, v78, s[38:39]
	v_cndmask_b32_e64 v77, v87, v81, s[38:39]
	v_cndmask_b32_e64 v76, v86, v80, s[38:39]
	global_store_dwordx4 v[84:85], v[76:79], off sc0 sc1
	s_nop 1
	v_pk_mul_f32 v[76:77], v[74:75], v[170:171]
	v_pk_mul_f32 v[78:79], v[72:73], v[168:169]
	v_pk_fma_f32 v[74:75], v[74:75], v[170:171], v[138:139]
	v_pk_fma_f32 v[72:73], v[72:73], v[168:169], v[136:137]
	v_cndmask_b32_e64 v75, v77, v75, s[38:39]
	v_cndmask_b32_e64 v74, v76, v74, s[38:39]
	v_cndmask_b32_e64 v73, v79, v73, s[38:39]
	v_cndmask_b32_e64 v72, v78, v72, s[38:39]
	global_store_dwordx4 v[84:85], v[72:75], off offset:64 sc0 sc1
	s_nop 1
	v_pk_mul_f32 v[72:73], v[70:71], v[166:167]
	v_pk_mul_f32 v[74:75], v[68:69], v[164:165]
	v_pk_fma_f32 v[70:71], v[70:71], v[166:167], v[134:135]
	v_pk_fma_f32 v[68:69], v[68:69], v[164:165], v[132:133]
	v_cndmask_b32_e64 v71, v73, v71, s[38:39]
	v_cndmask_b32_e64 v70, v72, v70, s[38:39]
	v_cndmask_b32_e64 v69, v75, v69, s[38:39]
	v_cndmask_b32_e64 v68, v74, v68, s[38:39]
	global_store_dwordx4 v[84:85], v[68:71], off offset:512 sc0 sc1
	s_nop 1
	v_pk_mul_f32 v[68:69], v[66:67], v[162:163]
	v_pk_fma_f32 v[66:67], v[66:67], v[162:163], v[130:131]
	v_pk_mul_f32 v[70:71], v[64:65], v[160:161]
	v_pk_fma_f32 v[64:65], v[64:65], v[160:161], v[128:129]
	v_cndmask_b32_e64 v66, v68, v66, s[38:39]
	v_add_u32_e32 v68, 0x80, v200
	v_cndmask_b32_e64 v67, v69, v67, s[38:39]
	v_cndmask_b32_e64 v65, v71, v65, s[38:39]
	v_cndmask_b32_e64 v64, v70, v64, s[38:39]
	v_ashrrev_i32_e32 v69, 31, v68
	global_store_dwordx4 v[84:85], v[64:67], off offset:576 sc0 sc1
	s_cbranch_vccnz .LBB0_3932
	s_nop 0
	v_lshlrev_b64 v[64:65], 13, v[200:201]
	s_mov_b64 s[28:29], 0x120000
	v_lshlrev_b64 v[66:67], 13, v[68:69]
	v_lshl_add_u64 v[64:65], v[64:65], 0, s[28:29]
	s_mov_b64 s[50:51], 0

;     __device__ __forceinline__ void operator()(AccRef acc, const pg8::Unit& u, int wr, int wc, int fr, int fq) const {
;     ...
; #pragma unroll
;                 for (int mm = 0; mm < 2; ++mm)
; #pragma unroll
;                     for (int bj = 0; bj < 2; ++bj)
; #pragma unroll
;                         for (int n = 0; n < 2; ++n) { const int m = 2 * mp + mm; const f32x4 d = gv[bj][n] * acc[ai][bj][m][n];
;                             *(f32x4*)(base + (size_t)(row0 + ai * 128 + m * 16) * DM + col0 + bj * 128 + n * 16) = part ? d : old[mm][bj][n] + d; }
;             }
.LBB0_3934:
	v_pk_mul_f32 v[68:69], v[62:63], v[174:175]
	v_pk_mul_f32 v[70:71], v[60:61], v[172:173]
	s_waitcnt vmcnt(0)
	v_pk_fma_f32 v[62:63], v[62:63], v[174:175], v[158:159]
	v_pk_fma_f32 v[60:61], v[60:61], v[172:173], v[156:157]
	v_lshl_add_u64 v[66:67], v[202:203], 0, v[66:67]
	v_cndmask_b32_e64 v63, v69, v63, s[38:39]
	v_cndmask_b32_e64 v62, v68, v62, s[38:39]
	v_cndmask_b32_e64 v61, v71, v61, s[38:39]
	v_cndmask_b32_e64 v60, v70, v60, s[38:39]
	global_store_dwordx4 v[66:67], v[60:63], off sc0 sc1
	s_mov_b64 s[50:51], -1
	s_and_b64 vcc, exec, s[40:41]
	v_pk_mul_f32 v[60:61], v[58:59], v[170:171]
	v_pk_mul_f32 v[62:63], v[56:57], v[168:169]
	v_pk_fma_f32 v[58:59], v[58:59], v[170:171], v[154:155]
	v_pk_fma_f32 v[56:57], v[56:57], v[168:169], v[152:153]
	v_cndmask_b32_e64 v59, v61, v59, s[38:39]
	v_cndmask_b32_e64 v58, v60, v58, s[38:39]
	v_cndmask_b32_e64 v57, v63, v57, s[38:39]
	v_cndmask_b32_e64 v56, v62, v56, s[38:39]
	global_store_dwordx4 v[66:67], v[56:59], off offset:64 sc0 sc1
	s_nop 1
	v_pk_mul_f32 v[56:57], v[54:55], v[166:167]
	v_pk_mul_f32 v[58:59], v[52:53], v[164:165]
	v_pk_fma_f32 v[54:55], v[54:55], v[166:167], v[150:151]
	v_pk_fma_f32 v[52:53], v[52:53], v[164:165], v[148:149]
	v_cndmask_b32_e64 v55, v57, v55, s[38:39]
	v_cndmask_b32_e64 v54, v56, v54, s[38:39]
	v_cndmask_b32_e64 v53, v59, v53, s[38:39]
	v_cndmask_b32_e64 v52, v58, v52, s[38:39]
	global_store_dwordx4 v[66:67], v[52:55], off offset:512 sc0 sc1
	s_nop 1
	v_pk_mul_f32 v[52:53], v[46:47], v[162:163]
	v_pk_mul_f32 v[54:55], v[44:45], v[160:161]
	v_pk_fma_f32 v[46:47], v[46:47], v[162:163], v[142:143]
	v_pk_fma_f32 v[44:45], v[44:45], v[160:161], v[140:141]
	v_cndmask_b32_e64 v47, v53, v47, s[38:39]
	v_cndmask_b32_e64 v46, v52, v46, s[38:39]
	v_cndmask_b32_e64 v45, v55, v45, s[38:39]
	v_cndmask_b32_e64 v44, v54, v44, s[38:39]
	global_store_dwordx4 v[66:67], v[44:47], off offset:576 sc0 sc1
	v_pk_mul_f32 v[54:55], v[48:49], v[172:173]
	v_pk_fma_f32 v[48:49], v[48:49], v[172:173], v[144:145]
	v_pk_mul_f32 v[44:45], v[50:51], v[174:175]
	v_pk_fma_f32 v[46:47], v[50:51], v[174:175], v[146:147]
	v_lshl_add_u64 v[52:53], v[202:203], 0, v[64:65]
	v_cndmask_b32_e64 v47, v45, v47, s[38:39]
	v_cndmask_b32_e64 v46, v44, v46, s[38:39]
	v_cndmask_b32_e64 v45, v55, v49, s[38:39]
	v_cndmask_b32_e64 v44, v54, v48, s[38:39]
	global_store_dwordx4 v[52:53], v[44:47], off sc0 sc1
	s_nop 1
	v_pk_mul_f32 v[44:45], v[42:43], v[170:171]
	v_pk_mul_f32 v[46:47], v[40:41], v[168:169]
	v_pk_fma_f32 v[42:43], v[42:43], v[170:171], v[138:139]
	v_pk_fma_f32 v[40:41], v[40:41], v[168:169], v[136:137]
	v_cndmask_b32_e64 v43, v45, v43, s[38:39]
	v_cndmask_b32_e64 v42, v44, v42, s[38:39]
	v_cndmask_b32_e64 v41, v47, v41, s[38:39]
	v_cndmask_b32_e64 v40, v46, v40, s[38:39]
	global_store_dwordx4 v[52:53], v[40:43], off offset:64 sc0 sc1
	s_nop 1
	v_pk_mul_f32 v[40:41], v[38:39], v[166:167]
	v_pk_mul_f32 v[42:43], v[36:37], v[164:165]
	v_pk_fma_f32 v[38:39], v[38:39], v[166:167], v[134:135]
	v_pk_fma_f32 v[36:37], v[36:37], v[164:165], v[132:133]
	v_cndmask_b32_e64 v39, v41, v39, s[38:39]
	v_cndmask_b32_e64 v38, v40, v38, s[38:39]
	v_cndmask_b32_e64 v37, v43, v37, s[38:39]
	v_cndmask_b32_e64 v36, v42, v36, s[38:39]
	global_store_dwordx4 v[52:53], v[36:39], off offset:512 sc0 sc1
	s_nop 1
	v_pk_mul_f32 v[36:37], v[34:35], v[162:163]
	v_pk_fma_f32 v[34:35], v[34:35], v[162:163], v[130:131]
	v_pk_mul_f32 v[38:39], v[32:33], v[160:161]
	v_pk_fma_f32 v[32:33], v[32:33], v[160:161], v[128:129]
	v_cndmask_b32_e64 v34, v36, v34, s[38:39]
	v_add_u32_e32 v36, 0xa0, v200
	v_cndmask_b32_e64 v35, v37, v35, s[38:39]
	v_cndmask_b32_e64 v33, v39, v33, s[38:39]
	v_cndmask_b32_e64 v32, v38, v32, s[38:39]
	v_ashrrev_i32_e32 v37, 31, v36
	global_store_dwordx4 v[52:53], v[32:35], off offset:576 sc0 sc1
	s_cbranch_vccnz .LBB0_3936
	s_nop 0
	v_lshlrev_b64 v[32:33], 13, v[200:201]
	s_mov_b64 s[28:29], 0x160000
	v_lshlrev_b64 v[34:35], 13, v[36:37]
	v_lshl_add_u64 v[32:33], v[32:33], 0, s[28:29]
	s_mov_b64 s[50:51], 0

; __device__ __forceinline__ int otid() { int t = threadIdx.x; asm volatile("" : "+v"(t)); return t; }
; __device__ __forceinline__ void final_phase(const float* __restrict__ X, float* __restrict__ out, const float* __restrict__ gain) {
;     const int tid_ = otid(); const int lane = tid_ & 63, gw = blockIdx.x * 8 + (tid_ >> 6), nw = gridDim.x * 8;
;     for (int row = gw; row < NLAT; row += nw) {
;         const float* xr = X + (size_t)row * DM;
;         f32x4 x[8]; float ss = 0.f;
; #pragma unroll
;         for (int i = 0; i < 8; ++i) { x[i] = *(const f32x4*)(xr + (i * 64 + lane) * 4); ss += x[i][0] * x[i][0] + x[i][1] * x[i][1] + x[i][2] * x[i][2] + x[i][3] * x[i][3]; }
;         ss = wave_sum(ss);
;         const float r = rsqrtf(ss * (1.f / DM) + EPS);
; #pragma unroll
;         for (int i = 0; i < 8; ++i) { const int c = (i * 64 + lane) * 4; *(f32x4*)(out + (size_t)row * DM + c) = x[i] * r * *(const f32x4*)(gain + c); }
;     }
.LBB0_3998:
	v_lshl_add_u64 v[54:55], v[36:37], 0, v[34:35]
	v_add_co_u32_e64 v82, s[0:1], s5, v54
	v_add_co_u32_e32 v80, vcc, 0x142dd000, v54
	s_nop 0
	v_addc_co_u32_e64 v83, s[0:1], 0, v55, s[0:1]
	global_load_dwordx4 v[46:49], v[82:83], off
	global_load_dwordx4 v[50:53], v[82:83], off offset:1024
	v_addc_co_u32_e32 v81, vcc, 0, v55, vcc
	global_load_dwordx4 v[54:57], v[82:83], off offset:2048
	global_load_dwordx4 v[58:61], v[80:81], off
	global_load_dwordx4 v[62:65], v[80:81], off offset:1024
	global_load_dwordx4 v[66:69], v[80:81], off offset:2048
	global_load_dwordx4 v[70:73], v[80:81], off offset:3072
	global_load_dwordx4 v[74:77], v[82:83], off offset:3072
	v_lshl_add_u64 v[78:79], v[38:39], 0, v[34:35]
	v_add_co_u32_e64 v84, s[0:1], s4, v78
	v_add_u32_e32 v32, s64, v32
	s_nop 0
	v_addc_co_u32_e64 v85, s[0:1], 0, v79, s[0:1]
	v_cmp_lt_i32_e64 s[0:1], s7, v32
	v_lshl_add_u64 v[36:37], v[36:37], 0, s[8:9]
	v_lshl_add_u64 v[38:39], v[38:39], 0, s[8:9]
	s_or_b64 s[2:3], s[0:1], s[2:3]
	s_waitcnt vmcnt(0)
	v_mov_b32_e32 v92, v55
	v_mul_f32_e32 v98, v59, v59
	v_mul_f32_e32 v99, v63, v63
	v_mov_b32_e32 v82, v47
	v_mov_b32_e32 v83, v51
	v_mul_f32_e32 v100, v67, v67
	v_fmac_f32_e32 v98, v58, v58
	v_fmac_f32_e32 v99, v62, v62
	v_mov_b32_e32 v80, v46
	v_mov_b32_e32 v81, v50
	v_mul_f32_e32 v101, v71, v71
	v_pk_mul_f32 v[82:83], v[82:83], v[82:83]
	v_fmac_f32_e32 v100, v66, v66
	v_fmac_f32_e32 v98, v60, v60
	v_fmac_f32_e32 v99, v64, v64
	v_mov_b32_e32 v86, v48
	v_mov_b32_e32 v87, v52
	v_fmac_f32_e32 v101, v70, v70
	v_pk_fma_f32 v[80:81], v[80:81], v[80:81], v[82:83]
	v_fmac_f32_e32 v100, v68, v68
	v_fmac_f32_e32 v98, v61, v61
	v_fmac_f32_e32 v99, v65, v65
	v_mov_b32_e32 v93, v75
	v_fmac_f32_e32 v101, v72, v72
	v_pk_fma_f32 v[80:81], v[86:87], v[86:87], v[80:81]
	v_fmac_f32_e32 v100, v69, v69
	v_add_f32_e32 v86, v98, v99
	v_mov_b32_e32 v88, v49
	v_mov_b32_e32 v89, v53
	v_mov_b32_e32 v90, v54
	v_mov_b32_e32 v91, v74
	v_pk_mul_f32 v[92:93], v[92:93], v[92:93]
	v_fmac_f32_e32 v101, v73, v73
	v_add_f32_e32 v86, v86, v100
	v_mov_b32_e32 v94, v56
	v_mov_b32_e32 v95, v76
	v_pk_fma_f32 v[82:83], v[90:91], v[90:91], v[92:93]
	v_pk_fma_f32 v[80:81], v[88:89], v[88:89], v[80:81]
	v_add_f32_e32 v86, v86, v101
	v_mov_b32_e32 v96, v57
	v_mov_b32_e32 v97, v77
	v_pk_fma_f32 v[82:83], v[94:95], v[94:95], v[82:83]
	v_add_f32_e32 v80, v86, v80
	v_pk_fma_f32 v[82:83], v[96:97], v[96:97], v[82:83]
	v_add_f32_e32 v80, v80, v81
	v_add_f32_e32 v80, v80, v82
	v_add_f32_e32 v80, v80, v83
	ds_bpermute_b32 v81, v40, v80
	s_waitcnt lgkmcnt(0)
	v_add_f32_e32 v80, v80, v81
	ds_bpermute_b32 v81, v41, v80
	s_waitcnt lgkmcnt(0)
	v_add_f32_e32 v80, v80, v81
	ds_bpermute_b32 v81, v42, v80
	s_waitcnt lgkmcnt(0)
	v_add_f32_e32 v80, v80, v81
	ds_bpermute_b32 v81, v43, v80
	s_waitcnt lgkmcnt(0)
	v_add_f32_e32 v80, v80, v81
	ds_bpermute_b32 v81, v44, v80
	s_waitcnt lgkmcnt(0)
	v_add_f32_e32 v80, v80, v81
	ds_bpermute_b32 v81, v45, v80
	s_waitcnt lgkmcnt(0)
	v_add_f32_e32 v80, v80, v81
	v_fmamk_f32 v80, v80, 0x3a000000, v33
	v_mul_f32_e32 v81, 0x4b800000, v80
	v_cmp_gt_f32_e32 vcc, s6, v80
	s_nop 1
	v_cndmask_b32_e32 v80, v80, v81, vcc
	v_rsq_f32_e32 v80, v80
	s_nop 0
	v_mul_f32_e32 v81, 0x45800000, v80
	v_cndmask_b32_e32 v80, v80, v81, vcc
	v_pk_mul_f32 v[58:59], v[58:59], v[80:81] op_sel_hi:[1,0]
	v_pk_mul_f32 v[60:61], v[60:61], v[80:81] op_sel_hi:[1,0]
	v_pk_mul_f32 v[62:63], v[62:63], v[80:81] op_sel_hi:[1,0]
	v_pk_mul_f32 v[64:65], v[64:65], v[80:81] op_sel_hi:[1,0]
	v_pk_mul_f32 v[66:67], v[66:67], v[80:81] op_sel_hi:[1,0]
	v_pk_mul_f32 v[68:69], v[68:69], v[80:81] op_sel_hi:[1,0]
	v_pk_mul_f32 v[70:71], v[70:71], v[80:81] op_sel_hi:[1,0]
	v_pk_mul_f32 v[72:73], v[72:73], v[80:81] op_sel_hi:[1,0]
	v_pk_mul_f32 v[82:83], v[46:47], v[80:81] op_sel_hi:[1,0]
	v_pk_mul_f32 v[86:87], v[48:49], v[80:81] op_sel_hi:[1,0]
	v_pk_mul_f32 v[88:89], v[50:51], v[80:81] op_sel_hi:[1,0]
	v_pk_mul_f32 v[90:91], v[52:53], v[80:81] op_sel_hi:[1,0]
	v_pk_mul_f32 v[92:93], v[54:55], v[80:81] op_sel_hi:[1,0]
	v_pk_mul_f32 v[94:95], v[56:57], v[80:81] op_sel_hi:[1,0]
	v_pk_mul_f32 v[74:75], v[74:75], v[80:81] op_sel_hi:[1,0]
	v_pk_mul_f32 v[76:77], v[76:77], v[80:81] op_sel_hi:[1,0]
	v_pk_mul_f32 v[48:49], v[2:3], v[60:61]
	v_pk_mul_f32 v[46:47], v[0:1], v[58:59]
	v_pk_mul_f32 v[52:53], v[6:7], v[64:65]
	v_pk_mul_f32 v[50:51], v[4:5], v[62:63]
	v_pk_mul_f32 v[56:57], v[10:11], v[68:69]
	v_pk_mul_f32 v[54:55], v[8:9], v[66:67]
	v_pk_mul_f32 v[60:61], v[14:15], v[72:73]
	v_pk_mul_f32 v[58:59], v[12:13], v[70:71]
	v_pk_mul_f32 v[64:65], v[18:19], v[86:87]
	v_pk_mul_f32 v[62:63], v[16:17], v[82:83]
	v_pk_mul_f32 v[68:69], v[22:23], v[90:91]
	v_pk_mul_f32 v[66:67], v[20:21], v[88:89]
	v_pk_mul_f32 v[72:73], v[26:27], v[94:95]
	v_pk_mul_f32 v[70:71], v[24:25], v[92:93]
	v_pk_mul_f32 v[76:77], v[30:31], v[76:77]
	v_pk_mul_f32 v[74:75], v[28:29], v[74:75]
	global_store_dwordx4 v[78:79], v[46:49], off sc0 sc1
	global_store_dwordx4 v[78:79], v[50:53], off offset:1024 sc0 sc1
	global_store_dwordx4 v[78:79], v[54:57], off offset:2048 sc0 sc1
	global_store_dwordx4 v[78:79], v[58:61], off offset:3072 sc0 sc1
	global_store_dwordx4 v[84:85], v[62:65], off sc0 sc1
	global_store_dwordx4 v[84:85], v[66:69], off offset:1024 sc0 sc1
	global_store_dwordx4 v[84:85], v[70:73], off offset:2048 sc0 sc1
	global_store_dwordx4 v[84:85], v[74:77], off offset:3072 sc0 sc1
	s_andn2_b64 exec, exec, s[2:3]
	s_cbranch_execnz .LBB0_3998
